# first K-iteration with C=0 MFMAs replaces accumulator zeroing in all 4 GEMM bodies; first seam uses the XCD barrier
# speedup vs baseline: 1.0185x; 1.0010x over previous
; __device__ __forceinline__ unsigned xb_ld(unsigned* p)              { return __hip_atomic_load(p, __ATOMIC_RELAXED, __HIP_MEMORY_SCOPE_AGENT); }
; __device__ __forceinline__ unsigned xb_add(unsigned* p, unsigned v) { return __hip_atomic_fetch_add(p, v, __ATOMIC_RELAXED, __HIP_MEMORY_SCOPE_AGENT); }
; #define XB_SPIN(cond, bar) do { unsigned _sp = 0; while (cond) { __builtin_amdgcn_s_sleep(1); \
;     if ((++_sp & 255u) == 0u) { if (xb_ld(&(bar)[XB_TMO])) break; if (_sp > XB_SPIN_CAP) { atomicAdd(&(bar)[XB_TMO], 1u); break; } } } } while (0)
; __device__ __forceinline__ void xcd_barrier_complete(unsigned* bar, unsigned x, unsigned& nloc, unsigned& nx) {
;     const unsigned G = gridDim.x * gridDim.y * gridDim.z;
;     unsigned sum, cnt, mine, sp = 0u;
;     for (;;) {
;         sum = 0u; cnt = 0u; mine = 0u;
; #pragma unroll
;         for (unsigned j = 0; j < 16; ++j) { const unsigned c = xb_ld(&bar[XB_XCNT(j)]); sum += c; cnt += (c > 0u) ? 1u : 0u; mine = (j == x) ? c : mine; }
;         if (sum == G) break;
;         __builtin_amdgcn_s_sleep(1);
;         if ((++sp & 255u) == 0u) { if (xb_ld(&bar[XB_TMO])) break; if (sp > XB_SPIN_CAP) { atomicAdd(&bar[XB_TMO], 1u); break; } }
;     }
;     nloc = mine > 0u ? mine : 1u; nx = cnt > 0u ? cnt : 1u;
; }
; __device__ __forceinline__ void xcd_barrier(const XcdBarrier& b) {
;     asm volatile("s_waitcnt vmcnt(0)" ::: "memory");
;     __syncthreads();
;     if (threadIdx.x == 0) {
;         unsigned* bar = b.bar;
;         __builtin_amdgcn_s_waitcnt(0);
;         unsigned nloc = b.st[0], nx = b.st[1];
;         if (nloc == 0u) { xcd_barrier_complete(bar, b.x, nloc, nx); b.st[0] = nloc; b.st[1] = nx; }
;         const unsigned old = xb_add(&bar[XB_XSUB(b.x)], 1u);
;         const unsigned gen = old / nloc;
;         if (old + 1u == (gen + 1u) * nloc) {
;             __builtin_amdgcn_fence(__ATOMIC_RELEASE, "agent");
;             asm volatile("s_waitcnt vmcnt(0)" ::: "memory");
;             const unsigned og = xb_add(&bar[XB_TOP], 1u);
;             const unsigned tg = og / nx;
;             if (og + 1u == (tg + 1u) * nx) xb_add(&bar[XB_TOPGEN], 1u);
;             else XB_SPIN(xb_ld(&bar[XB_TOPGEN]) == tg, bar);
;             __builtin_amdgcn_fence(__ATOMIC_ACQUIRE, "agent");
;             xb_add(&bar[XB_XGEN(b.x)], 1u);
.LBB0_6:
	s_add_i32 s4, s31, 2
	s_add_u32 s94, s92, 0x38200
	s_addc_u32 s95, s93, 0
	v_writelane_b32 v249, s4, 14
	s_add_u32 s4, s92, 0x38400
	s_addc_u32 s5, s93, 0
	v_writelane_b32 v249, s4, 15
	v_mov_b32_e32 v1, 0x1080
	s_load_dwordx16 s[60:75], s[0:1], 0x0
	v_writelane_b32 v249, s5, 16
	s_add_u32 s4, s92, 0x38500
	s_addc_u32 s5, s93, 0
	v_writelane_b32 v249, s4, 17
	v_mov_b32_e32 v198, 1
	v_mov_b32_e32 v162, 0x358637bd
	v_writelane_b32 v249, s5, 18
	s_add_u32 s4, s92, 0x38600
	s_addc_u32 s5, s93, 0
	v_writelane_b32 v249, s4, 19
	v_mov_b32_e32 v192, 0xc0135761
	v_mov_b32_e32 v199, 0x7f800000
	v_writelane_b32 v249, s5, 20
	s_add_u32 s4, s92, 0x38700
	s_addc_u32 s5, s93, 0
	v_writelane_b32 v249, s4, 21
	v_mov_b32_e32 v200, 0x7fc00000
	v_mov_b32_e32 v201, 0xff800000
	v_writelane_b32 v249, s5, 22
	s_add_u32 s4, s92, 0x38800
	s_addc_u32 s5, s93, 0
	v_writelane_b32 v249, s4, 23
	v_mov_b32_e32 v168, 0xbab6061a
	v_mov_b32_e32 v163, 0x3c08839e
	v_writelane_b32 v249, s5, 24
	s_add_u32 s4, s92, 0x38900
	s_addc_u32 s5, s93, 0
	v_writelane_b32 v249, s4, 25
	v_mov_b32_e32 v248, 0x60
	s_nop 0
	v_writelane_b32 v249, s5, 26
	s_add_u32 s4, s92, 0x38a00
	s_addc_u32 s5, s93, 0
	v_writelane_b32 v249, s4, 27
	s_nop 1
	v_writelane_b32 v249, s5, 28
	s_add_u32 s4, s92, 0x38b00
	s_addc_u32 s5, s93, 0
	v_writelane_b32 v249, s4, 29
	s_nop 1
	v_writelane_b32 v249, s5, 30
	s_add_u32 s4, s92, 0x38c00
	s_addc_u32 s5, s93, 0
	v_writelane_b32 v249, s4, 31
	s_nop 1
	v_writelane_b32 v249, s5, 32
	s_add_u32 s4, s92, 0x38d00
	s_addc_u32 s5, s93, 0
	v_writelane_b32 v249, s4, 33
	s_nop 1
	v_writelane_b32 v249, s5, 34
	s_add_u32 s4, s92, 0x38e00
	s_addc_u32 s5, s93, 0
	v_writelane_b32 v249, s4, 35
	s_nop 1
	v_writelane_b32 v249, s5, 36
	s_add_u32 s4, s92, 0x38f00
	s_addc_u32 s5, s93, 0
	v_writelane_b32 v249, s4, 37
	s_nop 1
	v_writelane_b32 v249, s5, 38
	s_add_u32 s4, s92, 0x39000
	s_addc_u32 s5, s93, 0
	v_writelane_b32 v249, s4, 39
	s_nop 1
	v_writelane_b32 v249, s5, 40
	s_add_u32 s4, s92, 0x39100
	s_addc_u32 s5, s93, 0
	v_writelane_b32 v249, s4, 41
	s_nop 1
	v_writelane_b32 v249, s5, 42
	s_add_u32 s4, s92, 0x39200
	s_addc_u32 s5, s93, 0
	v_writelane_b32 v249, s4, 43
	s_nop 1
	v_writelane_b32 v249, s5, 44
	s_add_u32 s4, s92, 0x39300
	s_addc_u32 s5, s93, 0
	v_writelane_b32 v249, s4, 45
	s_nop 1
	v_writelane_b32 v249, s5, 46
	s_add_u32 s4, s92, 0x3b400
	s_addc_u32 s5, s93, 0
	v_writelane_b32 v249, s4, 47
	s_nop 1
	v_writelane_b32 v249, s5, 48
	s_add_u32 s4, s92, 0x3b500
	s_addc_u32 s5, s93, 0
	v_writelane_b32 v249, s4, 49
	s_cmp_gt_i32 s2, 7
	s_nop 0
	v_writelane_b32 v249, s5, 50
	s_cselect_b64 s[4:5], -1, 0
	v_writelane_b32 v249, s4, 51
	s_nop 1
	v_writelane_b32 v249, s5, 52
	s_add_u32 s4, s92, 0x580b900
	s_addc_u32 s5, s93, 0
	s_add_u32 s16, s92, 0x1580b900
	v_writelane_b32 v249, s4, 53
	s_addc_u32 s17, s93, 0
	s_nop 0
	v_writelane_b32 v249, s5, 54
	s_add_u32 s4, s92, 0x1da0b900
	v_writelane_b32 v249, s4, 55
	s_addc_u32 s4, s93, 0
	s_lshl_b32 s18, s96, 4
	s_lshl_b32 s19, s2, 4
	v_writelane_b32 v249, s4, 56
	s_add_u32 s4, s92, 0x3b800
	s_addc_u32 s5, s93, 0
	v_writelane_b32 v249, s4, 57
	s_cmpk_lt_i32 s2, 0x800
	s_nop 0
	v_writelane_b32 v249, s5, 58
	s_cselect_b64 s[4:5], -1, 0
	v_writelane_b32 v249, s4, 59
	s_add_u32 s6, s92, 0xd80b900
	s_addc_u32 s7, s93, 0
	v_writelane_b32 v249, s5, 60
	s_and_b32 s4, s19, 0xffffff80
	v_writelane_b32 v249, s4, 61
	s_lshl_b32 s4, s2, 9
	v_writelane_b32 v249, s4, 62
	s_and_b32 s4, s4, 0xe00
	s_add_u32 s4, s6, s4
	v_writelane_b32 v249, s6, 63
	s_addc_u32 s5, s7, 0
	v_readlane_b32 s76, v249, 0
	v_writelane_b32 v250, s7, 0
	v_writelane_b32 v250, s4, 1
	v_readlane_b32 s82, v249, 6
	v_readlane_b32 s83, v249, 7
	v_writelane_b32 v250, s5, 2
	s_lshl_b32 s4, s2, 3
	v_writelane_b32 v250, s4, 3
	s_lshl_b32 s4, s96, 3
	s_add_u32 s20, s92, 0x4c0b900
	v_writelane_b32 v250, s4, 4
	s_addc_u32 s21, s93, 0
	s_ashr_i32 s4, s2, 31
	v_writelane_b32 v250, s4, 5
	s_lshr_b32 s4, s4, 29
	s_add_i32 s4, s2, s4
	s_ashr_i32 s22, s4, 3
	s_and_b32 s4, s4, -8
	s_sub_i32 s23, s2, s4
	s_lshl_b32 s6, s23, 8
	s_ashr_i32 s4, s96, 31
	v_writelane_b32 v250, s4, 6
	s_add_u32 s4, s92, 0xb98b900
	s_addc_u32 s5, s93, 0
	v_writelane_b32 v250, s4, 7
	v_readlane_b32 s77, v249, 1
	v_readlane_b32 s78, v249, 2
	v_writelane_b32 v250, s5, 8
	s_add_u32 s4, s92, 0xda0b900
	s_addc_u32 s5, s93, 0
	v_writelane_b32 v250, s4, 9
	v_readlane_b32 s79, v249, 3
	v_readlane_b32 s80, v249, 4
	v_writelane_b32 v250, s5, 10
	s_add_u32 s4, s92, 0xfa8b900
	s_addc_u32 s5, s93, 0
	v_writelane_b32 v250, s4, 11
	v_readlane_b32 s81, v249, 5
	s_nop 0
	v_writelane_b32 v250, s5, 12
	s_add_u32 s4, s92, 0x11b0b900
	s_addc_u32 s5, s93, 0
	s_add_u32 s58, s92, 0x1dc0b900
	s_addc_u32 s59, s93, 0
	v_writelane_b32 v250, s4, 13
	s_cmpk_lt_i32 s2, 0x400
	s_nop 0
	v_writelane_b32 v250, s5, 14
	s_cselect_b64 s[4:5], -1, 0
	v_writelane_b32 v250, s4, 15
	s_nop 1
	v_writelane_b32 v250, s5, 16
	s_add_u32 s4, s92, 0x1e01b900
	s_addc_u32 s5, s93, 0
	v_writelane_b32 v250, s4, 17
	s_nop 1
	v_writelane_b32 v250, s5, 18
	s_add_u32 s4, s92, 0x1990b900
	s_addc_u32 s5, s93, 0
	v_writelane_b32 v250, s4, 19
	s_cmpk_lt_i32 s2, 0x100
	s_nop 0
	v_writelane_b32 v250, s5, 20
	s_cselect_b64 s[4:5], -1, 0
	v_writelane_b32 v250, s4, 21
	s_nop 1
	v_writelane_b32 v250, s5, 22
	s_add_u32 s4, s92, 0x788b900
	s_addc_u32 s5, s93, 0
	v_writelane_b32 v250, s4, 23
	s_nop 1
	v_writelane_b32 v250, s5, 24
	s_add_u32 s4, s92, 0x990b900
	s_addc_u32 s5, s93, 0
	v_writelane_b32 v250, s4, 25
	s_nop 1
	v_writelane_b32 v250, s5, 26
	s_add_i32 s5, s96, 0xfff
	s_add_u32 s24, s92, 0x13b8b900
	s_addc_u32 s25, s93, 0
	s_cmpk_lt_i32 s2, 0x820
	s_mul_hi_i32 s4, s2, 0x7e07e07f
; __device__ void ph_convert(const P& p, LAS unsigned char* lds, int layer, int wid, int nwg, int v_lo, int v_hi) {
;     ...
;     const int nv = min(v_hi, layer ? 2880 : 2720);
;     ...
;     int v = v_lo + wid;
;     if (v < nv) { const int t = CONV_REMAP(v); CONV_LOAD(t) }
; __device__ __forceinline__ int ml_chunk_row0(int b, int d, int j) {
;     if (j < 2) { const int oc = d ? 1 - j : j; return T + b * 256 + oc * 128; }
;     const int oc = d ? 129 - j : j - 2; return (b << 14) + oc * 128;
; }
	s_cselect_b64 s[8:9], -1, 0
	s_lshr_b32 s7, s4, 31
	s_ashr_i32 s4, s4, 6
	s_add_i32 s10, s4, s7
	s_mul_i32 s4, s10, 0x82
	s_sub_i32 s7, s2, s4
	s_ashr_i32 s11, s10, 3
	s_and_b32 s4, s10, 1
	s_sub_i32 s12, 0x81, s7
	s_add_i32 s13, s7, -2
	s_lshl_b32 s14, s11, 14
	s_sub_i32 s15, 1, s7
	v_writelane_b32 v250, s8, 27
	s_cmp_eq_u32 s4, 0
	s_nop 0
	v_writelane_b32 v250, s9, 28
	s_cselect_b64 s[8:9], -1, 0
	v_writelane_b32 v250, s8, 29
	s_nop 1
	v_writelane_b32 v250, s9, 30
	s_and_b64 s[8:9], s[8:9], exec
	s_cselect_b32 s4, s13, s12
	s_cselect_b32 s8, s7, s15
	s_lshl_b32 s4, s4, 7
	s_add_i32 s9, s4, s14
	s_lshl_b32 s4, s11, 8
	s_lshl_b32 s8, s8, 7
	s_add_i32 s4, s4, s8
	s_add_i32 s8, s4, 0x8000
	s_lshl_b32 s4, s10, 6
	s_lshl_b32 s10, s10, 3
	s_and_b32 s4, s4, 0x180
	s_and_b32 s10, s10, 56
	s_add_u32 s10, s24, s10
	v_writelane_b32 v250, s24, 31
	s_addc_u32 s11, s25, 0
	s_nop 0
	v_writelane_b32 v250, s25, 32
	s_add_u32 s24, s92, 0x428b900
	v_writelane_b32 v250, s10, 33
	s_addc_u32 s25, s93, 0
	s_nop 0
	v_writelane_b32 v250, s11, 34
	s_add_u32 s10, s92, 0x7b900
	s_addc_u32 s11, s93, 0
	v_writelane_b32 v250, s10, 35
	s_cmpk_lt_i32 s2, 0x79e
	s_cselect_b64 s[12:13], -1, 0
	v_writelane_b32 v250, s11, 36
	s_mul_i32 s10, s23, 0xf3
	v_writelane_b32 v250, s12, 37
	s_add_i32 s10, s10, 6
	s_nop 0
	v_writelane_b32 v250, s13, 38
	s_add_u32 s12, s92, 0x540b900
	s_addc_u32 s13, s93, 0
	s_add_u32 s26, s92, 0x4a0b900
	s_addc_u32 s27, s93, 0
	s_add_u32 s15, s92, 0x2c8b900
	v_writelane_b32 v250, s12, 39
	s_addc_u32 s28, s93, 0
	s_ashr_i32 s11, s2, 2
	v_writelane_b32 v250, s13, 40
	s_add_i32 s12, s11, 0x80
	v_writelane_b32 v250, s12, 41
	s_and_b32 s12, s2, 3
	s_cmpk_lt_i32 s11, 0xff80
	v_writelane_b32 v250, s12, 42
	s_cselect_b64 s[12:13], -1, 0
	v_writelane_b32 v250, s12, 43
	s_lshr_b32 s11, s23, 31
	s_nop 0
	v_writelane_b32 v250, s13, 44
	v_writelane_b32 v250, s11, 45
	s_add_u32 s11, s92, 0x15a0b900
	v_writelane_b32 v250, s11, 46
	s_addc_u32 s11, s93, 0
	s_add_u32 s29, s92, 0x8b900
	v_writelane_b32 v250, s11, 47
	s_addc_u32 s30, s93, 0
	s_add_i32 s11, s96, -8
	s_add_i32 s12, s19, 0xffffff80
	v_writelane_b32 v250, s12, 48
	s_add_i32 s12, s2, 0x470
	s_lshl_b32 s34, s11, 4
	s_cmpk_lt_i32 s2, 0x6d0
	v_writelane_b32 v250, s11, 49
	s_cselect_b64 s[36:37], -1, 0
	s_cmpk_lt_u32 s12, 0x840
	s_movk_i32 s11, 0xcb0
	s_cselect_b32 s11, s11, 0xf10
	s_cmpk_gt_i32 s2, 0x10f
	s_cselect_b32 s11, s11, 0x9f0
	v_writelane_b32 v250, s36, 50
	s_add_i32 s11, s11, s2
	s_cmpk_gt_i32 s11, 0xaff
	v_writelane_b32 v250, s37, 51
	v_writelane_b32 v250, s12, 52
	s_cselect_b64 s[12:13], -1, 0
	v_writelane_b32 v250, s12, 53
	v_sub_co_u32_e32 v2, vcc, s11, v1
	s_nop 0
	v_writelane_b32 v250, s13, 54
	s_xor_b64 s[12:13], vcc, -1
	v_mov_b32_e32 v1, 0x1260
	v_writelane_b32 v250, s12, 55
	v_sub_co_u32_e32 v3, vcc, s11, v1
	s_nop 0
	v_writelane_b32 v250, s13, 56
	s_xor_b64 s[12:13], vcc, -1
	v_writelane_b32 v250, s12, 57
	s_cmpk_gt_u32 s11, 0x12df
	s_load_dwordx16 s[36:51], s[0:1], 0x40
	v_writelane_b32 v250, s13, 58
	s_cselect_b64 s[12:13], -1, 0
	v_writelane_b32 v250, s12, 59
	v_cvt_f32_u32_e32 v1, s96
	v_rcp_iflag_f32_e32 v1, v1
	v_writelane_b32 v250, s13, 60
	s_add_i32 s12, s11, 0xf500
	s_and_b32 s13, s12, 0xffff
	s_mul_i32 s13, s13, 0xba2f
	s_lshr_b32 s13, s13, 24
	s_mul_i32 s14, s13, 0x160
	s_sub_i32 s12, s12, s14
	s_and_b32 s12, s12, 0xffff
	v_writelane_b32 v250, s12, 61
	s_mul_i32 s12, s13, 0xb00000
	s_waitcnt lgkmcnt(0)
	s_add_u32 s52, s36, s12
	s_addc_u32 s53, s37, 0
	s_mul_i32 s13, s13, 0x580000
	s_add_u32 s12, s15, s13
	s_addc_u32 s13, s28, 0
	v_writelane_b32 v251, s12, 0
	v_writelane_b32 v250, s52, 62
	v_mul_f32_e32 v1, 0x4f7ffffe, v1
	v_writelane_b32 v251, s13, 1
	s_mul_hi_i32 s12, s11, 0x2e8ba2e9
	s_lshr_b32 s13, s12, 31
	s_ashr_i32 s12, s12, 7
	s_add_i32 s12, s12, s13
	s_mul_i32 s13, s12, 0x2c0
	s_sub_i32 s13, s11, s13
	s_mul_i32 s14, s12, 0x1600000
	v_writelane_b32 v251, s13, 2
	s_mul_hi_i32 s13, s12, 0x1600000
	s_add_u32 s0, s74, s14
	s_addc_u32 s1, s75, s13
	v_writelane_b32 v251, s0, 3
	v_writelane_b32 v250, s53, 63
	v_cvt_u32_f32_e32 v1, v1
	v_writelane_b32 v251, s1, 4
	s_mul_hi_i32 s0, s12, 0xb00000
	s_mul_i32 s12, s12, 0xb00000
	s_add_u32 s12, s29, s12
	s_addc_u32 s13, s30, s0
	v_writelane_b32 v251, s12, 5
	s_cmp_gt_i32 s2, -1
	s_cselect_b64 s[0:1], -1, 0
	v_writelane_b32 v251, s13, 6
	s_lshl_b32 s84, s96, 9
	v_writelane_b32 v251, s0, 7
	s_cmpk_lt_i32 s2, 0x120
	s_nop 0
	v_writelane_b32 v251, s1, 8
	s_cselect_b64 s[0:1], -1, 0
	v_writelane_b32 v251, s0, 9
	s_cmpk_lt_i32 s2, 0xaa0
	s_nop 0
	v_writelane_b32 v251, s1, 10
	s_cselect_b64 s[0:1], -1, 0
	v_writelane_b32 v251, s0, 11
	s_cmpk_lt_i32 s2, 0x478
	s_nop 0
	v_writelane_b32 v251, s1, 12
	s_cselect_b64 s[0:1], -1, 0
	v_writelane_b32 v251, s0, 13
	s_nop 1
	v_writelane_b32 v251, s1, 14
	s_add_i32 s0, s2, 0x580
	s_mul_hi_i32 s1, s0, 0x2e8ba2e9
	s_lshr_b32 s12, s1, 31
	s_ashr_i32 s1, s1, 7
	s_add_i32 s1, s1, s12
	s_mul_i32 s12, s1, 0x2c0
	s_sub_i32 s0, s0, s12
	s_mul_i32 s13, s1, 0x1600000
	s_mul_hi_i32 s12, s1, 0x1600000
	s_add_u32 s52, s74, s13
	s_addc_u32 s53, s75, s12
	v_writelane_b32 v251, s52, 15
	s_mul_hi_i32 s12, s1, 0xb00000
	s_mul_i32 s1, s1, 0xb00000
	v_writelane_b32 v251, s53, 16
	s_add_u32 s52, s29, s1
	s_mul_i32 s1, s0, 0xba3
	s_addc_u32 s53, s30, s12
	s_lshr_b32 s12, s1, 31
	s_ashr_i32 s1, s1, 18
	s_add_i32 s1, s1, s12
	v_writelane_b32 v251, s52, 17
	s_mul_i32 s12, s1, 0x58
	s_sub_i32 s0, s0, s12
	v_writelane_b32 v251, s53, 18
	s_lshl_b32 s1, s1, 7
	v_writelane_b32 v251, s1, 19
	s_sext_i32_i16 s1, s0
	s_lshl_b32 s12, s1, 6
	s_lshl_b32 s1, s1, 5
	s_and_b32 s1, s1, 0xffffff80
	v_writelane_b32 v251, s1, 20
	s_and_b32 s1, s12, 64
; __device__ void ph_convert(const P& p, LAS unsigned char* lds, int layer, int wid, int nwg, int v_lo, int v_hi) {
;     ...
;     const int nv = min(v_hi, layer ? 2880 : 2720);
;     ...
;     int v = v_lo + wid;
;     if (v < nv) { const int t = CONV_REMAP(v); CONV_LOAD(t) }
	v_writelane_b32 v251, s12, 21
	s_bitcmp0_b32 s0, 1
	v_writelane_b32 v251, s1, 22
	s_cselect_b32 s0, 0, 0xb00
	v_writelane_b32 v251, s0, 23
	s_cmp_lt_i32 s23, 0
	s_mul_i32 s0, s23, 0x101
	s_cselect_b32 s0, s0, s6
	s_add_i32 s0, s0, s22
	s_ashr_i32 s1, s0, 31
	s_lshr_b32 s1, s1, 25
	s_add_i32 s1, s0, s1
	s_and_b32 s6, s1, 0xff80
	s_sub_i32 s0, s0, s6
	s_bfe_i32 s6, s0, 0x80000
	s_bfe_u32 s6, s6, 0x3000c
	s_add_i32 s6, s0, s6
	s_and_b32 s12, s6, 0xf8
	s_sub_i32 s0, s0, s12
	s_ashr_i32 s1, s1, 7
	s_bfe_i32 s6, s6, 0x80000
	s_lshl_b32 s1, s1, 3
	s_sext_i32_i16 s6, s6
	s_sext_i32_i8 s0, s0
	s_add_i32 s12, s1, s0
	s_ashr_i32 s0, s6, 3
	v_writelane_b32 v251, s0, 24
	s_lshr_b32 s0, s6, 3
	s_cmp_lt_i32 s7, 2
	s_cselect_b32 s1, s8, s9
	v_writelane_b32 v251, s1, 25
	s_cmp_lt_i32 s23, 6
	s_mul_i32 s1, s23, 0xf4
	s_cselect_b32 s1, s1, s10
	s_add_i32 s1, s1, s22
	s_mul_hi_i32 s6, s1, 0x88888889
	s_add_i32 s6, s6, s1
	s_lshr_b32 s7, s6, 31
	s_ashr_i32 s6, s6, 6
	s_add_i32 s6, s6, s7
	s_mul_i32 s7, s6, 0x78
	s_lshl_b32 s9, s6, 3
	s_sub_i32 s8, s1, s7
	s_sub_i32 s1, 0x82, s9
	s_min_u32 s10, s1, 8
	v_writelane_b32 v251, s23, 26
	s_cmpk_lt_u32 s11, 0x14e0
	s_movk_i32 s6, 0x400
	v_writelane_b32 v251, s22, 27
	s_cselect_b32 s6, s6, 0x800
	v_writelane_b32 v251, s6, 28
	s_cselect_b32 s22, s48, s82
	s_cselect_b32 s23, s49, s83
	v_writelane_b32 v251, s22, 29
	s_movk_i32 s1, 0xed20
	s_cselect_b32 s7, 64, 16
	v_writelane_b32 v251, s23, 30
	s_cselect_b32 s1, s1, 0xffffeb20
	s_mov_b32 s6, 0x4c0b900
	v_writelane_b32 v251, s7, 31
	s_movk_i32 s7, 0x1000
	s_cselect_b32 s6, s6, 0x540b900
	s_cselect_b32 s14, s7, 0x400
	s_add_i32 s1, s11, s1
	v_writelane_b32 v251, s14, 32
	s_add_u32 s6, s92, s6
	s_addc_u32 s7, s93, 0
	v_writelane_b32 v251, s15, 33
	v_writelane_b32 v251, s1, 34
	s_cmpk_lt_u32 s2, 0x840
	s_movk_i32 s1, 0x580
	s_cselect_b32 s1, s1, 0x840
	s_cmpk_gt_i32 s2, 0x57f
	s_cselect_b32 s1, s1, 0
	s_add_i32 s11, s2, s1
	v_writelane_b32 v251, s6, 35
	s_cmpk_gt_i32 s11, 0xaff
	v_cvt_f32_ubyte0_e32 v4, s10
	v_writelane_b32 v251, s7, 36
	s_cselect_b64 s[6:7], -1, 0
	v_writelane_b32 v251, s6, 37
	s_cmpk_gt_u32 s11, 0x107f
	v_rcp_iflag_f32_e32 v5, v4
	v_writelane_b32 v251, s7, 38
	s_cselect_b64 s[6:7], -1, 0
	v_writelane_b32 v251, s6, 39
	s_add_i32 s1, s11, 0xf500
	s_nop 0
	v_writelane_b32 v251, s7, 40
	s_and_b32 s6, s1, 0xffff
	s_mul_i32 s6, s6, 0xba2f
	s_lshr_b32 s6, s6, 24
	s_mul_i32 s7, s6, 0x160
	s_sub_i32 s1, s1, s7
	s_and_b32 s1, s1, 0xffff
	v_writelane_b32 v251, s1, 41
	s_mul_i32 s1, s6, 0xb00000
	s_add_u32 s22, s36, s1
	s_addc_u32 s23, s37, 0
	v_writelane_b32 v251, s22, 42
	s_mul_i32 s6, s6, 0x580000
	s_add_u32 s6, s15, s6
	v_writelane_b32 v251, s23, 43
	v_writelane_b32 v251, s15, 44
	v_writelane_b32 v251, s28, 45
	s_addc_u32 s7, s28, 0
	v_writelane_b32 v251, s6, 46
	s_mul_hi_i32 s1, s11, 0x2e8ba2e9
	s_nop 0
	v_writelane_b32 v251, s7, 47
	s_lshr_b32 s6, s1, 31
	s_ashr_i32 s1, s1, 7
	s_add_i32 s1, s1, s6
	s_mul_i32 s6, s1, 0x2c0
	s_sub_i32 s6, s11, s6
	s_mul_i32 s7, s1, 0x1600000
	v_writelane_b32 v251, s6, 48
	s_mul_hi_i32 s6, s1, 0x1600000
	s_add_u32 s14, s74, s7
	v_writelane_b32 v251, s60, 49
	s_addc_u32 s15, s75, s6
	s_mul_hi_i32 s6, s1, 0xb00000
	v_writelane_b32 v252, s75, 0
	v_writelane_b32 v252, s14, 1
	s_mul_i32 s1, s1, 0xb00000
	v_writelane_b32 v251, s61, 50
	v_writelane_b32 v252, s15, 2
	v_writelane_b32 v252, s29, 3
	s_add_u32 s14, s29, s1
	v_writelane_b32 v252, s30, 4
	s_addc_u32 s15, s30, s6
	v_writelane_b32 v252, s14, 5
	s_mov_b32 s6, s12
	s_ashr_i32 s13, s12, 31
	v_writelane_b32 v252, s15, 6
	s_bfe_i64 s[0:1], s[0:1], 0x100000
	v_writelane_b32 v252, s6, 7
	s_lshl_b64 s[0:1], s[0:1], 19
	v_writelane_b32 v251, s62, 51
	v_writelane_b32 v252, s7, 8
	s_lshl_b64 s[6:7], s[12:13], 19
	s_add_u32 s0, s20, s0
	v_writelane_b32 v252, s20, 9
	s_addc_u32 s1, s21, s1
	s_add_u32 s12, s0, 0x40000
	v_writelane_b32 v252, s21, 10
	s_addc_u32 s13, s1, 0
	v_writelane_b32 v252, s12, 11
	s_add_u32 s6, s16, s6
	s_addc_u32 s7, s17, s7
	v_writelane_b32 v252, s13, 12
	s_add_u32 s12, s6, 0x40000
	v_writelane_b32 v252, s6, 13
	s_addc_u32 s13, s7, 0
	v_writelane_b32 v251, s63, 52
	v_writelane_b32 v252, s7, 14
	v_writelane_b32 v252, s12, 15
	s_add_u32 s6, s0, 0x40080
	v_writelane_b32 v251, s64, 53
	v_writelane_b32 v252, s13, 16
	v_writelane_b32 v252, s0, 17
	s_addc_u32 s7, s1, 0
	s_cmpk_lt_u32 s11, 0x1260
	v_writelane_b32 v252, s1, 18
	v_writelane_b32 v252, s6, 19
	s_cselect_b64 s[0:1], -1, 0
	v_writelane_b32 v251, s65, 54
	v_writelane_b32 v252, s7, 20
	v_writelane_b32 v252, s0, 21
	v_writelane_b32 v251, s66, 55
	v_writelane_b32 v251, s67, 56
	v_writelane_b32 v252, s1, 22
	s_and_b64 s[0:1], s[0:1], exec
	s_cselect_b32 s7, s25, s27
	v_writelane_b32 v252, s26, 23
	s_cselect_b32 s6, s24, s26
	s_cselect_b32 s1, 60, 16
	v_writelane_b32 v252, s27, 24
	v_writelane_b32 v252, s6, 25
	s_movk_i32 s0, 0xef80
	s_cselect_b32 s0, s0, 0xffffeda0
	v_writelane_b32 v252, s7, 26
	s_cselect_b32 s7, s39, s47
	v_writelane_b32 v252, s36, 27
	s_cselect_b32 s6, s38, s46
	v_writelane_b32 v251, s68, 57
	v_writelane_b32 v252, s37, 28
	v_writelane_b32 v252, s38, 29
	v_writelane_b32 v252, s39, 30
	v_writelane_b32 v252, s40, 31
	v_writelane_b32 v252, s41, 32
	v_writelane_b32 v252, s42, 33
; #define LAS __attribute__((address_space(3)))
; __device__ __forceinline__ unsigned xb_xcc_id() { return (unsigned)__builtin_amdgcn_s_getreg((3 << 11) | 20) & 0xFu; }
; __device__ void ph_na2(const P& p, LAS unsigned char* lds) {
;     ...
;     const int per = (4096 + gridDim.x - 1) / gridDim.x;
;     const int u_lo = blockIdx.x * per, u_hi = min(u_lo + per, 4096);
; __global__ void __launch_bounds__(NTHR, 2) fwd_kernel(P p) {
;     extern __shared__ __attribute__((aligned(16))) unsigned char lds_raw[];
;     LAS unsigned char* lds = (LAS unsigned char*)lds_raw;
;     ...
;     run_phase(p, p.ph_lo, false, lds);
;     ...
;     cg::grid_group grid = cg::this_grid();
;     volatile LAS unsigned* bar_st = (volatile LAS unsigned*)(lds + (LDS_BYTES - 16));
;     if (threadIdx.x < 4) bar_st[threadIdx.x] = 0u;
;     __syncthreads();
;     (void)xcd_barrier_post((unsigned*)(p.ws + WS_BAR), bar_st);
;     for (int it = 2 * p.ph_lo; it < 2 * p.ph_hi; ++it) {
;         const int ph = it >> 1;
;         if (ph == 18) continue;
;         if ((it & 1) && ph != 4 && !((DBL_MASK >> ph) & 1u)) continue;
;         if (it > 2 * p.ph_lo) {
;             if (it == 2 * p.ph_lo + 2) grid.sync();
;             else { XcdBarrier xb; xb.bar = (unsigned*)(p.ws + WS_BAR); xb.x = xb_xcc_id(); xb.st = bar_st; xcd_barrier(xb); }
;         }
;         run_phase(p, ph, (it & 1) != 0, lds);
;     }
	v_writelane_b32 v252, s43, 34
	v_writelane_b32 v252, s44, 35
	v_writelane_b32 v252, s45, 36
	v_writelane_b32 v252, s46, 37
	v_writelane_b32 v252, s47, 38
	v_writelane_b32 v252, s48, 39
	v_writelane_b32 v252, s49, 40
	v_writelane_b32 v252, s50, 41
	v_writelane_b32 v252, s51, 42
	v_writelane_b32 v252, s6, 43
	v_writelane_b32 v251, s69, 58
	v_writelane_b32 v251, s70, 59
	v_writelane_b32 v252, s7, 44
	v_writelane_b32 v252, s1, 45
	s_movk_i32 s1, 0xe10
	s_cselect_b32 s6, s1, 0x400
	v_writelane_b32 v252, s6, 46
	s_add_i32 s0, s11, s0
	v_readfirstlane_b32 s1, v1
	v_writelane_b32 v252, s7, 47
	v_writelane_b32 v252, s0, 48
	s_sub_i32 s0, 0, s96
	s_mul_i32 s0, s0, s1
	s_mul_hi_u32 s0, s1, s0
	s_add_i32 s1, s1, s0
	s_mul_hi_u32 s0, s5, s1
	s_mul_i32 s1, s0, s96
	s_sub_i32 s1, s5, s1
	s_add_i32 s5, s0, 1
	s_sub_i32 s6, s1, s96
	s_cmp_ge_u32 s1, s96
	s_cselect_b32 s0, s5, s0
	s_cselect_b32 s1, s6, s1
	s_add_i32 s5, s0, 1
	s_cmp_ge_u32 s1, s96
	s_cselect_b32 s0, s5, s0
	s_mul_i32 s1, s0, s2
	v_cvt_f32_i32_e32 v1, s8
	s_add_i32 s0, s1, s0
	s_min_i32 s86, s0, 0x1000
	s_cmp_lt_i32 s1, s86
	v_writelane_b32 v252, s1, 49
	s_cselect_b64 s[0:1], -1, 0
	v_mul_f32_e32 v5, v1, v5
	v_writelane_b32 v252, s0, 50
	v_trunc_f32_e32 v5, v5
	v_fma_f32 v1, -v5, v4, v1
	v_writelane_b32 v252, s1, 51
	s_ashr_i32 s0, s8, 30
	s_or_b32 s5, s0, 1
	v_cmp_ge_f32_e64 s[0:1], |v1|, v4
	v_cvt_i32_f32_e32 v1, v5
	s_and_b64 s[0:1], s[0:1], exec
	s_cselect_b32 s0, s5, 0
	s_mov_b32 s5, s19
	v_readfirstlane_b32 s1, v1
	s_add_i32 s0, s1, s0
	s_mul_i32 s1, s0, s10
	s_sub_i32 s1, s8, s1
	s_sext_i32_i8 s1, s1
	s_add_i32 s10, s9, s1
	s_mov_b32 s8, s10
	s_ashr_i32 s11, s10, 31
	s_bfe_i64 s[6:7], s[0:1], 0x80000
	v_writelane_b32 v252, s8, 52
	s_lshl_b64 s[6:7], s[6:7], 19
	s_sext_i32_i8 s0, s0
	v_writelane_b32 v252, s9, 53
	s_lshl_b64 s[8:9], s[10:11], 19
	s_add_u32 s6, s24, s6
	v_writelane_b32 v252, s24, 54
	s_addc_u32 s7, s25, s7
	s_add_u32 s10, s6, 0x40000
	v_writelane_b32 v252, s25, 55
	s_addc_u32 s11, s7, 0
	v_writelane_b32 v252, s10, 56
	s_add_u32 s8, s16, s8
	s_mul_i32 s1, s97, s96
	v_writelane_b32 v252, s11, 57
	v_writelane_b32 v252, s16, 58
	s_addc_u32 s9, s17, s9
	v_lshrrev_b32_e32 v1, 20, v0
	v_writelane_b32 v252, s17, 59
	v_lshrrev_b32_e32 v0, 10, v0
	v_writelane_b32 v252, s0, 60
	s_mul_i32 s87, s1, s3
	v_or_b32_e32 v0, v0, v1
	s_movk_i32 s1, 0x3ff
	s_add_u32 s0, s8, 0x40000
	v_writelane_b32 v252, s8, 61
	v_and_or_b32 v0, v0, s1, v169
	s_addc_u32 s1, s9, 0
	v_writelane_b32 v252, s9, 62
	v_writelane_b32 v252, s0, 63
	v_writelane_b32 v251, s71, 60
	v_writelane_b32 v251, s72, 61
	v_writelane_b32 v253, s1, 0
	s_add_u32 s0, s6, 0x40080
	v_writelane_b32 v253, s6, 1
	s_addc_u32 s1, s7, 0
	s_ashr_i32 s19, s18, 31
	v_writelane_b32 v253, s7, 2
	v_writelane_b32 v253, s0, 3
	s_lshl_b64 s[6:7], s[18:19], 12
	v_writelane_b32 v251, s73, 62
	v_writelane_b32 v253, s1, 4
	v_writelane_b32 v253, s5, 5
	s_add_i32 s1, s2, s96
	v_writelane_b32 v253, s1, 6
	s_lshl_b32 s1, s1, 8
	v_writelane_b32 v253, s1, 7
	s_lshl_b32 s1, s96, 8
	v_writelane_b32 v253, s1, 8
	s_add_i32 s0, s5, s18
	v_writelane_b32 v253, s6, 9
	v_mbcnt_lo_u32_b32 v4, -1, 0
	v_writelane_b32 v251, s74, 63
	v_writelane_b32 v253, s7, 10
	s_add_u32 s6, s92, 0x1580c500
	s_addc_u32 s7, s93, 0
	v_writelane_b32 v253, s6, 11
	s_lshl_b32 s1, s4, 1
	v_cmp_eq_u32_e64 s[4:5], 0, v0
	v_writelane_b32 v253, s7, 12
	v_writelane_b32 v253, s1, 13
	v_readfirstlane_b32 s1, v2
	s_ashr_i32 s35, s34, 31
	s_ashr_i32 s85, s84, 31
	v_writelane_b32 v253, s1, 14
	v_readfirstlane_b32 s1, v3
	s_mov_b32 s67, s33
	v_mov_b32_e32 v1, 0
	v_writelane_b32 v253, s1, 15
	s_add_i32 s1, s0, 0xffffff00
	v_writelane_b32 v253, s1, 16
	v_writelane_b32 v253, s0, 17
	s_add_i32 s0, s0, 0x8000
	v_writelane_b32 v253, s0, 18
	s_add_i32 s0, 0, 0x23ff0
	v_writelane_b32 v253, s0, 19
	s_add_i32 s0, 0, 0x23ff4
	v_writelane_b32 v253, s0, 20
	s_add_i32 s0, 0, 0x11800
	v_writelane_b32 v253, s0, 21
	s_add_i32 s0, 0, 0x1cc00
	v_writelane_b32 v253, s0, 22
	s_add_i32 s0, 0, 0x1ca00
	v_writelane_b32 v253, s0, 23
	s_add_i32 s0, 0, 0x13000
	v_writelane_b32 v253, s0, 24
	s_add_i32 s0, 0, 0x1c800
	v_writelane_b32 v253, s0, 25
	s_add_i32 s0, 0, 0x1ce00
	v_writelane_b32 v253, s0, 26
	s_add_i32 s0, 0, 0x18c00
	v_writelane_b32 v253, s0, 27
	s_add_i32 s0, 0, 0x21c00
	v_writelane_b32 v253, s0, 28
	v_writelane_b32 v253, s4, 29
	s_mov_b32 s1, s31
	s_mov_b32 s0, s34
	v_writelane_b32 v253, s5, 30
	s_lshl_b64 s[4:5], s[34:35], 11
	v_writelane_b32 v253, s4, 31
	v_mbcnt_hi_u32_b32 v193, -1, v4
	s_mov_b32 s66, 0x800000
	v_writelane_b32 v253, s5, 32
	v_writelane_b32 v253, s0, 33
	s_lshl_b64 s[4:5], s[34:35], 12
	s_movk_i32 s65, 0x130
	v_writelane_b32 v253, s1, 34
	v_writelane_b32 v253, s4, 35
	s_mov_b64 s[50:51], 0x80
	s_mov_b32 s64, 0x3e38aa3b
	v_writelane_b32 v253, s5, 36
	v_writelane_b32 v253, s18, 37
	s_lshl_b64 s[4:5], s[18:19], 11
	s_mov_b32 s61, 0
	v_writelane_b32 v253, s19, 38
	v_writelane_b32 v253, s4, 39
	s_nop 1
	v_writelane_b32 v253, s5, 40
	s_lshl_b64 s[4:5], s[84:85], 3
	v_writelane_b32 v253, s4, 41
	s_mov_b32 s85, s31
	s_nop 0
	v_writelane_b32 v253, s5, 42
	v_writelane_b32 v253, s86, 43
	s_branch .LBB0_9
.Lend_early:
	s_endpgm
.LBB0_7:
	v_readlane_b32 s6, v253, 46

; #define PG8_STAGE(bufoff, gbase, voff) do { _Pragma("unroll") for (int _i = 0; _i < 2; ++_i) \
;         __builtin_amdgcn_global_load_lds((const unsigned*)((const char*)(gbase) + (voff)[_i]), (LAS unsigned*)(lds + (bufoff) + ldsw + _i * 8192), 16, 0, 0); } while (0)
; #define PG8_LDA(dst, b, h) do { _Pragma("unroll") for (int m = 0; m < 4; ++m) _Pragma("unroll") for (int k = 0; k < 2; ++k) dst[m][k] = *(const LAS bf16x8*)(lds + PG8_SA(b, h) + aoff + m * 2048 + k * 1024); } while (0)
; #define PG8_LDB(dst, b, h) do { _Pragma("unroll") for (int n = 0; n < 2; ++n) _Pragma("unroll") for (int k = 0; k < 2; ++k) dst[n][k] = *(const LAS bf16x8*)(lds + PG8_SB(b, h) + boff + n * 2048 + k * 1024); } while (0)
; #define PG8_WAIT_V(n) asm volatile("s_waitcnt vmcnt(" #n ")" ::: "memory")
; #define PG8_WAIT_L(n) asm volatile("s_waitcnt lgkmcnt(" #n ")" ::: "memory")
; #define PG8_BAR __builtin_amdgcn_s_barrier()
; #define PG8_SCHED __builtin_amdgcn_sched_barrier(0)
; template <class Epi, bool ALIGN_EPI = PG8_ALIGN, bool SP2 = PG8_SP2>
; __device__ __forceinline__ void gemm_phase(LAS unsigned char* lds, const Gemm g, const StaticOrder& S, const Epi& E) {
;     ...
;         const bool has_next = S.next(ui + 1, nxt);
;         const char* nA = has_next ? (const char*)g.A + (size_t)nxt.pm * tstepA : cA; const char* nB = has_next ? (const char*)g.Bt + (size_t)nxt.pn * tstepB : cB;
;         for (int t = 0; t < nt; t += 2) {
;             const bool last = (t == nt - 2);
;             const char* a1 = cA + (size_t)(t + 1) * kstepA;
;             const char* a2 = last ? nA : cA + (size_t)(t + 2) * kstepA; const char* b2 = last ? nB : cB + (size_t)(t + 2) * kstepB;
;             const char* a3 = a2 + kstepA; const char* b3 = b2 + kstepB;
;             if constexpr (SP2) {
;             PG8_LDB(B0, 0, 0); PG8_LDB(B1, 0, 1); PG8_SCHED; PG8_LDA(At, 0, 0); PG8_STAGE(PG8_SA(1, 1), a1 + hstepA, voffA);
;             PG8_WAIT_V(8); PG8_WAIT_L(0); PG8_BAR; PG8_MMA(0, 0, At, B0); PG8_MMA(0, 1, At, B1); PG8_BAR; PG8_SCHED;
;             PG8_LDA(At, 0, 1); PG8_STAGE(PG8_SB(0, 0), b2, voffB); PG8_STAGE(PG8_SB(0, 1), b2 + hstepB, voffB); PG8_STAGE(PG8_SA(0, 0), a2, voffA);
;             PG8_WAIT_V(8); PG8_WAIT_L(0); PG8_BAR; PG8_MMA(1, 0, At, B0); PG8_MMA(1, 1, At, B1); PG8_BAR; PG8_SCHED;
.LBB0_138:
	s_ashr_i32 s17, s16, 31
	s_lshl_b64 s[18:19], s[16:17], 19
	v_readlane_b32 s20, v252, 58
	v_readlane_b32 s21, v252, 59
	s_add_u32 s18, s20, s18
	s_addc_u32 s19, s21, s19
	s_and_b64 s[20:21], s[6:7], exec
	s_cselect_b32 s17, s19, s5
	s_cselect_b32 s36, s18, s4
	s_ashr_i32 s15, s14, 31
	s_lshl_b64 s[20:21], s[14:15], 19
	v_readlane_b32 s24, v252, 9
	v_readlane_b32 s25, v252, 10
	s_add_u32 s20, s24, s20
	s_addc_u32 s21, s25, s21
	s_and_b64 s[24:25], s[6:7], exec
	s_cselect_b32 s15, s21, s23
	s_cselect_b32 s37, s20, s22
	s_add_u32 s4, s4, 0x40080
	s_addc_u32 s5, s5, 0
	s_add_u32 s38, s22, 0x100
	s_addc_u32 s39, s23, 0
	s_mov_b32 s40, -2
.LBB0_139:
	s_cmp_eq_u32 s40, -2
	s_cbranch_scc1 .Lfirst_iter_u139
	s_add_u32 s22, s4, 0xfffc0080
	s_addc_u32 s23, s5, -1
	s_add_i32 s41, 0, 0x10000
	s_cmp_eq_u32 s40, 12
	s_cselect_b32 s25, s17, s23
	s_cselect_b32 s24, s36, s22
	v_add_u32_e32 v0, s41, v143
	s_cselect_b32 s23, s15, s39
	s_cselect_b32 s22, s37, s38
	s_add_i32 s44, 0, 0x14000
	ds_read_b128 v[138:141], v0
	ds_read_b128 v[146:149], v0 offset:1024
	ds_read_b128 v[150:153], v0 offset:2048
	ds_read_b128 v[154:157], v0 offset:3072
	v_add_u32_e32 v0, s44, v143
	ds_read_b128 v[158:161], v0
	ds_read_b128 v[164:167], v0 offset:1024
	ds_read_b128 v[170:173], v0 offset:2048
	ds_read_b128 v[174:177], v0 offset:3072
	v_lshl_add_u64 v[190:191], s[4:5], 0, v[134:135]
	s_add_i32 m0, s26, 0xc000
	ds_read_b128 v[178:181], v145
	ds_read_b128 v[182:185], v145 offset:1024
	ds_read_b128 v[186:189], v145 offset:2048
	ds_read_b128 v[194:197], v145 offset:3072
	ds_read_b128 v[206:209], v145 offset:4096
	ds_read_b128 v[210:213], v145 offset:5120
	ds_read_b128 v[214:217], v145 offset:6144
	ds_read_b128 v[218:221], v145 offset:7168
	global_load_lds_dwordx4 v[190:191], off
	v_lshl_add_u64 v[190:191], s[4:5], 0, v[136:137]
	s_add_i32 m0, s26, 0xe000
	s_nop 0
	global_load_lds_dwordx4 v[190:191], off
	s_waitcnt vmcnt(8)
	s_waitcnt lgkmcnt(0)
	s_barrier
	s_setprio 1
	s_waitcnt lgkmcnt(0)
	v_mfma_f32_16x16x32_bf16 v[126:129], v[138:141], v[178:181], v[126:129]
	v_mfma_f32_16x16x32_bf16 v[122:125], v[150:153], v[178:181], v[122:125]
	v_mfma_f32_16x16x32_bf16 v[110:113], v[138:141], v[186:189], v[110:113]
	v_mfma_f32_16x16x32_bf16 v[106:109], v[150:153], v[186:189], v[106:109]
	v_mfma_f32_16x16x32_bf16 v[94:97], v[138:141], v[206:209], v[94:97]
	v_mfma_f32_16x16x32_bf16 v[90:93], v[150:153], v[206:209], v[90:93]
	v_mfma_f32_16x16x32_bf16 v[78:81], v[138:141], v[214:217], v[78:81]
	v_mfma_f32_16x16x32_bf16 v[74:77], v[150:153], v[214:217], v[74:77]
	v_mfma_f32_16x16x32_bf16 v[126:129], v[146:149], v[182:185], v[126:129]
	v_mfma_f32_16x16x32_bf16 v[122:125], v[154:157], v[182:185], v[122:125]
	v_mfma_f32_16x16x32_bf16 v[110:113], v[146:149], v[194:197], v[110:113]
	v_mfma_f32_16x16x32_bf16 v[106:109], v[154:157], v[194:197], v[106:109]
	v_mfma_f32_16x16x32_bf16 v[94:97], v[146:149], v[210:213], v[94:97]
	v_mfma_f32_16x16x32_bf16 v[90:93], v[154:157], v[210:213], v[90:93]
	v_mfma_f32_16x16x32_bf16 v[78:81], v[146:149], v[218:221], v[78:81]
	v_mfma_f32_16x16x32_bf16 v[74:77], v[154:157], v[218:221], v[74:77]
	s_setprio 0
	s_setprio 1
	v_mfma_f32_16x16x32_bf16 v[118:121], v[158:161], v[178:181], v[118:121]
	v_mfma_f32_16x16x32_bf16 v[114:117], v[170:173], v[178:181], v[114:117]
	v_mfma_f32_16x16x32_bf16 v[102:105], v[158:161], v[186:189], v[102:105]
	v_mfma_f32_16x16x32_bf16 v[98:101], v[170:173], v[186:189], v[98:101]
	v_mfma_f32_16x16x32_bf16 v[86:89], v[158:161], v[206:209], v[86:89]
	v_mfma_f32_16x16x32_bf16 v[82:85], v[170:173], v[206:209], v[82:85]
	v_mfma_f32_16x16x32_bf16 v[70:73], v[158:161], v[214:217], v[70:73]
	v_mfma_f32_16x16x32_bf16 v[66:69], v[170:173], v[214:217], v[66:69]
	v_mfma_f32_16x16x32_bf16 v[118:121], v[164:167], v[182:185], v[118:121]
	v_mfma_f32_16x16x32_bf16 v[114:117], v[174:177], v[182:185], v[114:117]
	v_mfma_f32_16x16x32_bf16 v[102:105], v[164:167], v[194:197], v[102:105]
	v_mfma_f32_16x16x32_bf16 v[98:101], v[174:177], v[194:197], v[98:101]
	v_mfma_f32_16x16x32_bf16 v[86:89], v[164:167], v[210:213], v[86:89]
	v_mfma_f32_16x16x32_bf16 v[82:85], v[174:177], v[210:213], v[82:85]
	v_mfma_f32_16x16x32_bf16 v[70:73], v[164:167], v[218:221], v[70:73]
	v_mfma_f32_16x16x32_bf16 v[66:69], v[174:177], v[218:221], v[66:69]
	s_setprio 0
	s_barrier
	s_add_i32 s41, s41, s3
	v_lshl_add_u64 v[190:191], s[22:23], 0, v[132:133]
	s_mov_b32 m0, s41
	ds_read_b128 v[178:181], v145 offset:16384
	ds_read_b128 v[182:185], v145 offset:17408
	ds_read_b128 v[186:189], v145 offset:18432
	ds_read_b128 v[194:197], v145 offset:19456
	ds_read_b128 v[206:209], v145 offset:20480
	ds_read_b128 v[210:213], v145 offset:21504
	ds_read_b128 v[214:217], v145 offset:22528
	ds_read_b128 v[218:221], v145 offset:23552
	global_load_lds_dwordx4 v[190:191], off
	s_add_i32 m0, s41, 0x2000
	s_add_u32 s42, s22, 0x40000
	v_lshl_add_u64 v[202:203], s[22:23], 0, v[130:131]
	s_addc_u32 s43, s23, 0
	s_add_i32 s41, s44, s3
	global_load_lds_dwordx4 v[202:203], off
	v_lshl_add_u64 v[204:205], s[42:43], 0, v[132:133]
	s_mov_b32 m0, s41
	v_lshl_add_u64 v[222:223], s[24:25], 0, v[130:131]
	global_load_lds_dwordx4 v[204:205], off
	v_lshl_add_u64 v[204:205], s[42:43], 0, v[130:131]
	s_add_i32 m0, s41, 0x2000
	s_nop 0
	global_load_lds_dwordx4 v[204:205], off
	v_lshl_add_u64 v[204:205], s[24:25], 0, v[132:133]
	s_mov_b32 m0, s26
	s_nop 0
	global_load_lds_dwordx4 v[204:205], off
	s_mov_b32 m0, s27
	s_nop 0
	global_load_lds_dwordx4 v[222:223], off
	s_waitcnt vmcnt(8)
	s_waitcnt lgkmcnt(0)
	s_barrier
; #define PG8_STAGE(bufoff, gbase, voff) do { _Pragma("unroll") for (int _i = 0; _i < 2; ++_i) \
;         __builtin_amdgcn_global_load_lds((const unsigned*)((const char*)(gbase) + (voff)[_i]), (LAS unsigned*)(lds + (bufoff) + ldsw + _i * 8192), 16, 0, 0); } while (0)
; #define PG8_LDA(dst, b, h) do { _Pragma("unroll") for (int m = 0; m < 4; ++m) _Pragma("unroll") for (int k = 0; k < 2; ++k) dst[m][k] = *(const LAS bf16x8*)(lds + PG8_SA(b, h) + aoff + m * 2048 + k * 1024); } while (0)
; #define PG8_LDB(dst, b, h) do { _Pragma("unroll") for (int n = 0; n < 2; ++n) _Pragma("unroll") for (int k = 0; k < 2; ++k) dst[n][k] = *(const LAS bf16x8*)(lds + PG8_SB(b, h) + boff + n * 2048 + k * 1024); } while (0)
; #define PG8_MMA(ai, bj, At, Bt) do { __builtin_amdgcn_s_setprio(1); _Pragma("unroll") for (int m = 0; m < 4; ++m) _Pragma("unroll") for (int n = 0; n < 2; ++n) _Pragma("unroll") for (int k = 0; k < 2; ++k) \
;         acc[ai][bj][m][n] = __builtin_amdgcn_mfma_f32_16x16x32_bf16(Bt[n][k], At[m][k], acc[ai][bj][m][n], 0, 0, 0); __builtin_amdgcn_s_setprio(0); } while (0)
; #define PG8_WAIT_V(n) asm volatile("s_waitcnt vmcnt(" #n ")" ::: "memory")
; #define PG8_WAIT_L(n) asm volatile("s_waitcnt lgkmcnt(" #n ")" ::: "memory")
; #define PG8_BAR __builtin_amdgcn_s_barrier()
; #define PG8_SCHED __builtin_amdgcn_sched_barrier(0)
; template <class Epi, bool ALIGN_EPI = PG8_ALIGN, bool SP2 = PG8_SP2>
; __device__ __forceinline__ void gemm_phase(LAS unsigned char* lds, const Gemm g, const StaticOrder& S, const Epi& E) {
;     ...
;             PG8_WAIT_V(8); PG8_WAIT_L(0); PG8_BAR; PG8_MMA(1, 0, At, B0); PG8_MMA(1, 1, At, B1); PG8_BAR; PG8_SCHED;
;             PG8_LDB(B0, 1, 0); PG8_LDB(B1, 1, 1); PG8_SCHED; PG8_LDA(At, 1, 0); PG8_STAGE(PG8_SA(0, 1), a2 + hstepA, voffA);
;             PG8_WAIT_V(8); PG8_WAIT_L(0); PG8_BAR; PG8_MMA(0, 0, At, B0); PG8_MMA(0, 1, At, B1); PG8_BAR; PG8_SCHED;
;             PG8_LDA(At, 1, 1); PG8_STAGE(PG8_SB(1, 0), b3, voffB); PG8_STAGE(PG8_SB(1, 1), b3 + hstepB, voffB); PG8_STAGE(PG8_SA(1, 0), a3, voffA);
	s_setprio 1
	s_waitcnt lgkmcnt(0)
	v_mfma_f32_16x16x32_bf16 v[62:65], v[138:141], v[178:181], v[62:65]
	v_mfma_f32_16x16x32_bf16 v[58:61], v[150:153], v[178:181], v[58:61]
	v_mfma_f32_16x16x32_bf16 v[46:49], v[138:141], v[186:189], v[46:49]
	v_mfma_f32_16x16x32_bf16 v[42:45], v[150:153], v[186:189], v[42:45]
	v_mfma_f32_16x16x32_bf16 v[30:33], v[138:141], v[206:209], v[30:33]
	v_mfma_f32_16x16x32_bf16 v[26:29], v[150:153], v[206:209], v[26:29]
	v_mfma_f32_16x16x32_bf16 v[14:17], v[138:141], v[214:217], v[14:17]
	v_mfma_f32_16x16x32_bf16 v[10:13], v[150:153], v[214:217], v[10:13]
	v_mfma_f32_16x16x32_bf16 v[62:65], v[146:149], v[182:185], v[62:65]
	v_mfma_f32_16x16x32_bf16 v[58:61], v[154:157], v[182:185], v[58:61]
	v_mfma_f32_16x16x32_bf16 v[46:49], v[146:149], v[194:197], v[46:49]
	v_mfma_f32_16x16x32_bf16 v[42:45], v[154:157], v[194:197], v[42:45]
	v_mfma_f32_16x16x32_bf16 v[30:33], v[146:149], v[210:213], v[30:33]
	v_mfma_f32_16x16x32_bf16 v[26:29], v[154:157], v[210:213], v[26:29]
	v_mfma_f32_16x16x32_bf16 v[14:17], v[146:149], v[218:221], v[14:17]
	v_mfma_f32_16x16x32_bf16 v[10:13], v[154:157], v[218:221], v[10:13]
	s_setprio 0
	s_setprio 1
	v_mfma_f32_16x16x32_bf16 v[54:57], v[158:161], v[178:181], v[54:57]
	v_mfma_f32_16x16x32_bf16 v[50:53], v[170:173], v[178:181], v[50:53]
	v_mfma_f32_16x16x32_bf16 v[38:41], v[158:161], v[186:189], v[38:41]
	v_mfma_f32_16x16x32_bf16 v[34:37], v[170:173], v[186:189], v[34:37]
	v_mfma_f32_16x16x32_bf16 v[22:25], v[158:161], v[206:209], v[22:25]
	v_mfma_f32_16x16x32_bf16 v[18:21], v[170:173], v[206:209], v[18:21]
	v_mfma_f32_16x16x32_bf16 v[6:9], v[158:161], v[214:217], v[6:9]
	v_mfma_f32_16x16x32_bf16 v[2:5], v[170:173], v[214:217], v[2:5]
	v_mfma_f32_16x16x32_bf16 v[54:57], v[164:167], v[182:185], v[54:57]
	v_mfma_f32_16x16x32_bf16 v[50:53], v[174:177], v[182:185], v[50:53]
	v_mfma_f32_16x16x32_bf16 v[38:41], v[164:167], v[194:197], v[38:41]
	v_mfma_f32_16x16x32_bf16 v[34:37], v[174:177], v[194:197], v[34:37]
	v_mfma_f32_16x16x32_bf16 v[22:25], v[164:167], v[210:213], v[22:25]
	v_mfma_f32_16x16x32_bf16 v[18:21], v[174:177], v[210:213], v[18:21]
	v_mfma_f32_16x16x32_bf16 v[6:9], v[164:167], v[218:221], v[6:9]
	v_mfma_f32_16x16x32_bf16 v[2:5], v[174:177], v[218:221], v[2:5]
	s_setprio 0
	s_barrier
	s_add_i32 s41, 0, 0x18000
	v_add_u32_e32 v0, s41, v143
	s_add_i32 s42, 0, 0x1c000
	ds_read_b128 v[138:141], v0
	ds_read_b128 v[146:149], v0 offset:1024
	ds_read_b128 v[150:153], v0 offset:2048
	ds_read_b128 v[154:157], v0 offset:3072
	v_add_u32_e32 v0, s42, v143
	ds_read_b128 v[158:161], v0
	ds_read_b128 v[164:167], v0 offset:1024
	ds_read_b128 v[170:173], v0 offset:2048
	ds_read_b128 v[174:177], v0 offset:3072
	s_add_u32 s24, s24, 0x40000
	s_addc_u32 s25, s25, 0
	s_mov_b32 m0, s28
	v_lshl_add_u64 v[224:225], s[24:25], 0, v[132:133]
	ds_read_b128 v[178:181], v145 offset:32768
	ds_read_b128 v[182:185], v145 offset:33792
	ds_read_b128 v[186:189], v145 offset:34816
	ds_read_b128 v[194:197], v145 offset:35840
	ds_read_b128 v[206:209], v145 offset:36864
	ds_read_b128 v[210:213], v145 offset:37888
	ds_read_b128 v[214:217], v145 offset:38912
	ds_read_b128 v[218:221], v145 offset:39936
	global_load_lds_dwordx4 v[224:225], off
	v_lshl_add_u64 v[224:225], s[24:25], 0, v[130:131]
	s_mov_b32 m0, s29
	s_nop 0
	global_load_lds_dwordx4 v[224:225], off
	s_waitcnt vmcnt(8)
	s_waitcnt lgkmcnt(0)
	s_barrier
	s_setprio 1
	s_waitcnt lgkmcnt(0)
	v_mfma_f32_16x16x32_bf16 v[126:129], v[138:141], v[178:181], v[126:129]
	v_mfma_f32_16x16x32_bf16 v[122:125], v[150:153], v[178:181], v[122:125]
	v_mfma_f32_16x16x32_bf16 v[110:113], v[138:141], v[186:189], v[110:113]
	v_mfma_f32_16x16x32_bf16 v[106:109], v[150:153], v[186:189], v[106:109]
	v_mfma_f32_16x16x32_bf16 v[94:97], v[138:141], v[206:209], v[94:97]
	v_mfma_f32_16x16x32_bf16 v[90:93], v[150:153], v[206:209], v[90:93]
	v_mfma_f32_16x16x32_bf16 v[78:81], v[138:141], v[214:217], v[78:81]
	v_mfma_f32_16x16x32_bf16 v[74:77], v[150:153], v[214:217], v[74:77]
	v_mfma_f32_16x16x32_bf16 v[126:129], v[146:149], v[182:185], v[126:129]
	v_mfma_f32_16x16x32_bf16 v[122:125], v[154:157], v[182:185], v[122:125]
	v_mfma_f32_16x16x32_bf16 v[110:113], v[146:149], v[194:197], v[110:113]
	v_mfma_f32_16x16x32_bf16 v[106:109], v[154:157], v[194:197], v[106:109]
	v_mfma_f32_16x16x32_bf16 v[94:97], v[146:149], v[210:213], v[94:97]
	v_mfma_f32_16x16x32_bf16 v[90:93], v[154:157], v[210:213], v[90:93]
	v_mfma_f32_16x16x32_bf16 v[78:81], v[146:149], v[218:221], v[78:81]
	v_mfma_f32_16x16x32_bf16 v[74:77], v[154:157], v[218:221], v[74:77]
	s_setprio 0
	s_setprio 1
	v_mfma_f32_16x16x32_bf16 v[118:121], v[158:161], v[178:181], v[118:121]
	v_mfma_f32_16x16x32_bf16 v[114:117], v[170:173], v[178:181], v[114:117]
	v_mfma_f32_16x16x32_bf16 v[102:105], v[158:161], v[186:189], v[102:105]
	v_mfma_f32_16x16x32_bf16 v[98:101], v[170:173], v[186:189], v[98:101]
	v_mfma_f32_16x16x32_bf16 v[86:89], v[158:161], v[206:209], v[86:89]
	v_mfma_f32_16x16x32_bf16 v[82:85], v[170:173], v[206:209], v[82:85]
	v_mfma_f32_16x16x32_bf16 v[70:73], v[158:161], v[214:217], v[70:73]
	v_mfma_f32_16x16x32_bf16 v[66:69], v[170:173], v[214:217], v[66:69]
	v_mfma_f32_16x16x32_bf16 v[118:121], v[164:167], v[182:185], v[118:121]
	v_mfma_f32_16x16x32_bf16 v[114:117], v[174:177], v[182:185], v[114:117]
	v_mfma_f32_16x16x32_bf16 v[102:105], v[164:167], v[194:197], v[102:105]
	v_mfma_f32_16x16x32_bf16 v[98:101], v[174:177], v[194:197], v[98:101]
	v_mfma_f32_16x16x32_bf16 v[86:89], v[164:167], v[210:213], v[86:89]
	v_mfma_f32_16x16x32_bf16 v[82:85], v[174:177], v[210:213], v[82:85]
	v_mfma_f32_16x16x32_bf16 v[70:73], v[164:167], v[218:221], v[70:73]
	v_mfma_f32_16x16x32_bf16 v[66:69], v[174:177], v[218:221], v[66:69]
	s_setprio 0
	s_barrier
; #define PG8_STAGE(bufoff, gbase, voff) do { _Pragma("unroll") for (int _i = 0; _i < 2; ++_i) \
;         __builtin_amdgcn_global_load_lds((const unsigned*)((const char*)(gbase) + (voff)[_i]), (LAS unsigned*)(lds + (bufoff) + ldsw + _i * 8192), 16, 0, 0); } while (0)
; #define PG8_LDA(dst, b, h) do { _Pragma("unroll") for (int m = 0; m < 4; ++m) _Pragma("unroll") for (int k = 0; k < 2; ++k) dst[m][k] = *(const LAS bf16x8*)(lds + PG8_SA(b, h) + aoff + m * 2048 + k * 1024); } while (0)
; #define PG8_MMA(ai, bj, At, Bt) do { __builtin_amdgcn_s_setprio(1); _Pragma("unroll") for (int m = 0; m < 4; ++m) _Pragma("unroll") for (int n = 0; n < 2; ++n) _Pragma("unroll") for (int k = 0; k < 2; ++k) \
;         acc[ai][bj][m][n] = __builtin_amdgcn_mfma_f32_16x16x32_bf16(Bt[n][k], At[m][k], acc[ai][bj][m][n], 0, 0, 0); __builtin_amdgcn_s_setprio(0); } while (0)
; #define PG8_WAIT_V(n) asm volatile("s_waitcnt vmcnt(" #n ")" ::: "memory")
; #define PG8_WAIT_L(n) asm volatile("s_waitcnt lgkmcnt(" #n ")" ::: "memory")
; #define PG8_BAR __builtin_amdgcn_s_barrier()
; #define PG8_SCHED __builtin_amdgcn_sched_barrier(0)
; template <class Epi, bool ALIGN_EPI = PG8_ALIGN, bool SP2 = PG8_SP2>
; __device__ __forceinline__ void gemm_phase(LAS unsigned char* lds, const Gemm g, const StaticOrder& S, const Epi& E) {
;     ...
;             PG8_WAIT_V(8); PG8_WAIT_L(0); PG8_BAR; PG8_MMA(0, 0, At, B0); PG8_MMA(0, 1, At, B1); PG8_BAR; PG8_SCHED;
;             PG8_LDA(At, 1, 1); PG8_STAGE(PG8_SB(1, 0), b3, voffB); PG8_STAGE(PG8_SB(1, 1), b3 + hstepB, voffB); PG8_STAGE(PG8_SA(1, 0), a3, voffA);
;             PG8_WAIT_V(8); PG8_WAIT_L(0); PG8_BAR; PG8_MMA(1, 0, At, B0); PG8_MMA(1, 1, At, B1); PG8_BAR; PG8_SCHED;
	s_add_i32 s24, s41, s3
	v_lshl_add_u64 v[190:191], v[190:191], 0, s[50:51]
	s_mov_b32 m0, s24
	ds_read_b128 v[178:181], v145 offset:49152
	ds_read_b128 v[182:185], v145 offset:50176
	ds_read_b128 v[186:189], v145 offset:51200
	ds_read_b128 v[194:197], v145 offset:52224
	ds_read_b128 v[206:209], v145 offset:53248
	ds_read_b128 v[210:213], v145 offset:54272
	ds_read_b128 v[214:217], v145 offset:55296
	ds_read_b128 v[218:221], v145 offset:56320
	global_load_lds_dwordx4 v[190:191], off
	s_add_i32 m0, s24, 0x2000
	s_add_u32 s22, s22, 0x40080
	v_lshl_add_u64 v[190:191], v[202:203], 0, s[50:51]
	s_addc_u32 s23, s23, 0
	s_add_i32 s24, s42, s3
	global_load_lds_dwordx4 v[190:191], off
	v_lshl_add_u64 v[190:191], s[22:23], 0, v[132:133]
	s_mov_b32 m0, s24
	s_nop 0
	global_load_lds_dwordx4 v[190:191], off
	v_lshl_add_u64 v[190:191], s[22:23], 0, v[130:131]
	s_add_i32 m0, s24, 0x2000
	s_nop 0
	global_load_lds_dwordx4 v[190:191], off
	v_lshl_add_u64 v[190:191], v[204:205], 0, s[50:51]
	s_mov_b32 m0, s30
	s_nop 0
	global_load_lds_dwordx4 v[190:191], off
	v_lshl_add_u64 v[190:191], v[222:223], 0, s[50:51]
	s_mov_b32 m0, s31
	s_nop 0
	global_load_lds_dwordx4 v[190:191], off
	s_waitcnt vmcnt(8)
	s_waitcnt lgkmcnt(0)
	s_barrier
	s_setprio 1
	s_waitcnt lgkmcnt(0)
	v_mfma_f32_16x16x32_bf16 v[62:65], v[138:141], v[178:181], v[62:65]
	v_mfma_f32_16x16x32_bf16 v[58:61], v[150:153], v[178:181], v[58:61]
	v_mfma_f32_16x16x32_bf16 v[46:49], v[138:141], v[186:189], v[46:49]
	v_mfma_f32_16x16x32_bf16 v[42:45], v[150:153], v[186:189], v[42:45]
	v_mfma_f32_16x16x32_bf16 v[30:33], v[138:141], v[206:209], v[30:33]
	v_mfma_f32_16x16x32_bf16 v[26:29], v[150:153], v[206:209], v[26:29]
	v_mfma_f32_16x16x32_bf16 v[14:17], v[138:141], v[214:217], v[14:17]
	v_mfma_f32_16x16x32_bf16 v[10:13], v[150:153], v[214:217], v[10:13]
	v_mfma_f32_16x16x32_bf16 v[62:65], v[146:149], v[182:185], v[62:65]
	v_mfma_f32_16x16x32_bf16 v[58:61], v[154:157], v[182:185], v[58:61]
	v_mfma_f32_16x16x32_bf16 v[46:49], v[146:149], v[194:197], v[46:49]
	v_mfma_f32_16x16x32_bf16 v[42:45], v[154:157], v[194:197], v[42:45]
	v_mfma_f32_16x16x32_bf16 v[30:33], v[146:149], v[210:213], v[30:33]
	v_mfma_f32_16x16x32_bf16 v[26:29], v[154:157], v[210:213], v[26:29]
	v_mfma_f32_16x16x32_bf16 v[14:17], v[146:149], v[218:221], v[14:17]
	v_mfma_f32_16x16x32_bf16 v[10:13], v[154:157], v[218:221], v[10:13]
	s_setprio 0
	s_setprio 1
	v_mfma_f32_16x16x32_bf16 v[54:57], v[158:161], v[178:181], v[54:57]
	v_mfma_f32_16x16x32_bf16 v[50:53], v[170:173], v[178:181], v[50:53]
	v_mfma_f32_16x16x32_bf16 v[38:41], v[158:161], v[186:189], v[38:41]
	v_mfma_f32_16x16x32_bf16 v[34:37], v[170:173], v[186:189], v[34:37]
	v_mfma_f32_16x16x32_bf16 v[22:25], v[158:161], v[206:209], v[22:25]
	v_mfma_f32_16x16x32_bf16 v[18:21], v[170:173], v[206:209], v[18:21]
	v_mfma_f32_16x16x32_bf16 v[6:9], v[158:161], v[214:217], v[6:9]
	v_mfma_f32_16x16x32_bf16 v[2:5], v[170:173], v[214:217], v[2:5]
	v_mfma_f32_16x16x32_bf16 v[54:57], v[164:167], v[182:185], v[54:57]
	v_mfma_f32_16x16x32_bf16 v[50:53], v[174:177], v[182:185], v[50:53]
	v_mfma_f32_16x16x32_bf16 v[38:41], v[164:167], v[194:197], v[38:41]
	v_mfma_f32_16x16x32_bf16 v[34:37], v[174:177], v[194:197], v[34:37]
	v_mfma_f32_16x16x32_bf16 v[22:25], v[164:167], v[210:213], v[22:25]
	v_mfma_f32_16x16x32_bf16 v[18:21], v[174:177], v[210:213], v[18:21]
	v_mfma_f32_16x16x32_bf16 v[6:9], v[164:167], v[218:221], v[6:9]
	v_mfma_f32_16x16x32_bf16 v[2:5], v[174:177], v[218:221], v[2:5]
	s_setprio 0
	s_barrier
	s_add_i32 s40, s40, 2
	s_add_u32 s4, s4, 0x100
	s_addc_u32 s5, s5, 0
	s_add_u32 s38, s38, 0x100
	s_addc_u32 s39, s39, 0
	s_cmp_gt_u32 s40, 13
	s_cbranch_scc0 .LBB0_139
	s_and_b64 vcc, exec, s[12:13]
	s_cbranch_vccz .LBB0_142
	s_barrier

; #define PG8_STAGE(bufoff, gbase, voff) do { _Pragma("unroll") for (int _i = 0; _i < 2; ++_i) \
;         __builtin_amdgcn_global_load_lds((const unsigned*)((const char*)(gbase) + (voff)[_i]), (LAS unsigned*)(lds + (bufoff) + ldsw + _i * 8192), 16, 0, 0); } while (0)
; #define PG8_LDA(dst, b, h) do { _Pragma("unroll") for (int m = 0; m < 4; ++m) _Pragma("unroll") for (int k = 0; k < 2; ++k) dst[m][k] = *(const LAS bf16x8*)(lds + PG8_SA(b, h) + aoff + m * 2048 + k * 1024); } while (0)
; #define PG8_LDB(dst, b, h) do { _Pragma("unroll") for (int n = 0; n < 2; ++n) _Pragma("unroll") for (int k = 0; k < 2; ++k) dst[n][k] = *(const LAS bf16x8*)(lds + PG8_SB(b, h) + boff + n * 2048 + k * 1024); } while (0)
; #define PG8_MMA(ai, bj, At, Bt) do { __builtin_amdgcn_s_setprio(1); _Pragma("unroll") for (int m = 0; m < 4; ++m) _Pragma("unroll") for (int n = 0; n < 2; ++n) _Pragma("unroll") for (int k = 0; k < 2; ++k) \
;         acc[ai][bj][m][n] = __builtin_amdgcn_mfma_f32_16x16x32_bf16(Bt[n][k], At[m][k], acc[ai][bj][m][n], 0, 0, 0); __builtin_amdgcn_s_setprio(0); } while (0)
; #define PG8_WAIT_V(n) asm volatile("s_waitcnt vmcnt(" #n ")" ::: "memory")
; #define PG8_WAIT_L(n) asm volatile("s_waitcnt lgkmcnt(" #n ")" ::: "memory")
; #define PG8_BAR __builtin_amdgcn_s_barrier()
; template <class Epi, bool ALIGN_EPI = PG8_ALIGN, bool SP2 = PG8_SP2>
; __device__ __forceinline__ void gemm_phase(LAS unsigned char* lds, const Gemm g, const StaticOrder& S, const Epi& E) {
;     ...
;         for (int t = 0; t < nt; t += 2) {
;             const bool last = (t == nt - 2);
;             const char* a1 = cA + (size_t)(t + 1) * kstepA;
;             const char* a2 = last ? nA : cA + (size_t)(t + 2) * kstepA; const char* b2 = last ? nB : cB + (size_t)(t + 2) * kstepB;
;             const char* a3 = a2 + kstepA; const char* b3 = b2 + kstepB;
;             if constexpr (SP2) {
;             PG8_LDB(B0, 0, 0); PG8_LDB(B1, 0, 1); PG8_SCHED; PG8_LDA(At, 0, 0); PG8_STAGE(PG8_SA(1, 1), a1 + hstepA, voffA);
;             PG8_WAIT_V(8); PG8_WAIT_L(0); PG8_BAR; PG8_MMA(0, 0, At, B0); PG8_MMA(0, 1, At, B1); PG8_BAR; PG8_SCHED;
;             PG8_LDA(At, 0, 1); PG8_STAGE(PG8_SB(0, 0), b2, voffB); PG8_STAGE(PG8_SB(0, 1), b2 + hstepB, voffB); PG8_STAGE(PG8_SA(0, 0), a2, voffA);
;             PG8_WAIT_V(8); PG8_WAIT_L(0); PG8_BAR; PG8_MMA(1, 0, At, B0); PG8_MMA(1, 1, At, B1); PG8_BAR; PG8_SCHED;
.Lfirst_iter_u139:
	s_add_u32 s22, s4, 0xfffc0080
	s_addc_u32 s23, s5, -1
	s_add_i32 s41, 0, 0x10000
	s_cmp_eq_u32 s40, 12
	s_cselect_b32 s25, s17, s23
	s_cselect_b32 s24, s36, s22
	v_add_u32_e32 v0, s41, v143
	s_cselect_b32 s23, s15, s39
	s_cselect_b32 s22, s37, s38
	s_add_i32 s44, 0, 0x14000
	ds_read_b128 v[138:141], v0
	ds_read_b128 v[146:149], v0 offset:1024
	ds_read_b128 v[150:153], v0 offset:2048
	ds_read_b128 v[154:157], v0 offset:3072
	v_add_u32_e32 v0, s44, v143
	ds_read_b128 v[158:161], v0
	ds_read_b128 v[164:167], v0 offset:1024
	ds_read_b128 v[170:173], v0 offset:2048
	ds_read_b128 v[174:177], v0 offset:3072
	v_lshl_add_u64 v[190:191], s[4:5], 0, v[134:135]
	s_add_i32 m0, s26, 0xc000
	ds_read_b128 v[178:181], v145
	ds_read_b128 v[182:185], v145 offset:1024
	ds_read_b128 v[186:189], v145 offset:2048
	ds_read_b128 v[194:197], v145 offset:3072
	ds_read_b128 v[206:209], v145 offset:4096
	ds_read_b128 v[210:213], v145 offset:5120
	ds_read_b128 v[214:217], v145 offset:6144
	ds_read_b128 v[218:221], v145 offset:7168
	global_load_lds_dwordx4 v[190:191], off
	v_lshl_add_u64 v[190:191], s[4:5], 0, v[136:137]
	s_add_i32 m0, s26, 0xe000
	s_nop 0
	global_load_lds_dwordx4 v[190:191], off
	s_waitcnt vmcnt(8)
	s_waitcnt lgkmcnt(0)
	s_barrier
	s_setprio 1
	s_waitcnt lgkmcnt(0)
	v_mfma_f32_16x16x32_bf16 v[126:129], v[138:141], v[178:181], 0
	v_mfma_f32_16x16x32_bf16 v[122:125], v[150:153], v[178:181], 0
	v_mfma_f32_16x16x32_bf16 v[110:113], v[138:141], v[186:189], 0
	v_mfma_f32_16x16x32_bf16 v[106:109], v[150:153], v[186:189], 0
	v_mfma_f32_16x16x32_bf16 v[94:97], v[138:141], v[206:209], 0
	v_mfma_f32_16x16x32_bf16 v[90:93], v[150:153], v[206:209], 0
	v_mfma_f32_16x16x32_bf16 v[78:81], v[138:141], v[214:217], 0
	v_mfma_f32_16x16x32_bf16 v[74:77], v[150:153], v[214:217], 0
	v_mfma_f32_16x16x32_bf16 v[126:129], v[146:149], v[182:185], v[126:129]
	v_mfma_f32_16x16x32_bf16 v[122:125], v[154:157], v[182:185], v[122:125]
	v_mfma_f32_16x16x32_bf16 v[110:113], v[146:149], v[194:197], v[110:113]
	v_mfma_f32_16x16x32_bf16 v[106:109], v[154:157], v[194:197], v[106:109]
	v_mfma_f32_16x16x32_bf16 v[94:97], v[146:149], v[210:213], v[94:97]
	v_mfma_f32_16x16x32_bf16 v[90:93], v[154:157], v[210:213], v[90:93]
	v_mfma_f32_16x16x32_bf16 v[78:81], v[146:149], v[218:221], v[78:81]
	v_mfma_f32_16x16x32_bf16 v[74:77], v[154:157], v[218:221], v[74:77]
	s_setprio 0
	s_setprio 1
	v_mfma_f32_16x16x32_bf16 v[118:121], v[158:161], v[178:181], 0
	v_mfma_f32_16x16x32_bf16 v[114:117], v[170:173], v[178:181], 0
	v_mfma_f32_16x16x32_bf16 v[102:105], v[158:161], v[186:189], 0
	v_mfma_f32_16x16x32_bf16 v[98:101], v[170:173], v[186:189], 0
	v_mfma_f32_16x16x32_bf16 v[86:89], v[158:161], v[206:209], 0
	v_mfma_f32_16x16x32_bf16 v[82:85], v[170:173], v[206:209], 0
	v_mfma_f32_16x16x32_bf16 v[70:73], v[158:161], v[214:217], 0
	v_mfma_f32_16x16x32_bf16 v[66:69], v[170:173], v[214:217], 0
	v_mfma_f32_16x16x32_bf16 v[118:121], v[164:167], v[182:185], v[118:121]
	v_mfma_f32_16x16x32_bf16 v[114:117], v[174:177], v[182:185], v[114:117]
	v_mfma_f32_16x16x32_bf16 v[102:105], v[164:167], v[194:197], v[102:105]
	v_mfma_f32_16x16x32_bf16 v[98:101], v[174:177], v[194:197], v[98:101]
	v_mfma_f32_16x16x32_bf16 v[86:89], v[164:167], v[210:213], v[86:89]
	v_mfma_f32_16x16x32_bf16 v[82:85], v[174:177], v[210:213], v[82:85]
	v_mfma_f32_16x16x32_bf16 v[70:73], v[164:167], v[218:221], v[70:73]
	v_mfma_f32_16x16x32_bf16 v[66:69], v[174:177], v[218:221], v[66:69]
	s_setprio 0
	s_barrier
	s_add_i32 s41, s41, s3
	v_lshl_add_u64 v[190:191], s[22:23], 0, v[132:133]
	s_mov_b32 m0, s41
	ds_read_b128 v[178:181], v145 offset:16384
	ds_read_b128 v[182:185], v145 offset:17408
	ds_read_b128 v[186:189], v145 offset:18432
	ds_read_b128 v[194:197], v145 offset:19456
	ds_read_b128 v[206:209], v145 offset:20480
	ds_read_b128 v[210:213], v145 offset:21504
	ds_read_b128 v[214:217], v145 offset:22528
	ds_read_b128 v[218:221], v145 offset:23552
	global_load_lds_dwordx4 v[190:191], off
	s_add_i32 m0, s41, 0x2000
	s_add_u32 s42, s22, 0x40000
	v_lshl_add_u64 v[202:203], s[22:23], 0, v[130:131]
	s_addc_u32 s43, s23, 0
	s_add_i32 s41, s44, s3
	global_load_lds_dwordx4 v[202:203], off
	v_lshl_add_u64 v[204:205], s[42:43], 0, v[132:133]
	s_mov_b32 m0, s41
	v_lshl_add_u64 v[222:223], s[24:25], 0, v[130:131]
	global_load_lds_dwordx4 v[204:205], off
	v_lshl_add_u64 v[204:205], s[42:43], 0, v[130:131]
	s_add_i32 m0, s41, 0x2000
	s_nop 0
	global_load_lds_dwordx4 v[204:205], off
	v_lshl_add_u64 v[204:205], s[24:25], 0, v[132:133]
	s_mov_b32 m0, s26
	s_nop 0
	global_load_lds_dwordx4 v[204:205], off
	s_mov_b32 m0, s27
	s_nop 0
	global_load_lds_dwordx4 v[222:223], off
	s_waitcnt vmcnt(8)
	s_waitcnt lgkmcnt(0)
	s_barrier
; #define PG8_STAGE(bufoff, gbase, voff) do { _Pragma("unroll") for (int _i = 0; _i < 2; ++_i) \
;         __builtin_amdgcn_global_load_lds((const unsigned*)((const char*)(gbase) + (voff)[_i]), (LAS unsigned*)(lds + (bufoff) + ldsw + _i * 8192), 16, 0, 0); } while (0)
; #define PG8_LDA(dst, b, h) do { _Pragma("unroll") for (int m = 0; m < 4; ++m) _Pragma("unroll") for (int k = 0; k < 2; ++k) dst[m][k] = *(const LAS bf16x8*)(lds + PG8_SA(b, h) + aoff + m * 2048 + k * 1024); } while (0)
; #define PG8_LDB(dst, b, h) do { _Pragma("unroll") for (int n = 0; n < 2; ++n) _Pragma("unroll") for (int k = 0; k < 2; ++k) dst[n][k] = *(const LAS bf16x8*)(lds + PG8_SB(b, h) + boff + n * 2048 + k * 1024); } while (0)
; #define PG8_MMA(ai, bj, At, Bt) do { __builtin_amdgcn_s_setprio(1); _Pragma("unroll") for (int m = 0; m < 4; ++m) _Pragma("unroll") for (int n = 0; n < 2; ++n) _Pragma("unroll") for (int k = 0; k < 2; ++k) \
;         acc[ai][bj][m][n] = __builtin_amdgcn_mfma_f32_16x16x32_bf16(Bt[n][k], At[m][k], acc[ai][bj][m][n], 0, 0, 0); __builtin_amdgcn_s_setprio(0); } while (0)
; #define PG8_WAIT_V(n) asm volatile("s_waitcnt vmcnt(" #n ")" ::: "memory")
; #define PG8_WAIT_L(n) asm volatile("s_waitcnt lgkmcnt(" #n ")" ::: "memory")
; #define PG8_BAR __builtin_amdgcn_s_barrier()
; #define PG8_SCHED __builtin_amdgcn_sched_barrier(0)
; template <class Epi, bool ALIGN_EPI = PG8_ALIGN, bool SP2 = PG8_SP2>
; __device__ __forceinline__ void gemm_phase(LAS unsigned char* lds, const Gemm g, const StaticOrder& S, const Epi& E) {
;     ...
;             PG8_WAIT_V(8); PG8_WAIT_L(0); PG8_BAR; PG8_MMA(1, 0, At, B0); PG8_MMA(1, 1, At, B1); PG8_BAR; PG8_SCHED;
;             PG8_LDB(B0, 1, 0); PG8_LDB(B1, 1, 1); PG8_SCHED; PG8_LDA(At, 1, 0); PG8_STAGE(PG8_SA(0, 1), a2 + hstepA, voffA);
;             PG8_WAIT_V(8); PG8_WAIT_L(0); PG8_BAR; PG8_MMA(0, 0, At, B0); PG8_MMA(0, 1, At, B1); PG8_BAR; PG8_SCHED;
;             PG8_LDA(At, 1, 1); PG8_STAGE(PG8_SB(1, 0), b3, voffB); PG8_STAGE(PG8_SB(1, 1), b3 + hstepB, voffB); PG8_STAGE(PG8_SA(1, 0), a3, voffA);
	s_setprio 1
	s_waitcnt lgkmcnt(0)
	v_mfma_f32_16x16x32_bf16 v[62:65], v[138:141], v[178:181], 0
	v_mfma_f32_16x16x32_bf16 v[58:61], v[150:153], v[178:181], 0
	v_mfma_f32_16x16x32_bf16 v[46:49], v[138:141], v[186:189], 0
	v_mfma_f32_16x16x32_bf16 v[42:45], v[150:153], v[186:189], 0
	v_mfma_f32_16x16x32_bf16 v[30:33], v[138:141], v[206:209], 0
	v_mfma_f32_16x16x32_bf16 v[26:29], v[150:153], v[206:209], 0
	v_mfma_f32_16x16x32_bf16 v[14:17], v[138:141], v[214:217], 0
	v_mfma_f32_16x16x32_bf16 v[10:13], v[150:153], v[214:217], 0
	v_mfma_f32_16x16x32_bf16 v[62:65], v[146:149], v[182:185], v[62:65]
	v_mfma_f32_16x16x32_bf16 v[58:61], v[154:157], v[182:185], v[58:61]
	v_mfma_f32_16x16x32_bf16 v[46:49], v[146:149], v[194:197], v[46:49]
	v_mfma_f32_16x16x32_bf16 v[42:45], v[154:157], v[194:197], v[42:45]
	v_mfma_f32_16x16x32_bf16 v[30:33], v[146:149], v[210:213], v[30:33]
	v_mfma_f32_16x16x32_bf16 v[26:29], v[154:157], v[210:213], v[26:29]
	v_mfma_f32_16x16x32_bf16 v[14:17], v[146:149], v[218:221], v[14:17]
	v_mfma_f32_16x16x32_bf16 v[10:13], v[154:157], v[218:221], v[10:13]
	s_setprio 0
	s_setprio 1
	v_mfma_f32_16x16x32_bf16 v[54:57], v[158:161], v[178:181], 0
	v_mfma_f32_16x16x32_bf16 v[50:53], v[170:173], v[178:181], 0
	v_mfma_f32_16x16x32_bf16 v[38:41], v[158:161], v[186:189], 0
	v_mfma_f32_16x16x32_bf16 v[34:37], v[170:173], v[186:189], 0
	v_mfma_f32_16x16x32_bf16 v[22:25], v[158:161], v[206:209], 0
	v_mfma_f32_16x16x32_bf16 v[18:21], v[170:173], v[206:209], 0
	v_mfma_f32_16x16x32_bf16 v[6:9], v[158:161], v[214:217], 0
	v_mfma_f32_16x16x32_bf16 v[2:5], v[170:173], v[214:217], 0
	v_mfma_f32_16x16x32_bf16 v[54:57], v[164:167], v[182:185], v[54:57]
	v_mfma_f32_16x16x32_bf16 v[50:53], v[174:177], v[182:185], v[50:53]
	v_mfma_f32_16x16x32_bf16 v[38:41], v[164:167], v[194:197], v[38:41]
	v_mfma_f32_16x16x32_bf16 v[34:37], v[174:177], v[194:197], v[34:37]
	v_mfma_f32_16x16x32_bf16 v[22:25], v[164:167], v[210:213], v[22:25]
	v_mfma_f32_16x16x32_bf16 v[18:21], v[174:177], v[210:213], v[18:21]
	v_mfma_f32_16x16x32_bf16 v[6:9], v[164:167], v[218:221], v[6:9]
	v_mfma_f32_16x16x32_bf16 v[2:5], v[174:177], v[218:221], v[2:5]
	s_setprio 0
	s_barrier
	s_add_i32 s41, 0, 0x18000
	v_add_u32_e32 v0, s41, v143
	s_add_i32 s42, 0, 0x1c000
	ds_read_b128 v[138:141], v0
	ds_read_b128 v[146:149], v0 offset:1024
	ds_read_b128 v[150:153], v0 offset:2048
	ds_read_b128 v[154:157], v0 offset:3072
	v_add_u32_e32 v0, s42, v143
	ds_read_b128 v[158:161], v0
	ds_read_b128 v[164:167], v0 offset:1024
	ds_read_b128 v[170:173], v0 offset:2048
	ds_read_b128 v[174:177], v0 offset:3072
	s_add_u32 s24, s24, 0x40000
	s_addc_u32 s25, s25, 0
	s_mov_b32 m0, s28
	v_lshl_add_u64 v[224:225], s[24:25], 0, v[132:133]
	ds_read_b128 v[178:181], v145 offset:32768
	ds_read_b128 v[182:185], v145 offset:33792
	ds_read_b128 v[186:189], v145 offset:34816
	ds_read_b128 v[194:197], v145 offset:35840
	ds_read_b128 v[206:209], v145 offset:36864
	ds_read_b128 v[210:213], v145 offset:37888
	ds_read_b128 v[214:217], v145 offset:38912
	ds_read_b128 v[218:221], v145 offset:39936
	global_load_lds_dwordx4 v[224:225], off
	v_lshl_add_u64 v[224:225], s[24:25], 0, v[130:131]
	s_mov_b32 m0, s29
	s_nop 0
	global_load_lds_dwordx4 v[224:225], off
	s_waitcnt vmcnt(8)
	s_waitcnt lgkmcnt(0)
	s_barrier
	s_setprio 1
	s_waitcnt lgkmcnt(0)
	v_mfma_f32_16x16x32_bf16 v[126:129], v[138:141], v[178:181], v[126:129]
	v_mfma_f32_16x16x32_bf16 v[122:125], v[150:153], v[178:181], v[122:125]
	v_mfma_f32_16x16x32_bf16 v[110:113], v[138:141], v[186:189], v[110:113]
	v_mfma_f32_16x16x32_bf16 v[106:109], v[150:153], v[186:189], v[106:109]
	v_mfma_f32_16x16x32_bf16 v[94:97], v[138:141], v[206:209], v[94:97]
	v_mfma_f32_16x16x32_bf16 v[90:93], v[150:153], v[206:209], v[90:93]
	v_mfma_f32_16x16x32_bf16 v[78:81], v[138:141], v[214:217], v[78:81]
	v_mfma_f32_16x16x32_bf16 v[74:77], v[150:153], v[214:217], v[74:77]
	v_mfma_f32_16x16x32_bf16 v[126:129], v[146:149], v[182:185], v[126:129]
	v_mfma_f32_16x16x32_bf16 v[122:125], v[154:157], v[182:185], v[122:125]
	v_mfma_f32_16x16x32_bf16 v[110:113], v[146:149], v[194:197], v[110:113]
	v_mfma_f32_16x16x32_bf16 v[106:109], v[154:157], v[194:197], v[106:109]
	v_mfma_f32_16x16x32_bf16 v[94:97], v[146:149], v[210:213], v[94:97]
	v_mfma_f32_16x16x32_bf16 v[90:93], v[154:157], v[210:213], v[90:93]
	v_mfma_f32_16x16x32_bf16 v[78:81], v[146:149], v[218:221], v[78:81]
	v_mfma_f32_16x16x32_bf16 v[74:77], v[154:157], v[218:221], v[74:77]
	s_setprio 0
	s_setprio 1
	v_mfma_f32_16x16x32_bf16 v[118:121], v[158:161], v[178:181], v[118:121]
	v_mfma_f32_16x16x32_bf16 v[114:117], v[170:173], v[178:181], v[114:117]
	v_mfma_f32_16x16x32_bf16 v[102:105], v[158:161], v[186:189], v[102:105]
	v_mfma_f32_16x16x32_bf16 v[98:101], v[170:173], v[186:189], v[98:101]
	v_mfma_f32_16x16x32_bf16 v[86:89], v[158:161], v[206:209], v[86:89]
	v_mfma_f32_16x16x32_bf16 v[82:85], v[170:173], v[206:209], v[82:85]
	v_mfma_f32_16x16x32_bf16 v[70:73], v[158:161], v[214:217], v[70:73]
	v_mfma_f32_16x16x32_bf16 v[66:69], v[170:173], v[214:217], v[66:69]
	v_mfma_f32_16x16x32_bf16 v[118:121], v[164:167], v[182:185], v[118:121]
	v_mfma_f32_16x16x32_bf16 v[114:117], v[174:177], v[182:185], v[114:117]
	v_mfma_f32_16x16x32_bf16 v[102:105], v[164:167], v[194:197], v[102:105]
	v_mfma_f32_16x16x32_bf16 v[98:101], v[174:177], v[194:197], v[98:101]
	v_mfma_f32_16x16x32_bf16 v[86:89], v[164:167], v[210:213], v[86:89]
	v_mfma_f32_16x16x32_bf16 v[82:85], v[174:177], v[210:213], v[82:85]
	v_mfma_f32_16x16x32_bf16 v[70:73], v[164:167], v[218:221], v[70:73]
	v_mfma_f32_16x16x32_bf16 v[66:69], v[174:177], v[218:221], v[66:69]
	s_setprio 0
	s_barrier
; #define PG8_STAGE(bufoff, gbase, voff) do { _Pragma("unroll") for (int _i = 0; _i < 2; ++_i) \
;         __builtin_amdgcn_global_load_lds((const unsigned*)((const char*)(gbase) + (voff)[_i]), (LAS unsigned*)(lds + (bufoff) + ldsw + _i * 8192), 16, 0, 0); } while (0)
; #define PG8_LDA(dst, b, h) do { _Pragma("unroll") for (int m = 0; m < 4; ++m) _Pragma("unroll") for (int k = 0; k < 2; ++k) dst[m][k] = *(const LAS bf16x8*)(lds + PG8_SA(b, h) + aoff + m * 2048 + k * 1024); } while (0)
; #define PG8_MMA(ai, bj, At, Bt) do { __builtin_amdgcn_s_setprio(1); _Pragma("unroll") for (int m = 0; m < 4; ++m) _Pragma("unroll") for (int n = 0; n < 2; ++n) _Pragma("unroll") for (int k = 0; k < 2; ++k) \
;         acc[ai][bj][m][n] = __builtin_amdgcn_mfma_f32_16x16x32_bf16(Bt[n][k], At[m][k], acc[ai][bj][m][n], 0, 0, 0); __builtin_amdgcn_s_setprio(0); } while (0)
; #define PG8_WAIT_V(n) asm volatile("s_waitcnt vmcnt(" #n ")" ::: "memory")
; #define PG8_WAIT_L(n) asm volatile("s_waitcnt lgkmcnt(" #n ")" ::: "memory")
; #define PG8_BAR __builtin_amdgcn_s_barrier()
; #define PG8_SCHED __builtin_amdgcn_sched_barrier(0)
; template <class Epi, bool ALIGN_EPI = PG8_ALIGN, bool SP2 = PG8_SP2>
; __device__ __forceinline__ void gemm_phase(LAS unsigned char* lds, const Gemm g, const StaticOrder& S, const Epi& E) {
;     ...
;             PG8_WAIT_V(8); PG8_WAIT_L(0); PG8_BAR; PG8_MMA(0, 0, At, B0); PG8_MMA(0, 1, At, B1); PG8_BAR; PG8_SCHED;
;             PG8_LDA(At, 1, 1); PG8_STAGE(PG8_SB(1, 0), b3, voffB); PG8_STAGE(PG8_SB(1, 1), b3 + hstepB, voffB); PG8_STAGE(PG8_SA(1, 0), a3, voffA);
;             PG8_WAIT_V(8); PG8_WAIT_L(0); PG8_BAR; PG8_MMA(1, 0, At, B0); PG8_MMA(1, 1, At, B1); PG8_BAR; PG8_SCHED;
	s_add_i32 s24, s41, s3
	v_lshl_add_u64 v[190:191], v[190:191], 0, s[50:51]
	s_mov_b32 m0, s24
	ds_read_b128 v[178:181], v145 offset:49152
	ds_read_b128 v[182:185], v145 offset:50176
	ds_read_b128 v[186:189], v145 offset:51200
	ds_read_b128 v[194:197], v145 offset:52224
	ds_read_b128 v[206:209], v145 offset:53248
	ds_read_b128 v[210:213], v145 offset:54272
	ds_read_b128 v[214:217], v145 offset:55296
	ds_read_b128 v[218:221], v145 offset:56320
	global_load_lds_dwordx4 v[190:191], off
	s_add_i32 m0, s24, 0x2000
	s_add_u32 s22, s22, 0x40080
	v_lshl_add_u64 v[190:191], v[202:203], 0, s[50:51]
	s_addc_u32 s23, s23, 0
	s_add_i32 s24, s42, s3
	global_load_lds_dwordx4 v[190:191], off
	v_lshl_add_u64 v[190:191], s[22:23], 0, v[132:133]
	s_mov_b32 m0, s24
	s_nop 0
	global_load_lds_dwordx4 v[190:191], off
	v_lshl_add_u64 v[190:191], s[22:23], 0, v[130:131]
	s_add_i32 m0, s24, 0x2000
	s_nop 0
	global_load_lds_dwordx4 v[190:191], off
	v_lshl_add_u64 v[190:191], v[204:205], 0, s[50:51]
	s_mov_b32 m0, s30
	s_nop 0
	global_load_lds_dwordx4 v[190:191], off
	v_lshl_add_u64 v[190:191], v[222:223], 0, s[50:51]
	s_mov_b32 m0, s31
	s_nop 0
	global_load_lds_dwordx4 v[190:191], off
	s_waitcnt vmcnt(8)
	s_waitcnt lgkmcnt(0)
	s_barrier
	s_setprio 1
	s_waitcnt lgkmcnt(0)
	v_mfma_f32_16x16x32_bf16 v[62:65], v[138:141], v[178:181], v[62:65]
	v_mfma_f32_16x16x32_bf16 v[58:61], v[150:153], v[178:181], v[58:61]
	v_mfma_f32_16x16x32_bf16 v[46:49], v[138:141], v[186:189], v[46:49]
	v_mfma_f32_16x16x32_bf16 v[42:45], v[150:153], v[186:189], v[42:45]
	v_mfma_f32_16x16x32_bf16 v[30:33], v[138:141], v[206:209], v[30:33]
	v_mfma_f32_16x16x32_bf16 v[26:29], v[150:153], v[206:209], v[26:29]
	v_mfma_f32_16x16x32_bf16 v[14:17], v[138:141], v[214:217], v[14:17]
	v_mfma_f32_16x16x32_bf16 v[10:13], v[150:153], v[214:217], v[10:13]
	v_mfma_f32_16x16x32_bf16 v[62:65], v[146:149], v[182:185], v[62:65]
	v_mfma_f32_16x16x32_bf16 v[58:61], v[154:157], v[182:185], v[58:61]
	v_mfma_f32_16x16x32_bf16 v[46:49], v[146:149], v[194:197], v[46:49]
	v_mfma_f32_16x16x32_bf16 v[42:45], v[154:157], v[194:197], v[42:45]
	v_mfma_f32_16x16x32_bf16 v[30:33], v[146:149], v[210:213], v[30:33]
	v_mfma_f32_16x16x32_bf16 v[26:29], v[154:157], v[210:213], v[26:29]
	v_mfma_f32_16x16x32_bf16 v[14:17], v[146:149], v[218:221], v[14:17]
	v_mfma_f32_16x16x32_bf16 v[10:13], v[154:157], v[218:221], v[10:13]
	s_setprio 0
	s_setprio 1
	v_mfma_f32_16x16x32_bf16 v[54:57], v[158:161], v[178:181], v[54:57]
	v_mfma_f32_16x16x32_bf16 v[50:53], v[170:173], v[178:181], v[50:53]
	v_mfma_f32_16x16x32_bf16 v[38:41], v[158:161], v[186:189], v[38:41]
	v_mfma_f32_16x16x32_bf16 v[34:37], v[170:173], v[186:189], v[34:37]
	v_mfma_f32_16x16x32_bf16 v[22:25], v[158:161], v[206:209], v[22:25]
	v_mfma_f32_16x16x32_bf16 v[18:21], v[170:173], v[206:209], v[18:21]
	v_mfma_f32_16x16x32_bf16 v[6:9], v[158:161], v[214:217], v[6:9]
	v_mfma_f32_16x16x32_bf16 v[2:5], v[170:173], v[214:217], v[2:5]
	v_mfma_f32_16x16x32_bf16 v[54:57], v[164:167], v[182:185], v[54:57]
	v_mfma_f32_16x16x32_bf16 v[50:53], v[174:177], v[182:185], v[50:53]
	v_mfma_f32_16x16x32_bf16 v[38:41], v[164:167], v[194:197], v[38:41]
	v_mfma_f32_16x16x32_bf16 v[34:37], v[174:177], v[194:197], v[34:37]
	v_mfma_f32_16x16x32_bf16 v[22:25], v[164:167], v[210:213], v[22:25]
	v_mfma_f32_16x16x32_bf16 v[18:21], v[174:177], v[210:213], v[18:21]
	v_mfma_f32_16x16x32_bf16 v[6:9], v[164:167], v[218:221], v[6:9]
	v_mfma_f32_16x16x32_bf16 v[2:5], v[174:177], v[218:221], v[2:5]
	s_setprio 0
	s_barrier
	s_add_i32 s40, s40, 2
	s_add_u32 s4, s4, 0x100
	s_addc_u32 s5, s5, 0
	s_add_u32 s38, s38, 0x100
	s_addc_u32 s39, s39, 0
	s_cmp_gt_u32 s40, 13
	s_branch .LBB0_139

; #define PG8_STAGE(bufoff, gbase, voff) do { _Pragma("unroll") for (int _i = 0; _i < 2; ++_i) \
;         __builtin_amdgcn_global_load_lds((const unsigned*)((const char*)(gbase) + (voff)[_i]), (LAS unsigned*)(lds + (bufoff) + ldsw + _i * 8192), 16, 0, 0); } while (0)
; #define PG8_LDA(dst, b, h) do { _Pragma("unroll") for (int m = 0; m < 4; ++m) _Pragma("unroll") for (int k = 0; k < 2; ++k) dst[m][k] = *(const LAS bf16x8*)(lds + PG8_SA(b, h) + aoff + m * 2048 + k * 1024); } while (0)
; #define PG8_LDB(dst, b, h) do { _Pragma("unroll") for (int n = 0; n < 2; ++n) _Pragma("unroll") for (int k = 0; k < 2; ++k) dst[n][k] = *(const LAS bf16x8*)(lds + PG8_SB(b, h) + boff + n * 2048 + k * 1024); } while (0)
; #define PG8_WAIT_V(n) asm volatile("s_waitcnt vmcnt(" #n ")" ::: "memory")
; #define PG8_WAIT_L(n) asm volatile("s_waitcnt lgkmcnt(" #n ")" ::: "memory")
; #define PG8_BAR __builtin_amdgcn_s_barrier()
; #define PG8_SCHED __builtin_amdgcn_sched_barrier(0)
; template <class Epi, bool ALIGN_EPI = PG8_ALIGN, bool SP2 = PG8_SP2>
; __device__ __forceinline__ void gemm_phase(LAS unsigned char* lds, const Gemm g, const StaticOrder& S, const Epi& E) {
;     ...
;         const bool has_next = S.next(ui + 1, nxt);
;         const char* nA = has_next ? (const char*)g.A + (size_t)nxt.pm * tstepA : cA; const char* nB = has_next ? (const char*)g.Bt + (size_t)nxt.pn * tstepB : cB;
;         for (int t = 0; t < nt; t += 2) {
;             const bool last = (t == nt - 2);
;             const char* a1 = cA + (size_t)(t + 1) * kstepA;
;             const char* a2 = last ? nA : cA + (size_t)(t + 2) * kstepA; const char* b2 = last ? nB : cB + (size_t)(t + 2) * kstepB;
;             const char* a3 = a2 + kstepA; const char* b3 = b2 + kstepB;
;             if constexpr (SP2) {
;             PG8_LDB(B0, 0, 0); PG8_LDB(B1, 0, 1); PG8_SCHED; PG8_LDA(At, 0, 0); PG8_STAGE(PG8_SA(1, 1), a1 + hstepA, voffA);
;             PG8_WAIT_V(8); PG8_WAIT_L(0); PG8_BAR; PG8_MMA(0, 0, At, B0); PG8_MMA(0, 1, At, B1); PG8_BAR; PG8_SCHED;
;             PG8_LDA(At, 0, 1); PG8_STAGE(PG8_SB(0, 0), b2, voffB); PG8_STAGE(PG8_SB(0, 1), b2 + hstepB, voffB); PG8_STAGE(PG8_SA(0, 0), a2, voffA);
;             PG8_WAIT_V(8); PG8_WAIT_L(0); PG8_BAR; PG8_MMA(1, 0, At, B0); PG8_MMA(1, 1, At, B1); PG8_BAR; PG8_SCHED;
.LBB0_534:
	s_ashr_i32 s19, s18, 31
	s_lshl_b64 s[8:9], s[18:19], 19
	v_readlane_b32 s20, v252, 58
	v_readlane_b32 s21, v252, 59
	s_add_u32 s20, s20, s8
	s_addc_u32 s21, s21, s9
	s_and_b64 s[8:9], s[6:7], exec
	s_cselect_b32 s19, s21, s1
	s_cselect_b32 s35, s20, s0
	s_ashr_i32 s17, s16, 31
	s_lshl_b64 s[8:9], s[16:17], 19
	v_readlane_b32 s22, v252, 54
	v_readlane_b32 s23, v252, 55
	s_add_u32 s22, s22, s8
	s_addc_u32 s23, s23, s9
	s_and_b64 s[8:9], s[6:7], exec
	s_cselect_b32 s17, s23, s5
	s_cselect_b32 s36, s22, s4
	s_add_u32 s0, s0, 0x40080
	s_addc_u32 s1, s1, 0
	s_add_u32 s37, s4, 0x100
	s_addc_u32 s38, s5, 0
	s_mov_b32 s39, -2
.LBB0_535:
	s_cmp_eq_u32 s39, -2
	s_cbranch_scc1 .Lfirst_iter_u535
	s_add_u32 s4, s0, 0xfffc0080
	s_addc_u32 s5, s1, -1
	s_add_i32 s40, 0, 0x10000
	s_cmp_eq_u32 s39, 12
	s_cselect_b32 s9, s19, s5
	s_cselect_b32 s8, s35, s4
	v_add_u32_e32 v0, s40, v206
	s_cselect_b32 s5, s17, s38
	s_cselect_b32 s4, s36, s37
	s_add_i32 s42, 0, 0x14000
	ds_read_b128 v[114:117], v0
	ds_read_b128 v[122:125], v0 offset:1024
	ds_read_b128 v[130:133], v0 offset:2048
	ds_read_b128 v[134:137], v0 offset:3072
	v_add_u32_e32 v0, s42, v206
	ds_read_b128 v[146:149], v0
	ds_read_b128 v[150:153], v0 offset:1024
	ds_read_b128 v[154:157], v0 offset:2048
	ds_read_b128 v[158:161], v0 offset:3072
	v_lshl_add_u64 v[190:191], s[0:1], 0, v[178:179]
	s_add_i32 m0, s24, 0xc000
	ds_read_b128 v[164:167], v211
	ds_read_b128 v[182:185], v211 offset:1024
	ds_read_b128 v[186:189], v211 offset:2048
	ds_read_b128 v[194:197], v211 offset:3072
	ds_read_b128 v[212:215], v211 offset:4096
	ds_read_b128 v[216:219], v211 offset:5120
	ds_read_b128 v[220:223], v211 offset:6144
	ds_read_b128 v[224:227], v211 offset:7168
	global_load_lds_dwordx4 v[190:191], off
	v_lshl_add_u64 v[190:191], s[0:1], 0, v[180:181]
	s_add_i32 m0, s24, 0xe000
	s_nop 0
	global_load_lds_dwordx4 v[190:191], off
	s_waitcnt vmcnt(8)
	s_waitcnt lgkmcnt(0)
	s_barrier
	s_setprio 1
	s_waitcnt lgkmcnt(0)
	v_mfma_f32_16x16x32_bf16 v[70:73], v[114:117], v[164:167], v[70:73]
	v_mfma_f32_16x16x32_bf16 v[30:33], v[130:133], v[164:167], v[30:33]
	v_mfma_f32_16x16x32_bf16 v[58:61], v[114:117], v[186:189], v[58:61]
	v_mfma_f32_16x16x32_bf16 v[26:29], v[130:133], v[186:189], v[26:29]
	v_mfma_f32_16x16x32_bf16 v[54:57], v[114:117], v[212:215], v[54:57]
	v_mfma_f32_16x16x32_bf16 v[22:25], v[130:133], v[212:215], v[22:25]
	v_mfma_f32_16x16x32_bf16 v[50:53], v[114:117], v[220:223], v[50:53]
	v_mfma_f32_16x16x32_bf16 v[18:21], v[130:133], v[220:223], v[18:21]
	v_mfma_f32_16x16x32_bf16 v[70:73], v[122:125], v[182:185], v[70:73]
	v_mfma_f32_16x16x32_bf16 v[30:33], v[134:137], v[182:185], v[30:33]
	v_mfma_f32_16x16x32_bf16 v[58:61], v[122:125], v[194:197], v[58:61]
	v_mfma_f32_16x16x32_bf16 v[26:29], v[134:137], v[194:197], v[26:29]
	v_mfma_f32_16x16x32_bf16 v[54:57], v[122:125], v[216:219], v[54:57]
	v_mfma_f32_16x16x32_bf16 v[22:25], v[134:137], v[216:219], v[22:25]
	v_mfma_f32_16x16x32_bf16 v[50:53], v[122:125], v[224:227], v[50:53]
	v_mfma_f32_16x16x32_bf16 v[18:21], v[134:137], v[224:227], v[18:21]
	s_setprio 0
	s_setprio 1
	v_mfma_f32_16x16x32_bf16 v[142:145], v[146:149], v[164:167], v[142:145]
	v_mfma_f32_16x16x32_bf16 v[138:141], v[154:157], v[164:167], v[138:141]
	v_mfma_f32_16x16x32_bf16 v[126:129], v[146:149], v[186:189], v[126:129]
	v_mfma_f32_16x16x32_bf16 v[118:121], v[154:157], v[186:189], v[118:121]
	v_mfma_f32_16x16x32_bf16 v[110:113], v[146:149], v[212:215], v[110:113]
	v_mfma_f32_16x16x32_bf16 v[106:109], v[154:157], v[212:215], v[106:109]
	v_mfma_f32_16x16x32_bf16 v[102:105], v[146:149], v[220:223], v[102:105]
	v_mfma_f32_16x16x32_bf16 v[98:101], v[154:157], v[220:223], v[98:101]
	v_mfma_f32_16x16x32_bf16 v[142:145], v[150:153], v[182:185], v[142:145]
	v_mfma_f32_16x16x32_bf16 v[138:141], v[158:161], v[182:185], v[138:141]
	v_mfma_f32_16x16x32_bf16 v[126:129], v[150:153], v[194:197], v[126:129]
	v_mfma_f32_16x16x32_bf16 v[118:121], v[158:161], v[194:197], v[118:121]
	v_mfma_f32_16x16x32_bf16 v[110:113], v[150:153], v[216:219], v[110:113]
	v_mfma_f32_16x16x32_bf16 v[106:109], v[158:161], v[216:219], v[106:109]
	v_mfma_f32_16x16x32_bf16 v[102:105], v[150:153], v[224:227], v[102:105]
	v_mfma_f32_16x16x32_bf16 v[98:101], v[158:161], v[224:227], v[98:101]
	s_setprio 0
	s_barrier
	s_add_i32 s40, s40, s3
	v_lshl_add_u64 v[190:191], s[4:5], 0, v[172:173]
	s_mov_b32 m0, s40
	ds_read_b128 v[164:167], v211 offset:16384
	ds_read_b128 v[182:185], v211 offset:17408
	ds_read_b128 v[186:189], v211 offset:18432
	ds_read_b128 v[194:197], v211 offset:19456
	ds_read_b128 v[212:215], v211 offset:20480
	ds_read_b128 v[216:219], v211 offset:21504
	ds_read_b128 v[220:223], v211 offset:22528
	ds_read_b128 v[224:227], v211 offset:23552
	global_load_lds_dwordx4 v[190:191], off
	s_add_i32 m0, s40, 0x2000
	s_add_u32 s40, s4, 0x40000
	v_lshl_add_u64 v[202:203], s[4:5], 0, v[170:171]
	s_addc_u32 s41, s5, 0
	s_add_i32 s42, s42, s3
	global_load_lds_dwordx4 v[202:203], off
	v_lshl_add_u64 v[228:229], s[40:41], 0, v[172:173]
	s_mov_b32 m0, s42
	v_lshl_add_u64 v[230:231], s[8:9], 0, v[170:171]
	global_load_lds_dwordx4 v[228:229], off
	v_lshl_add_u64 v[228:229], s[40:41], 0, v[170:171]
	s_add_i32 m0, s42, 0x2000
	s_nop 0
	global_load_lds_dwordx4 v[228:229], off
	v_lshl_add_u64 v[228:229], s[8:9], 0, v[172:173]
	s_mov_b32 m0, s24
	s_nop 0
	global_load_lds_dwordx4 v[228:229], off
	s_mov_b32 m0, s25
	s_nop 0
	global_load_lds_dwordx4 v[230:231], off
	s_waitcnt vmcnt(8)
	s_waitcnt lgkmcnt(0)
	s_barrier
; #define PG8_STAGE(bufoff, gbase, voff) do { _Pragma("unroll") for (int _i = 0; _i < 2; ++_i) \
;         __builtin_amdgcn_global_load_lds((const unsigned*)((const char*)(gbase) + (voff)[_i]), (LAS unsigned*)(lds + (bufoff) + ldsw + _i * 8192), 16, 0, 0); } while (0)
; #define PG8_LDA(dst, b, h) do { _Pragma("unroll") for (int m = 0; m < 4; ++m) _Pragma("unroll") for (int k = 0; k < 2; ++k) dst[m][k] = *(const LAS bf16x8*)(lds + PG8_SA(b, h) + aoff + m * 2048 + k * 1024); } while (0)
; #define PG8_LDB(dst, b, h) do { _Pragma("unroll") for (int n = 0; n < 2; ++n) _Pragma("unroll") for (int k = 0; k < 2; ++k) dst[n][k] = *(const LAS bf16x8*)(lds + PG8_SB(b, h) + boff + n * 2048 + k * 1024); } while (0)
; #define PG8_MMA(ai, bj, At, Bt) do { __builtin_amdgcn_s_setprio(1); _Pragma("unroll") for (int m = 0; m < 4; ++m) _Pragma("unroll") for (int n = 0; n < 2; ++n) _Pragma("unroll") for (int k = 0; k < 2; ++k) \
;         acc[ai][bj][m][n] = __builtin_amdgcn_mfma_f32_16x16x32_bf16(Bt[n][k], At[m][k], acc[ai][bj][m][n], 0, 0, 0); __builtin_amdgcn_s_setprio(0); } while (0)
; #define PG8_WAIT_V(n) asm volatile("s_waitcnt vmcnt(" #n ")" ::: "memory")
; #define PG8_WAIT_L(n) asm volatile("s_waitcnt lgkmcnt(" #n ")" ::: "memory")
; #define PG8_BAR __builtin_amdgcn_s_barrier()
; #define PG8_SCHED __builtin_amdgcn_sched_barrier(0)
; template <class Epi, bool ALIGN_EPI = PG8_ALIGN, bool SP2 = PG8_SP2>
; __device__ __forceinline__ void gemm_phase(LAS unsigned char* lds, const Gemm g, const StaticOrder& S, const Epi& E) {
;     ...
;             PG8_WAIT_V(8); PG8_WAIT_L(0); PG8_BAR; PG8_MMA(1, 0, At, B0); PG8_MMA(1, 1, At, B1); PG8_BAR; PG8_SCHED;
;             PG8_LDB(B0, 1, 0); PG8_LDB(B1, 1, 1); PG8_SCHED; PG8_LDA(At, 1, 0); PG8_STAGE(PG8_SA(0, 1), a2 + hstepA, voffA);
;             PG8_WAIT_V(8); PG8_WAIT_L(0); PG8_BAR; PG8_MMA(0, 0, At, B0); PG8_MMA(0, 1, At, B1); PG8_BAR; PG8_SCHED;
	s_setprio 1
	s_waitcnt lgkmcnt(0)
	v_mfma_f32_16x16x32_bf16 v[46:49], v[114:117], v[164:167], v[46:49]
	v_mfma_f32_16x16x32_bf16 v[14:17], v[130:133], v[164:167], v[14:17]
	v_mfma_f32_16x16x32_bf16 v[42:45], v[114:117], v[186:189], v[42:45]
	v_mfma_f32_16x16x32_bf16 v[10:13], v[130:133], v[186:189], v[10:13]
	v_mfma_f32_16x16x32_bf16 v[38:41], v[114:117], v[212:215], v[38:41]
	v_mfma_f32_16x16x32_bf16 v[6:9], v[130:133], v[212:215], v[6:9]
	v_mfma_f32_16x16x32_bf16 v[34:37], v[114:117], v[220:223], v[34:37]
	v_mfma_f32_16x16x32_bf16 v[2:5], v[130:133], v[220:223], v[2:5]
	v_mfma_f32_16x16x32_bf16 v[46:49], v[122:125], v[182:185], v[46:49]
	v_mfma_f32_16x16x32_bf16 v[14:17], v[134:137], v[182:185], v[14:17]
	v_mfma_f32_16x16x32_bf16 v[42:45], v[122:125], v[194:197], v[42:45]
	v_mfma_f32_16x16x32_bf16 v[10:13], v[134:137], v[194:197], v[10:13]
	v_mfma_f32_16x16x32_bf16 v[38:41], v[122:125], v[216:219], v[38:41]
	v_mfma_f32_16x16x32_bf16 v[6:9], v[134:137], v[216:219], v[6:9]
	v_mfma_f32_16x16x32_bf16 v[34:37], v[122:125], v[224:227], v[34:37]
	v_mfma_f32_16x16x32_bf16 v[2:5], v[134:137], v[224:227], v[2:5]
	s_setprio 0
	s_setprio 1
	v_mfma_f32_16x16x32_bf16 v[94:97], v[146:149], v[164:167], v[94:97]
	v_mfma_f32_16x16x32_bf16 v[90:93], v[154:157], v[164:167], v[90:93]
	v_mfma_f32_16x16x32_bf16 v[86:89], v[146:149], v[186:189], v[86:89]
	v_mfma_f32_16x16x32_bf16 v[82:85], v[154:157], v[186:189], v[82:85]
	v_mfma_f32_16x16x32_bf16 v[78:81], v[146:149], v[212:215], v[78:81]
	v_mfma_f32_16x16x32_bf16 v[74:77], v[154:157], v[212:215], v[74:77]
	v_mfma_f32_16x16x32_bf16 v[66:69], v[146:149], v[220:223], v[66:69]
	v_mfma_f32_16x16x32_bf16 v[62:65], v[154:157], v[220:223], v[62:65]
	v_mfma_f32_16x16x32_bf16 v[94:97], v[150:153], v[182:185], v[94:97]
	v_mfma_f32_16x16x32_bf16 v[90:93], v[158:161], v[182:185], v[90:93]
	v_mfma_f32_16x16x32_bf16 v[86:89], v[150:153], v[194:197], v[86:89]
	v_mfma_f32_16x16x32_bf16 v[82:85], v[158:161], v[194:197], v[82:85]
	v_mfma_f32_16x16x32_bf16 v[78:81], v[150:153], v[216:219], v[78:81]
	v_mfma_f32_16x16x32_bf16 v[74:77], v[158:161], v[216:219], v[74:77]
	v_mfma_f32_16x16x32_bf16 v[66:69], v[150:153], v[224:227], v[66:69]
	v_mfma_f32_16x16x32_bf16 v[62:65], v[158:161], v[224:227], v[62:65]
	s_setprio 0
	s_barrier
	s_add_i32 s40, 0, 0x18000
	v_add_u32_e32 v0, s40, v206
	s_add_i32 s41, 0, 0x1c000
	ds_read_b128 v[114:117], v0
	ds_read_b128 v[122:125], v0 offset:1024
	ds_read_b128 v[130:133], v0 offset:2048
	ds_read_b128 v[134:137], v0 offset:3072
	v_add_u32_e32 v0, s41, v206
	ds_read_b128 v[146:149], v0
	ds_read_b128 v[150:153], v0 offset:1024
	ds_read_b128 v[154:157], v0 offset:2048
	ds_read_b128 v[158:161], v0 offset:3072
	s_add_u32 s8, s8, 0x40000
	s_addc_u32 s9, s9, 0
	s_mov_b32 m0, s26
	v_lshl_add_u64 v[232:233], s[8:9], 0, v[172:173]
	ds_read_b128 v[164:167], v211 offset:32768
	ds_read_b128 v[182:185], v211 offset:33792
	ds_read_b128 v[186:189], v211 offset:34816
	ds_read_b128 v[194:197], v211 offset:35840
	ds_read_b128 v[212:215], v211 offset:36864
	ds_read_b128 v[216:219], v211 offset:37888
	ds_read_b128 v[220:223], v211 offset:38912
	ds_read_b128 v[224:227], v211 offset:39936
	global_load_lds_dwordx4 v[232:233], off
	v_lshl_add_u64 v[232:233], s[8:9], 0, v[170:171]
	s_mov_b32 m0, s27
	s_nop 0
	global_load_lds_dwordx4 v[232:233], off
	s_waitcnt vmcnt(8)
	s_waitcnt lgkmcnt(0)
	s_barrier
	s_setprio 1
	s_waitcnt lgkmcnt(0)
	v_mfma_f32_16x16x32_bf16 v[70:73], v[114:117], v[164:167], v[70:73]
	v_mfma_f32_16x16x32_bf16 v[30:33], v[130:133], v[164:167], v[30:33]
	v_mfma_f32_16x16x32_bf16 v[58:61], v[114:117], v[186:189], v[58:61]
	v_mfma_f32_16x16x32_bf16 v[26:29], v[130:133], v[186:189], v[26:29]
	v_mfma_f32_16x16x32_bf16 v[54:57], v[114:117], v[212:215], v[54:57]
	v_mfma_f32_16x16x32_bf16 v[22:25], v[130:133], v[212:215], v[22:25]
	v_mfma_f32_16x16x32_bf16 v[50:53], v[114:117], v[220:223], v[50:53]
	v_mfma_f32_16x16x32_bf16 v[18:21], v[130:133], v[220:223], v[18:21]
	v_mfma_f32_16x16x32_bf16 v[70:73], v[122:125], v[182:185], v[70:73]
	v_mfma_f32_16x16x32_bf16 v[30:33], v[134:137], v[182:185], v[30:33]
	v_mfma_f32_16x16x32_bf16 v[58:61], v[122:125], v[194:197], v[58:61]
	v_mfma_f32_16x16x32_bf16 v[26:29], v[134:137], v[194:197], v[26:29]
	v_mfma_f32_16x16x32_bf16 v[54:57], v[122:125], v[216:219], v[54:57]
	v_mfma_f32_16x16x32_bf16 v[22:25], v[134:137], v[216:219], v[22:25]
	v_mfma_f32_16x16x32_bf16 v[50:53], v[122:125], v[224:227], v[50:53]
	v_mfma_f32_16x16x32_bf16 v[18:21], v[134:137], v[224:227], v[18:21]
	s_setprio 0
	s_setprio 1
	v_mfma_f32_16x16x32_bf16 v[142:145], v[146:149], v[164:167], v[142:145]
	v_mfma_f32_16x16x32_bf16 v[138:141], v[154:157], v[164:167], v[138:141]
	v_mfma_f32_16x16x32_bf16 v[126:129], v[146:149], v[186:189], v[126:129]
	v_mfma_f32_16x16x32_bf16 v[118:121], v[154:157], v[186:189], v[118:121]
	v_mfma_f32_16x16x32_bf16 v[110:113], v[146:149], v[212:215], v[110:113]
	v_mfma_f32_16x16x32_bf16 v[106:109], v[154:157], v[212:215], v[106:109]
	v_mfma_f32_16x16x32_bf16 v[102:105], v[146:149], v[220:223], v[102:105]
	v_mfma_f32_16x16x32_bf16 v[98:101], v[154:157], v[220:223], v[98:101]
	v_mfma_f32_16x16x32_bf16 v[142:145], v[150:153], v[182:185], v[142:145]
	v_mfma_f32_16x16x32_bf16 v[138:141], v[158:161], v[182:185], v[138:141]
	v_mfma_f32_16x16x32_bf16 v[126:129], v[150:153], v[194:197], v[126:129]
	v_mfma_f32_16x16x32_bf16 v[118:121], v[158:161], v[194:197], v[118:121]
	v_mfma_f32_16x16x32_bf16 v[110:113], v[150:153], v[216:219], v[110:113]
	v_mfma_f32_16x16x32_bf16 v[106:109], v[158:161], v[216:219], v[106:109]
	v_mfma_f32_16x16x32_bf16 v[102:105], v[150:153], v[224:227], v[102:105]
	v_mfma_f32_16x16x32_bf16 v[98:101], v[158:161], v[224:227], v[98:101]
	s_setprio 0
	s_barrier
; #define PG8_STAGE(bufoff, gbase, voff) do { _Pragma("unroll") for (int _i = 0; _i < 2; ++_i) \
;         __builtin_amdgcn_global_load_lds((const unsigned*)((const char*)(gbase) + (voff)[_i]), (LAS unsigned*)(lds + (bufoff) + ldsw + _i * 8192), 16, 0, 0); } while (0)
; #define PG8_LDA(dst, b, h) do { _Pragma("unroll") for (int m = 0; m < 4; ++m) _Pragma("unroll") for (int k = 0; k < 2; ++k) dst[m][k] = *(const LAS bf16x8*)(lds + PG8_SA(b, h) + aoff + m * 2048 + k * 1024); } while (0)
; #define PG8_MMA(ai, bj, At, Bt) do { __builtin_amdgcn_s_setprio(1); _Pragma("unroll") for (int m = 0; m < 4; ++m) _Pragma("unroll") for (int n = 0; n < 2; ++n) _Pragma("unroll") for (int k = 0; k < 2; ++k) \
;         acc[ai][bj][m][n] = __builtin_amdgcn_mfma_f32_16x16x32_bf16(Bt[n][k], At[m][k], acc[ai][bj][m][n], 0, 0, 0); __builtin_amdgcn_s_setprio(0); } while (0)
; #define PG8_WAIT_V(n) asm volatile("s_waitcnt vmcnt(" #n ")" ::: "memory")
; #define PG8_WAIT_L(n) asm volatile("s_waitcnt lgkmcnt(" #n ")" ::: "memory")
; #define PG8_BAR __builtin_amdgcn_s_barrier()
; #define PG8_SCHED __builtin_amdgcn_sched_barrier(0)
; template <class Epi, bool ALIGN_EPI = PG8_ALIGN, bool SP2 = PG8_SP2>
; __device__ __forceinline__ void gemm_phase(LAS unsigned char* lds, const Gemm g, const StaticOrder& S, const Epi& E) {
;     ...
;         for (int t = 0; t < nt; t += 2) {
;             const bool last = (t == nt - 2);
;             const char* a1 = cA + (size_t)(t + 1) * kstepA;
;             const char* a2 = last ? nA : cA + (size_t)(t + 2) * kstepA; const char* b2 = last ? nB : cB + (size_t)(t + 2) * kstepB;
;     ...
;             PG8_LDA(At, 1, 1); PG8_STAGE(PG8_SB(1, 0), b3, voffB); PG8_STAGE(PG8_SB(1, 1), b3 + hstepB, voffB); PG8_STAGE(PG8_SA(1, 0), a3, voffA);
;             PG8_WAIT_V(8); PG8_WAIT_L(0); PG8_BAR; PG8_MMA(1, 0, At, B0); PG8_MMA(1, 1, At, B1); PG8_BAR; PG8_SCHED;
	s_add_i32 s8, s40, s3
	v_lshl_add_u64 v[190:191], v[190:191], 0, s[50:51]
	s_mov_b32 m0, s8
	ds_read_b128 v[164:167], v211 offset:49152
	ds_read_b128 v[182:185], v211 offset:50176
	ds_read_b128 v[186:189], v211 offset:51200
	ds_read_b128 v[194:197], v211 offset:52224
	ds_read_b128 v[212:215], v211 offset:53248
	ds_read_b128 v[216:219], v211 offset:54272
	ds_read_b128 v[220:223], v211 offset:55296
	ds_read_b128 v[224:227], v211 offset:56320
	global_load_lds_dwordx4 v[190:191], off
	s_add_i32 m0, s8, 0x2000
	s_add_u32 s4, s4, 0x40080
	v_lshl_add_u64 v[190:191], v[202:203], 0, s[50:51]
	s_addc_u32 s5, s5, 0
	s_add_i32 s8, s41, s3
	global_load_lds_dwordx4 v[190:191], off
	v_lshl_add_u64 v[190:191], s[4:5], 0, v[172:173]
	s_mov_b32 m0, s8
	s_nop 0
	global_load_lds_dwordx4 v[190:191], off
	v_lshl_add_u64 v[190:191], s[4:5], 0, v[170:171]
	s_add_i32 m0, s8, 0x2000
	s_nop 0
	global_load_lds_dwordx4 v[190:191], off
	v_lshl_add_u64 v[190:191], v[228:229], 0, s[50:51]
	s_mov_b32 m0, s29
	s_nop 0
	global_load_lds_dwordx4 v[190:191], off
	v_lshl_add_u64 v[190:191], v[230:231], 0, s[50:51]
	s_mov_b32 m0, s30
	s_nop 0
	global_load_lds_dwordx4 v[190:191], off
	s_waitcnt vmcnt(8)
	s_waitcnt lgkmcnt(0)
	s_barrier
	s_setprio 1
	s_waitcnt lgkmcnt(0)
	v_mfma_f32_16x16x32_bf16 v[46:49], v[114:117], v[164:167], v[46:49]
	v_mfma_f32_16x16x32_bf16 v[14:17], v[130:133], v[164:167], v[14:17]
	v_mfma_f32_16x16x32_bf16 v[42:45], v[114:117], v[186:189], v[42:45]
	v_mfma_f32_16x16x32_bf16 v[10:13], v[130:133], v[186:189], v[10:13]
	v_mfma_f32_16x16x32_bf16 v[38:41], v[114:117], v[212:215], v[38:41]
	v_mfma_f32_16x16x32_bf16 v[6:9], v[130:133], v[212:215], v[6:9]
	v_mfma_f32_16x16x32_bf16 v[34:37], v[114:117], v[220:223], v[34:37]
	v_mfma_f32_16x16x32_bf16 v[2:5], v[130:133], v[220:223], v[2:5]
	v_mfma_f32_16x16x32_bf16 v[46:49], v[122:125], v[182:185], v[46:49]
	v_mfma_f32_16x16x32_bf16 v[14:17], v[134:137], v[182:185], v[14:17]
	v_mfma_f32_16x16x32_bf16 v[42:45], v[122:125], v[194:197], v[42:45]
	v_mfma_f32_16x16x32_bf16 v[10:13], v[134:137], v[194:197], v[10:13]
	v_mfma_f32_16x16x32_bf16 v[38:41], v[122:125], v[216:219], v[38:41]
	v_mfma_f32_16x16x32_bf16 v[6:9], v[134:137], v[216:219], v[6:9]
	v_mfma_f32_16x16x32_bf16 v[34:37], v[122:125], v[224:227], v[34:37]
	v_mfma_f32_16x16x32_bf16 v[2:5], v[134:137], v[224:227], v[2:5]
	s_setprio 0
	s_setprio 1
	v_mfma_f32_16x16x32_bf16 v[94:97], v[146:149], v[164:167], v[94:97]
	v_mfma_f32_16x16x32_bf16 v[90:93], v[154:157], v[164:167], v[90:93]
	v_mfma_f32_16x16x32_bf16 v[86:89], v[146:149], v[186:189], v[86:89]
	v_mfma_f32_16x16x32_bf16 v[82:85], v[154:157], v[186:189], v[82:85]
	v_mfma_f32_16x16x32_bf16 v[78:81], v[146:149], v[212:215], v[78:81]
	v_mfma_f32_16x16x32_bf16 v[74:77], v[154:157], v[212:215], v[74:77]
	v_mfma_f32_16x16x32_bf16 v[66:69], v[146:149], v[220:223], v[66:69]
	v_mfma_f32_16x16x32_bf16 v[62:65], v[154:157], v[220:223], v[62:65]
	v_mfma_f32_16x16x32_bf16 v[94:97], v[150:153], v[182:185], v[94:97]
	v_mfma_f32_16x16x32_bf16 v[90:93], v[158:161], v[182:185], v[90:93]
	v_mfma_f32_16x16x32_bf16 v[86:89], v[150:153], v[194:197], v[86:89]
	v_mfma_f32_16x16x32_bf16 v[82:85], v[158:161], v[194:197], v[82:85]
	v_mfma_f32_16x16x32_bf16 v[78:81], v[150:153], v[216:219], v[78:81]
	v_mfma_f32_16x16x32_bf16 v[74:77], v[158:161], v[216:219], v[74:77]
	v_mfma_f32_16x16x32_bf16 v[66:69], v[150:153], v[224:227], v[66:69]
	v_mfma_f32_16x16x32_bf16 v[62:65], v[158:161], v[224:227], v[62:65]
	s_setprio 0
	s_barrier
	s_add_i32 s39, s39, 2
	s_add_u32 s0, s0, 0x100
	s_addc_u32 s1, s1, 0
	s_add_u32 s37, s37, 0x100
	s_addc_u32 s38, s38, 0
	s_cmp_gt_u32 s39, 13
	s_cbranch_scc0 .LBB0_535
	s_and_b64 vcc, exec, s[12:13]
	s_cbranch_vccz .LBB0_538
	s_barrier

; #define PG8_STAGE(bufoff, gbase, voff) do { _Pragma("unroll") for (int _i = 0; _i < 2; ++_i) \
;         __builtin_amdgcn_global_load_lds((const unsigned*)((const char*)(gbase) + (voff)[_i]), (LAS unsigned*)(lds + (bufoff) + ldsw + _i * 8192), 16, 0, 0); } while (0)
; #define PG8_LDA(dst, b, h) do { _Pragma("unroll") for (int m = 0; m < 4; ++m) _Pragma("unroll") for (int k = 0; k < 2; ++k) dst[m][k] = *(const LAS bf16x8*)(lds + PG8_SA(b, h) + aoff + m * 2048 + k * 1024); } while (0)
; #define PG8_LDB(dst, b, h) do { _Pragma("unroll") for (int n = 0; n < 2; ++n) _Pragma("unroll") for (int k = 0; k < 2; ++k) dst[n][k] = *(const LAS bf16x8*)(lds + PG8_SB(b, h) + boff + n * 2048 + k * 1024); } while (0)
; #define PG8_WAIT_V(n) asm volatile("s_waitcnt vmcnt(" #n ")" ::: "memory")
; #define PG8_WAIT_L(n) asm volatile("s_waitcnt lgkmcnt(" #n ")" ::: "memory")
; #define PG8_BAR __builtin_amdgcn_s_barrier()
; #define PG8_SCHED __builtin_amdgcn_sched_barrier(0)
; template <class Epi, bool ALIGN_EPI = PG8_ALIGN, bool SP2 = PG8_SP2>
; __device__ __forceinline__ void gemm_phase(LAS unsigned char* lds, const Gemm g, const StaticOrder& S, const Epi& E) {
;     ...
;         const bool has_next = S.next(ui + 1, nxt);
;         const char* nA = has_next ? (const char*)g.A + (size_t)nxt.pm * tstepA : cA; const char* nB = has_next ? (const char*)g.Bt + (size_t)nxt.pn * tstepB : cB;
;         for (int t = 0; t < nt; t += 2) {
;             const bool last = (t == nt - 2);
;             const char* a1 = cA + (size_t)(t + 1) * kstepA;
;             const char* a2 = last ? nA : cA + (size_t)(t + 2) * kstepA; const char* b2 = last ? nB : cB + (size_t)(t + 2) * kstepB;
;             const char* a3 = a2 + kstepA; const char* b3 = b2 + kstepB;
;             if constexpr (SP2) {
;             PG8_LDB(B0, 0, 0); PG8_LDB(B1, 0, 1); PG8_SCHED; PG8_LDA(At, 0, 0); PG8_STAGE(PG8_SA(1, 1), a1 + hstepA, voffA);
;             PG8_WAIT_V(8); PG8_WAIT_L(0); PG8_BAR; PG8_MMA(0, 0, At, B0); PG8_MMA(0, 1, At, B1); PG8_BAR; PG8_SCHED;
;             PG8_LDA(At, 0, 1); PG8_STAGE(PG8_SB(0, 0), b2, voffB); PG8_STAGE(PG8_SB(0, 1), b2 + hstepB, voffB); PG8_STAGE(PG8_SA(0, 0), a2, voffA);
;             PG8_WAIT_V(8); PG8_WAIT_L(0); PG8_BAR; PG8_MMA(1, 0, At, B0); PG8_MMA(1, 1, At, B1); PG8_BAR; PG8_SCHED;
.Lfirst_iter_u535:
	s_add_u32 s4, s0, 0xfffc0080
	s_addc_u32 s5, s1, -1
	s_add_i32 s40, 0, 0x10000
	s_cmp_eq_u32 s39, 12
	s_cselect_b32 s9, s19, s5
	s_cselect_b32 s8, s35, s4
	v_add_u32_e32 v0, s40, v206
	s_cselect_b32 s5, s17, s38
	s_cselect_b32 s4, s36, s37
	s_add_i32 s42, 0, 0x14000
	ds_read_b128 v[114:117], v0
	ds_read_b128 v[122:125], v0 offset:1024
	ds_read_b128 v[130:133], v0 offset:2048
	ds_read_b128 v[134:137], v0 offset:3072
	v_add_u32_e32 v0, s42, v206
	ds_read_b128 v[146:149], v0
	ds_read_b128 v[150:153], v0 offset:1024
	ds_read_b128 v[154:157], v0 offset:2048
	ds_read_b128 v[158:161], v0 offset:3072
	v_lshl_add_u64 v[190:191], s[0:1], 0, v[178:179]
	s_add_i32 m0, s24, 0xc000
	ds_read_b128 v[164:167], v211
	ds_read_b128 v[182:185], v211 offset:1024
	ds_read_b128 v[186:189], v211 offset:2048
	ds_read_b128 v[194:197], v211 offset:3072
	ds_read_b128 v[212:215], v211 offset:4096
	ds_read_b128 v[216:219], v211 offset:5120
	ds_read_b128 v[220:223], v211 offset:6144
	ds_read_b128 v[224:227], v211 offset:7168
	global_load_lds_dwordx4 v[190:191], off
	v_lshl_add_u64 v[190:191], s[0:1], 0, v[180:181]
	s_add_i32 m0, s24, 0xe000
	s_nop 0
	global_load_lds_dwordx4 v[190:191], off
	s_waitcnt vmcnt(8)
	s_waitcnt lgkmcnt(0)
	s_barrier
	s_setprio 1
	s_waitcnt lgkmcnt(0)
	v_mfma_f32_16x16x32_bf16 v[70:73], v[114:117], v[164:167], 0
	v_mfma_f32_16x16x32_bf16 v[30:33], v[130:133], v[164:167], 0
	v_mfma_f32_16x16x32_bf16 v[58:61], v[114:117], v[186:189], 0
	v_mfma_f32_16x16x32_bf16 v[26:29], v[130:133], v[186:189], 0
	v_mfma_f32_16x16x32_bf16 v[54:57], v[114:117], v[212:215], 0
	v_mfma_f32_16x16x32_bf16 v[22:25], v[130:133], v[212:215], 0
	v_mfma_f32_16x16x32_bf16 v[50:53], v[114:117], v[220:223], 0
	v_mfma_f32_16x16x32_bf16 v[18:21], v[130:133], v[220:223], 0
	v_mfma_f32_16x16x32_bf16 v[70:73], v[122:125], v[182:185], v[70:73]
	v_mfma_f32_16x16x32_bf16 v[30:33], v[134:137], v[182:185], v[30:33]
	v_mfma_f32_16x16x32_bf16 v[58:61], v[122:125], v[194:197], v[58:61]
	v_mfma_f32_16x16x32_bf16 v[26:29], v[134:137], v[194:197], v[26:29]
	v_mfma_f32_16x16x32_bf16 v[54:57], v[122:125], v[216:219], v[54:57]
	v_mfma_f32_16x16x32_bf16 v[22:25], v[134:137], v[216:219], v[22:25]
	v_mfma_f32_16x16x32_bf16 v[50:53], v[122:125], v[224:227], v[50:53]
	v_mfma_f32_16x16x32_bf16 v[18:21], v[134:137], v[224:227], v[18:21]
	s_setprio 0
	s_setprio 1
	v_mfma_f32_16x16x32_bf16 v[142:145], v[146:149], v[164:167], 0
	v_mfma_f32_16x16x32_bf16 v[138:141], v[154:157], v[164:167], 0
	v_mfma_f32_16x16x32_bf16 v[126:129], v[146:149], v[186:189], 0
	v_mfma_f32_16x16x32_bf16 v[118:121], v[154:157], v[186:189], 0
	v_mfma_f32_16x16x32_bf16 v[110:113], v[146:149], v[212:215], 0
	v_mfma_f32_16x16x32_bf16 v[106:109], v[154:157], v[212:215], 0
	v_mfma_f32_16x16x32_bf16 v[102:105], v[146:149], v[220:223], 0
	v_mfma_f32_16x16x32_bf16 v[98:101], v[154:157], v[220:223], 0
	v_mfma_f32_16x16x32_bf16 v[142:145], v[150:153], v[182:185], v[142:145]
	v_mfma_f32_16x16x32_bf16 v[138:141], v[158:161], v[182:185], v[138:141]
	v_mfma_f32_16x16x32_bf16 v[126:129], v[150:153], v[194:197], v[126:129]
	v_mfma_f32_16x16x32_bf16 v[118:121], v[158:161], v[194:197], v[118:121]
	v_mfma_f32_16x16x32_bf16 v[110:113], v[150:153], v[216:219], v[110:113]
	v_mfma_f32_16x16x32_bf16 v[106:109], v[158:161], v[216:219], v[106:109]
	v_mfma_f32_16x16x32_bf16 v[102:105], v[150:153], v[224:227], v[102:105]
	v_mfma_f32_16x16x32_bf16 v[98:101], v[158:161], v[224:227], v[98:101]
	s_setprio 0
	s_barrier
	s_add_i32 s40, s40, s3
	v_lshl_add_u64 v[190:191], s[4:5], 0, v[172:173]
	s_mov_b32 m0, s40
	ds_read_b128 v[164:167], v211 offset:16384
	ds_read_b128 v[182:185], v211 offset:17408
	ds_read_b128 v[186:189], v211 offset:18432
	ds_read_b128 v[194:197], v211 offset:19456
	ds_read_b128 v[212:215], v211 offset:20480
	ds_read_b128 v[216:219], v211 offset:21504
	ds_read_b128 v[220:223], v211 offset:22528
	ds_read_b128 v[224:227], v211 offset:23552
	global_load_lds_dwordx4 v[190:191], off
	s_add_i32 m0, s40, 0x2000
	s_add_u32 s40, s4, 0x40000
	v_lshl_add_u64 v[202:203], s[4:5], 0, v[170:171]
	s_addc_u32 s41, s5, 0
	s_add_i32 s42, s42, s3
	global_load_lds_dwordx4 v[202:203], off
	v_lshl_add_u64 v[228:229], s[40:41], 0, v[172:173]
	s_mov_b32 m0, s42
	v_lshl_add_u64 v[230:231], s[8:9], 0, v[170:171]
	global_load_lds_dwordx4 v[228:229], off
	v_lshl_add_u64 v[228:229], s[40:41], 0, v[170:171]
	s_add_i32 m0, s42, 0x2000
	s_nop 0
	global_load_lds_dwordx4 v[228:229], off
	v_lshl_add_u64 v[228:229], s[8:9], 0, v[172:173]
	s_mov_b32 m0, s24
	s_nop 0
	global_load_lds_dwordx4 v[228:229], off
	s_mov_b32 m0, s25
	s_nop 0
	global_load_lds_dwordx4 v[230:231], off
	s_waitcnt vmcnt(8)
	s_waitcnt lgkmcnt(0)
	s_barrier
; #define PG8_STAGE(bufoff, gbase, voff) do { _Pragma("unroll") for (int _i = 0; _i < 2; ++_i) \
;         __builtin_amdgcn_global_load_lds((const unsigned*)((const char*)(gbase) + (voff)[_i]), (LAS unsigned*)(lds + (bufoff) + ldsw + _i * 8192), 16, 0, 0); } while (0)
; #define PG8_LDA(dst, b, h) do { _Pragma("unroll") for (int m = 0; m < 4; ++m) _Pragma("unroll") for (int k = 0; k < 2; ++k) dst[m][k] = *(const LAS bf16x8*)(lds + PG8_SA(b, h) + aoff + m * 2048 + k * 1024); } while (0)
; #define PG8_LDB(dst, b, h) do { _Pragma("unroll") for (int n = 0; n < 2; ++n) _Pragma("unroll") for (int k = 0; k < 2; ++k) dst[n][k] = *(const LAS bf16x8*)(lds + PG8_SB(b, h) + boff + n * 2048 + k * 1024); } while (0)
; #define PG8_MMA(ai, bj, At, Bt) do { __builtin_amdgcn_s_setprio(1); _Pragma("unroll") for (int m = 0; m < 4; ++m) _Pragma("unroll") for (int n = 0; n < 2; ++n) _Pragma("unroll") for (int k = 0; k < 2; ++k) \
;         acc[ai][bj][m][n] = __builtin_amdgcn_mfma_f32_16x16x32_bf16(Bt[n][k], At[m][k], acc[ai][bj][m][n], 0, 0, 0); __builtin_amdgcn_s_setprio(0); } while (0)
; #define PG8_WAIT_V(n) asm volatile("s_waitcnt vmcnt(" #n ")" ::: "memory")
; #define PG8_WAIT_L(n) asm volatile("s_waitcnt lgkmcnt(" #n ")" ::: "memory")
; #define PG8_BAR __builtin_amdgcn_s_barrier()
; #define PG8_SCHED __builtin_amdgcn_sched_barrier(0)
; template <class Epi, bool ALIGN_EPI = PG8_ALIGN, bool SP2 = PG8_SP2>
; __device__ __forceinline__ void gemm_phase(LAS unsigned char* lds, const Gemm g, const StaticOrder& S, const Epi& E) {
;     ...
;             PG8_WAIT_V(8); PG8_WAIT_L(0); PG8_BAR; PG8_MMA(1, 0, At, B0); PG8_MMA(1, 1, At, B1); PG8_BAR; PG8_SCHED;
;             PG8_LDB(B0, 1, 0); PG8_LDB(B1, 1, 1); PG8_SCHED; PG8_LDA(At, 1, 0); PG8_STAGE(PG8_SA(0, 1), a2 + hstepA, voffA);
;             PG8_WAIT_V(8); PG8_WAIT_L(0); PG8_BAR; PG8_MMA(0, 0, At, B0); PG8_MMA(0, 1, At, B1); PG8_BAR; PG8_SCHED;
	s_setprio 1
	s_waitcnt lgkmcnt(0)
	v_mfma_f32_16x16x32_bf16 v[46:49], v[114:117], v[164:167], 0
	v_mfma_f32_16x16x32_bf16 v[14:17], v[130:133], v[164:167], 0
	v_mfma_f32_16x16x32_bf16 v[42:45], v[114:117], v[186:189], 0
	v_mfma_f32_16x16x32_bf16 v[10:13], v[130:133], v[186:189], 0
	v_mfma_f32_16x16x32_bf16 v[38:41], v[114:117], v[212:215], 0
	v_mfma_f32_16x16x32_bf16 v[6:9], v[130:133], v[212:215], 0
	v_mfma_f32_16x16x32_bf16 v[34:37], v[114:117], v[220:223], 0
	v_mfma_f32_16x16x32_bf16 v[2:5], v[130:133], v[220:223], 0
	v_mfma_f32_16x16x32_bf16 v[46:49], v[122:125], v[182:185], v[46:49]
	v_mfma_f32_16x16x32_bf16 v[14:17], v[134:137], v[182:185], v[14:17]
	v_mfma_f32_16x16x32_bf16 v[42:45], v[122:125], v[194:197], v[42:45]
	v_mfma_f32_16x16x32_bf16 v[10:13], v[134:137], v[194:197], v[10:13]
	v_mfma_f32_16x16x32_bf16 v[38:41], v[122:125], v[216:219], v[38:41]
	v_mfma_f32_16x16x32_bf16 v[6:9], v[134:137], v[216:219], v[6:9]
	v_mfma_f32_16x16x32_bf16 v[34:37], v[122:125], v[224:227], v[34:37]
	v_mfma_f32_16x16x32_bf16 v[2:5], v[134:137], v[224:227], v[2:5]
	s_setprio 0
	s_setprio 1
	v_mfma_f32_16x16x32_bf16 v[94:97], v[146:149], v[164:167], 0
	v_mfma_f32_16x16x32_bf16 v[90:93], v[154:157], v[164:167], 0
	v_mfma_f32_16x16x32_bf16 v[86:89], v[146:149], v[186:189], 0
	v_mfma_f32_16x16x32_bf16 v[82:85], v[154:157], v[186:189], 0
	v_mfma_f32_16x16x32_bf16 v[78:81], v[146:149], v[212:215], 0
	v_mfma_f32_16x16x32_bf16 v[74:77], v[154:157], v[212:215], 0
	v_mfma_f32_16x16x32_bf16 v[66:69], v[146:149], v[220:223], 0
	v_mfma_f32_16x16x32_bf16 v[62:65], v[154:157], v[220:223], 0
	v_mfma_f32_16x16x32_bf16 v[94:97], v[150:153], v[182:185], v[94:97]
	v_mfma_f32_16x16x32_bf16 v[90:93], v[158:161], v[182:185], v[90:93]
	v_mfma_f32_16x16x32_bf16 v[86:89], v[150:153], v[194:197], v[86:89]
	v_mfma_f32_16x16x32_bf16 v[82:85], v[158:161], v[194:197], v[82:85]
	v_mfma_f32_16x16x32_bf16 v[78:81], v[150:153], v[216:219], v[78:81]
	v_mfma_f32_16x16x32_bf16 v[74:77], v[158:161], v[216:219], v[74:77]
	v_mfma_f32_16x16x32_bf16 v[66:69], v[150:153], v[224:227], v[66:69]
	v_mfma_f32_16x16x32_bf16 v[62:65], v[158:161], v[224:227], v[62:65]
	s_setprio 0
	s_barrier
	s_add_i32 s40, 0, 0x18000
	v_add_u32_e32 v0, s40, v206
	s_add_i32 s41, 0, 0x1c000
	ds_read_b128 v[114:117], v0
	ds_read_b128 v[122:125], v0 offset:1024
	ds_read_b128 v[130:133], v0 offset:2048
	ds_read_b128 v[134:137], v0 offset:3072
	v_add_u32_e32 v0, s41, v206
	ds_read_b128 v[146:149], v0
	ds_read_b128 v[150:153], v0 offset:1024
	ds_read_b128 v[154:157], v0 offset:2048
	ds_read_b128 v[158:161], v0 offset:3072
	s_add_u32 s8, s8, 0x40000
	s_addc_u32 s9, s9, 0
	s_mov_b32 m0, s26
	v_lshl_add_u64 v[232:233], s[8:9], 0, v[172:173]
	ds_read_b128 v[164:167], v211 offset:32768
	ds_read_b128 v[182:185], v211 offset:33792
	ds_read_b128 v[186:189], v211 offset:34816
	ds_read_b128 v[194:197], v211 offset:35840
	ds_read_b128 v[212:215], v211 offset:36864
	ds_read_b128 v[216:219], v211 offset:37888
	ds_read_b128 v[220:223], v211 offset:38912
	ds_read_b128 v[224:227], v211 offset:39936
	global_load_lds_dwordx4 v[232:233], off
	v_lshl_add_u64 v[232:233], s[8:9], 0, v[170:171]
	s_mov_b32 m0, s27
	s_nop 0
	global_load_lds_dwordx4 v[232:233], off
	s_waitcnt vmcnt(8)
	s_waitcnt lgkmcnt(0)
	s_barrier
	s_setprio 1
	s_waitcnt lgkmcnt(0)
	v_mfma_f32_16x16x32_bf16 v[70:73], v[114:117], v[164:167], v[70:73]
	v_mfma_f32_16x16x32_bf16 v[30:33], v[130:133], v[164:167], v[30:33]
	v_mfma_f32_16x16x32_bf16 v[58:61], v[114:117], v[186:189], v[58:61]
	v_mfma_f32_16x16x32_bf16 v[26:29], v[130:133], v[186:189], v[26:29]
	v_mfma_f32_16x16x32_bf16 v[54:57], v[114:117], v[212:215], v[54:57]
	v_mfma_f32_16x16x32_bf16 v[22:25], v[130:133], v[212:215], v[22:25]
	v_mfma_f32_16x16x32_bf16 v[50:53], v[114:117], v[220:223], v[50:53]
	v_mfma_f32_16x16x32_bf16 v[18:21], v[130:133], v[220:223], v[18:21]
	v_mfma_f32_16x16x32_bf16 v[70:73], v[122:125], v[182:185], v[70:73]
	v_mfma_f32_16x16x32_bf16 v[30:33], v[134:137], v[182:185], v[30:33]
	v_mfma_f32_16x16x32_bf16 v[58:61], v[122:125], v[194:197], v[58:61]
	v_mfma_f32_16x16x32_bf16 v[26:29], v[134:137], v[194:197], v[26:29]
	v_mfma_f32_16x16x32_bf16 v[54:57], v[122:125], v[216:219], v[54:57]
	v_mfma_f32_16x16x32_bf16 v[22:25], v[134:137], v[216:219], v[22:25]
	v_mfma_f32_16x16x32_bf16 v[50:53], v[122:125], v[224:227], v[50:53]
	v_mfma_f32_16x16x32_bf16 v[18:21], v[134:137], v[224:227], v[18:21]
	s_setprio 0
	s_setprio 1
	v_mfma_f32_16x16x32_bf16 v[142:145], v[146:149], v[164:167], v[142:145]
	v_mfma_f32_16x16x32_bf16 v[138:141], v[154:157], v[164:167], v[138:141]
	v_mfma_f32_16x16x32_bf16 v[126:129], v[146:149], v[186:189], v[126:129]
	v_mfma_f32_16x16x32_bf16 v[118:121], v[154:157], v[186:189], v[118:121]
	v_mfma_f32_16x16x32_bf16 v[110:113], v[146:149], v[212:215], v[110:113]
	v_mfma_f32_16x16x32_bf16 v[106:109], v[154:157], v[212:215], v[106:109]
	v_mfma_f32_16x16x32_bf16 v[102:105], v[146:149], v[220:223], v[102:105]
	v_mfma_f32_16x16x32_bf16 v[98:101], v[154:157], v[220:223], v[98:101]
	v_mfma_f32_16x16x32_bf16 v[142:145], v[150:153], v[182:185], v[142:145]
	v_mfma_f32_16x16x32_bf16 v[138:141], v[158:161], v[182:185], v[138:141]
	v_mfma_f32_16x16x32_bf16 v[126:129], v[150:153], v[194:197], v[126:129]
	v_mfma_f32_16x16x32_bf16 v[118:121], v[158:161], v[194:197], v[118:121]
	v_mfma_f32_16x16x32_bf16 v[110:113], v[150:153], v[216:219], v[110:113]
	v_mfma_f32_16x16x32_bf16 v[106:109], v[158:161], v[216:219], v[106:109]
	v_mfma_f32_16x16x32_bf16 v[102:105], v[150:153], v[224:227], v[102:105]
	v_mfma_f32_16x16x32_bf16 v[98:101], v[158:161], v[224:227], v[98:101]
	s_setprio 0
	s_barrier
; __device__ __forceinline__ float log_sigmoid_f(float v) { return fminf(v, 0.f) - log1pf(__expf(-fabsf(v))); }
; #define PG8_STAGE(bufoff, gbase, voff) do { _Pragma("unroll") for (int _i = 0; _i < 2; ++_i) \
;         __builtin_amdgcn_global_load_lds((const unsigned*)((const char*)(gbase) + (voff)[_i]), (LAS unsigned*)(lds + (bufoff) + ldsw + _i * 8192), 16, 0, 0); } while (0)
; #define PG8_LDA(dst, b, h) do { _Pragma("unroll") for (int m = 0; m < 4; ++m) _Pragma("unroll") for (int k = 0; k < 2; ++k) dst[m][k] = *(const LAS bf16x8*)(lds + PG8_SA(b, h) + aoff + m * 2048 + k * 1024); } while (0)
; #define PG8_MMA(ai, bj, At, Bt) do { __builtin_amdgcn_s_setprio(1); _Pragma("unroll") for (int m = 0; m < 4; ++m) _Pragma("unroll") for (int n = 0; n < 2; ++n) _Pragma("unroll") for (int k = 0; k < 2; ++k) \
;         acc[ai][bj][m][n] = __builtin_amdgcn_mfma_f32_16x16x32_bf16(Bt[n][k], At[m][k], acc[ai][bj][m][n], 0, 0, 0); __builtin_amdgcn_s_setprio(0); } while (0)
; #define PG8_WAIT_V(n) asm volatile("s_waitcnt vmcnt(" #n ")" ::: "memory")
; #define PG8_WAIT_L(n) asm volatile("s_waitcnt lgkmcnt(" #n ")" ::: "memory")
; #define PG8_BAR __builtin_amdgcn_s_barrier()
; template <class Epi, bool ALIGN_EPI = PG8_ALIGN, bool SP2 = PG8_SP2>
; __device__ __forceinline__ void gemm_phase(LAS unsigned char* lds, const Gemm g, const StaticOrder& S, const Epi& E) {
;     ...
;             PG8_LDA(At, 1, 1); PG8_STAGE(PG8_SB(1, 0), b3, voffB); PG8_STAGE(PG8_SB(1, 1), b3 + hstepB, voffB); PG8_STAGE(PG8_SA(1, 0), a3, voffA);
;             PG8_WAIT_V(8); PG8_WAIT_L(0); PG8_BAR; PG8_MMA(1, 0, At, B0); PG8_MMA(1, 1, At, B1); PG8_BAR; PG8_SCHED;
;     __device__ __forceinline__ void operator()(const f32x4 (&acc)[2][2][4][2], const pg8::Unit& u, int wr, int wc, int fr, int fq) const {
;     ...
;         if (u.pn == 14) {
;             if (wc == 0 && fq < 2) {
; #pragma unroll
;                 for (int nn = 0; nn < 2; ++nn) { const int head = 2 * fq + nn; const f32x4 gb = *(const f32x4*)(gate_b + 4 * head);
; #pragma unroll
;                     for (int ai = 0; ai < 2; ++ai)
; #pragma unroll
;                         for (int m = 0; m < 4; ++m) { const int row = row0 + ai * 128 + m * 16; f32x4 v = acc[ai][0][m][nn] + gb;
;                             v[1] = log_sigmoid_f(v[1]); v[3] = log_sigmoid_f(v[3]);
;                             *(f32x4*)(G + (size_t)row * 16 + 4 * head) = v; } }
	s_add_i32 s8, s40, s3
	v_lshl_add_u64 v[190:191], v[190:191], 0, s[50:51]
	s_mov_b32 m0, s8
	ds_read_b128 v[164:167], v211 offset:49152
	ds_read_b128 v[182:185], v211 offset:50176
	ds_read_b128 v[186:189], v211 offset:51200
	ds_read_b128 v[194:197], v211 offset:52224
	ds_read_b128 v[212:215], v211 offset:53248
	ds_read_b128 v[216:219], v211 offset:54272
	ds_read_b128 v[220:223], v211 offset:55296
	ds_read_b128 v[224:227], v211 offset:56320
	global_load_lds_dwordx4 v[190:191], off
	s_add_i32 m0, s8, 0x2000
	s_add_u32 s4, s4, 0x40080
	v_lshl_add_u64 v[190:191], v[202:203], 0, s[50:51]
	s_addc_u32 s5, s5, 0
	s_add_i32 s8, s41, s3
	global_load_lds_dwordx4 v[190:191], off
	v_lshl_add_u64 v[190:191], s[4:5], 0, v[172:173]
	s_mov_b32 m0, s8
	s_nop 0
	global_load_lds_dwordx4 v[190:191], off
	v_lshl_add_u64 v[190:191], s[4:5], 0, v[170:171]
	s_add_i32 m0, s8, 0x2000
	s_nop 0
	global_load_lds_dwordx4 v[190:191], off
	v_lshl_add_u64 v[190:191], v[228:229], 0, s[50:51]
	s_mov_b32 m0, s29
	s_nop 0
	global_load_lds_dwordx4 v[190:191], off
	v_lshl_add_u64 v[190:191], v[230:231], 0, s[50:51]
	s_mov_b32 m0, s30
	s_nop 0
	global_load_lds_dwordx4 v[190:191], off
	s_waitcnt vmcnt(8)
	s_waitcnt lgkmcnt(0)
	s_barrier
	s_setprio 1
	s_waitcnt lgkmcnt(0)
	v_mfma_f32_16x16x32_bf16 v[46:49], v[114:117], v[164:167], v[46:49]
	v_mfma_f32_16x16x32_bf16 v[14:17], v[130:133], v[164:167], v[14:17]
	v_mfma_f32_16x16x32_bf16 v[42:45], v[114:117], v[186:189], v[42:45]
	v_mfma_f32_16x16x32_bf16 v[10:13], v[130:133], v[186:189], v[10:13]
	v_mfma_f32_16x16x32_bf16 v[38:41], v[114:117], v[212:215], v[38:41]
	v_mfma_f32_16x16x32_bf16 v[6:9], v[130:133], v[212:215], v[6:9]
	v_mfma_f32_16x16x32_bf16 v[34:37], v[114:117], v[220:223], v[34:37]
	v_mfma_f32_16x16x32_bf16 v[2:5], v[130:133], v[220:223], v[2:5]
	v_mfma_f32_16x16x32_bf16 v[46:49], v[122:125], v[182:185], v[46:49]
	v_mfma_f32_16x16x32_bf16 v[14:17], v[134:137], v[182:185], v[14:17]
	v_mfma_f32_16x16x32_bf16 v[42:45], v[122:125], v[194:197], v[42:45]
	v_mfma_f32_16x16x32_bf16 v[10:13], v[134:137], v[194:197], v[10:13]
	v_mfma_f32_16x16x32_bf16 v[38:41], v[122:125], v[216:219], v[38:41]
	v_mfma_f32_16x16x32_bf16 v[6:9], v[134:137], v[216:219], v[6:9]
	v_mfma_f32_16x16x32_bf16 v[34:37], v[122:125], v[224:227], v[34:37]
	v_mfma_f32_16x16x32_bf16 v[2:5], v[134:137], v[224:227], v[2:5]
	s_setprio 0
	s_setprio 1
	v_mfma_f32_16x16x32_bf16 v[94:97], v[146:149], v[164:167], v[94:97]
	v_mfma_f32_16x16x32_bf16 v[90:93], v[154:157], v[164:167], v[90:93]
	v_mfma_f32_16x16x32_bf16 v[86:89], v[146:149], v[186:189], v[86:89]
	v_mfma_f32_16x16x32_bf16 v[82:85], v[154:157], v[186:189], v[82:85]
	v_mfma_f32_16x16x32_bf16 v[78:81], v[146:149], v[212:215], v[78:81]
	v_mfma_f32_16x16x32_bf16 v[74:77], v[154:157], v[212:215], v[74:77]
	v_mfma_f32_16x16x32_bf16 v[66:69], v[146:149], v[220:223], v[66:69]
	v_mfma_f32_16x16x32_bf16 v[62:65], v[154:157], v[220:223], v[62:65]
	v_mfma_f32_16x16x32_bf16 v[94:97], v[150:153], v[182:185], v[94:97]
	v_mfma_f32_16x16x32_bf16 v[90:93], v[158:161], v[182:185], v[90:93]
	v_mfma_f32_16x16x32_bf16 v[86:89], v[150:153], v[194:197], v[86:89]
	v_mfma_f32_16x16x32_bf16 v[82:85], v[158:161], v[194:197], v[82:85]
	v_mfma_f32_16x16x32_bf16 v[78:81], v[150:153], v[216:219], v[78:81]
	v_mfma_f32_16x16x32_bf16 v[74:77], v[158:161], v[216:219], v[74:77]
	v_mfma_f32_16x16x32_bf16 v[66:69], v[150:153], v[224:227], v[66:69]
	v_mfma_f32_16x16x32_bf16 v[62:65], v[158:161], v[224:227], v[62:65]
	s_setprio 0
	s_barrier
	s_add_i32 s39, s39, 2
	s_add_u32 s0, s0, 0x100
	s_addc_u32 s1, s1, 0
	s_add_u32 s37, s37, 0x100
	s_addc_u32 s38, s38, 0
	s_cmp_gt_u32 s39, 13
	s_branch .LBB0_535
.Lisland_7:
	s_branch .LBB0_7
.LBB0_545:
	s_and_b64 vcc, exec, s[0:1]
	s_cbranch_vccz .LBB0_544
	s_and_saveexec_b64 s[4:5], s[14:15]
	s_cbranch_execz .LBB0_548
	global_load_dwordx4 v[62:65], v[174:175], off
	s_mov_b32 s8, 0xbfb8aa3b
	s_mov_b32 s9, 0x3f2aaaab
	s_mov_b32 s0, 0x3ecc95a3
	s_mov_b32 s34, 0x3e9b6dac
	s_mov_b32 s36, 0x3f2aaada
	s_mov_b32 s38, 0x3f317218
	s_mov_b32 s40, 0xb102e308
	s_mov_b32 s17, 0x7f800000
	s_mov_b32 s19, 0x33800000
	v_ashrrev_i32_e32 v183, 31, v182
	s_waitcnt vmcnt(0)
	v_pk_add_f32 v[66:67], v[70:71], v[62:63]
	s_nop 0
	v_mul_f32_e64 v0, |v67|, s8
	v_exp_f32_e32 v0, v0
	v_pk_add_f32 v[68:69], v[72:73], v[64:65]
	v_min_f32_e32 v72, 0, v67
	v_pk_add_f32 v[58:59], v[58:59], v[62:63]
	v_add_f32_e32 v67, 1.0, v0
	v_add_f32_e32 v70, -1.0, v67
	v_sub_f32_e32 v71, v70, v67
	v_add_f32_e32 v71, 1.0, v71
	v_sub_f32_e32 v70, v0, v70
	v_add_f32_e32 v73, v70, v71
	v_frexp_mant_f32_e32 v70, v67
	v_cmp_gt_f32_e32 vcc, s9, v70
	v_cvt_f64_f32_e32 v[70:71], v67
	v_frexp_exp_i32_f64_e32 v70, v[70:71]
	v_subbrev_co_u32_e32 v82, vcc, 0, v70, vcc
	v_sub_u32_e32 v71, 0, v82
	v_ldexp_f32 v70, v67, v71
	v_mul_f32_e64 v67, |v69|, s8
	v_exp_f32_e32 v67, v67
	v_ldexp_f32 v74, v73, v71
	v_min_f32_e32 v73, 0, v69
	v_pk_add_f32 v[60:61], v[60:61], v[64:65]
	v_add_f32_e32 v71, 1.0, v67
	v_add_f32_e32 v69, -1.0, v71
	v_sub_f32_e32 v75, v69, v71
	v_add_f32_e32 v75, 1.0, v75
	v_sub_f32_e32 v69, v67, v69
	v_add_f32_e32 v75, v69, v75
	v_frexp_mant_f32_e32 v69, v71
	v_cvt_f64_f32_e32 v[76:77], v71
	v_cmp_gt_f32_e32 vcc, s9, v69
	v_frexp_exp_i32_f64_e32 v69, v[76:77]
	v_pk_add_f32 v[54:55], v[54:55], v[62:63]
	v_subbrev_co_u32_e32 v69, vcc, 0, v69, vcc
	v_sub_u32_e32 v76, 0, v69
	v_ldexp_f32 v71, v71, v76
	v_ldexp_f32 v75, v75, v76
	v_pk_add_f32 v[76:77], v[70:71], 1.0 op_sel_hi:[1,0]
	v_pk_add_f32 v[86:87], v[70:71], -1.0 op_sel_hi:[1,0]
	v_pk_add_f32 v[78:79], v[76:77], -1.0 op_sel_hi:[1,0]
	v_pk_add_f32 v[88:89], v[86:87], 1.0 op_sel_hi:[1,0]
; __device__ __forceinline__ float log_sigmoid_f(float v) { return fminf(v, 0.f) - log1pf(__expf(-fabsf(v))); }
;     __device__ __forceinline__ void operator()(const f32x4 (&acc)[2][2][4][2], const pg8::Unit& u, int wr, int wc, int fr, int fq) const {
;     ...
;                 for (int nn = 0; nn < 2; ++nn) { const int head = 2 * fq + nn; const f32x4 gb = *(const f32x4*)(gate_b + 4 * head);
; #pragma unroll
;                     for (int ai = 0; ai < 2; ++ai)
; #pragma unroll
;                         for (int m = 0; m < 4; ++m) { const int row = row0 + ai * 128 + m * 16; f32x4 v = acc[ai][0][m][nn] + gb;
;                             v[1] = log_sigmoid_f(v[1]); v[3] = log_sigmoid_f(v[3]);
;                             *(f32x4*)(G + (size_t)row * 16 + 4 * head) = v; } }
	v_pk_add_f32 v[78:79], v[70:71], v[78:79] neg_lo:[0,1] neg_hi:[0,1]
	v_pk_add_f32 v[70:71], v[70:71], v[88:89] neg_lo:[0,1] neg_hi:[0,1]
	v_pk_add_f32 v[78:79], v[74:75], v[78:79]
	v_pk_add_f32 v[70:71], v[74:75], v[70:71]
	v_pk_add_f32 v[80:81], v[76:77], v[78:79]
	v_pk_add_f32 v[74:75], v[86:87], v[70:71]
	v_rcp_f32_e32 v84, v80
	v_rcp_f32_e32 v85, v81
	v_pk_add_f32 v[76:77], v[80:81], v[76:77] neg_lo:[0,1] neg_hi:[0,1]
	v_pk_add_f32 v[86:87], v[74:75], v[86:87] neg_lo:[0,1] neg_hi:[0,1]
	v_pk_add_f32 v[76:77], v[78:79], v[76:77] neg_lo:[0,1] neg_hi:[0,1]
	v_pk_mul_f32 v[78:79], v[74:75], v[84:85]
	v_pk_add_f32 v[70:71], v[70:71], v[86:87] neg_lo:[0,1] neg_hi:[0,1]
	v_pk_mul_f32 v[86:87], v[80:81], v[78:79]
	v_cmp_neq_f32_e32 vcc, s17, v0
	v_pk_fma_f32 v[88:89], v[78:79], v[80:81], v[86:87] neg_lo:[0,0,1] neg_hi:[0,0,1]
	v_pk_add_f32 v[56:57], v[56:57], v[64:65]
	v_pk_fma_f32 v[88:89], v[78:79], v[76:77], v[88:89]
	v_pk_add_f32 v[50:51], v[50:51], v[62:63]
	v_pk_add_f32 v[90:91], v[86:87], v[88:89]
	v_pk_add_f32 v[52:53], v[52:53], v[64:65]
	v_pk_add_f32 v[92:93], v[74:75], v[90:91] neg_lo:[0,1] neg_hi:[0,1]
	v_pk_add_f32 v[86:87], v[90:91], v[86:87] neg_lo:[0,1] neg_hi:[0,1]
	v_pk_add_f32 v[74:75], v[74:75], v[92:93] neg_lo:[0,1] neg_hi:[0,1]
	v_pk_add_f32 v[46:47], v[46:47], v[62:63]
	v_pk_add_f32 v[74:75], v[74:75], v[90:91] neg_lo:[0,1] neg_hi:[0,1]
	v_pk_add_f32 v[48:49], v[48:49], v[64:65]
	v_pk_add_f32 v[70:71], v[70:71], v[74:75]
	v_pk_add_f32 v[74:75], v[86:87], v[88:89] neg_lo:[0,1] neg_hi:[0,1]
	v_pk_add_f32 v[42:43], v[42:43], v[62:63]
	v_pk_add_f32 v[70:71], v[74:75], v[70:71]
	v_pk_add_f32 v[44:45], v[44:45], v[64:65]
	v_pk_add_f32 v[74:75], v[92:93], v[70:71]
	v_pk_add_f32 v[38:39], v[38:39], v[62:63]
	v_pk_mul_f32 v[86:87], v[84:85], v[74:75]
	v_pk_add_f32 v[40:41], v[40:41], v[64:65]
	v_pk_mul_f32 v[88:89], v[80:81], v[86:87]
	v_pk_add_f32 v[34:35], v[34:35], v[62:63]
	v_pk_fma_f32 v[80:81], v[86:87], v[80:81], v[88:89] neg_lo:[0,0,1] neg_hi:[0,0,1]
	v_pk_add_f32 v[36:37], v[36:37], v[64:65]
	v_pk_fma_f32 v[76:77], v[86:87], v[76:77], v[80:81]
	v_pk_add_f32 v[80:81], v[92:93], v[74:75] neg_lo:[0,1] neg_hi:[0,1]
	s_nop 0
	v_pk_add_f32 v[70:71], v[70:71], v[80:81]
	v_pk_add_f32 v[80:81], v[88:89], v[76:77]
	s_nop 0
	v_pk_add_f32 v[90:91], v[74:75], v[80:81] neg_lo:[0,1] neg_hi:[0,1]
	v_pk_add_f32 v[88:89], v[80:81], v[88:89] neg_lo:[0,1] neg_hi:[0,1]
	v_pk_add_f32 v[74:75], v[74:75], v[90:91] neg_lo:[0,1] neg_hi:[0,1]
	s_nop 0
	v_pk_add_f32 v[74:75], v[74:75], v[80:81] neg_lo:[0,1] neg_hi:[0,1]
	s_nop 0
	v_pk_add_f32 v[70:71], v[70:71], v[74:75]
	v_pk_add_f32 v[74:75], v[88:89], v[76:77] neg_lo:[0,1] neg_hi:[0,1]
	s_nop 0
	v_pk_add_f32 v[70:71], v[74:75], v[70:71]
	v_pk_add_f32 v[74:75], v[78:79], v[86:87]
	v_pk_add_f32 v[70:71], v[90:91], v[70:71]
	v_pk_add_f32 v[76:77], v[74:75], v[78:79] neg_lo:[0,1] neg_hi:[0,1]
	v_pk_mul_f32 v[70:71], v[84:85], v[70:71]
	v_pk_add_f32 v[76:77], v[86:87], v[76:77] neg_lo:[0,1] neg_hi:[0,1]
	s_nop 0
	v_pk_add_f32 v[70:71], v[76:77], v[70:71]
	s_nop 0
	v_pk_add_f32 v[78:79], v[74:75], v[70:71]
	s_nop 0
	v_pk_add_f32 v[74:75], v[78:79], v[74:75] neg_lo:[0,1] neg_hi:[0,1]
	v_pk_mul_f32 v[80:81], v[78:79], v[78:79]
	v_pk_add_f32 v[74:75], v[70:71], v[74:75] neg_lo:[0,1] neg_hi:[0,1]
	v_mov_b64_e32 v[70:71], s[0:1]
	v_pk_fma_f32 v[84:85], v[80:81], s[34:35], v[70:71] op_sel_hi:[1,0,0]
	v_ldexp_f32 v76, v78, 1
	v_pk_fma_f32 v[84:85], v[80:81], v[84:85], s[36:37] op_sel_hi:[1,1,0]
	v_ldexp_f32 v77, v79, 1
	v_pk_mul_f32 v[78:79], v[78:79], v[80:81]
	v_cvt_f32_i32_e32 v81, v69
	v_cvt_f32_i32_e32 v80, v82
	v_pk_mul_f32 v[84:85], v[78:79], v[84:85]
	v_ldexp_f32 v87, v75, 1
	v_pk_add_f32 v[78:79], v[76:77], v[84:85]
	v_pk_mul_f32 v[90:91], v[80:81], s[38:39] op_sel_hi:[1,0]
	v_pk_add_f32 v[76:77], v[78:79], v[76:77] neg_lo:[0,1] neg_hi:[0,1]
	v_pk_fma_f32 v[82:83], v[80:81], s[38:39], v[90:91] op_sel_hi:[1,0,1] neg_lo:[0,0,1] neg_hi:[0,0,1]
	v_pk_add_f32 v[84:85], v[84:85], v[76:77] neg_lo:[0,1] neg_hi:[0,1]
	v_pk_fma_f32 v[80:81], v[80:81], s[40:41], v[82:83] op_sel_hi:[1,0,1]
	v_ldexp_f32 v74, v74, 1
	v_mov_b32_e32 v76, v90
	v_mov_b32_e32 v77, v85
	v_mov_b32_e32 v86, v80
	v_mov_b32_e32 v75, v87
	v_pk_add_f32 v[76:77], v[76:77], v[86:87]
	v_pk_add_f32 v[86:87], v[74:75], v[84:85]
	v_pk_add_f32 v[82:83], v[90:91], v[80:81]
	v_mov_b32_e32 v75, v87
	v_mov_b32_e32 v85, v79
	v_pk_add_f32 v[88:89], v[78:79], v[86:87]
	v_pk_add_f32 v[84:85], v[74:75], v[84:85]
	v_pk_add_f32 v[74:75], v[82:83], v[88:89]
	v_mov_b32_e32 v96, v88
	v_mov_b32_e32 v97, v75
	v_mov_b32_e32 v98, v78
	v_mov_b32_e32 v99, v83
	v_pk_add_f32 v[96:97], v[96:97], v[98:99] neg_lo:[0,1] neg_hi:[0,1]
	v_mov_b32_e32 v92, v74
	v_mov_b32_e32 v93, v83
	v_mov_b32_e32 v94, v82
	v_mov_b32_e32 v95, v91
	v_mov_b32_e32 v98, v82
	v_mov_b32_e32 v99, v75
	v_mov_b32_e32 v91, v97
	v_pk_add_f32 v[92:93], v[92:93], v[94:95] neg_lo:[0,1] neg_hi:[0,1]
	v_mov_b32_e32 v94, v88
	v_mov_b32_e32 v95, v81
	v_pk_add_f32 v[90:91], v[98:99], v[90:91] neg_lo:[0,1] neg_hi:[0,1]
	v_pk_add_f32 v[94:95], v[94:95], v[92:93] neg_lo:[0,1] neg_hi:[0,1]
	v_mov_b32_e32 v98, v90
	v_mov_b32_e32 v99, v93
	v_mov_b32_e32 v100, v74
	v_mov_b32_e32 v101, v89
	v_mov_b32_e32 v93, v79
	v_pk_add_f32 v[98:99], v[80:81], v[98:99] neg_lo:[0,1] neg_hi:[0,1]
	v_pk_add_f32 v[92:93], v[100:101], v[92:93] neg_lo:[0,1] neg_hi:[0,1]
	v_mov_b32_e32 v81, v83
	v_pk_add_f32 v[76:77], v[76:77], v[92:93] neg_lo:[0,1] neg_hi:[0,1]
	v_pk_add_f32 v[80:81], v[80:81], v[90:91] neg_lo:[0,1] neg_hi:[0,1]
	v_pk_add_f32 v[82:83], v[84:85], v[96:97] neg_lo:[0,1] neg_hi:[0,1]
	v_pk_add_f32 v[78:79], v[88:89], v[78:79] neg_lo:[0,1] neg_hi:[0,1]
; __device__ __forceinline__ float log_sigmoid_f(float v) { return fminf(v, 0.f) - log1pf(__expf(-fabsf(v))); }
;     __device__ __forceinline__ void operator()(const f32x4 (&acc)[2][2][4][2], const pg8::Unit& u, int wr, int wc, int fr, int fq) const {
;     ...
;                 for (int nn = 0; nn < 2; ++nn) { const int head = 2 * fq + nn; const f32x4 gb = *(const f32x4*)(gate_b + 4 * head);
; #pragma unroll
;                     for (int ai = 0; ai < 2; ++ai)
; #pragma unroll
;                         for (int m = 0; m < 4; ++m) { const int row = row0 + ai * 128 + m * 16; f32x4 v = acc[ai][0][m][nn] + gb;
;                             v[1] = log_sigmoid_f(v[1]); v[3] = log_sigmoid_f(v[3]);
;                             *(f32x4*)(G + (size_t)row * 16 + 4 * head) = v; } }
	v_pk_add_f32 v[84:85], v[82:83], v[80:81]
	v_mov_b32_e32 v81, v95
	v_mov_b32_e32 v83, v77
	v_pk_add_f32 v[78:79], v[86:87], v[78:79] neg_lo:[0,1] neg_hi:[0,1]
	v_pk_add_f32 v[86:87], v[94:95], v[76:77]
	v_pk_add_f32 v[76:77], v[80:81], v[82:83]
	v_mov_b32_e32 v82, v84
	v_pk_add_f32 v[76:77], v[76:77], v[98:99] neg_lo:[0,1] neg_hi:[0,1]
	v_mov_b32_e32 v83, v87
	v_pk_add_f32 v[82:83], v[82:83], v[76:77] neg_lo:[0,1] neg_hi:[0,1]
	v_pk_add_f32 v[76:77], v[78:79], v[76:77] neg_lo:[0,1] neg_hi:[0,1]
	v_pk_add_f32 v[80:81], v[80:81], v[82:83] neg_lo:[0,1] neg_hi:[0,1]
	v_pk_add_f32 v[78:79], v[86:87], v[84:85]
	v_pk_add_f32 v[76:77], v[76:77], v[80:81]
	v_pk_add_f32 v[80:81], v[74:75], v[78:79]
	v_cmp_lt_f32_e64 s[0:1], |v0|, s19
	v_pk_add_f32 v[74:75], v[80:81], v[74:75] neg_lo:[0,1] neg_hi:[0,1]
	s_nop 0
	v_pk_add_f32 v[74:75], v[78:79], v[74:75] neg_lo:[0,1] neg_hi:[0,1]
	s_nop 0
	v_pk_add_f32 v[74:75], v[76:77], v[74:75]
	s_nop 0
	v_pk_add_f32 v[74:75], v[80:81], v[74:75]
	s_nop 0
	v_cndmask_b32_e32 v69, v199, v74, vcc
	v_cmp_neq_f32_e32 vcc, s17, v67
	s_nop 1
	v_cndmask_b32_e32 v74, v199, v75, vcc
	v_cmp_ngt_f32_e32 vcc, -1.0, v67
	s_nop 1
	v_cndmask_b32_e32 v74, v200, v74, vcc
	v_cmp_ngt_f32_e32 vcc, -1.0, v0
	s_nop 1
	v_cndmask_b32_e32 v69, v200, v69, vcc
	v_cmp_neq_f32_e32 vcc, -1.0, v0
	s_nop 1
	v_cndmask_b32_e32 v69, v201, v69, vcc
	v_cmp_neq_f32_e32 vcc, -1.0, v67
	s_nop 1
	v_cndmask_b32_e32 v74, v201, v74, vcc
	v_cmp_lt_f32_e64 vcc, |v67|, s19
	s_nop 1
	v_cndmask_b32_e32 v75, v74, v67, vcc
	v_cndmask_b32_e64 v74, v69, v0, s[0:1]
	v_mul_f32_e64 v0, |v59|, s8
	v_exp_f32_e32 v0, v0
	v_pk_add_f32 v[74:75], v[72:73], v[74:75] neg_lo:[0,1] neg_hi:[0,1]
	v_lshlrev_b64 v[72:73], 6, v[182:183]
	v_lshl_add_u64 v[72:73], v[176:177], 0, v[72:73]
	v_mov_b32_e32 v67, v74
	v_mov_b32_e32 v69, v75
	global_store_dwordx4 v[72:73], v[66:69], off
	v_cmp_lt_f32_e64 s[0:1], |v0|, s19
	s_nop 0
	v_min_f32_e32 v68, 0, v59
	v_add_f32_e32 v59, 1.0, v0
	v_add_f32_e32 v67, -1.0, v59
	v_sub_f32_e32 v69, v67, v59
	v_add_f32_e32 v69, 1.0, v69
	v_sub_f32_e32 v67, v0, v67
	v_add_f32_e32 v67, v67, v69
	v_frexp_mant_f32_e32 v69, v59
	v_cvt_f64_f32_e32 v[74:75], v59
	v_cmp_gt_f32_e32 vcc, s9, v69
	v_frexp_exp_i32_f64_e32 v69, v[74:75]
	v_or_b32_e32 v66, 16, v182
	v_subbrev_co_u32_e32 v94, vcc, 0, v69, vcc
	v_sub_u32_e32 v69, 0, v94
	v_ldexp_f32 v74, v59, v69
	v_mul_f32_e64 v59, |v61|, s8
	v_exp_f32_e32 v59, v59
	v_ldexp_f32 v76, v67, v69
	v_min_f32_e32 v69, 0, v61
	v_add_f32_e32 v61, 1.0, v59
	v_add_f32_e32 v67, -1.0, v61
	v_sub_f32_e32 v75, v67, v61
	v_add_f32_e32 v75, 1.0, v75
	v_sub_f32_e32 v67, v59, v67
	v_add_f32_e32 v67, v67, v75
	v_frexp_mant_f32_e32 v75, v61
	v_cvt_f64_f32_e32 v[78:79], v61
	v_cmp_gt_f32_e32 vcc, s9, v75
	v_frexp_exp_i32_f64_e32 v75, v[78:79]
	s_nop 0
	v_subbrev_co_u32_e32 v95, vcc, 0, v75, vcc
	v_sub_u32_e32 v77, 0, v95
	v_ldexp_f32 v75, v61, v77
	v_pk_add_f32 v[78:79], v[74:75], 1.0 op_sel_hi:[1,0]
	v_ldexp_f32 v77, v67, v77
	v_pk_add_f32 v[80:81], v[78:79], -1.0 op_sel_hi:[1,0]
	v_pk_add_f32 v[86:87], v[74:75], -1.0 op_sel_hi:[1,0]
	v_pk_add_f32 v[80:81], v[74:75], v[80:81] neg_lo:[0,1] neg_hi:[0,1]
	v_pk_add_f32 v[88:89], v[86:87], 1.0 op_sel_hi:[1,0]
	v_pk_add_f32 v[80:81], v[76:77], v[80:81]
	v_pk_add_f32 v[74:75], v[74:75], v[88:89] neg_lo:[0,1] neg_hi:[0,1]
	v_pk_add_f32 v[82:83], v[78:79], v[80:81]
	v_pk_add_f32 v[74:75], v[76:77], v[74:75]
	v_rcp_f32_e32 v84, v82
	v_rcp_f32_e32 v85, v83
	v_pk_add_f32 v[76:77], v[86:87], v[74:75]
	v_pk_add_f32 v[78:79], v[82:83], v[78:79] neg_lo:[0,1] neg_hi:[0,1]
	v_pk_add_f32 v[86:87], v[76:77], v[86:87] neg_lo:[0,1] neg_hi:[0,1]
	v_pk_add_f32 v[78:79], v[80:81], v[78:79] neg_lo:[0,1] neg_hi:[0,1]
	v_pk_mul_f32 v[80:81], v[76:77], v[84:85]
	v_pk_add_f32 v[74:75], v[74:75], v[86:87] neg_lo:[0,1] neg_hi:[0,1]
	v_pk_mul_f32 v[86:87], v[82:83], v[80:81]
	v_cmp_neq_f32_e32 vcc, s17, v0
	v_pk_fma_f32 v[88:89], v[80:81], v[82:83], v[86:87] neg_lo:[0,0,1] neg_hi:[0,0,1]
	s_nop 0
	v_pk_fma_f32 v[88:89], v[80:81], v[78:79], v[88:89]
	s_nop 0
	v_pk_add_f32 v[90:91], v[86:87], v[88:89]
	s_nop 0
	v_pk_add_f32 v[92:93], v[76:77], v[90:91] neg_lo:[0,1] neg_hi:[0,1]
	v_pk_add_f32 v[86:87], v[90:91], v[86:87] neg_lo:[0,1] neg_hi:[0,1]
	v_pk_add_f32 v[76:77], v[76:77], v[92:93] neg_lo:[0,1] neg_hi:[0,1]
	s_nop 0
	v_pk_add_f32 v[76:77], v[76:77], v[90:91] neg_lo:[0,1] neg_hi:[0,1]
	s_nop 0
	v_pk_add_f32 v[74:75], v[74:75], v[76:77]
	v_pk_add_f32 v[76:77], v[86:87], v[88:89] neg_lo:[0,1] neg_hi:[0,1]
	s_nop 0
	v_pk_add_f32 v[74:75], v[76:77], v[74:75]
	s_nop 0
	v_pk_add_f32 v[76:77], v[92:93], v[74:75]
	s_nop 0
	v_pk_mul_f32 v[86:87], v[84:85], v[76:77]
	s_nop 0
	v_pk_mul_f32 v[88:89], v[82:83], v[86:87]
	s_nop 0
	v_pk_fma_f32 v[82:83], v[86:87], v[82:83], v[88:89] neg_lo:[0,0,1] neg_hi:[0,0,1]
	s_nop 0
	v_pk_fma_f32 v[78:79], v[86:87], v[78:79], v[82:83]
	v_pk_add_f32 v[82:83], v[92:93], v[76:77] neg_lo:[0,1] neg_hi:[0,1]
	s_nop 0
	v_pk_add_f32 v[74:75], v[74:75], v[82:83]
	v_pk_add_f32 v[82:83], v[88:89], v[78:79]
	s_nop 0
	v_pk_add_f32 v[90:91], v[76:77], v[82:83] neg_lo:[0,1] neg_hi:[0,1]
	v_pk_add_f32 v[88:89], v[82:83], v[88:89] neg_lo:[0,1] neg_hi:[0,1]
	v_pk_add_f32 v[76:77], v[76:77], v[90:91] neg_lo:[0,1] neg_hi:[0,1]
	s_nop 0
	v_pk_add_f32 v[76:77], v[76:77], v[82:83] neg_lo:[0,1] neg_hi:[0,1]
	s_nop 0
	v_pk_add_f32 v[74:75], v[74:75], v[76:77]
	v_pk_add_f32 v[76:77], v[88:89], v[78:79] neg_lo:[0,1] neg_hi:[0,1]
	s_nop 0
	v_pk_add_f32 v[74:75], v[76:77], v[74:75]
	v_pk_add_f32 v[76:77], v[80:81], v[86:87]
	v_pk_add_f32 v[74:75], v[90:91], v[74:75]
	v_pk_add_f32 v[78:79], v[76:77], v[80:81] neg_lo:[0,1] neg_hi:[0,1]
; __device__ __forceinline__ float log_sigmoid_f(float v) { return fminf(v, 0.f) - log1pf(__expf(-fabsf(v))); }
;     __device__ __forceinline__ void operator()(const f32x4 (&acc)[2][2][4][2], const pg8::Unit& u, int wr, int wc, int fr, int fq) const {
;     ...
;                 for (int nn = 0; nn < 2; ++nn) { const int head = 2 * fq + nn; const f32x4 gb = *(const f32x4*)(gate_b + 4 * head);
; #pragma unroll
;                     for (int ai = 0; ai < 2; ++ai)
; #pragma unroll
;                         for (int m = 0; m < 4; ++m) { const int row = row0 + ai * 128 + m * 16; f32x4 v = acc[ai][0][m][nn] + gb;
;                             v[1] = log_sigmoid_f(v[1]); v[3] = log_sigmoid_f(v[3]);
;                             *(f32x4*)(G + (size_t)row * 16 + 4 * head) = v; } }
	v_pk_mul_f32 v[74:75], v[84:85], v[74:75]
	v_pk_add_f32 v[78:79], v[86:87], v[78:79] neg_lo:[0,1] neg_hi:[0,1]
	s_nop 0
	v_pk_add_f32 v[74:75], v[78:79], v[74:75]
	s_nop 0
	v_pk_add_f32 v[78:79], v[76:77], v[74:75]
	s_nop 0
	v_pk_mul_f32 v[80:81], v[78:79], v[78:79]
	v_pk_add_f32 v[76:77], v[78:79], v[76:77] neg_lo:[0,1] neg_hi:[0,1]
	v_pk_fma_f32 v[82:83], v[80:81], s[34:35], v[70:71] op_sel_hi:[1,0,0]
	v_pk_add_f32 v[74:75], v[74:75], v[76:77] neg_lo:[0,1] neg_hi:[0,1]
	v_ldexp_f32 v76, v78, 1
	v_pk_fma_f32 v[82:83], v[80:81], v[82:83], s[36:37] op_sel_hi:[1,1,0]
	v_ldexp_f32 v77, v79, 1
	v_pk_mul_f32 v[78:79], v[78:79], v[80:81]
	v_cvt_f32_i32_e32 v81, v95
	v_cvt_f32_i32_e32 v80, v94
	v_pk_mul_f32 v[78:79], v[78:79], v[82:83]
	v_ldexp_f32 v85, v75, 1
	v_pk_add_f32 v[82:83], v[76:77], v[78:79]
	v_pk_mul_f32 v[86:87], v[80:81], s[38:39] op_sel_hi:[1,0]
	v_pk_add_f32 v[76:77], v[82:83], v[76:77] neg_lo:[0,1] neg_hi:[0,1]
	v_pk_fma_f32 v[88:89], v[80:81], s[38:39], v[86:87] op_sel_hi:[1,0,1] neg_lo:[0,0,1] neg_hi:[0,0,1]
	v_pk_add_f32 v[76:77], v[78:79], v[76:77] neg_lo:[0,1] neg_hi:[0,1]
	v_pk_fma_f32 v[80:81], v[80:81], s[40:41], v[88:89] op_sel_hi:[1,0,1]
	v_ldexp_f32 v74, v74, 1
	v_mov_b32_e32 v78, v86
	v_mov_b32_e32 v79, v77
	v_mov_b32_e32 v84, v80
	v_mov_b32_e32 v75, v85
	v_pk_add_f32 v[78:79], v[78:79], v[84:85]
	v_pk_add_f32 v[84:85], v[74:75], v[76:77]
	v_mov_b32_e32 v77, v83
	v_mov_b32_e32 v75, v85
	v_pk_add_f32 v[88:89], v[86:87], v[80:81]
	v_pk_add_f32 v[74:75], v[74:75], v[76:77]
	v_pk_add_f32 v[76:77], v[82:83], v[84:85]
	v_mov_b32_e32 v98, v82
	v_pk_add_f32 v[90:91], v[88:89], v[76:77]
	v_mov_b32_e32 v96, v76
	v_mov_b32_e32 v97, v91
	v_mov_b32_e32 v99, v89
	v_pk_add_f32 v[96:97], v[96:97], v[98:99] neg_lo:[0,1] neg_hi:[0,1]
	v_mov_b32_e32 v92, v90
	v_mov_b32_e32 v93, v89
	v_mov_b32_e32 v94, v88
	v_mov_b32_e32 v95, v87
	v_mov_b32_e32 v98, v88
	v_mov_b32_e32 v99, v91
	v_mov_b32_e32 v87, v97
	v_pk_add_f32 v[92:93], v[92:93], v[94:95] neg_lo:[0,1] neg_hi:[0,1]
	v_mov_b32_e32 v94, v76
	v_mov_b32_e32 v95, v81
	v_pk_add_f32 v[86:87], v[98:99], v[86:87] neg_lo:[0,1] neg_hi:[0,1]
	v_pk_add_f32 v[94:95], v[94:95], v[92:93] neg_lo:[0,1] neg_hi:[0,1]
	v_mov_b32_e32 v98, v86
	v_mov_b32_e32 v99, v93
	v_mov_b32_e32 v100, v90
	v_mov_b32_e32 v101, v77
	v_mov_b32_e32 v93, v83
	v_pk_add_f32 v[98:99], v[80:81], v[98:99] neg_lo:[0,1] neg_hi:[0,1]
	v_pk_add_f32 v[92:93], v[100:101], v[92:93] neg_lo:[0,1] neg_hi:[0,1]
	v_mov_b32_e32 v81, v89
	v_pk_add_f32 v[78:79], v[78:79], v[92:93] neg_lo:[0,1] neg_hi:[0,1]
	v_pk_add_f32 v[80:81], v[80:81], v[86:87] neg_lo:[0,1] neg_hi:[0,1]
	v_pk_add_f32 v[74:75], v[74:75], v[96:97] neg_lo:[0,1] neg_hi:[0,1]
	v_pk_add_f32 v[76:77], v[76:77], v[82:83] neg_lo:[0,1] neg_hi:[0,1]
	v_pk_add_f32 v[82:83], v[74:75], v[80:81]
	v_mov_b32_e32 v81, v95
	v_mov_b32_e32 v75, v79
	v_pk_add_f32 v[76:77], v[84:85], v[76:77] neg_lo:[0,1] neg_hi:[0,1]
	v_pk_add_f32 v[84:85], v[94:95], v[78:79]
	v_pk_add_f32 v[74:75], v[80:81], v[74:75]
	v_mov_b32_e32 v78, v82
	v_pk_add_f32 v[74:75], v[74:75], v[98:99] neg_lo:[0,1] neg_hi:[0,1]
	v_mov_b32_e32 v79, v85
	v_pk_add_f32 v[78:79], v[78:79], v[74:75] neg_lo:[0,1] neg_hi:[0,1]
	v_pk_add_f32 v[74:75], v[76:77], v[74:75] neg_lo:[0,1] neg_hi:[0,1]
	v_pk_add_f32 v[78:79], v[80:81], v[78:79] neg_lo:[0,1] neg_hi:[0,1]
	v_pk_add_f32 v[76:77], v[84:85], v[82:83]
	v_pk_add_f32 v[74:75], v[74:75], v[78:79]
	v_pk_add_f32 v[78:79], v[90:91], v[76:77]
	s_nop 0
	v_pk_add_f32 v[80:81], v[78:79], v[90:91] neg_lo:[0,1] neg_hi:[0,1]
	s_nop 0
	v_pk_add_f32 v[76:77], v[76:77], v[80:81] neg_lo:[0,1] neg_hi:[0,1]
	s_nop 0
	v_pk_add_f32 v[74:75], v[74:75], v[76:77]
	s_nop 0
	v_pk_add_f32 v[74:75], v[78:79], v[74:75]
	s_nop 0
	v_cndmask_b32_e32 v61, v199, v74, vcc
	v_cmp_neq_f32_e32 vcc, s17, v59
	s_nop 1
	v_cndmask_b32_e32 v67, v199, v75, vcc
	v_cmp_ngt_f32_e32 vcc, -1.0, v59
	s_nop 1
	v_cndmask_b32_e32 v67, v200, v67, vcc
	v_cmp_ngt_f32_e32 vcc, -1.0, v0
	s_nop 1
	v_cndmask_b32_e32 v61, v200, v61, vcc
	v_cmp_neq_f32_e32 vcc, -1.0, v0
	s_nop 1
	v_cndmask_b32_e32 v61, v201, v61, vcc
	v_cmp_neq_f32_e32 vcc, -1.0, v59
	v_cndmask_b32_e64 v74, v61, v0, s[0:1]
	v_mul_f32_e64 v0, |v55|, s8
	v_cndmask_b32_e32 v67, v201, v67, vcc
	v_cmp_lt_f32_e64 vcc, |v59|, s19
	v_exp_f32_e32 v0, v0
	s_nop 0
	v_cndmask_b32_e32 v75, v67, v59, vcc
	v_ashrrev_i32_e32 v67, 31, v66
	v_pk_add_f32 v[68:69], v[68:69], v[74:75] neg_lo:[0,1] neg_hi:[0,1]
	v_lshlrev_b64 v[66:67], 6, v[66:67]
	v_lshl_add_u64 v[66:67], v[176:177], 0, v[66:67]
	v_mov_b32_e32 v59, v68
	v_mov_b32_e32 v61, v69
	global_store_dwordx4 v[66:67], v[58:61], off
	v_cmp_lt_f32_e64 s[0:1], |v0|, s19
	s_nop 0
	v_min_f32_e32 v60, 0, v55
	v_add_f32_e32 v55, 1.0, v0
	v_add_f32_e32 v59, -1.0, v55
	v_sub_f32_e32 v61, v59, v55
	v_add_f32_e32 v61, 1.0, v61
	v_sub_f32_e32 v59, v0, v59
	v_add_f32_e32 v59, v59, v61
	v_frexp_mant_f32_e32 v61, v55
	v_cvt_f64_f32_e32 v[68:69], v55
	v_cmp_gt_f32_e32 vcc, s9, v61
	v_frexp_exp_i32_f64_e32 v61, v[68:69]
	v_or_b32_e32 v58, 32, v182
	v_subbrev_co_u32_e32 v92, vcc, 0, v61, vcc
	v_sub_u32_e32 v61, 0, v92
	v_ldexp_f32 v68, v55, v61
	v_mul_f32_e64 v55, |v57|, s8
	v_exp_f32_e32 v55, v55
	v_ldexp_f32 v74, v59, v61
	v_min_f32_e32 v61, 0, v57
	v_add_f32_e32 v57, 1.0, v55
	v_add_f32_e32 v59, -1.0, v57
	v_sub_f32_e32 v69, v59, v57
	v_add_f32_e32 v69, 1.0, v69
	v_sub_f32_e32 v59, v55, v59
	v_add_f32_e32 v59, v59, v69
	v_frexp_mant_f32_e32 v69, v57
	v_cvt_f64_f32_e32 v[76:77], v57
	v_cmp_gt_f32_e32 vcc, s9, v69
	v_frexp_exp_i32_f64_e32 v69, v[76:77]
	s_nop 0
	v_subbrev_co_u32_e32 v93, vcc, 0, v69, vcc
	v_sub_u32_e32 v75, 0, v93
	v_ldexp_f32 v69, v57, v75
; __device__ __forceinline__ float log_sigmoid_f(float v) { return fminf(v, 0.f) - log1pf(__expf(-fabsf(v))); }
;     __device__ __forceinline__ void operator()(const f32x4 (&acc)[2][2][4][2], const pg8::Unit& u, int wr, int wc, int fr, int fq) const {
;     ...
;                 for (int nn = 0; nn < 2; ++nn) { const int head = 2 * fq + nn; const f32x4 gb = *(const f32x4*)(gate_b + 4 * head);
; #pragma unroll
;                     for (int ai = 0; ai < 2; ++ai)
; #pragma unroll
;                         for (int m = 0; m < 4; ++m) { const int row = row0 + ai * 128 + m * 16; f32x4 v = acc[ai][0][m][nn] + gb;
;                             v[1] = log_sigmoid_f(v[1]); v[3] = log_sigmoid_f(v[3]);
;                             *(f32x4*)(G + (size_t)row * 16 + 4 * head) = v; } }
	v_pk_add_f32 v[76:77], v[68:69], 1.0 op_sel_hi:[1,0]
	v_ldexp_f32 v75, v59, v75
	v_pk_add_f32 v[78:79], v[76:77], -1.0 op_sel_hi:[1,0]
	v_pk_add_f32 v[84:85], v[68:69], -1.0 op_sel_hi:[1,0]
	v_pk_add_f32 v[78:79], v[68:69], v[78:79] neg_lo:[0,1] neg_hi:[0,1]
	v_pk_add_f32 v[86:87], v[84:85], 1.0 op_sel_hi:[1,0]
	v_pk_add_f32 v[78:79], v[74:75], v[78:79]
	v_pk_add_f32 v[68:69], v[68:69], v[86:87] neg_lo:[0,1] neg_hi:[0,1]
	v_pk_add_f32 v[80:81], v[76:77], v[78:79]
	v_pk_add_f32 v[68:69], v[74:75], v[68:69]
	v_rcp_f32_e32 v82, v80
	v_rcp_f32_e32 v83, v81
	v_pk_add_f32 v[74:75], v[84:85], v[68:69]
	v_pk_add_f32 v[76:77], v[80:81], v[76:77] neg_lo:[0,1] neg_hi:[0,1]
	v_pk_add_f32 v[84:85], v[74:75], v[84:85] neg_lo:[0,1] neg_hi:[0,1]
	v_pk_add_f32 v[76:77], v[78:79], v[76:77] neg_lo:[0,1] neg_hi:[0,1]
	v_pk_mul_f32 v[78:79], v[74:75], v[82:83]
	v_pk_add_f32 v[68:69], v[68:69], v[84:85] neg_lo:[0,1] neg_hi:[0,1]
	v_pk_mul_f32 v[84:85], v[80:81], v[78:79]
	v_cmp_neq_f32_e32 vcc, s17, v0
	v_pk_fma_f32 v[86:87], v[78:79], v[80:81], v[84:85] neg_lo:[0,0,1] neg_hi:[0,0,1]
	s_nop 0
	v_pk_fma_f32 v[86:87], v[78:79], v[76:77], v[86:87]
	s_nop 0
	v_pk_add_f32 v[88:89], v[84:85], v[86:87]
	s_nop 0
	v_pk_add_f32 v[90:91], v[74:75], v[88:89] neg_lo:[0,1] neg_hi:[0,1]
	v_pk_add_f32 v[84:85], v[88:89], v[84:85] neg_lo:[0,1] neg_hi:[0,1]
	v_pk_add_f32 v[74:75], v[74:75], v[90:91] neg_lo:[0,1] neg_hi:[0,1]
	s_nop 0
	v_pk_add_f32 v[74:75], v[74:75], v[88:89] neg_lo:[0,1] neg_hi:[0,1]
	s_nop 0
	v_pk_add_f32 v[68:69], v[68:69], v[74:75]
	v_pk_add_f32 v[74:75], v[84:85], v[86:87] neg_lo:[0,1] neg_hi:[0,1]
	s_nop 0
	v_pk_add_f32 v[68:69], v[74:75], v[68:69]
	s_nop 0
	v_pk_add_f32 v[74:75], v[90:91], v[68:69]
	s_nop 0
	v_pk_mul_f32 v[84:85], v[82:83], v[74:75]
	s_nop 0
	v_pk_mul_f32 v[86:87], v[80:81], v[84:85]
	s_nop 0
	v_pk_fma_f32 v[80:81], v[84:85], v[80:81], v[86:87] neg_lo:[0,0,1] neg_hi:[0,0,1]
	s_nop 0
	v_pk_fma_f32 v[76:77], v[84:85], v[76:77], v[80:81]
	v_pk_add_f32 v[80:81], v[90:91], v[74:75] neg_lo:[0,1] neg_hi:[0,1]
	s_nop 0
	v_pk_add_f32 v[68:69], v[68:69], v[80:81]
	v_pk_add_f32 v[80:81], v[86:87], v[76:77]
	s_nop 0
	v_pk_add_f32 v[88:89], v[74:75], v[80:81] neg_lo:[0,1] neg_hi:[0,1]
	v_pk_add_f32 v[86:87], v[80:81], v[86:87] neg_lo:[0,1] neg_hi:[0,1]
	v_pk_add_f32 v[74:75], v[74:75], v[88:89] neg_lo:[0,1] neg_hi:[0,1]
	s_nop 0
	v_pk_add_f32 v[74:75], v[74:75], v[80:81] neg_lo:[0,1] neg_hi:[0,1]
	s_nop 0
	v_pk_add_f32 v[68:69], v[68:69], v[74:75]
	v_pk_add_f32 v[74:75], v[86:87], v[76:77] neg_lo:[0,1] neg_hi:[0,1]
	s_nop 0
	v_pk_add_f32 v[68:69], v[74:75], v[68:69]
	v_pk_add_f32 v[74:75], v[78:79], v[84:85]
	v_pk_add_f32 v[68:69], v[88:89], v[68:69]
	v_pk_add_f32 v[76:77], v[74:75], v[78:79] neg_lo:[0,1] neg_hi:[0,1]
	v_pk_mul_f32 v[68:69], v[82:83], v[68:69]
	v_pk_add_f32 v[76:77], v[84:85], v[76:77] neg_lo:[0,1] neg_hi:[0,1]
	s_nop 0
	v_pk_add_f32 v[68:69], v[76:77], v[68:69]
	s_nop 0
	v_pk_add_f32 v[76:77], v[74:75], v[68:69]
	s_nop 0
	v_pk_mul_f32 v[78:79], v[76:77], v[76:77]
	v_pk_add_f32 v[74:75], v[76:77], v[74:75] neg_lo:[0,1] neg_hi:[0,1]
	v_pk_fma_f32 v[80:81], v[78:79], s[34:35], v[70:71] op_sel_hi:[1,0,0]
	v_pk_add_f32 v[68:69], v[68:69], v[74:75] neg_lo:[0,1] neg_hi:[0,1]
	v_ldexp_f32 v74, v76, 1
	v_pk_fma_f32 v[80:81], v[78:79], v[80:81], s[36:37] op_sel_hi:[1,1,0]
	v_ldexp_f32 v75, v77, 1
	v_pk_mul_f32 v[76:77], v[76:77], v[78:79]
	v_cvt_f32_i32_e32 v79, v93
	v_cvt_f32_i32_e32 v78, v92
	v_pk_mul_f32 v[76:77], v[76:77], v[80:81]
	v_ldexp_f32 v83, v69, 1
	v_pk_add_f32 v[80:81], v[74:75], v[76:77]
	v_pk_mul_f32 v[84:85], v[78:79], s[38:39] op_sel_hi:[1,0]
	v_pk_add_f32 v[74:75], v[80:81], v[74:75] neg_lo:[0,1] neg_hi:[0,1]
	v_pk_fma_f32 v[86:87], v[78:79], s[38:39], v[84:85] op_sel_hi:[1,0,1] neg_lo:[0,0,1] neg_hi:[0,0,1]
	v_pk_add_f32 v[74:75], v[76:77], v[74:75] neg_lo:[0,1] neg_hi:[0,1]
	v_pk_fma_f32 v[78:79], v[78:79], s[40:41], v[86:87] op_sel_hi:[1,0,1]
	v_ldexp_f32 v68, v68, 1
	v_mov_b32_e32 v76, v84
	v_mov_b32_e32 v77, v75
	v_mov_b32_e32 v82, v78
	v_mov_b32_e32 v69, v83
	v_pk_add_f32 v[76:77], v[76:77], v[82:83]
	v_pk_add_f32 v[82:83], v[68:69], v[74:75]
	v_mov_b32_e32 v75, v81
	v_mov_b32_e32 v69, v83
	v_pk_add_f32 v[86:87], v[84:85], v[78:79]
	v_pk_add_f32 v[68:69], v[68:69], v[74:75]
	v_pk_add_f32 v[74:75], v[80:81], v[82:83]
	v_mov_b32_e32 v96, v80
	v_pk_add_f32 v[88:89], v[86:87], v[74:75]
	v_mov_b32_e32 v94, v74
	v_mov_b32_e32 v95, v89
	v_mov_b32_e32 v97, v87
	v_pk_add_f32 v[94:95], v[94:95], v[96:97] neg_lo:[0,1] neg_hi:[0,1]
	v_mov_b32_e32 v90, v88
	v_mov_b32_e32 v91, v87
	v_mov_b32_e32 v92, v86
	v_mov_b32_e32 v93, v85
	v_mov_b32_e32 v96, v86
	v_mov_b32_e32 v97, v89
	v_mov_b32_e32 v85, v95
	v_pk_add_f32 v[90:91], v[90:91], v[92:93] neg_lo:[0,1] neg_hi:[0,1]
	v_mov_b32_e32 v92, v74
	v_mov_b32_e32 v93, v79
	v_pk_add_f32 v[84:85], v[96:97], v[84:85] neg_lo:[0,1] neg_hi:[0,1]
	v_pk_add_f32 v[92:93], v[92:93], v[90:91] neg_lo:[0,1] neg_hi:[0,1]
	v_mov_b32_e32 v96, v84
	v_mov_b32_e32 v97, v91
	v_mov_b32_e32 v98, v88
	v_mov_b32_e32 v99, v75
	v_mov_b32_e32 v91, v81
	v_pk_add_f32 v[96:97], v[78:79], v[96:97] neg_lo:[0,1] neg_hi:[0,1]
	v_pk_add_f32 v[90:91], v[98:99], v[90:91] neg_lo:[0,1] neg_hi:[0,1]
	v_mov_b32_e32 v79, v87
	v_pk_add_f32 v[76:77], v[76:77], v[90:91] neg_lo:[0,1] neg_hi:[0,1]
	v_pk_add_f32 v[78:79], v[78:79], v[84:85] neg_lo:[0,1] neg_hi:[0,1]
	v_pk_add_f32 v[68:69], v[68:69], v[94:95] neg_lo:[0,1] neg_hi:[0,1]
	v_pk_add_f32 v[74:75], v[74:75], v[80:81] neg_lo:[0,1] neg_hi:[0,1]
	v_pk_add_f32 v[80:81], v[68:69], v[78:79]
	v_mov_b32_e32 v79, v93
	v_mov_b32_e32 v69, v77
	v_pk_add_f32 v[74:75], v[82:83], v[74:75] neg_lo:[0,1] neg_hi:[0,1]
; __device__ __forceinline__ float log_sigmoid_f(float v) { return fminf(v, 0.f) - log1pf(__expf(-fabsf(v))); }
;     __device__ __forceinline__ void operator()(const f32x4 (&acc)[2][2][4][2], const pg8::Unit& u, int wr, int wc, int fr, int fq) const {
;     ...
;                 for (int nn = 0; nn < 2; ++nn) { const int head = 2 * fq + nn; const f32x4 gb = *(const f32x4*)(gate_b + 4 * head);
; #pragma unroll
;                     for (int ai = 0; ai < 2; ++ai)
; #pragma unroll
;                         for (int m = 0; m < 4; ++m) { const int row = row0 + ai * 128 + m * 16; f32x4 v = acc[ai][0][m][nn] + gb;
;                             v[1] = log_sigmoid_f(v[1]); v[3] = log_sigmoid_f(v[3]);
;                             *(f32x4*)(G + (size_t)row * 16 + 4 * head) = v; } }
	v_pk_add_f32 v[82:83], v[92:93], v[76:77]
	v_pk_add_f32 v[68:69], v[78:79], v[68:69]
	v_mov_b32_e32 v76, v80
	v_pk_add_f32 v[68:69], v[68:69], v[96:97] neg_lo:[0,1] neg_hi:[0,1]
	v_mov_b32_e32 v77, v83
	v_pk_add_f32 v[76:77], v[76:77], v[68:69] neg_lo:[0,1] neg_hi:[0,1]
	v_pk_add_f32 v[68:69], v[74:75], v[68:69] neg_lo:[0,1] neg_hi:[0,1]
	v_pk_add_f32 v[76:77], v[78:79], v[76:77] neg_lo:[0,1] neg_hi:[0,1]
	v_pk_add_f32 v[74:75], v[82:83], v[80:81]
	v_pk_add_f32 v[68:69], v[68:69], v[76:77]
	v_pk_add_f32 v[76:77], v[88:89], v[74:75]
	s_nop 0
	v_pk_add_f32 v[78:79], v[76:77], v[88:89] neg_lo:[0,1] neg_hi:[0,1]
	s_nop 0
	v_pk_add_f32 v[74:75], v[74:75], v[78:79] neg_lo:[0,1] neg_hi:[0,1]
	s_nop 0
	v_pk_add_f32 v[68:69], v[68:69], v[74:75]
	s_nop 0
	v_pk_add_f32 v[68:69], v[76:77], v[68:69]
	s_nop 0
	v_cndmask_b32_e32 v57, v199, v68, vcc
	v_cmp_neq_f32_e32 vcc, s17, v55
	s_nop 1
	v_cndmask_b32_e32 v59, v199, v69, vcc
	v_cmp_ngt_f32_e32 vcc, -1.0, v55
	s_nop 1
	v_cndmask_b32_e32 v59, v200, v59, vcc
	v_cmp_ngt_f32_e32 vcc, -1.0, v0
	s_nop 1
	v_cndmask_b32_e32 v57, v200, v57, vcc
	v_cmp_neq_f32_e32 vcc, -1.0, v0
	s_nop 1
	v_cndmask_b32_e32 v57, v201, v57, vcc
	v_cmp_neq_f32_e32 vcc, -1.0, v55
	v_cndmask_b32_e64 v68, v57, v0, s[0:1]
	v_mul_f32_e64 v0, |v51|, s8
	v_cndmask_b32_e32 v59, v201, v59, vcc
	v_cmp_lt_f32_e64 vcc, |v55|, s19
	v_exp_f32_e32 v0, v0
	s_nop 0
	v_cndmask_b32_e32 v69, v59, v55, vcc
	v_ashrrev_i32_e32 v59, 31, v58
	v_pk_add_f32 v[60:61], v[60:61], v[68:69] neg_lo:[0,1] neg_hi:[0,1]
	v_lshlrev_b64 v[58:59], 6, v[58:59]
	v_lshl_add_u64 v[58:59], v[176:177], 0, v[58:59]
	v_mov_b32_e32 v55, v60
	v_mov_b32_e32 v57, v61
	global_store_dwordx4 v[58:59], v[54:57], off
	v_cmp_lt_f32_e64 s[0:1], |v0|, s19
	s_nop 0
	v_min_f32_e32 v56, 0, v51
	v_add_f32_e32 v51, 1.0, v0
	v_add_f32_e32 v55, -1.0, v51
	v_sub_f32_e32 v57, v55, v51
	v_add_f32_e32 v57, 1.0, v57
	v_sub_f32_e32 v55, v0, v55
	v_add_f32_e32 v55, v55, v57
	v_frexp_mant_f32_e32 v57, v51
	v_cvt_f64_f32_e32 v[60:61], v51
	v_cmp_gt_f32_e32 vcc, s9, v57
	v_frexp_exp_i32_f64_e32 v57, v[60:61]
	v_or_b32_e32 v54, 48, v182
	v_subbrev_co_u32_e32 v90, vcc, 0, v57, vcc
	v_sub_u32_e32 v57, 0, v90
	v_ldexp_f32 v60, v51, v57
	v_mul_f32_e64 v51, |v53|, s8
	v_exp_f32_e32 v51, v51
	v_ldexp_f32 v68, v55, v57
	v_min_f32_e32 v57, 0, v53
	v_add_f32_e32 v53, 1.0, v51
	v_add_f32_e32 v55, -1.0, v53
	v_sub_f32_e32 v61, v55, v53
	v_add_f32_e32 v61, 1.0, v61
	v_sub_f32_e32 v55, v51, v55
	v_add_f32_e32 v55, v55, v61
	v_frexp_mant_f32_e32 v61, v53
	v_cvt_f64_f32_e32 v[74:75], v53
	v_cmp_gt_f32_e32 vcc, s9, v61
	v_frexp_exp_i32_f64_e32 v61, v[74:75]
	s_nop 0
	v_subbrev_co_u32_e32 v91, vcc, 0, v61, vcc
	v_sub_u32_e32 v69, 0, v91
	v_ldexp_f32 v61, v53, v69
	v_pk_add_f32 v[74:75], v[60:61], 1.0 op_sel_hi:[1,0]
	v_ldexp_f32 v69, v55, v69
	v_pk_add_f32 v[76:77], v[74:75], -1.0 op_sel_hi:[1,0]
	v_pk_add_f32 v[82:83], v[60:61], -1.0 op_sel_hi:[1,0]
	v_pk_add_f32 v[76:77], v[60:61], v[76:77] neg_lo:[0,1] neg_hi:[0,1]
	v_pk_add_f32 v[84:85], v[82:83], 1.0 op_sel_hi:[1,0]
	v_pk_add_f32 v[76:77], v[68:69], v[76:77]
	v_pk_add_f32 v[60:61], v[60:61], v[84:85] neg_lo:[0,1] neg_hi:[0,1]
	v_pk_add_f32 v[78:79], v[74:75], v[76:77]
	v_pk_add_f32 v[60:61], v[68:69], v[60:61]
	v_rcp_f32_e32 v80, v78
	v_rcp_f32_e32 v81, v79
	v_pk_add_f32 v[68:69], v[82:83], v[60:61]
	v_pk_add_f32 v[74:75], v[78:79], v[74:75] neg_lo:[0,1] neg_hi:[0,1]
	v_pk_add_f32 v[82:83], v[68:69], v[82:83] neg_lo:[0,1] neg_hi:[0,1]
	v_pk_add_f32 v[74:75], v[76:77], v[74:75] neg_lo:[0,1] neg_hi:[0,1]
	v_pk_mul_f32 v[76:77], v[68:69], v[80:81]
	v_pk_add_f32 v[60:61], v[60:61], v[82:83] neg_lo:[0,1] neg_hi:[0,1]
	v_pk_mul_f32 v[82:83], v[78:79], v[76:77]
	v_cmp_neq_f32_e32 vcc, s17, v0
	v_pk_fma_f32 v[84:85], v[76:77], v[78:79], v[82:83] neg_lo:[0,0,1] neg_hi:[0,0,1]
	s_nop 0
	v_pk_fma_f32 v[84:85], v[76:77], v[74:75], v[84:85]
	s_nop 0
	v_pk_add_f32 v[86:87], v[82:83], v[84:85]
	s_nop 0
	v_pk_add_f32 v[88:89], v[68:69], v[86:87] neg_lo:[0,1] neg_hi:[0,1]
	v_pk_add_f32 v[82:83], v[86:87], v[82:83] neg_lo:[0,1] neg_hi:[0,1]
	v_pk_add_f32 v[68:69], v[68:69], v[88:89] neg_lo:[0,1] neg_hi:[0,1]
	s_nop 0
	v_pk_add_f32 v[68:69], v[68:69], v[86:87] neg_lo:[0,1] neg_hi:[0,1]
	s_nop 0
	v_pk_add_f32 v[60:61], v[60:61], v[68:69]
	v_pk_add_f32 v[68:69], v[82:83], v[84:85] neg_lo:[0,1] neg_hi:[0,1]
	s_nop 0
	v_pk_add_f32 v[60:61], v[68:69], v[60:61]
	s_nop 0
	v_pk_add_f32 v[68:69], v[88:89], v[60:61]
	s_nop 0
	v_pk_mul_f32 v[82:83], v[80:81], v[68:69]
	s_nop 0
	v_pk_mul_f32 v[84:85], v[78:79], v[82:83]
	s_nop 0
	v_pk_fma_f32 v[78:79], v[82:83], v[78:79], v[84:85] neg_lo:[0,0,1] neg_hi:[0,0,1]
	s_nop 0
	v_pk_fma_f32 v[74:75], v[82:83], v[74:75], v[78:79]
	v_pk_add_f32 v[78:79], v[88:89], v[68:69] neg_lo:[0,1] neg_hi:[0,1]
	s_nop 0
	v_pk_add_f32 v[60:61], v[60:61], v[78:79]
	v_pk_add_f32 v[78:79], v[84:85], v[74:75]
	s_nop 0
	v_pk_add_f32 v[86:87], v[68:69], v[78:79] neg_lo:[0,1] neg_hi:[0,1]
	v_pk_add_f32 v[84:85], v[78:79], v[84:85] neg_lo:[0,1] neg_hi:[0,1]
	v_pk_add_f32 v[68:69], v[68:69], v[86:87] neg_lo:[0,1] neg_hi:[0,1]
	s_nop 0
	v_pk_add_f32 v[68:69], v[68:69], v[78:79] neg_lo:[0,1] neg_hi:[0,1]
	s_nop 0
	v_pk_add_f32 v[60:61], v[60:61], v[68:69]
	v_pk_add_f32 v[68:69], v[84:85], v[74:75] neg_lo:[0,1] neg_hi:[0,1]
	s_nop 0
	v_pk_add_f32 v[60:61], v[68:69], v[60:61]
	v_pk_add_f32 v[68:69], v[76:77], v[82:83]
	v_pk_add_f32 v[60:61], v[86:87], v[60:61]
	v_pk_add_f32 v[74:75], v[68:69], v[76:77] neg_lo:[0,1] neg_hi:[0,1]
	v_pk_mul_f32 v[60:61], v[80:81], v[60:61]
	v_pk_add_f32 v[74:75], v[82:83], v[74:75] neg_lo:[0,1] neg_hi:[0,1]
	s_nop 0
	v_pk_add_f32 v[60:61], v[74:75], v[60:61]
; __device__ __forceinline__ float log_sigmoid_f(float v) { return fminf(v, 0.f) - log1pf(__expf(-fabsf(v))); }
;     __device__ __forceinline__ void operator()(const f32x4 (&acc)[2][2][4][2], const pg8::Unit& u, int wr, int wc, int fr, int fq) const {
;     ...
;                 for (int nn = 0; nn < 2; ++nn) { const int head = 2 * fq + nn; const f32x4 gb = *(const f32x4*)(gate_b + 4 * head);
; #pragma unroll
;                     for (int ai = 0; ai < 2; ++ai)
; #pragma unroll
;                         for (int m = 0; m < 4; ++m) { const int row = row0 + ai * 128 + m * 16; f32x4 v = acc[ai][0][m][nn] + gb;
;                             v[1] = log_sigmoid_f(v[1]); v[3] = log_sigmoid_f(v[3]);
;                             *(f32x4*)(G + (size_t)row * 16 + 4 * head) = v; } }
	s_nop 0
	v_pk_add_f32 v[74:75], v[68:69], v[60:61]
	s_nop 0
	v_pk_mul_f32 v[76:77], v[74:75], v[74:75]
	v_pk_add_f32 v[68:69], v[74:75], v[68:69] neg_lo:[0,1] neg_hi:[0,1]
	v_pk_fma_f32 v[78:79], v[76:77], s[34:35], v[70:71] op_sel_hi:[1,0,0]
	v_pk_add_f32 v[60:61], v[60:61], v[68:69] neg_lo:[0,1] neg_hi:[0,1]
	v_ldexp_f32 v68, v74, 1
	v_pk_fma_f32 v[78:79], v[76:77], v[78:79], s[36:37] op_sel_hi:[1,1,0]
	v_ldexp_f32 v69, v75, 1
	v_pk_mul_f32 v[74:75], v[74:75], v[76:77]
	v_cvt_f32_i32_e32 v77, v91
	v_cvt_f32_i32_e32 v76, v90
	v_pk_mul_f32 v[74:75], v[74:75], v[78:79]
	v_ldexp_f32 v81, v61, 1
	v_pk_add_f32 v[78:79], v[68:69], v[74:75]
	v_pk_mul_f32 v[82:83], v[76:77], s[38:39] op_sel_hi:[1,0]
	v_pk_add_f32 v[68:69], v[78:79], v[68:69] neg_lo:[0,1] neg_hi:[0,1]
	v_pk_fma_f32 v[84:85], v[76:77], s[38:39], v[82:83] op_sel_hi:[1,0,1] neg_lo:[0,0,1] neg_hi:[0,0,1]
	v_pk_add_f32 v[68:69], v[74:75], v[68:69] neg_lo:[0,1] neg_hi:[0,1]
	v_pk_fma_f32 v[76:77], v[76:77], s[40:41], v[84:85] op_sel_hi:[1,0,1]
	v_ldexp_f32 v60, v60, 1
	v_mov_b32_e32 v74, v82
	v_mov_b32_e32 v75, v69
	v_mov_b32_e32 v80, v76
	v_mov_b32_e32 v61, v81
	v_pk_add_f32 v[74:75], v[74:75], v[80:81]
	v_pk_add_f32 v[80:81], v[60:61], v[68:69]
	v_mov_b32_e32 v69, v79
	v_mov_b32_e32 v61, v81
	v_pk_add_f32 v[84:85], v[82:83], v[76:77]
	v_pk_add_f32 v[60:61], v[60:61], v[68:69]
	v_pk_add_f32 v[68:69], v[78:79], v[80:81]
	v_mov_b32_e32 v94, v78
	v_pk_add_f32 v[86:87], v[84:85], v[68:69]
	v_mov_b32_e32 v92, v68
	v_mov_b32_e32 v93, v87
	v_mov_b32_e32 v95, v85
	v_pk_add_f32 v[92:93], v[92:93], v[94:95] neg_lo:[0,1] neg_hi:[0,1]
	v_mov_b32_e32 v88, v86
	v_mov_b32_e32 v89, v85
	v_mov_b32_e32 v90, v84
	v_mov_b32_e32 v91, v83
	v_mov_b32_e32 v94, v84
	v_mov_b32_e32 v95, v87
	v_mov_b32_e32 v83, v93
	v_pk_add_f32 v[88:89], v[88:89], v[90:91] neg_lo:[0,1] neg_hi:[0,1]
	v_mov_b32_e32 v90, v68
	v_mov_b32_e32 v91, v77
	v_pk_add_f32 v[82:83], v[94:95], v[82:83] neg_lo:[0,1] neg_hi:[0,1]
	v_pk_add_f32 v[90:91], v[90:91], v[88:89] neg_lo:[0,1] neg_hi:[0,1]
	v_mov_b32_e32 v94, v82
	v_mov_b32_e32 v95, v89
	v_mov_b32_e32 v96, v86
	v_mov_b32_e32 v97, v69
	v_mov_b32_e32 v89, v79
	v_pk_add_f32 v[94:95], v[76:77], v[94:95] neg_lo:[0,1] neg_hi:[0,1]
	v_pk_add_f32 v[88:89], v[96:97], v[88:89] neg_lo:[0,1] neg_hi:[0,1]
	v_mov_b32_e32 v77, v85
	v_pk_add_f32 v[74:75], v[74:75], v[88:89] neg_lo:[0,1] neg_hi:[0,1]
	v_pk_add_f32 v[76:77], v[76:77], v[82:83] neg_lo:[0,1] neg_hi:[0,1]
	v_pk_add_f32 v[60:61], v[60:61], v[92:93] neg_lo:[0,1] neg_hi:[0,1]
	v_pk_add_f32 v[68:69], v[68:69], v[78:79] neg_lo:[0,1] neg_hi:[0,1]
	v_pk_add_f32 v[78:79], v[60:61], v[76:77]
	v_mov_b32_e32 v77, v91
	v_mov_b32_e32 v61, v75
	v_pk_add_f32 v[68:69], v[80:81], v[68:69] neg_lo:[0,1] neg_hi:[0,1]
	v_pk_add_f32 v[80:81], v[90:91], v[74:75]
	v_pk_add_f32 v[60:61], v[76:77], v[60:61]
	v_mov_b32_e32 v74, v78
	v_pk_add_f32 v[60:61], v[60:61], v[94:95] neg_lo:[0,1] neg_hi:[0,1]
	v_mov_b32_e32 v75, v81
	v_pk_add_f32 v[74:75], v[74:75], v[60:61] neg_lo:[0,1] neg_hi:[0,1]
	v_pk_add_f32 v[60:61], v[68:69], v[60:61] neg_lo:[0,1] neg_hi:[0,1]
	v_pk_add_f32 v[74:75], v[76:77], v[74:75] neg_lo:[0,1] neg_hi:[0,1]
	v_pk_add_f32 v[68:69], v[80:81], v[78:79]
	v_pk_add_f32 v[60:61], v[60:61], v[74:75]
	v_pk_add_f32 v[74:75], v[86:87], v[68:69]
	s_nop 0
	v_pk_add_f32 v[76:77], v[74:75], v[86:87] neg_lo:[0,1] neg_hi:[0,1]
	s_nop 0
	v_pk_add_f32 v[68:69], v[68:69], v[76:77] neg_lo:[0,1] neg_hi:[0,1]
	s_nop 0
	v_pk_add_f32 v[60:61], v[60:61], v[68:69]
	s_nop 0
	v_pk_add_f32 v[60:61], v[74:75], v[60:61]
	s_nop 0
	v_cndmask_b32_e32 v53, v199, v60, vcc
	v_cmp_neq_f32_e32 vcc, s17, v51
	s_nop 1
	v_cndmask_b32_e32 v55, v199, v61, vcc
	v_cmp_ngt_f32_e32 vcc, -1.0, v51
	s_nop 1
	v_cndmask_b32_e32 v55, v200, v55, vcc
	v_cmp_ngt_f32_e32 vcc, -1.0, v0
	s_nop 1
	v_cndmask_b32_e32 v53, v200, v53, vcc
	v_cmp_neq_f32_e32 vcc, -1.0, v0
	s_nop 1
	v_cndmask_b32_e32 v53, v201, v53, vcc
	v_cmp_neq_f32_e32 vcc, -1.0, v51
	v_cndmask_b32_e64 v60, v53, v0, s[0:1]
	v_mul_f32_e64 v0, |v47|, s8
	v_cndmask_b32_e32 v55, v201, v55, vcc
	v_cmp_lt_f32_e64 vcc, |v51|, s19
	v_exp_f32_e32 v0, v0
	s_nop 0
	v_cndmask_b32_e32 v61, v55, v51, vcc
	v_ashrrev_i32_e32 v55, 31, v54
	v_pk_add_f32 v[56:57], v[56:57], v[60:61] neg_lo:[0,1] neg_hi:[0,1]
	v_lshlrev_b64 v[54:55], 6, v[54:55]
	v_lshl_add_u64 v[54:55], v[176:177], 0, v[54:55]
	v_mov_b32_e32 v51, v56
	v_mov_b32_e32 v53, v57
	global_store_dwordx4 v[54:55], v[50:53], off
	v_cmp_lt_f32_e64 s[0:1], |v0|, s19
	s_nop 0
	v_min_f32_e32 v50, 0, v47
	v_add_f32_e32 v47, 1.0, v0
	v_add_f32_e32 v51, -1.0, v47
	v_sub_f32_e32 v52, v51, v47
	v_add_f32_e32 v52, 1.0, v52
	v_sub_f32_e32 v51, v0, v51
	v_add_f32_e32 v51, v51, v52
	v_frexp_mant_f32_e32 v52, v47
	v_cmp_gt_f32_e32 vcc, s9, v52
	v_cvt_f64_f32_e32 v[52:53], v47
	v_frexp_exp_i32_f64_e32 v52, v[52:53]
	v_subbrev_co_u32_e32 v86, vcc, 0, v52, vcc
	v_sub_u32_e32 v53, 0, v86
	v_ldexp_f32 v52, v47, v53
	v_mul_f32_e64 v47, |v49|, s8
	v_exp_f32_e32 v47, v47
	v_ldexp_f32 v56, v51, v53
	v_min_f32_e32 v51, 0, v49
	v_add_f32_e32 v49, 1.0, v47
	v_add_f32_e32 v53, -1.0, v49
	v_sub_f32_e32 v57, v53, v49
	v_add_f32_e32 v57, 1.0, v57
	v_sub_f32_e32 v53, v47, v53
	v_add_f32_e32 v57, v53, v57
	v_frexp_mant_f32_e32 v53, v49
	v_cvt_f64_f32_e32 v[60:61], v49
	v_cmp_gt_f32_e32 vcc, s9, v53
	v_frexp_exp_i32_f64_e32 v53, v[60:61]
	s_nop 0
	v_subbrev_co_u32_e32 v87, vcc, 0, v53, vcc
	v_sub_u32_e32 v60, 0, v87
	v_ldexp_f32 v53, v49, v60
	v_ldexp_f32 v57, v57, v60
	v_pk_add_f32 v[60:61], v[52:53], 1.0 op_sel_hi:[1,0]
	v_pk_add_f32 v[78:79], v[52:53], -1.0 op_sel_hi:[1,0]
	v_pk_add_f32 v[68:69], v[60:61], -1.0 op_sel_hi:[1,0]
; __device__ __forceinline__ float log_sigmoid_f(float v) { return fminf(v, 0.f) - log1pf(__expf(-fabsf(v))); }
;     __device__ __forceinline__ void operator()(const f32x4 (&acc)[2][2][4][2], const pg8::Unit& u, int wr, int wc, int fr, int fq) const {
;     ...
;                 for (int nn = 0; nn < 2; ++nn) { const int head = 2 * fq + nn; const f32x4 gb = *(const f32x4*)(gate_b + 4 * head);
; #pragma unroll
;                     for (int ai = 0; ai < 2; ++ai)
; #pragma unroll
;                         for (int m = 0; m < 4; ++m) { const int row = row0 + ai * 128 + m * 16; f32x4 v = acc[ai][0][m][nn] + gb;
;                             v[1] = log_sigmoid_f(v[1]); v[3] = log_sigmoid_f(v[3]);
;                             *(f32x4*)(G + (size_t)row * 16 + 4 * head) = v; } }
	v_pk_add_f32 v[80:81], v[78:79], 1.0 op_sel_hi:[1,0]
	v_pk_add_f32 v[68:69], v[52:53], v[68:69] neg_lo:[0,1] neg_hi:[0,1]
	v_pk_add_f32 v[52:53], v[52:53], v[80:81] neg_lo:[0,1] neg_hi:[0,1]
	v_pk_add_f32 v[68:69], v[56:57], v[68:69]
	v_pk_add_f32 v[52:53], v[56:57], v[52:53]
	v_pk_add_f32 v[74:75], v[60:61], v[68:69]
	v_pk_add_f32 v[56:57], v[78:79], v[52:53]
	v_rcp_f32_e32 v76, v74
	v_rcp_f32_e32 v77, v75
	v_pk_add_f32 v[60:61], v[74:75], v[60:61] neg_lo:[0,1] neg_hi:[0,1]
	v_pk_add_f32 v[78:79], v[56:57], v[78:79] neg_lo:[0,1] neg_hi:[0,1]
	v_pk_add_f32 v[60:61], v[68:69], v[60:61] neg_lo:[0,1] neg_hi:[0,1]
	v_pk_mul_f32 v[68:69], v[56:57], v[76:77]
	v_pk_add_f32 v[52:53], v[52:53], v[78:79] neg_lo:[0,1] neg_hi:[0,1]
	v_pk_mul_f32 v[78:79], v[74:75], v[68:69]
	v_cmp_neq_f32_e32 vcc, s17, v0
	v_pk_fma_f32 v[80:81], v[68:69], v[74:75], v[78:79] neg_lo:[0,0,1] neg_hi:[0,0,1]
	s_nop 0
	v_pk_fma_f32 v[80:81], v[68:69], v[60:61], v[80:81]
	s_nop 0
	v_pk_add_f32 v[82:83], v[78:79], v[80:81]
	s_nop 0
	v_pk_add_f32 v[84:85], v[56:57], v[82:83] neg_lo:[0,1] neg_hi:[0,1]
	v_pk_add_f32 v[78:79], v[82:83], v[78:79] neg_lo:[0,1] neg_hi:[0,1]
	v_pk_add_f32 v[56:57], v[56:57], v[84:85] neg_lo:[0,1] neg_hi:[0,1]
	s_nop 0
	v_pk_add_f32 v[56:57], v[56:57], v[82:83] neg_lo:[0,1] neg_hi:[0,1]
	s_nop 0
	v_pk_add_f32 v[52:53], v[52:53], v[56:57]
	v_pk_add_f32 v[56:57], v[78:79], v[80:81] neg_lo:[0,1] neg_hi:[0,1]
	s_nop 0
	v_pk_add_f32 v[52:53], v[56:57], v[52:53]
	s_nop 0
	v_pk_add_f32 v[56:57], v[84:85], v[52:53]
	s_nop 0
	v_pk_mul_f32 v[78:79], v[76:77], v[56:57]
	s_nop 0
	v_pk_mul_f32 v[80:81], v[74:75], v[78:79]
	s_nop 0
	v_pk_fma_f32 v[74:75], v[78:79], v[74:75], v[80:81] neg_lo:[0,0,1] neg_hi:[0,0,1]
	s_nop 0
	v_pk_fma_f32 v[60:61], v[78:79], v[60:61], v[74:75]
	v_pk_add_f32 v[74:75], v[84:85], v[56:57] neg_lo:[0,1] neg_hi:[0,1]
	s_nop 0
	v_pk_add_f32 v[52:53], v[52:53], v[74:75]
	v_pk_add_f32 v[74:75], v[80:81], v[60:61]
	s_nop 0
	v_pk_add_f32 v[82:83], v[56:57], v[74:75] neg_lo:[0,1] neg_hi:[0,1]
	v_pk_add_f32 v[80:81], v[74:75], v[80:81] neg_lo:[0,1] neg_hi:[0,1]
	v_pk_add_f32 v[56:57], v[56:57], v[82:83] neg_lo:[0,1] neg_hi:[0,1]
	s_nop 0
	v_pk_add_f32 v[56:57], v[56:57], v[74:75] neg_lo:[0,1] neg_hi:[0,1]
	s_nop 0
	v_pk_add_f32 v[52:53], v[52:53], v[56:57]
	v_pk_add_f32 v[56:57], v[80:81], v[60:61] neg_lo:[0,1] neg_hi:[0,1]
	s_nop 0
	v_pk_add_f32 v[52:53], v[56:57], v[52:53]
	v_pk_add_f32 v[56:57], v[68:69], v[78:79]
	v_pk_add_f32 v[52:53], v[82:83], v[52:53]
	v_pk_add_f32 v[60:61], v[56:57], v[68:69] neg_lo:[0,1] neg_hi:[0,1]
	v_pk_mul_f32 v[52:53], v[76:77], v[52:53]
	v_pk_add_f32 v[60:61], v[78:79], v[60:61] neg_lo:[0,1] neg_hi:[0,1]
	s_nop 0
	v_pk_add_f32 v[52:53], v[60:61], v[52:53]
	s_nop 0
	v_pk_add_f32 v[60:61], v[56:57], v[52:53]
	s_nop 0
	v_pk_mul_f32 v[68:69], v[60:61], v[60:61]
	v_pk_add_f32 v[56:57], v[60:61], v[56:57] neg_lo:[0,1] neg_hi:[0,1]
	v_pk_fma_f32 v[74:75], v[68:69], s[34:35], v[70:71] op_sel_hi:[1,0,0]
	v_pk_add_f32 v[52:53], v[52:53], v[56:57] neg_lo:[0,1] neg_hi:[0,1]
	v_ldexp_f32 v56, v60, 1
	v_pk_fma_f32 v[74:75], v[68:69], v[74:75], s[36:37] op_sel_hi:[1,1,0]
	v_ldexp_f32 v57, v61, 1
	v_pk_mul_f32 v[60:61], v[60:61], v[68:69]
	v_cvt_f32_i32_e32 v69, v87
	v_cvt_f32_i32_e32 v68, v86
	v_pk_mul_f32 v[60:61], v[60:61], v[74:75]
	v_ldexp_f32 v77, v53, 1
	v_pk_add_f32 v[74:75], v[56:57], v[60:61]
	v_pk_mul_f32 v[78:79], v[68:69], s[38:39] op_sel_hi:[1,0]
	v_pk_add_f32 v[56:57], v[74:75], v[56:57] neg_lo:[0,1] neg_hi:[0,1]
	v_pk_fma_f32 v[80:81], v[68:69], s[38:39], v[78:79] op_sel_hi:[1,0,1] neg_lo:[0,0,1] neg_hi:[0,0,1]
	v_pk_add_f32 v[56:57], v[60:61], v[56:57] neg_lo:[0,1] neg_hi:[0,1]
	v_pk_fma_f32 v[68:69], v[68:69], s[40:41], v[80:81] op_sel_hi:[1,0,1]
	v_ldexp_f32 v52, v52, 1
	v_mov_b32_e32 v60, v78
	v_mov_b32_e32 v61, v57
	v_mov_b32_e32 v76, v68
	v_mov_b32_e32 v53, v77
	v_pk_add_f32 v[60:61], v[60:61], v[76:77]
	v_pk_add_f32 v[76:77], v[52:53], v[56:57]
	v_mov_b32_e32 v57, v75
	v_mov_b32_e32 v53, v77
	v_pk_add_f32 v[80:81], v[78:79], v[68:69]
	v_pk_add_f32 v[52:53], v[52:53], v[56:57]
	v_pk_add_f32 v[56:57], v[74:75], v[76:77]
	v_mov_b32_e32 v90, v74
	v_pk_add_f32 v[82:83], v[80:81], v[56:57]
	v_mov_b32_e32 v88, v56
	v_mov_b32_e32 v89, v83
	v_mov_b32_e32 v91, v81
	v_pk_add_f32 v[88:89], v[88:89], v[90:91] neg_lo:[0,1] neg_hi:[0,1]
	v_mov_b32_e32 v84, v82
	v_mov_b32_e32 v85, v81
	v_mov_b32_e32 v86, v80
	v_mov_b32_e32 v87, v79
	v_mov_b32_e32 v90, v80
	v_mov_b32_e32 v91, v83
	v_mov_b32_e32 v79, v89
	v_pk_add_f32 v[84:85], v[84:85], v[86:87] neg_lo:[0,1] neg_hi:[0,1]
	v_mov_b32_e32 v86, v56
	v_mov_b32_e32 v87, v69
	v_pk_add_f32 v[78:79], v[90:91], v[78:79] neg_lo:[0,1] neg_hi:[0,1]
	v_pk_add_f32 v[86:87], v[86:87], v[84:85] neg_lo:[0,1] neg_hi:[0,1]
	v_mov_b32_e32 v90, v78
	v_mov_b32_e32 v91, v85
	v_mov_b32_e32 v92, v82
	v_mov_b32_e32 v93, v57
	v_mov_b32_e32 v85, v75
	v_pk_add_f32 v[90:91], v[68:69], v[90:91] neg_lo:[0,1] neg_hi:[0,1]
	v_pk_add_f32 v[84:85], v[92:93], v[84:85] neg_lo:[0,1] neg_hi:[0,1]
	v_mov_b32_e32 v69, v81
	v_pk_add_f32 v[60:61], v[60:61], v[84:85] neg_lo:[0,1] neg_hi:[0,1]
	v_pk_add_f32 v[68:69], v[68:69], v[78:79] neg_lo:[0,1] neg_hi:[0,1]
	v_pk_add_f32 v[52:53], v[52:53], v[88:89] neg_lo:[0,1] neg_hi:[0,1]
	v_pk_add_f32 v[56:57], v[56:57], v[74:75] neg_lo:[0,1] neg_hi:[0,1]
	v_pk_add_f32 v[74:75], v[52:53], v[68:69]
	v_mov_b32_e32 v69, v87
	v_mov_b32_e32 v53, v61
	v_pk_add_f32 v[56:57], v[76:77], v[56:57] neg_lo:[0,1] neg_hi:[0,1]
	v_pk_add_f32 v[76:77], v[86:87], v[60:61]
	v_pk_add_f32 v[52:53], v[68:69], v[52:53]
	v_mov_b32_e32 v60, v74
	v_pk_add_f32 v[52:53], v[52:53], v[90:91] neg_lo:[0,1] neg_hi:[0,1]
; __device__ __forceinline__ float log_sigmoid_f(float v) { return fminf(v, 0.f) - log1pf(__expf(-fabsf(v))); }
;     __device__ __forceinline__ void operator()(const f32x4 (&acc)[2][2][4][2], const pg8::Unit& u, int wr, int wc, int fr, int fq) const {
;     ...
;                 for (int nn = 0; nn < 2; ++nn) { const int head = 2 * fq + nn; const f32x4 gb = *(const f32x4*)(gate_b + 4 * head);
; #pragma unroll
;                     for (int ai = 0; ai < 2; ++ai)
; #pragma unroll
;                         for (int m = 0; m < 4; ++m) { const int row = row0 + ai * 128 + m * 16; f32x4 v = acc[ai][0][m][nn] + gb;
;                             v[1] = log_sigmoid_f(v[1]); v[3] = log_sigmoid_f(v[3]);
;                             *(f32x4*)(G + (size_t)row * 16 + 4 * head) = v; } }
	v_mov_b32_e32 v61, v77
	v_pk_add_f32 v[60:61], v[60:61], v[52:53] neg_lo:[0,1] neg_hi:[0,1]
	v_pk_add_f32 v[52:53], v[56:57], v[52:53] neg_lo:[0,1] neg_hi:[0,1]
	v_pk_add_f32 v[60:61], v[68:69], v[60:61] neg_lo:[0,1] neg_hi:[0,1]
	v_pk_add_f32 v[56:57], v[76:77], v[74:75]
	v_pk_add_f32 v[52:53], v[52:53], v[60:61]
	v_pk_add_f32 v[60:61], v[82:83], v[56:57]
	s_nop 0
	v_pk_add_f32 v[68:69], v[60:61], v[82:83] neg_lo:[0,1] neg_hi:[0,1]
	s_nop 0
	v_pk_add_f32 v[56:57], v[56:57], v[68:69] neg_lo:[0,1] neg_hi:[0,1]
	s_nop 0
	v_pk_add_f32 v[52:53], v[52:53], v[56:57]
	s_nop 0
	v_pk_add_f32 v[52:53], v[60:61], v[52:53]
	s_nop 0
	v_cndmask_b32_e32 v49, v199, v52, vcc
	v_cmp_neq_f32_e32 vcc, s17, v47
	s_nop 1
	v_cndmask_b32_e32 v52, v199, v53, vcc
	v_cmp_ngt_f32_e32 vcc, -1.0, v47
	s_nop 1
	v_cndmask_b32_e32 v52, v200, v52, vcc
	v_cmp_ngt_f32_e32 vcc, -1.0, v0
	s_nop 1
	v_cndmask_b32_e32 v49, v200, v49, vcc
	v_cmp_neq_f32_e32 vcc, -1.0, v0
	s_nop 1
	v_cndmask_b32_e32 v49, v201, v49, vcc
	v_cmp_neq_f32_e32 vcc, -1.0, v47
	s_nop 1
	v_cndmask_b32_e32 v52, v201, v52, vcc
	v_cmp_lt_f32_e64 vcc, |v47|, s19
	s_nop 1
	v_cndmask_b32_e32 v53, v52, v47, vcc
	v_cndmask_b32_e64 v52, v49, v0, s[0:1]
	v_mul_f32_e64 v0, |v43|, s8
	s_mov_b64 s[0:1], 0x2000
	v_exp_f32_e32 v0, v0
	v_pk_add_f32 v[52:53], v[50:51], v[52:53] neg_lo:[0,1] neg_hi:[0,1]
	v_lshl_add_u64 v[50:51], v[72:73], 0, s[0:1]
	s_movk_i32 s0, 0x2000
	v_mov_b32_e32 v47, v52
	v_add_co_u32_e32 v52, vcc, s0, v72
	v_mov_b32_e32 v49, v53
	s_nop 0
	v_addc_co_u32_e32 v53, vcc, 0, v73, vcc
	global_store_dwordx4 v[52:53], v[46:49], off
	v_cmp_lt_f32_e64 s[0:1], |v0|, s19
	s_nop 0
	v_min_f32_e32 v46, 0, v43
	v_add_f32_e32 v43, 1.0, v0
	v_add_f32_e32 v47, -1.0, v43
	v_sub_f32_e32 v48, v47, v43
	v_add_f32_e32 v48, 1.0, v48
	v_sub_f32_e32 v47, v0, v47
	v_add_f32_e32 v47, v47, v48
	v_frexp_mant_f32_e32 v48, v43
	v_cmp_gt_f32_e32 vcc, s9, v48
	v_cvt_f64_f32_e32 v[48:49], v43
	v_frexp_exp_i32_f64_e32 v48, v[48:49]
	v_subbrev_co_u32_e32 v86, vcc, 0, v48, vcc
	v_sub_u32_e32 v49, 0, v86
	v_ldexp_f32 v48, v43, v49
	v_mul_f32_e64 v43, |v45|, s8
	v_exp_f32_e32 v43, v43
	v_ldexp_f32 v56, v47, v49
	v_min_f32_e32 v47, 0, v45
	v_add_f32_e32 v45, 1.0, v43
	v_add_f32_e32 v49, -1.0, v45
	v_sub_f32_e32 v57, v49, v45
	v_add_f32_e32 v57, 1.0, v57
	v_sub_f32_e32 v49, v43, v49
	v_add_f32_e32 v57, v49, v57
	v_frexp_mant_f32_e32 v49, v45
	v_cvt_f64_f32_e32 v[60:61], v45
	v_cmp_gt_f32_e32 vcc, s9, v49
	v_frexp_exp_i32_f64_e32 v49, v[60:61]
	s_nop 0
	v_subbrev_co_u32_e32 v87, vcc, 0, v49, vcc
	v_sub_u32_e32 v60, 0, v87
	v_ldexp_f32 v49, v45, v60
	v_ldexp_f32 v57, v57, v60
	v_pk_add_f32 v[60:61], v[48:49], 1.0 op_sel_hi:[1,0]
	v_pk_add_f32 v[78:79], v[48:49], -1.0 op_sel_hi:[1,0]
	v_pk_add_f32 v[68:69], v[60:61], -1.0 op_sel_hi:[1,0]
	v_pk_add_f32 v[80:81], v[78:79], 1.0 op_sel_hi:[1,0]
	v_pk_add_f32 v[68:69], v[48:49], v[68:69] neg_lo:[0,1] neg_hi:[0,1]
	v_pk_add_f32 v[48:49], v[48:49], v[80:81] neg_lo:[0,1] neg_hi:[0,1]
	v_pk_add_f32 v[68:69], v[56:57], v[68:69]
	v_pk_add_f32 v[48:49], v[56:57], v[48:49]
	v_pk_add_f32 v[74:75], v[60:61], v[68:69]
	v_pk_add_f32 v[56:57], v[78:79], v[48:49]
	v_rcp_f32_e32 v76, v74
	v_rcp_f32_e32 v77, v75
	v_pk_add_f32 v[60:61], v[74:75], v[60:61] neg_lo:[0,1] neg_hi:[0,1]
	v_pk_add_f32 v[78:79], v[56:57], v[78:79] neg_lo:[0,1] neg_hi:[0,1]
	v_pk_add_f32 v[60:61], v[68:69], v[60:61] neg_lo:[0,1] neg_hi:[0,1]
	v_pk_mul_f32 v[68:69], v[56:57], v[76:77]
	v_pk_add_f32 v[48:49], v[48:49], v[78:79] neg_lo:[0,1] neg_hi:[0,1]
	v_pk_mul_f32 v[78:79], v[74:75], v[68:69]
	v_cmp_neq_f32_e32 vcc, s17, v0
	v_pk_fma_f32 v[80:81], v[68:69], v[74:75], v[78:79] neg_lo:[0,0,1] neg_hi:[0,0,1]
	s_nop 0
	v_pk_fma_f32 v[80:81], v[68:69], v[60:61], v[80:81]
	s_nop 0
	v_pk_add_f32 v[82:83], v[78:79], v[80:81]
	s_nop 0
	v_pk_add_f32 v[84:85], v[56:57], v[82:83] neg_lo:[0,1] neg_hi:[0,1]
	v_pk_add_f32 v[78:79], v[82:83], v[78:79] neg_lo:[0,1] neg_hi:[0,1]
	v_pk_add_f32 v[56:57], v[56:57], v[84:85] neg_lo:[0,1] neg_hi:[0,1]
	s_nop 0
	v_pk_add_f32 v[56:57], v[56:57], v[82:83] neg_lo:[0,1] neg_hi:[0,1]
	s_nop 0
	v_pk_add_f32 v[48:49], v[48:49], v[56:57]
	v_pk_add_f32 v[56:57], v[78:79], v[80:81] neg_lo:[0,1] neg_hi:[0,1]
	s_nop 0
	v_pk_add_f32 v[48:49], v[56:57], v[48:49]
	s_nop 0
	v_pk_add_f32 v[56:57], v[84:85], v[48:49]
	s_nop 0
	v_pk_mul_f32 v[78:79], v[76:77], v[56:57]
	s_nop 0
	v_pk_mul_f32 v[80:81], v[74:75], v[78:79]
	s_nop 0
	v_pk_fma_f32 v[74:75], v[78:79], v[74:75], v[80:81] neg_lo:[0,0,1] neg_hi:[0,0,1]
	s_nop 0
	v_pk_fma_f32 v[60:61], v[78:79], v[60:61], v[74:75]
	v_pk_add_f32 v[74:75], v[84:85], v[56:57] neg_lo:[0,1] neg_hi:[0,1]
	s_nop 0
	v_pk_add_f32 v[48:49], v[48:49], v[74:75]
	v_pk_add_f32 v[74:75], v[80:81], v[60:61]
	s_nop 0
	v_pk_add_f32 v[82:83], v[56:57], v[74:75] neg_lo:[0,1] neg_hi:[0,1]
	v_pk_add_f32 v[80:81], v[74:75], v[80:81] neg_lo:[0,1] neg_hi:[0,1]
	v_pk_add_f32 v[56:57], v[56:57], v[82:83] neg_lo:[0,1] neg_hi:[0,1]
	s_nop 0
	v_pk_add_f32 v[56:57], v[56:57], v[74:75] neg_lo:[0,1] neg_hi:[0,1]
	s_nop 0
	v_pk_add_f32 v[48:49], v[48:49], v[56:57]
	v_pk_add_f32 v[56:57], v[80:81], v[60:61] neg_lo:[0,1] neg_hi:[0,1]
	s_nop 0
	v_pk_add_f32 v[48:49], v[56:57], v[48:49]
	v_pk_add_f32 v[56:57], v[68:69], v[78:79]
	v_pk_add_f32 v[48:49], v[82:83], v[48:49]
	v_pk_add_f32 v[60:61], v[56:57], v[68:69] neg_lo:[0,1] neg_hi:[0,1]
	v_pk_mul_f32 v[48:49], v[76:77], v[48:49]
	v_pk_add_f32 v[60:61], v[78:79], v[60:61] neg_lo:[0,1] neg_hi:[0,1]
	s_nop 0
	v_pk_add_f32 v[48:49], v[60:61], v[48:49]
	s_nop 0
	v_pk_add_f32 v[60:61], v[56:57], v[48:49]
	s_nop 0
	v_pk_mul_f32 v[68:69], v[60:61], v[60:61]
; __device__ __forceinline__ float log_sigmoid_f(float v) { return fminf(v, 0.f) - log1pf(__expf(-fabsf(v))); }
;     __device__ __forceinline__ void operator()(const f32x4 (&acc)[2][2][4][2], const pg8::Unit& u, int wr, int wc, int fr, int fq) const {
;     ...
;                 for (int nn = 0; nn < 2; ++nn) { const int head = 2 * fq + nn; const f32x4 gb = *(const f32x4*)(gate_b + 4 * head);
; #pragma unroll
;                     for (int ai = 0; ai < 2; ++ai)
; #pragma unroll
;                         for (int m = 0; m < 4; ++m) { const int row = row0 + ai * 128 + m * 16; f32x4 v = acc[ai][0][m][nn] + gb;
;                             v[1] = log_sigmoid_f(v[1]); v[3] = log_sigmoid_f(v[3]);
;                             *(f32x4*)(G + (size_t)row * 16 + 4 * head) = v; } }
	v_pk_add_f32 v[56:57], v[60:61], v[56:57] neg_lo:[0,1] neg_hi:[0,1]
	v_pk_fma_f32 v[74:75], v[68:69], s[34:35], v[70:71] op_sel_hi:[1,0,0]
	v_pk_add_f32 v[48:49], v[48:49], v[56:57] neg_lo:[0,1] neg_hi:[0,1]
	v_ldexp_f32 v56, v60, 1
	v_pk_fma_f32 v[74:75], v[68:69], v[74:75], s[36:37] op_sel_hi:[1,1,0]
	v_ldexp_f32 v57, v61, 1
	v_pk_mul_f32 v[60:61], v[60:61], v[68:69]
	v_cvt_f32_i32_e32 v69, v87
	v_cvt_f32_i32_e32 v68, v86
	v_pk_mul_f32 v[60:61], v[60:61], v[74:75]
	v_ldexp_f32 v77, v49, 1
	v_pk_add_f32 v[74:75], v[56:57], v[60:61]
	v_pk_mul_f32 v[78:79], v[68:69], s[38:39] op_sel_hi:[1,0]
	v_pk_add_f32 v[56:57], v[74:75], v[56:57] neg_lo:[0,1] neg_hi:[0,1]
	v_pk_fma_f32 v[80:81], v[68:69], s[38:39], v[78:79] op_sel_hi:[1,0,1] neg_lo:[0,0,1] neg_hi:[0,0,1]
	v_pk_add_f32 v[56:57], v[60:61], v[56:57] neg_lo:[0,1] neg_hi:[0,1]
	v_pk_fma_f32 v[68:69], v[68:69], s[40:41], v[80:81] op_sel_hi:[1,0,1]
	v_ldexp_f32 v48, v48, 1
	v_mov_b32_e32 v60, v78
	v_mov_b32_e32 v61, v57
	v_mov_b32_e32 v76, v68
	v_mov_b32_e32 v49, v77
	v_pk_add_f32 v[60:61], v[60:61], v[76:77]
	v_pk_add_f32 v[76:77], v[48:49], v[56:57]
	v_mov_b32_e32 v57, v75
	v_mov_b32_e32 v49, v77
	v_pk_add_f32 v[80:81], v[78:79], v[68:69]
	v_pk_add_f32 v[48:49], v[48:49], v[56:57]
	v_pk_add_f32 v[56:57], v[74:75], v[76:77]
	v_mov_b32_e32 v90, v74
	v_pk_add_f32 v[82:83], v[80:81], v[56:57]
	v_mov_b32_e32 v88, v56
	v_mov_b32_e32 v89, v83
	v_mov_b32_e32 v91, v81
	v_pk_add_f32 v[88:89], v[88:89], v[90:91] neg_lo:[0,1] neg_hi:[0,1]
	v_mov_b32_e32 v84, v82
	v_mov_b32_e32 v85, v81
	v_mov_b32_e32 v86, v80
	v_mov_b32_e32 v87, v79
	v_mov_b32_e32 v90, v80
	v_mov_b32_e32 v91, v83
	v_mov_b32_e32 v79, v89
	v_pk_add_f32 v[84:85], v[84:85], v[86:87] neg_lo:[0,1] neg_hi:[0,1]
	v_mov_b32_e32 v86, v56
	v_mov_b32_e32 v87, v69
	v_pk_add_f32 v[78:79], v[90:91], v[78:79] neg_lo:[0,1] neg_hi:[0,1]
	v_pk_add_f32 v[86:87], v[86:87], v[84:85] neg_lo:[0,1] neg_hi:[0,1]
	v_mov_b32_e32 v90, v78
	v_mov_b32_e32 v91, v85
	v_mov_b32_e32 v92, v82
	v_mov_b32_e32 v93, v57
	v_mov_b32_e32 v85, v75
	v_pk_add_f32 v[90:91], v[68:69], v[90:91] neg_lo:[0,1] neg_hi:[0,1]
	v_pk_add_f32 v[84:85], v[92:93], v[84:85] neg_lo:[0,1] neg_hi:[0,1]
	v_mov_b32_e32 v69, v81
	v_pk_add_f32 v[60:61], v[60:61], v[84:85] neg_lo:[0,1] neg_hi:[0,1]
	v_pk_add_f32 v[68:69], v[68:69], v[78:79] neg_lo:[0,1] neg_hi:[0,1]
	v_pk_add_f32 v[48:49], v[48:49], v[88:89] neg_lo:[0,1] neg_hi:[0,1]
	v_pk_add_f32 v[56:57], v[56:57], v[74:75] neg_lo:[0,1] neg_hi:[0,1]
	v_pk_add_f32 v[74:75], v[48:49], v[68:69]
	v_mov_b32_e32 v69, v87
	v_mov_b32_e32 v49, v61
	v_pk_add_f32 v[56:57], v[76:77], v[56:57] neg_lo:[0,1] neg_hi:[0,1]
	v_pk_add_f32 v[76:77], v[86:87], v[60:61]
	v_pk_add_f32 v[48:49], v[68:69], v[48:49]
	v_mov_b32_e32 v60, v74
	v_pk_add_f32 v[48:49], v[48:49], v[90:91] neg_lo:[0,1] neg_hi:[0,1]
	v_mov_b32_e32 v61, v77
	v_pk_add_f32 v[60:61], v[60:61], v[48:49] neg_lo:[0,1] neg_hi:[0,1]
	v_pk_add_f32 v[48:49], v[56:57], v[48:49] neg_lo:[0,1] neg_hi:[0,1]
	v_pk_add_f32 v[60:61], v[68:69], v[60:61] neg_lo:[0,1] neg_hi:[0,1]
	v_pk_add_f32 v[56:57], v[76:77], v[74:75]
	v_pk_add_f32 v[48:49], v[48:49], v[60:61]
	v_pk_add_f32 v[60:61], v[82:83], v[56:57]
	s_nop 0
	v_pk_add_f32 v[68:69], v[60:61], v[82:83] neg_lo:[0,1] neg_hi:[0,1]
	s_nop 0
	v_pk_add_f32 v[56:57], v[56:57], v[68:69] neg_lo:[0,1] neg_hi:[0,1]
	s_nop 0
	v_pk_add_f32 v[48:49], v[48:49], v[56:57]
	s_nop 0
	v_pk_add_f32 v[48:49], v[60:61], v[48:49]
	s_nop 0
	v_cndmask_b32_e32 v45, v199, v48, vcc
	v_cmp_neq_f32_e32 vcc, s17, v43
	s_nop 1
	v_cndmask_b32_e32 v48, v199, v49, vcc
	v_cmp_ngt_f32_e32 vcc, -1.0, v43
	s_nop 1
	v_cndmask_b32_e32 v48, v200, v48, vcc
	v_cmp_ngt_f32_e32 vcc, -1.0, v0
	s_nop 1
	v_cndmask_b32_e32 v45, v200, v45, vcc
	v_cmp_neq_f32_e32 vcc, -1.0, v0
	s_nop 1
	v_cndmask_b32_e32 v45, v201, v45, vcc
	v_cmp_neq_f32_e32 vcc, -1.0, v43
	s_nop 1
	v_cndmask_b32_e32 v48, v201, v48, vcc
	v_cmp_lt_f32_e64 vcc, |v43|, s19
	s_nop 1
	v_cndmask_b32_e32 v49, v48, v43, vcc
	v_cndmask_b32_e64 v48, v45, v0, s[0:1]
	v_mul_f32_e64 v0, |v39|, s8
	v_exp_f32_e32 v0, v0
	v_pk_add_f32 v[48:49], v[46:47], v[48:49] neg_lo:[0,1] neg_hi:[0,1]
	s_mov_b64 s[0:1], 0x2400
	v_mov_b32_e32 v43, v48
	v_mov_b32_e32 v45, v49
	global_store_dwordx4 v[52:53], v[42:45], off offset:1024
	v_lshl_add_u64 v[46:47], v[72:73], 0, s[0:1]
	v_cmp_lt_f32_e64 s[0:1], |v0|, s19
	v_min_f32_e32 v42, 0, v39
	v_add_f32_e32 v39, 1.0, v0
	v_add_f32_e32 v43, -1.0, v39
	v_sub_f32_e32 v44, v43, v39
	v_add_f32_e32 v44, 1.0, v44
	v_sub_f32_e32 v43, v0, v43
	v_add_f32_e32 v43, v43, v44
	v_frexp_mant_f32_e32 v44, v39
	v_cmp_gt_f32_e32 vcc, s9, v44
	v_cvt_f64_f32_e32 v[44:45], v39
	v_frexp_exp_i32_f64_e32 v44, v[44:45]
	v_subbrev_co_u32_e32 v84, vcc, 0, v44, vcc
	v_sub_u32_e32 v45, 0, v84
	v_ldexp_f32 v44, v39, v45
	v_mul_f32_e64 v39, |v41|, s8
	v_exp_f32_e32 v39, v39
	v_ldexp_f32 v48, v43, v45
	v_min_f32_e32 v43, 0, v41
	v_add_f32_e32 v41, 1.0, v39
	v_add_f32_e32 v45, -1.0, v41
	v_sub_f32_e32 v49, v45, v41
	v_add_f32_e32 v49, 1.0, v49
	v_sub_f32_e32 v45, v39, v45
	v_add_f32_e32 v49, v45, v49
	v_frexp_mant_f32_e32 v45, v41
	v_cvt_f64_f32_e32 v[56:57], v41
	v_cmp_gt_f32_e32 vcc, s9, v45
	v_frexp_exp_i32_f64_e32 v45, v[56:57]
	s_nop 0
	v_subbrev_co_u32_e32 v85, vcc, 0, v45, vcc
	v_sub_u32_e32 v56, 0, v85
	v_ldexp_f32 v45, v41, v56
	v_ldexp_f32 v49, v49, v56
	v_pk_add_f32 v[56:57], v[44:45], 1.0 op_sel_hi:[1,0]
	v_pk_add_f32 v[76:77], v[44:45], -1.0 op_sel_hi:[1,0]
	v_pk_add_f32 v[60:61], v[56:57], -1.0 op_sel_hi:[1,0]
	v_pk_add_f32 v[78:79], v[76:77], 1.0 op_sel_hi:[1,0]
	v_pk_add_f32 v[60:61], v[44:45], v[60:61] neg_lo:[0,1] neg_hi:[0,1]
; __device__ __forceinline__ float log_sigmoid_f(float v) { return fminf(v, 0.f) - log1pf(__expf(-fabsf(v))); }
;     __device__ __forceinline__ void operator()(const f32x4 (&acc)[2][2][4][2], const pg8::Unit& u, int wr, int wc, int fr, int fq) const {
;     ...
;                 for (int nn = 0; nn < 2; ++nn) { const int head = 2 * fq + nn; const f32x4 gb = *(const f32x4*)(gate_b + 4 * head);
; #pragma unroll
;                     for (int ai = 0; ai < 2; ++ai)
; #pragma unroll
;                         for (int m = 0; m < 4; ++m) { const int row = row0 + ai * 128 + m * 16; f32x4 v = acc[ai][0][m][nn] + gb;
;                             v[1] = log_sigmoid_f(v[1]); v[3] = log_sigmoid_f(v[3]);
;                             *(f32x4*)(G + (size_t)row * 16 + 4 * head) = v; } }
	v_pk_add_f32 v[44:45], v[44:45], v[78:79] neg_lo:[0,1] neg_hi:[0,1]
	v_pk_add_f32 v[60:61], v[48:49], v[60:61]
	v_pk_add_f32 v[44:45], v[48:49], v[44:45]
	v_pk_add_f32 v[68:69], v[56:57], v[60:61]
	v_pk_add_f32 v[48:49], v[76:77], v[44:45]
	v_rcp_f32_e32 v74, v68
	v_rcp_f32_e32 v75, v69
	v_pk_add_f32 v[56:57], v[68:69], v[56:57] neg_lo:[0,1] neg_hi:[0,1]
	v_pk_add_f32 v[76:77], v[48:49], v[76:77] neg_lo:[0,1] neg_hi:[0,1]
	v_pk_add_f32 v[56:57], v[60:61], v[56:57] neg_lo:[0,1] neg_hi:[0,1]
	v_pk_mul_f32 v[60:61], v[48:49], v[74:75]
	v_pk_add_f32 v[44:45], v[44:45], v[76:77] neg_lo:[0,1] neg_hi:[0,1]
	v_pk_mul_f32 v[76:77], v[68:69], v[60:61]
	v_cmp_neq_f32_e32 vcc, s17, v0
	v_pk_fma_f32 v[78:79], v[60:61], v[68:69], v[76:77] neg_lo:[0,0,1] neg_hi:[0,0,1]
	s_nop 0
	v_pk_fma_f32 v[78:79], v[60:61], v[56:57], v[78:79]
	s_nop 0
	v_pk_add_f32 v[80:81], v[76:77], v[78:79]
	s_nop 0
	v_pk_add_f32 v[82:83], v[48:49], v[80:81] neg_lo:[0,1] neg_hi:[0,1]
	v_pk_add_f32 v[76:77], v[80:81], v[76:77] neg_lo:[0,1] neg_hi:[0,1]
	v_pk_add_f32 v[48:49], v[48:49], v[82:83] neg_lo:[0,1] neg_hi:[0,1]
	s_nop 0
	v_pk_add_f32 v[48:49], v[48:49], v[80:81] neg_lo:[0,1] neg_hi:[0,1]
	s_nop 0
	v_pk_add_f32 v[44:45], v[44:45], v[48:49]
	v_pk_add_f32 v[48:49], v[76:77], v[78:79] neg_lo:[0,1] neg_hi:[0,1]
	s_nop 0
	v_pk_add_f32 v[44:45], v[48:49], v[44:45]
	s_nop 0
	v_pk_add_f32 v[48:49], v[82:83], v[44:45]
	s_nop 0
	v_pk_mul_f32 v[76:77], v[74:75], v[48:49]
	s_nop 0
	v_pk_mul_f32 v[78:79], v[68:69], v[76:77]
	s_nop 0
	v_pk_fma_f32 v[68:69], v[76:77], v[68:69], v[78:79] neg_lo:[0,0,1] neg_hi:[0,0,1]
	s_nop 0
	v_pk_fma_f32 v[56:57], v[76:77], v[56:57], v[68:69]
	v_pk_add_f32 v[68:69], v[82:83], v[48:49] neg_lo:[0,1] neg_hi:[0,1]
	s_nop 0
	v_pk_add_f32 v[44:45], v[44:45], v[68:69]
	v_pk_add_f32 v[68:69], v[78:79], v[56:57]
	s_nop 0
	v_pk_add_f32 v[80:81], v[48:49], v[68:69] neg_lo:[0,1] neg_hi:[0,1]
	v_pk_add_f32 v[78:79], v[68:69], v[78:79] neg_lo:[0,1] neg_hi:[0,1]
	v_pk_add_f32 v[48:49], v[48:49], v[80:81] neg_lo:[0,1] neg_hi:[0,1]
	s_nop 0
	v_pk_add_f32 v[48:49], v[48:49], v[68:69] neg_lo:[0,1] neg_hi:[0,1]
	s_nop 0
	v_pk_add_f32 v[44:45], v[44:45], v[48:49]
	v_pk_add_f32 v[48:49], v[78:79], v[56:57] neg_lo:[0,1] neg_hi:[0,1]
	s_nop 0
	v_pk_add_f32 v[44:45], v[48:49], v[44:45]
	v_pk_add_f32 v[48:49], v[60:61], v[76:77]
	v_pk_add_f32 v[44:45], v[80:81], v[44:45]
	v_pk_add_f32 v[56:57], v[48:49], v[60:61] neg_lo:[0,1] neg_hi:[0,1]
	v_pk_mul_f32 v[44:45], v[74:75], v[44:45]
	v_pk_add_f32 v[56:57], v[76:77], v[56:57] neg_lo:[0,1] neg_hi:[0,1]
	s_nop 0
	v_pk_add_f32 v[44:45], v[56:57], v[44:45]
	s_nop 0
	v_pk_add_f32 v[56:57], v[48:49], v[44:45]
	s_nop 0
	v_pk_mul_f32 v[60:61], v[56:57], v[56:57]
	v_pk_add_f32 v[48:49], v[56:57], v[48:49] neg_lo:[0,1] neg_hi:[0,1]
	v_pk_fma_f32 v[68:69], v[60:61], s[34:35], v[70:71] op_sel_hi:[1,0,0]
	v_pk_add_f32 v[44:45], v[44:45], v[48:49] neg_lo:[0,1] neg_hi:[0,1]
	v_ldexp_f32 v48, v56, 1
	v_pk_fma_f32 v[68:69], v[60:61], v[68:69], s[36:37] op_sel_hi:[1,1,0]
	v_ldexp_f32 v49, v57, 1
	v_pk_mul_f32 v[56:57], v[56:57], v[60:61]
	v_cvt_f32_i32_e32 v61, v85
	v_cvt_f32_i32_e32 v60, v84
	v_pk_mul_f32 v[56:57], v[56:57], v[68:69]
	v_ldexp_f32 v75, v45, 1
	v_pk_add_f32 v[68:69], v[48:49], v[56:57]
	v_pk_mul_f32 v[76:77], v[60:61], s[38:39] op_sel_hi:[1,0]
	v_pk_add_f32 v[48:49], v[68:69], v[48:49] neg_lo:[0,1] neg_hi:[0,1]
	v_pk_fma_f32 v[78:79], v[60:61], s[38:39], v[76:77] op_sel_hi:[1,0,1] neg_lo:[0,0,1] neg_hi:[0,0,1]
	v_pk_add_f32 v[48:49], v[56:57], v[48:49] neg_lo:[0,1] neg_hi:[0,1]
	v_pk_fma_f32 v[60:61], v[60:61], s[40:41], v[78:79] op_sel_hi:[1,0,1]
	v_ldexp_f32 v44, v44, 1
	v_mov_b32_e32 v56, v76
	v_mov_b32_e32 v57, v49
	v_mov_b32_e32 v74, v60
	v_mov_b32_e32 v45, v75
	v_pk_add_f32 v[56:57], v[56:57], v[74:75]
	v_pk_add_f32 v[74:75], v[44:45], v[48:49]
	v_mov_b32_e32 v49, v69
	v_mov_b32_e32 v45, v75
	v_pk_add_f32 v[78:79], v[76:77], v[60:61]
	v_pk_add_f32 v[44:45], v[44:45], v[48:49]
	v_pk_add_f32 v[48:49], v[68:69], v[74:75]
	v_mov_b32_e32 v88, v68
	v_pk_add_f32 v[80:81], v[78:79], v[48:49]
	v_mov_b32_e32 v86, v48
	v_mov_b32_e32 v87, v81
	v_mov_b32_e32 v89, v79
	v_pk_add_f32 v[86:87], v[86:87], v[88:89] neg_lo:[0,1] neg_hi:[0,1]
	v_mov_b32_e32 v82, v80
	v_mov_b32_e32 v83, v79
	v_mov_b32_e32 v84, v78
	v_mov_b32_e32 v85, v77
	v_mov_b32_e32 v88, v78
	v_mov_b32_e32 v89, v81
	v_mov_b32_e32 v77, v87
	v_pk_add_f32 v[82:83], v[82:83], v[84:85] neg_lo:[0,1] neg_hi:[0,1]
	v_mov_b32_e32 v84, v48
	v_mov_b32_e32 v85, v61
	v_pk_add_f32 v[76:77], v[88:89], v[76:77] neg_lo:[0,1] neg_hi:[0,1]
	v_pk_add_f32 v[84:85], v[84:85], v[82:83] neg_lo:[0,1] neg_hi:[0,1]
	v_mov_b32_e32 v88, v76
	v_mov_b32_e32 v89, v83
	v_mov_b32_e32 v90, v80
	v_mov_b32_e32 v91, v49
	v_mov_b32_e32 v83, v69
	v_pk_add_f32 v[88:89], v[60:61], v[88:89] neg_lo:[0,1] neg_hi:[0,1]
	v_pk_add_f32 v[82:83], v[90:91], v[82:83] neg_lo:[0,1] neg_hi:[0,1]
	v_mov_b32_e32 v61, v79
	v_pk_add_f32 v[56:57], v[56:57], v[82:83] neg_lo:[0,1] neg_hi:[0,1]
	v_pk_add_f32 v[60:61], v[60:61], v[76:77] neg_lo:[0,1] neg_hi:[0,1]
	v_pk_add_f32 v[44:45], v[44:45], v[86:87] neg_lo:[0,1] neg_hi:[0,1]
	v_pk_add_f32 v[48:49], v[48:49], v[68:69] neg_lo:[0,1] neg_hi:[0,1]
	v_pk_add_f32 v[68:69], v[44:45], v[60:61]
	v_mov_b32_e32 v61, v85
	v_mov_b32_e32 v45, v57
	v_pk_add_f32 v[48:49], v[74:75], v[48:49] neg_lo:[0,1] neg_hi:[0,1]
	v_pk_add_f32 v[74:75], v[84:85], v[56:57]
	v_pk_add_f32 v[44:45], v[60:61], v[44:45]
	v_mov_b32_e32 v56, v68
	v_pk_add_f32 v[44:45], v[44:45], v[88:89] neg_lo:[0,1] neg_hi:[0,1]
	v_mov_b32_e32 v57, v75
	v_pk_add_f32 v[56:57], v[56:57], v[44:45] neg_lo:[0,1] neg_hi:[0,1]
; __device__ __forceinline__ float log_sigmoid_f(float v) { return fminf(v, 0.f) - log1pf(__expf(-fabsf(v))); }
;     __device__ __forceinline__ void operator()(const f32x4 (&acc)[2][2][4][2], const pg8::Unit& u, int wr, int wc, int fr, int fq) const {
;     ...
;                 for (int nn = 0; nn < 2; ++nn) { const int head = 2 * fq + nn; const f32x4 gb = *(const f32x4*)(gate_b + 4 * head);
; #pragma unroll
;                     for (int ai = 0; ai < 2; ++ai)
; #pragma unroll
;                         for (int m = 0; m < 4; ++m) { const int row = row0 + ai * 128 + m * 16; f32x4 v = acc[ai][0][m][nn] + gb;
;                             v[1] = log_sigmoid_f(v[1]); v[3] = log_sigmoid_f(v[3]);
;                             *(f32x4*)(G + (size_t)row * 16 + 4 * head) = v; } }
	v_pk_add_f32 v[44:45], v[48:49], v[44:45] neg_lo:[0,1] neg_hi:[0,1]
	v_pk_add_f32 v[56:57], v[60:61], v[56:57] neg_lo:[0,1] neg_hi:[0,1]
	v_pk_add_f32 v[48:49], v[74:75], v[68:69]
	v_pk_add_f32 v[44:45], v[44:45], v[56:57]
	v_pk_add_f32 v[56:57], v[80:81], v[48:49]
	s_nop 0
	v_pk_add_f32 v[60:61], v[56:57], v[80:81] neg_lo:[0,1] neg_hi:[0,1]
	s_nop 0
	v_pk_add_f32 v[48:49], v[48:49], v[60:61] neg_lo:[0,1] neg_hi:[0,1]
	s_nop 0
	v_pk_add_f32 v[44:45], v[44:45], v[48:49]
	s_nop 0
	v_pk_add_f32 v[44:45], v[56:57], v[44:45]
	s_nop 0
	v_cndmask_b32_e32 v41, v199, v44, vcc
	v_cmp_neq_f32_e32 vcc, s17, v39
	s_nop 1
	v_cndmask_b32_e32 v44, v199, v45, vcc
	v_cmp_ngt_f32_e32 vcc, -1.0, v39
	s_nop 1
	v_cndmask_b32_e32 v44, v200, v44, vcc
	v_cmp_ngt_f32_e32 vcc, -1.0, v0
	s_nop 1
	v_cndmask_b32_e32 v41, v200, v41, vcc
	v_cmp_neq_f32_e32 vcc, -1.0, v0
	s_nop 1
	v_cndmask_b32_e32 v41, v201, v41, vcc
	v_cmp_neq_f32_e32 vcc, -1.0, v39
	s_nop 1
	v_cndmask_b32_e32 v44, v201, v44, vcc
	v_cmp_lt_f32_e64 vcc, |v39|, s19
	s_nop 1
	v_cndmask_b32_e32 v45, v44, v39, vcc
	v_cndmask_b32_e64 v44, v41, v0, s[0:1]
	v_mul_f32_e64 v0, |v35|, s8
	v_exp_f32_e32 v0, v0
	v_pk_add_f32 v[44:45], v[42:43], v[44:45] neg_lo:[0,1] neg_hi:[0,1]
	s_mov_b64 s[0:1], 0x2800
	v_mov_b32_e32 v39, v44
	v_mov_b32_e32 v41, v45
	global_store_dwordx4 v[52:53], v[38:41], off offset:2048
	v_lshl_add_u64 v[42:43], v[72:73], 0, s[0:1]
	v_cmp_lt_f32_e64 s[0:1], |v0|, s19
	v_min_f32_e32 v38, 0, v35
	v_add_f32_e32 v35, 1.0, v0
	v_add_f32_e32 v39, -1.0, v35
	v_sub_f32_e32 v40, v39, v35
	v_add_f32_e32 v40, 1.0, v40
	v_sub_f32_e32 v39, v0, v39
	v_add_f32_e32 v39, v39, v40
	v_frexp_mant_f32_e32 v40, v35
	v_cmp_gt_f32_e32 vcc, s9, v40
	v_cvt_f64_f32_e32 v[40:41], v35
	v_frexp_exp_i32_f64_e32 v40, v[40:41]
	v_subbrev_co_u32_e32 v78, vcc, 0, v40, vcc
	v_sub_u32_e32 v41, 0, v78
	v_ldexp_f32 v40, v35, v41
	v_mul_f32_e64 v35, |v37|, s8
	v_exp_f32_e32 v35, v35
	v_ldexp_f32 v44, v39, v41
	v_min_f32_e32 v39, 0, v37
	v_add_f32_e32 v37, 1.0, v35
	v_add_f32_e32 v41, -1.0, v37
	v_sub_f32_e32 v45, v41, v37
	v_add_f32_e32 v45, 1.0, v45
	v_sub_f32_e32 v41, v35, v41
	v_add_f32_e32 v45, v41, v45
	v_frexp_mant_f32_e32 v41, v37
	v_cvt_f64_f32_e32 v[48:49], v37
	v_cmp_gt_f32_e32 vcc, s9, v41
	v_frexp_exp_i32_f64_e32 v41, v[48:49]
	s_nop 0
	v_subbrev_co_u32_e32 v79, vcc, 0, v41, vcc
	v_sub_u32_e32 v48, 0, v79
	v_ldexp_f32 v41, v37, v48
	v_ldexp_f32 v45, v45, v48
	v_pk_add_f32 v[48:49], v[40:41], 1.0 op_sel_hi:[1,0]
	v_pk_add_f32 v[64:65], v[40:41], -1.0 op_sel_hi:[1,0]
	v_pk_add_f32 v[56:57], v[48:49], -1.0 op_sel_hi:[1,0]
	v_pk_add_f32 v[68:69], v[64:65], 1.0 op_sel_hi:[1,0]
	v_pk_add_f32 v[56:57], v[40:41], v[56:57] neg_lo:[0,1] neg_hi:[0,1]
	v_pk_add_f32 v[40:41], v[40:41], v[68:69] neg_lo:[0,1] neg_hi:[0,1]
	v_pk_add_f32 v[56:57], v[44:45], v[56:57]
	v_pk_add_f32 v[40:41], v[44:45], v[40:41]
	v_pk_add_f32 v[60:61], v[48:49], v[56:57]
	v_pk_add_f32 v[44:45], v[64:65], v[40:41]
	v_rcp_f32_e32 v62, v60
	v_rcp_f32_e32 v63, v61
	v_pk_add_f32 v[48:49], v[60:61], v[48:49] neg_lo:[0,1] neg_hi:[0,1]
	v_pk_add_f32 v[64:65], v[44:45], v[64:65] neg_lo:[0,1] neg_hi:[0,1]
	v_pk_add_f32 v[48:49], v[56:57], v[48:49] neg_lo:[0,1] neg_hi:[0,1]
	v_pk_mul_f32 v[56:57], v[44:45], v[62:63]
	v_pk_add_f32 v[40:41], v[40:41], v[64:65] neg_lo:[0,1] neg_hi:[0,1]
	v_pk_mul_f32 v[64:65], v[60:61], v[56:57]
	v_cmp_neq_f32_e32 vcc, s17, v0
	v_pk_fma_f32 v[68:69], v[56:57], v[60:61], v[64:65] neg_lo:[0,0,1] neg_hi:[0,0,1]
	s_nop 0
	v_pk_fma_f32 v[68:69], v[56:57], v[48:49], v[68:69]
	s_nop 0
	v_pk_add_f32 v[74:75], v[64:65], v[68:69]
	s_nop 0
	v_pk_add_f32 v[76:77], v[44:45], v[74:75] neg_lo:[0,1] neg_hi:[0,1]
	v_pk_add_f32 v[64:65], v[74:75], v[64:65] neg_lo:[0,1] neg_hi:[0,1]
	v_pk_add_f32 v[44:45], v[44:45], v[76:77] neg_lo:[0,1] neg_hi:[0,1]
	s_nop 0
	v_pk_add_f32 v[44:45], v[44:45], v[74:75] neg_lo:[0,1] neg_hi:[0,1]
	s_nop 0
	v_pk_add_f32 v[40:41], v[40:41], v[44:45]
	v_pk_add_f32 v[44:45], v[64:65], v[68:69] neg_lo:[0,1] neg_hi:[0,1]
	s_nop 0
	v_pk_add_f32 v[40:41], v[44:45], v[40:41]
	s_nop 0
	v_pk_add_f32 v[44:45], v[76:77], v[40:41]
	s_nop 0
	v_pk_mul_f32 v[64:65], v[62:63], v[44:45]
	s_nop 0
	v_pk_mul_f32 v[68:69], v[60:61], v[64:65]
	s_nop 0
	v_pk_fma_f32 v[60:61], v[64:65], v[60:61], v[68:69] neg_lo:[0,0,1] neg_hi:[0,0,1]
	s_nop 0
	v_pk_fma_f32 v[48:49], v[64:65], v[48:49], v[60:61]
	v_pk_add_f32 v[60:61], v[76:77], v[44:45] neg_lo:[0,1] neg_hi:[0,1]
	s_nop 0
	v_pk_add_f32 v[40:41], v[40:41], v[60:61]
	v_pk_add_f32 v[60:61], v[68:69], v[48:49]
	s_nop 0
	v_pk_add_f32 v[74:75], v[44:45], v[60:61] neg_lo:[0,1] neg_hi:[0,1]
	v_pk_add_f32 v[68:69], v[60:61], v[68:69] neg_lo:[0,1] neg_hi:[0,1]
	v_pk_add_f32 v[44:45], v[44:45], v[74:75] neg_lo:[0,1] neg_hi:[0,1]
	s_nop 0
	v_pk_add_f32 v[44:45], v[44:45], v[60:61] neg_lo:[0,1] neg_hi:[0,1]
	s_nop 0
	v_pk_add_f32 v[40:41], v[40:41], v[44:45]
	v_pk_add_f32 v[44:45], v[68:69], v[48:49] neg_lo:[0,1] neg_hi:[0,1]
	s_nop 0
	v_pk_add_f32 v[40:41], v[44:45], v[40:41]
	v_pk_add_f32 v[44:45], v[56:57], v[64:65]
	v_pk_add_f32 v[40:41], v[74:75], v[40:41]
	v_pk_add_f32 v[48:49], v[44:45], v[56:57] neg_lo:[0,1] neg_hi:[0,1]
	v_pk_mul_f32 v[40:41], v[62:63], v[40:41]
	v_pk_add_f32 v[48:49], v[64:65], v[48:49] neg_lo:[0,1] neg_hi:[0,1]
	s_nop 0
	v_pk_add_f32 v[40:41], v[48:49], v[40:41]
	s_nop 0
	v_pk_add_f32 v[48:49], v[44:45], v[40:41]
	s_nop 0
	v_pk_mul_f32 v[56:57], v[48:49], v[48:49]
	v_pk_add_f32 v[44:45], v[48:49], v[44:45] neg_lo:[0,1] neg_hi:[0,1]
	v_pk_fma_f32 v[60:61], v[56:57], s[34:35], v[70:71] op_sel_hi:[1,0,0]
	v_pk_add_f32 v[40:41], v[40:41], v[44:45] neg_lo:[0,1] neg_hi:[0,1]
	v_ldexp_f32 v44, v48, 1
; __device__ __forceinline__ float log_sigmoid_f(float v) { return fminf(v, 0.f) - log1pf(__expf(-fabsf(v))); }
;     __device__ __forceinline__ void operator()(const f32x4 (&acc)[2][2][4][2], const pg8::Unit& u, int wr, int wc, int fr, int fq) const {
;     ...
;                 for (int nn = 0; nn < 2; ++nn) { const int head = 2 * fq + nn; const f32x4 gb = *(const f32x4*)(gate_b + 4 * head);
; #pragma unroll
;                     for (int ai = 0; ai < 2; ++ai)
; #pragma unroll
;                         for (int m = 0; m < 4; ++m) { const int row = row0 + ai * 128 + m * 16; f32x4 v = acc[ai][0][m][nn] + gb;
;                             v[1] = log_sigmoid_f(v[1]); v[3] = log_sigmoid_f(v[3]);
;                             *(f32x4*)(G + (size_t)row * 16 + 4 * head) = v; } }
	v_pk_fma_f32 v[60:61], v[56:57], v[60:61], s[36:37] op_sel_hi:[1,1,0]
	v_ldexp_f32 v45, v49, 1
	v_pk_mul_f32 v[48:49], v[48:49], v[56:57]
	v_cvt_f32_i32_e32 v57, v79
	v_cvt_f32_i32_e32 v56, v78
	v_pk_mul_f32 v[48:49], v[48:49], v[60:61]
	v_ldexp_f32 v63, v41, 1
	v_pk_add_f32 v[60:61], v[44:45], v[48:49]
	v_pk_mul_f32 v[64:65], v[56:57], s[38:39] op_sel_hi:[1,0]
	v_pk_add_f32 v[44:45], v[60:61], v[44:45] neg_lo:[0,1] neg_hi:[0,1]
	v_pk_fma_f32 v[68:69], v[56:57], s[38:39], v[64:65] op_sel_hi:[1,0,1] neg_lo:[0,0,1] neg_hi:[0,0,1]
	v_pk_add_f32 v[44:45], v[48:49], v[44:45] neg_lo:[0,1] neg_hi:[0,1]
	v_pk_fma_f32 v[56:57], v[56:57], s[40:41], v[68:69] op_sel_hi:[1,0,1]
	v_ldexp_f32 v40, v40, 1
	v_mov_b32_e32 v48, v64
	v_mov_b32_e32 v49, v45
	v_mov_b32_e32 v62, v56
	v_mov_b32_e32 v41, v63
	v_pk_add_f32 v[48:49], v[48:49], v[62:63]
	v_pk_add_f32 v[62:63], v[40:41], v[44:45]
	v_mov_b32_e32 v45, v61
	v_mov_b32_e32 v41, v63
	v_pk_add_f32 v[68:69], v[64:65], v[56:57]
	v_pk_add_f32 v[40:41], v[40:41], v[44:45]
	v_pk_add_f32 v[44:45], v[60:61], v[62:63]
	v_mov_b32_e32 v82, v60
	v_pk_add_f32 v[74:75], v[68:69], v[44:45]
	v_mov_b32_e32 v80, v44
	v_mov_b32_e32 v81, v75
	v_mov_b32_e32 v83, v69
	v_pk_add_f32 v[80:81], v[80:81], v[82:83] neg_lo:[0,1] neg_hi:[0,1]
	v_mov_b32_e32 v76, v74
	v_mov_b32_e32 v77, v69
	v_mov_b32_e32 v78, v68
	v_mov_b32_e32 v79, v65
	v_mov_b32_e32 v82, v68
	v_mov_b32_e32 v83, v75
	v_mov_b32_e32 v65, v81
	v_pk_add_f32 v[76:77], v[76:77], v[78:79] neg_lo:[0,1] neg_hi:[0,1]
	v_mov_b32_e32 v78, v44
	v_mov_b32_e32 v79, v57
	v_pk_add_f32 v[64:65], v[82:83], v[64:65] neg_lo:[0,1] neg_hi:[0,1]
	v_pk_add_f32 v[78:79], v[78:79], v[76:77] neg_lo:[0,1] neg_hi:[0,1]
	v_mov_b32_e32 v82, v64
	v_mov_b32_e32 v83, v77
	v_mov_b32_e32 v84, v74
	v_mov_b32_e32 v85, v45
	v_mov_b32_e32 v77, v61
	v_pk_add_f32 v[82:83], v[56:57], v[82:83] neg_lo:[0,1] neg_hi:[0,1]
	v_pk_add_f32 v[76:77], v[84:85], v[76:77] neg_lo:[0,1] neg_hi:[0,1]
	v_mov_b32_e32 v57, v69
	v_pk_add_f32 v[48:49], v[48:49], v[76:77] neg_lo:[0,1] neg_hi:[0,1]
	v_pk_add_f32 v[56:57], v[56:57], v[64:65] neg_lo:[0,1] neg_hi:[0,1]
	v_pk_add_f32 v[40:41], v[40:41], v[80:81] neg_lo:[0,1] neg_hi:[0,1]
	v_pk_add_f32 v[44:45], v[44:45], v[60:61] neg_lo:[0,1] neg_hi:[0,1]
	v_pk_add_f32 v[60:61], v[40:41], v[56:57]
	v_mov_b32_e32 v57, v79
	v_mov_b32_e32 v41, v49
	v_pk_add_f32 v[44:45], v[62:63], v[44:45] neg_lo:[0,1] neg_hi:[0,1]
	v_pk_add_f32 v[62:63], v[78:79], v[48:49]
	v_pk_add_f32 v[40:41], v[56:57], v[40:41]
	v_mov_b32_e32 v48, v60
	v_pk_add_f32 v[40:41], v[40:41], v[82:83] neg_lo:[0,1] neg_hi:[0,1]
	v_mov_b32_e32 v49, v63
	v_pk_add_f32 v[48:49], v[48:49], v[40:41] neg_lo:[0,1] neg_hi:[0,1]
	v_pk_add_f32 v[40:41], v[44:45], v[40:41] neg_lo:[0,1] neg_hi:[0,1]
	v_pk_add_f32 v[48:49], v[56:57], v[48:49] neg_lo:[0,1] neg_hi:[0,1]
	v_pk_add_f32 v[44:45], v[62:63], v[60:61]
	v_pk_add_f32 v[40:41], v[40:41], v[48:49]
	v_pk_add_f32 v[48:49], v[74:75], v[44:45]
	s_nop 0
	v_pk_add_f32 v[56:57], v[48:49], v[74:75] neg_lo:[0,1] neg_hi:[0,1]
	s_nop 0
	v_pk_add_f32 v[44:45], v[44:45], v[56:57] neg_lo:[0,1] neg_hi:[0,1]
	s_nop 0
	v_pk_add_f32 v[40:41], v[40:41], v[44:45]
	s_nop 0
	v_pk_add_f32 v[40:41], v[48:49], v[40:41]
	s_nop 0
	v_cndmask_b32_e32 v37, v199, v40, vcc
	v_cmp_neq_f32_e32 vcc, s17, v35
	s_nop 1
	v_cndmask_b32_e32 v40, v199, v41, vcc
	v_cmp_ngt_f32_e32 vcc, -1.0, v35
	s_nop 1
	v_cndmask_b32_e32 v40, v200, v40, vcc
	v_cmp_ngt_f32_e32 vcc, -1.0, v0
	s_nop 1
	v_cndmask_b32_e32 v37, v200, v37, vcc
	v_cmp_neq_f32_e32 vcc, -1.0, v0
	s_nop 1
	v_cndmask_b32_e32 v37, v201, v37, vcc
	v_cmp_neq_f32_e32 vcc, -1.0, v35
	s_nop 1
	v_cndmask_b32_e32 v40, v201, v40, vcc
	v_cmp_lt_f32_e64 vcc, |v35|, s19
	s_nop 1
	v_cndmask_b32_e32 v41, v40, v35, vcc
	v_cndmask_b32_e64 v40, v37, v0, s[0:1]
	v_pk_add_f32 v[40:41], v[38:39], v[40:41] neg_lo:[0,1] neg_hi:[0,1]
	s_mov_b64 s[0:1], 0x2c00
	v_mov_b32_e32 v35, v40
	v_mov_b32_e32 v37, v41
	global_store_dwordx4 v[52:53], v[34:37], off offset:3072
	global_load_dwordx4 v[34:37], v[174:175], off offset:16
	v_lshl_add_u64 v[38:39], v[72:73], 0, s[0:1]
	s_waitcnt vmcnt(0)
	v_pk_add_f32 v[30:31], v[30:31], v[34:35]
	s_nop 0
	v_mul_f32_e64 v0, |v31|, s8
	v_exp_f32_e32 v0, v0
	v_min_f32_e32 v40, 0, v31
	v_pk_add_f32 v[32:33], v[32:33], v[36:37]
	v_pk_add_f32 v[26:27], v[26:27], v[34:35]
	v_add_f32_e32 v31, 1.0, v0
	v_add_f32_e32 v41, -1.0, v31
	v_sub_f32_e32 v44, v41, v31
	v_add_f32_e32 v44, 1.0, v44
	v_sub_f32_e32 v41, v0, v41
	v_add_f32_e32 v41, v41, v44
	v_frexp_mant_f32_e32 v44, v31
	v_cmp_gt_f32_e32 vcc, s9, v44
	v_cvt_f64_f32_e32 v[44:45], v31
	v_frexp_exp_i32_f64_e32 v44, v[44:45]
	v_subbrev_co_u32_e32 v78, vcc, 0, v44, vcc
	v_sub_u32_e32 v45, 0, v78
	v_ldexp_f32 v44, v31, v45
	v_mul_f32_e64 v31, |v33|, s8
	v_exp_f32_e32 v31, v31
	v_ldexp_f32 v48, v41, v45
	v_min_f32_e32 v41, 0, v33
	v_cmp_lt_f32_e64 s[0:1], |v0|, s19
	v_add_f32_e32 v33, 1.0, v31
	v_add_f32_e32 v45, -1.0, v33
	v_sub_f32_e32 v49, v45, v33
	v_add_f32_e32 v49, 1.0, v49
	v_sub_f32_e32 v45, v31, v45
	v_add_f32_e32 v49, v45, v49
	v_frexp_mant_f32_e32 v45, v33
	v_cvt_f64_f32_e32 v[52:53], v33
	v_cmp_gt_f32_e32 vcc, s9, v45
	v_frexp_exp_i32_f64_e32 v45, v[52:53]
	v_pk_add_f32 v[28:29], v[28:29], v[36:37]
	v_subbrev_co_u32_e32 v79, vcc, 0, v45, vcc
	v_sub_u32_e32 v52, 0, v79
	v_ldexp_f32 v45, v33, v52
	v_ldexp_f32 v49, v49, v52
	v_pk_add_f32 v[52:53], v[44:45], 1.0 op_sel_hi:[1,0]
	v_pk_add_f32 v[64:65], v[44:45], -1.0 op_sel_hi:[1,0]
	v_pk_add_f32 v[56:57], v[52:53], -1.0 op_sel_hi:[1,0]
	v_pk_add_f32 v[68:69], v[64:65], 1.0 op_sel_hi:[1,0]
	v_pk_add_f32 v[56:57], v[44:45], v[56:57] neg_lo:[0,1] neg_hi:[0,1]
; __device__ __forceinline__ float log_sigmoid_f(float v) { return fminf(v, 0.f) - log1pf(__expf(-fabsf(v))); }
;     __device__ __forceinline__ void operator()(const f32x4 (&acc)[2][2][4][2], const pg8::Unit& u, int wr, int wc, int fr, int fq) const {
;     ...
;                 for (int nn = 0; nn < 2; ++nn) { const int head = 2 * fq + nn; const f32x4 gb = *(const f32x4*)(gate_b + 4 * head);
; #pragma unroll
;                     for (int ai = 0; ai < 2; ++ai)
; #pragma unroll
;                         for (int m = 0; m < 4; ++m) { const int row = row0 + ai * 128 + m * 16; f32x4 v = acc[ai][0][m][nn] + gb;
;                             v[1] = log_sigmoid_f(v[1]); v[3] = log_sigmoid_f(v[3]);
;                             *(f32x4*)(G + (size_t)row * 16 + 4 * head) = v; } }
	v_pk_add_f32 v[44:45], v[44:45], v[68:69] neg_lo:[0,1] neg_hi:[0,1]
	v_pk_add_f32 v[56:57], v[48:49], v[56:57]
	v_pk_add_f32 v[44:45], v[48:49], v[44:45]
	v_pk_add_f32 v[60:61], v[52:53], v[56:57]
	v_pk_add_f32 v[48:49], v[64:65], v[44:45]
	v_rcp_f32_e32 v62, v60
	v_rcp_f32_e32 v63, v61
	v_pk_add_f32 v[52:53], v[60:61], v[52:53] neg_lo:[0,1] neg_hi:[0,1]
	v_pk_add_f32 v[64:65], v[48:49], v[64:65] neg_lo:[0,1] neg_hi:[0,1]
	v_pk_add_f32 v[52:53], v[56:57], v[52:53] neg_lo:[0,1] neg_hi:[0,1]
	v_pk_mul_f32 v[56:57], v[48:49], v[62:63]
	v_pk_add_f32 v[44:45], v[44:45], v[64:65] neg_lo:[0,1] neg_hi:[0,1]
	v_pk_mul_f32 v[64:65], v[60:61], v[56:57]
	v_cmp_neq_f32_e32 vcc, s17, v0
	v_pk_fma_f32 v[68:69], v[56:57], v[60:61], v[64:65] neg_lo:[0,0,1] neg_hi:[0,0,1]
	v_pk_add_f32 v[22:23], v[22:23], v[34:35]
	v_pk_fma_f32 v[68:69], v[56:57], v[52:53], v[68:69]
	v_pk_add_f32 v[24:25], v[24:25], v[36:37]
	v_pk_add_f32 v[74:75], v[64:65], v[68:69]
	v_pk_add_f32 v[18:19], v[18:19], v[34:35]
	v_pk_add_f32 v[76:77], v[48:49], v[74:75] neg_lo:[0,1] neg_hi:[0,1]
	v_pk_add_f32 v[64:65], v[74:75], v[64:65] neg_lo:[0,1] neg_hi:[0,1]
	v_pk_add_f32 v[48:49], v[48:49], v[76:77] neg_lo:[0,1] neg_hi:[0,1]
	v_pk_add_f32 v[20:21], v[20:21], v[36:37]
	v_pk_add_f32 v[48:49], v[48:49], v[74:75] neg_lo:[0,1] neg_hi:[0,1]
	v_pk_add_f32 v[14:15], v[14:15], v[34:35]
	v_pk_add_f32 v[44:45], v[44:45], v[48:49]
	v_pk_add_f32 v[48:49], v[64:65], v[68:69] neg_lo:[0,1] neg_hi:[0,1]
	v_pk_add_f32 v[16:17], v[16:17], v[36:37]
	v_pk_add_f32 v[44:45], v[48:49], v[44:45]
	v_pk_add_f32 v[10:11], v[10:11], v[34:35]
	v_pk_add_f32 v[48:49], v[76:77], v[44:45]
	v_pk_add_f32 v[12:13], v[12:13], v[36:37]
	v_pk_mul_f32 v[64:65], v[62:63], v[48:49]
	v_pk_add_f32 v[6:7], v[6:7], v[34:35]
	v_pk_mul_f32 v[68:69], v[60:61], v[64:65]
	v_pk_add_f32 v[8:9], v[8:9], v[36:37]
	v_pk_fma_f32 v[60:61], v[64:65], v[60:61], v[68:69] neg_lo:[0,0,1] neg_hi:[0,0,1]
	v_pk_add_f32 v[2:3], v[2:3], v[34:35]
	v_pk_fma_f32 v[52:53], v[64:65], v[52:53], v[60:61]
	v_pk_add_f32 v[60:61], v[76:77], v[48:49] neg_lo:[0,1] neg_hi:[0,1]
	v_pk_add_f32 v[4:5], v[4:5], v[36:37]
	v_pk_add_f32 v[44:45], v[44:45], v[60:61]
	v_pk_add_f32 v[60:61], v[68:69], v[52:53]
	s_nop 0
	v_pk_add_f32 v[74:75], v[48:49], v[60:61] neg_lo:[0,1] neg_hi:[0,1]
	v_pk_add_f32 v[68:69], v[60:61], v[68:69] neg_lo:[0,1] neg_hi:[0,1]
	v_pk_add_f32 v[48:49], v[48:49], v[74:75] neg_lo:[0,1] neg_hi:[0,1]
	s_nop 0
	v_pk_add_f32 v[48:49], v[48:49], v[60:61] neg_lo:[0,1] neg_hi:[0,1]
	s_nop 0
	v_pk_add_f32 v[44:45], v[44:45], v[48:49]
	v_pk_add_f32 v[48:49], v[68:69], v[52:53] neg_lo:[0,1] neg_hi:[0,1]
	s_nop 0
	v_pk_add_f32 v[44:45], v[48:49], v[44:45]
	v_pk_add_f32 v[48:49], v[56:57], v[64:65]
	v_pk_add_f32 v[44:45], v[74:75], v[44:45]
	v_pk_add_f32 v[52:53], v[48:49], v[56:57] neg_lo:[0,1] neg_hi:[0,1]
	v_pk_mul_f32 v[44:45], v[62:63], v[44:45]
	v_pk_add_f32 v[52:53], v[64:65], v[52:53] neg_lo:[0,1] neg_hi:[0,1]
	s_nop 0
	v_pk_add_f32 v[44:45], v[52:53], v[44:45]
	s_nop 0
	v_pk_add_f32 v[52:53], v[48:49], v[44:45]
	s_nop 0
	v_pk_mul_f32 v[56:57], v[52:53], v[52:53]
	v_pk_add_f32 v[48:49], v[52:53], v[48:49] neg_lo:[0,1] neg_hi:[0,1]
	v_pk_fma_f32 v[60:61], v[56:57], s[34:35], v[70:71] op_sel_hi:[1,0,0]
	v_pk_add_f32 v[44:45], v[44:45], v[48:49] neg_lo:[0,1] neg_hi:[0,1]
	v_ldexp_f32 v48, v52, 1
	v_pk_fma_f32 v[60:61], v[56:57], v[60:61], s[36:37] op_sel_hi:[1,1,0]
	v_ldexp_f32 v49, v53, 1
	v_pk_mul_f32 v[52:53], v[52:53], v[56:57]
	v_cvt_f32_i32_e32 v57, v79
	v_cvt_f32_i32_e32 v56, v78
	v_pk_mul_f32 v[52:53], v[52:53], v[60:61]
	v_ldexp_f32 v63, v45, 1
	v_pk_add_f32 v[60:61], v[48:49], v[52:53]
	v_pk_mul_f32 v[64:65], v[56:57], s[38:39] op_sel_hi:[1,0]
	v_pk_add_f32 v[48:49], v[60:61], v[48:49] neg_lo:[0,1] neg_hi:[0,1]
	v_pk_fma_f32 v[68:69], v[56:57], s[38:39], v[64:65] op_sel_hi:[1,0,1] neg_lo:[0,0,1] neg_hi:[0,0,1]
	v_pk_add_f32 v[48:49], v[52:53], v[48:49] neg_lo:[0,1] neg_hi:[0,1]
	v_pk_fma_f32 v[56:57], v[56:57], s[40:41], v[68:69] op_sel_hi:[1,0,1]
	v_ldexp_f32 v44, v44, 1
	v_mov_b32_e32 v52, v64
	v_mov_b32_e32 v53, v49
	v_mov_b32_e32 v62, v56
	v_mov_b32_e32 v45, v63
	v_pk_add_f32 v[52:53], v[52:53], v[62:63]
	v_pk_add_f32 v[62:63], v[44:45], v[48:49]
	v_mov_b32_e32 v49, v61
	v_mov_b32_e32 v45, v63
	v_pk_add_f32 v[68:69], v[64:65], v[56:57]
	v_pk_add_f32 v[44:45], v[44:45], v[48:49]
	v_pk_add_f32 v[48:49], v[60:61], v[62:63]
	v_mov_b32_e32 v82, v60
	v_pk_add_f32 v[74:75], v[68:69], v[48:49]
	v_mov_b32_e32 v80, v48
	v_mov_b32_e32 v81, v75
	v_mov_b32_e32 v83, v69
	v_pk_add_f32 v[80:81], v[80:81], v[82:83] neg_lo:[0,1] neg_hi:[0,1]
	v_mov_b32_e32 v76, v74
	v_mov_b32_e32 v77, v69
	v_mov_b32_e32 v78, v68
	v_mov_b32_e32 v79, v65
	v_mov_b32_e32 v82, v68
	v_mov_b32_e32 v83, v75
	v_mov_b32_e32 v65, v81
	v_pk_add_f32 v[76:77], v[76:77], v[78:79] neg_lo:[0,1] neg_hi:[0,1]
	v_mov_b32_e32 v78, v48
	v_mov_b32_e32 v79, v57
	v_pk_add_f32 v[64:65], v[82:83], v[64:65] neg_lo:[0,1] neg_hi:[0,1]
	v_pk_add_f32 v[78:79], v[78:79], v[76:77] neg_lo:[0,1] neg_hi:[0,1]
	v_mov_b32_e32 v82, v64
	v_mov_b32_e32 v83, v77
	v_mov_b32_e32 v84, v74
	v_mov_b32_e32 v85, v49
	v_mov_b32_e32 v77, v61
	v_pk_add_f32 v[82:83], v[56:57], v[82:83] neg_lo:[0,1] neg_hi:[0,1]
	v_pk_add_f32 v[76:77], v[84:85], v[76:77] neg_lo:[0,1] neg_hi:[0,1]
	v_mov_b32_e32 v57, v69
	v_pk_add_f32 v[52:53], v[52:53], v[76:77] neg_lo:[0,1] neg_hi:[0,1]
	v_pk_add_f32 v[56:57], v[56:57], v[64:65] neg_lo:[0,1] neg_hi:[0,1]
	v_pk_add_f32 v[44:45], v[44:45], v[80:81] neg_lo:[0,1] neg_hi:[0,1]
	v_pk_add_f32 v[48:49], v[48:49], v[60:61] neg_lo:[0,1] neg_hi:[0,1]
	v_pk_add_f32 v[60:61], v[44:45], v[56:57]
; __device__ __forceinline__ float log_sigmoid_f(float v) { return fminf(v, 0.f) - log1pf(__expf(-fabsf(v))); }
;     __device__ __forceinline__ void operator()(const f32x4 (&acc)[2][2][4][2], const pg8::Unit& u, int wr, int wc, int fr, int fq) const {
;     ...
;                 for (int nn = 0; nn < 2; ++nn) { const int head = 2 * fq + nn; const f32x4 gb = *(const f32x4*)(gate_b + 4 * head);
; #pragma unroll
;                     for (int ai = 0; ai < 2; ++ai)
; #pragma unroll
;                         for (int m = 0; m < 4; ++m) { const int row = row0 + ai * 128 + m * 16; f32x4 v = acc[ai][0][m][nn] + gb;
;                             v[1] = log_sigmoid_f(v[1]); v[3] = log_sigmoid_f(v[3]);
;                             *(f32x4*)(G + (size_t)row * 16 + 4 * head) = v; } }
	v_mov_b32_e32 v57, v79
	v_mov_b32_e32 v45, v53
	v_pk_add_f32 v[48:49], v[62:63], v[48:49] neg_lo:[0,1] neg_hi:[0,1]
	v_pk_add_f32 v[62:63], v[78:79], v[52:53]
	v_pk_add_f32 v[44:45], v[56:57], v[44:45]
	v_mov_b32_e32 v52, v60
	v_pk_add_f32 v[44:45], v[44:45], v[82:83] neg_lo:[0,1] neg_hi:[0,1]
	v_mov_b32_e32 v53, v63
	v_pk_add_f32 v[52:53], v[52:53], v[44:45] neg_lo:[0,1] neg_hi:[0,1]
	v_pk_add_f32 v[44:45], v[48:49], v[44:45] neg_lo:[0,1] neg_hi:[0,1]
	v_pk_add_f32 v[52:53], v[56:57], v[52:53] neg_lo:[0,1] neg_hi:[0,1]
	v_pk_add_f32 v[48:49], v[62:63], v[60:61]
	v_pk_add_f32 v[44:45], v[44:45], v[52:53]
	v_pk_add_f32 v[52:53], v[74:75], v[48:49]
	s_nop 0
	v_pk_add_f32 v[56:57], v[52:53], v[74:75] neg_lo:[0,1] neg_hi:[0,1]
	s_nop 0
	v_pk_add_f32 v[48:49], v[48:49], v[56:57] neg_lo:[0,1] neg_hi:[0,1]
	s_nop 0
	v_pk_add_f32 v[44:45], v[44:45], v[48:49]
	s_nop 0
	v_pk_add_f32 v[44:45], v[52:53], v[44:45]
	s_nop 0
	v_cndmask_b32_e32 v33, v199, v44, vcc
	v_cmp_neq_f32_e32 vcc, s17, v31
	s_nop 1
	v_cndmask_b32_e32 v44, v199, v45, vcc
	v_cmp_ngt_f32_e32 vcc, -1.0, v31
	s_nop 1
	v_cndmask_b32_e32 v44, v200, v44, vcc
	v_cmp_ngt_f32_e32 vcc, -1.0, v0
	s_nop 1
	v_cndmask_b32_e32 v33, v200, v33, vcc
	v_cmp_neq_f32_e32 vcc, -1.0, v0
	s_nop 1
	v_cndmask_b32_e32 v33, v201, v33, vcc
	v_cmp_neq_f32_e32 vcc, -1.0, v31
	s_nop 1
	v_cndmask_b32_e32 v44, v201, v44, vcc
	v_cmp_lt_f32_e64 vcc, |v31|, s19
	s_nop 1
	v_cndmask_b32_e32 v45, v44, v31, vcc
	v_cndmask_b32_e64 v44, v33, v0, s[0:1]
	v_mul_f32_e64 v0, |v27|, s8
	v_exp_f32_e32 v0, v0
	v_pk_add_f32 v[40:41], v[40:41], v[44:45] neg_lo:[0,1] neg_hi:[0,1]
	v_cmp_lt_f32_e64 s[0:1], |v0|, s19
	v_mov_b32_e32 v31, v40
	v_mov_b32_e32 v33, v41
	global_store_dwordx4 v[72:73], v[30:33], off offset:16
	s_nop 1
	v_min_f32_e32 v30, 0, v27
	v_add_f32_e32 v27, 1.0, v0
	v_add_f32_e32 v31, -1.0, v27
	v_sub_f32_e32 v32, v31, v27
	v_add_f32_e32 v32, 1.0, v32
	v_sub_f32_e32 v31, v0, v31
	v_add_f32_e32 v31, v31, v32
	v_frexp_mant_f32_e32 v32, v27
	v_cmp_gt_f32_e32 vcc, s9, v32
	v_cvt_f64_f32_e32 v[32:33], v27
	v_frexp_exp_i32_f64_e32 v32, v[32:33]
	v_subbrev_co_u32_e32 v72, vcc, 0, v32, vcc
	v_sub_u32_e32 v33, 0, v72
	v_ldexp_f32 v32, v27, v33
	v_mul_f32_e64 v27, |v29|, s8
	v_exp_f32_e32 v27, v27
	v_ldexp_f32 v40, v31, v33
	v_min_f32_e32 v31, 0, v29
	v_add_f32_e32 v29, 1.0, v27
	v_add_f32_e32 v33, -1.0, v29
	v_sub_f32_e32 v41, v33, v29
	v_add_f32_e32 v41, 1.0, v41
	v_sub_f32_e32 v33, v27, v33
	v_add_f32_e32 v41, v33, v41
	v_frexp_mant_f32_e32 v33, v29
	v_cvt_f64_f32_e32 v[44:45], v29
	v_cmp_gt_f32_e32 vcc, s9, v33
	v_frexp_exp_i32_f64_e32 v33, v[44:45]
	s_nop 0
	v_subbrev_co_u32_e32 v73, vcc, 0, v33, vcc
	v_sub_u32_e32 v44, 0, v73
	v_ldexp_f32 v33, v29, v44
	v_ldexp_f32 v41, v41, v44
	v_pk_add_f32 v[44:45], v[32:33], 1.0 op_sel_hi:[1,0]
	v_pk_add_f32 v[60:61], v[32:33], -1.0 op_sel_hi:[1,0]
	v_pk_add_f32 v[48:49], v[44:45], -1.0 op_sel_hi:[1,0]
	v_pk_add_f32 v[62:63], v[60:61], 1.0 op_sel_hi:[1,0]
	v_pk_add_f32 v[48:49], v[32:33], v[48:49] neg_lo:[0,1] neg_hi:[0,1]
	v_pk_add_f32 v[32:33], v[32:33], v[62:63] neg_lo:[0,1] neg_hi:[0,1]
	v_pk_add_f32 v[48:49], v[40:41], v[48:49]
	v_pk_add_f32 v[32:33], v[40:41], v[32:33]
	v_pk_add_f32 v[52:53], v[44:45], v[48:49]
	v_pk_add_f32 v[40:41], v[60:61], v[32:33]
	v_rcp_f32_e32 v56, v52
	v_rcp_f32_e32 v57, v53
	v_pk_add_f32 v[44:45], v[52:53], v[44:45] neg_lo:[0,1] neg_hi:[0,1]
	v_pk_add_f32 v[60:61], v[40:41], v[60:61] neg_lo:[0,1] neg_hi:[0,1]
	v_pk_add_f32 v[44:45], v[48:49], v[44:45] neg_lo:[0,1] neg_hi:[0,1]
	v_pk_mul_f32 v[48:49], v[40:41], v[56:57]
	v_pk_add_f32 v[32:33], v[32:33], v[60:61] neg_lo:[0,1] neg_hi:[0,1]
	v_pk_mul_f32 v[60:61], v[52:53], v[48:49]
	v_cmp_neq_f32_e32 vcc, s17, v0
	v_pk_fma_f32 v[62:63], v[48:49], v[52:53], v[60:61] neg_lo:[0,0,1] neg_hi:[0,0,1]
	s_nop 0
	v_pk_fma_f32 v[62:63], v[48:49], v[44:45], v[62:63]
	s_nop 0
	v_pk_add_f32 v[64:65], v[60:61], v[62:63]
	s_nop 0
	v_pk_add_f32 v[68:69], v[40:41], v[64:65] neg_lo:[0,1] neg_hi:[0,1]
	v_pk_add_f32 v[60:61], v[64:65], v[60:61] neg_lo:[0,1] neg_hi:[0,1]
	v_pk_add_f32 v[40:41], v[40:41], v[68:69] neg_lo:[0,1] neg_hi:[0,1]
	s_nop 0
	v_pk_add_f32 v[40:41], v[40:41], v[64:65] neg_lo:[0,1] neg_hi:[0,1]
	s_nop 0
	v_pk_add_f32 v[32:33], v[32:33], v[40:41]
	v_pk_add_f32 v[40:41], v[60:61], v[62:63] neg_lo:[0,1] neg_hi:[0,1]
	s_nop 0
	v_pk_add_f32 v[32:33], v[40:41], v[32:33]
	s_nop 0
	v_pk_add_f32 v[40:41], v[68:69], v[32:33]
	s_nop 0
	v_pk_mul_f32 v[60:61], v[56:57], v[40:41]
	s_nop 0
	v_pk_mul_f32 v[62:63], v[52:53], v[60:61]
	s_nop 0
	v_pk_fma_f32 v[52:53], v[60:61], v[52:53], v[62:63] neg_lo:[0,0,1] neg_hi:[0,0,1]
	s_nop 0
	v_pk_fma_f32 v[44:45], v[60:61], v[44:45], v[52:53]
	v_pk_add_f32 v[52:53], v[68:69], v[40:41] neg_lo:[0,1] neg_hi:[0,1]
	s_nop 0
	v_pk_add_f32 v[32:33], v[32:33], v[52:53]
	v_pk_add_f32 v[52:53], v[62:63], v[44:45]
	s_nop 0
	v_pk_add_f32 v[64:65], v[40:41], v[52:53] neg_lo:[0,1] neg_hi:[0,1]
	v_pk_add_f32 v[62:63], v[52:53], v[62:63] neg_lo:[0,1] neg_hi:[0,1]
	v_pk_add_f32 v[40:41], v[40:41], v[64:65] neg_lo:[0,1] neg_hi:[0,1]
	s_nop 0
	v_pk_add_f32 v[40:41], v[40:41], v[52:53] neg_lo:[0,1] neg_hi:[0,1]
	s_nop 0
	v_pk_add_f32 v[32:33], v[32:33], v[40:41]
	v_pk_add_f32 v[40:41], v[62:63], v[44:45] neg_lo:[0,1] neg_hi:[0,1]
	s_nop 0
	v_pk_add_f32 v[32:33], v[40:41], v[32:33]
	v_pk_add_f32 v[40:41], v[48:49], v[60:61]
	v_pk_add_f32 v[32:33], v[64:65], v[32:33]
	v_pk_add_f32 v[44:45], v[40:41], v[48:49] neg_lo:[0,1] neg_hi:[0,1]
	v_pk_mul_f32 v[32:33], v[56:57], v[32:33]
	v_pk_add_f32 v[44:45], v[60:61], v[44:45] neg_lo:[0,1] neg_hi:[0,1]
	s_nop 0
	v_pk_add_f32 v[32:33], v[44:45], v[32:33]
; __device__ __forceinline__ float log_sigmoid_f(float v) { return fminf(v, 0.f) - log1pf(__expf(-fabsf(v))); }
;     __device__ __forceinline__ void operator()(const f32x4 (&acc)[2][2][4][2], const pg8::Unit& u, int wr, int wc, int fr, int fq) const {
;     ...
;                 for (int nn = 0; nn < 2; ++nn) { const int head = 2 * fq + nn; const f32x4 gb = *(const f32x4*)(gate_b + 4 * head);
; #pragma unroll
;                     for (int ai = 0; ai < 2; ++ai)
; #pragma unroll
;                         for (int m = 0; m < 4; ++m) { const int row = row0 + ai * 128 + m * 16; f32x4 v = acc[ai][0][m][nn] + gb;
;                             v[1] = log_sigmoid_f(v[1]); v[3] = log_sigmoid_f(v[3]);
;                             *(f32x4*)(G + (size_t)row * 16 + 4 * head) = v; } }
	s_nop 0
	v_pk_add_f32 v[44:45], v[40:41], v[32:33]
	s_nop 0
	v_pk_mul_f32 v[48:49], v[44:45], v[44:45]
	v_pk_add_f32 v[40:41], v[44:45], v[40:41] neg_lo:[0,1] neg_hi:[0,1]
	v_pk_fma_f32 v[52:53], v[48:49], s[34:35], v[70:71] op_sel_hi:[1,0,0]
	v_pk_add_f32 v[32:33], v[32:33], v[40:41] neg_lo:[0,1] neg_hi:[0,1]
	v_ldexp_f32 v40, v44, 1
	v_pk_fma_f32 v[52:53], v[48:49], v[52:53], s[36:37] op_sel_hi:[1,1,0]
	v_ldexp_f32 v41, v45, 1
	v_pk_mul_f32 v[44:45], v[44:45], v[48:49]
	v_cvt_f32_i32_e32 v49, v73
	v_cvt_f32_i32_e32 v48, v72
	v_pk_mul_f32 v[44:45], v[44:45], v[52:53]
	v_ldexp_f32 v57, v33, 1
	v_pk_add_f32 v[52:53], v[40:41], v[44:45]
	v_pk_mul_f32 v[60:61], v[48:49], s[38:39] op_sel_hi:[1,0]
	v_pk_add_f32 v[40:41], v[52:53], v[40:41] neg_lo:[0,1] neg_hi:[0,1]
	v_pk_fma_f32 v[62:63], v[48:49], s[38:39], v[60:61] op_sel_hi:[1,0,1] neg_lo:[0,0,1] neg_hi:[0,0,1]
	v_pk_add_f32 v[40:41], v[44:45], v[40:41] neg_lo:[0,1] neg_hi:[0,1]
	v_pk_fma_f32 v[48:49], v[48:49], s[40:41], v[62:63] op_sel_hi:[1,0,1]
	v_ldexp_f32 v32, v32, 1
	v_mov_b32_e32 v44, v60
	v_mov_b32_e32 v45, v41
	v_mov_b32_e32 v56, v48
	v_mov_b32_e32 v33, v57
	v_pk_add_f32 v[44:45], v[44:45], v[56:57]
	v_pk_add_f32 v[56:57], v[32:33], v[40:41]
	v_mov_b32_e32 v41, v53
	v_mov_b32_e32 v33, v57
	v_pk_add_f32 v[62:63], v[60:61], v[48:49]
	v_pk_add_f32 v[32:33], v[32:33], v[40:41]
	v_pk_add_f32 v[40:41], v[52:53], v[56:57]
	v_mov_b32_e32 v76, v52
	v_pk_add_f32 v[64:65], v[62:63], v[40:41]
	v_mov_b32_e32 v74, v40
	v_mov_b32_e32 v75, v65
	v_mov_b32_e32 v77, v63
	v_pk_add_f32 v[74:75], v[74:75], v[76:77] neg_lo:[0,1] neg_hi:[0,1]
	v_mov_b32_e32 v68, v64
	v_mov_b32_e32 v69, v63
	v_mov_b32_e32 v72, v62
	v_mov_b32_e32 v73, v61
	v_mov_b32_e32 v76, v62
	v_mov_b32_e32 v77, v65
	v_mov_b32_e32 v61, v75
	v_pk_add_f32 v[68:69], v[68:69], v[72:73] neg_lo:[0,1] neg_hi:[0,1]
	v_mov_b32_e32 v72, v40
	v_mov_b32_e32 v73, v49
	v_pk_add_f32 v[60:61], v[76:77], v[60:61] neg_lo:[0,1] neg_hi:[0,1]
	v_pk_add_f32 v[72:73], v[72:73], v[68:69] neg_lo:[0,1] neg_hi:[0,1]
	v_mov_b32_e32 v76, v60
	v_mov_b32_e32 v77, v69
	v_mov_b32_e32 v78, v64
	v_mov_b32_e32 v79, v41
	v_mov_b32_e32 v69, v53
	v_pk_add_f32 v[76:77], v[48:49], v[76:77] neg_lo:[0,1] neg_hi:[0,1]
	v_pk_add_f32 v[68:69], v[78:79], v[68:69] neg_lo:[0,1] neg_hi:[0,1]
	v_mov_b32_e32 v49, v63
	v_pk_add_f32 v[44:45], v[44:45], v[68:69] neg_lo:[0,1] neg_hi:[0,1]
	v_pk_add_f32 v[48:49], v[48:49], v[60:61] neg_lo:[0,1] neg_hi:[0,1]
	v_pk_add_f32 v[32:33], v[32:33], v[74:75] neg_lo:[0,1] neg_hi:[0,1]
	v_pk_add_f32 v[40:41], v[40:41], v[52:53] neg_lo:[0,1] neg_hi:[0,1]
	v_pk_add_f32 v[52:53], v[32:33], v[48:49]
	v_mov_b32_e32 v49, v73
	v_mov_b32_e32 v33, v45
	v_pk_add_f32 v[40:41], v[56:57], v[40:41] neg_lo:[0,1] neg_hi:[0,1]
	v_pk_add_f32 v[56:57], v[72:73], v[44:45]
	v_pk_add_f32 v[32:33], v[48:49], v[32:33]
	v_mov_b32_e32 v44, v52
	v_pk_add_f32 v[32:33], v[32:33], v[76:77] neg_lo:[0,1] neg_hi:[0,1]
	v_mov_b32_e32 v45, v57
	v_pk_add_f32 v[44:45], v[44:45], v[32:33] neg_lo:[0,1] neg_hi:[0,1]
	v_pk_add_f32 v[32:33], v[40:41], v[32:33] neg_lo:[0,1] neg_hi:[0,1]
	v_pk_add_f32 v[44:45], v[48:49], v[44:45] neg_lo:[0,1] neg_hi:[0,1]
	v_pk_add_f32 v[40:41], v[56:57], v[52:53]
	v_pk_add_f32 v[32:33], v[32:33], v[44:45]
	v_pk_add_f32 v[44:45], v[64:65], v[40:41]
	s_nop 0
	v_pk_add_f32 v[48:49], v[44:45], v[64:65] neg_lo:[0,1] neg_hi:[0,1]
	s_nop 0
	v_pk_add_f32 v[40:41], v[40:41], v[48:49] neg_lo:[0,1] neg_hi:[0,1]
	s_nop 0
	v_pk_add_f32 v[32:33], v[32:33], v[40:41]
	s_nop 0
	v_pk_add_f32 v[32:33], v[44:45], v[32:33]
	s_nop 0
	v_cndmask_b32_e32 v29, v199, v32, vcc
	v_cmp_neq_f32_e32 vcc, s17, v27
	s_nop 1
	v_cndmask_b32_e32 v32, v199, v33, vcc
	v_cmp_ngt_f32_e32 vcc, -1.0, v27
	s_nop 1
	v_cndmask_b32_e32 v32, v200, v32, vcc
	v_cmp_ngt_f32_e32 vcc, -1.0, v0
	s_nop 1
	v_cndmask_b32_e32 v29, v200, v29, vcc
	v_cmp_neq_f32_e32 vcc, -1.0, v0
	s_nop 1
	v_cndmask_b32_e32 v29, v201, v29, vcc
	v_cmp_neq_f32_e32 vcc, -1.0, v27
	s_nop 1
	v_cndmask_b32_e32 v32, v201, v32, vcc
	v_cmp_lt_f32_e64 vcc, |v27|, s19
	s_nop 1
	v_cndmask_b32_e32 v33, v32, v27, vcc
	v_cndmask_b32_e64 v32, v29, v0, s[0:1]
	v_mul_f32_e64 v0, |v23|, s8
	v_exp_f32_e32 v0, v0
	v_pk_add_f32 v[30:31], v[30:31], v[32:33] neg_lo:[0,1] neg_hi:[0,1]
	v_cmp_lt_f32_e64 s[0:1], |v0|, s19
	v_mov_b32_e32 v27, v30
	v_mov_b32_e32 v29, v31
	global_store_dwordx4 v[66:67], v[26:29], off offset:16
	s_nop 1
	v_min_f32_e32 v26, 0, v23
	v_add_f32_e32 v23, 1.0, v0
	v_add_f32_e32 v27, -1.0, v23
	v_sub_f32_e32 v28, v27, v23
	v_add_f32_e32 v28, 1.0, v28
	v_sub_f32_e32 v27, v0, v27
	v_add_f32_e32 v27, v27, v28
	v_frexp_mant_f32_e32 v28, v23
	v_cmp_gt_f32_e32 vcc, s9, v28
	v_cvt_f64_f32_e32 v[28:29], v23
	v_frexp_exp_i32_f64_e32 v28, v[28:29]
	v_subbrev_co_u32_e32 v64, vcc, 0, v28, vcc
	v_sub_u32_e32 v29, 0, v64
	v_ldexp_f32 v28, v23, v29
	v_mul_f32_e64 v23, |v25|, s8
	v_exp_f32_e32 v23, v23
	v_ldexp_f32 v30, v27, v29
	v_min_f32_e32 v27, 0, v25
	v_add_f32_e32 v25, 1.0, v23
	v_add_f32_e32 v29, -1.0, v25
	v_sub_f32_e32 v31, v29, v25
	v_add_f32_e32 v31, 1.0, v31
	v_sub_f32_e32 v29, v23, v29
	v_add_f32_e32 v31, v29, v31
	v_frexp_mant_f32_e32 v29, v25
	v_cvt_f64_f32_e32 v[32:33], v25
	v_cmp_gt_f32_e32 vcc, s9, v29
	v_frexp_exp_i32_f64_e32 v29, v[32:33]
	s_nop 0
	v_subbrev_co_u32_e32 v65, vcc, 0, v29, vcc
	v_sub_u32_e32 v32, 0, v65
	v_ldexp_f32 v29, v25, v32
	v_ldexp_f32 v31, v31, v32
	v_pk_add_f32 v[32:33], v[28:29], 1.0 op_sel_hi:[1,0]
	v_pk_add_f32 v[52:53], v[28:29], -1.0 op_sel_hi:[1,0]
	v_pk_add_f32 v[40:41], v[32:33], -1.0 op_sel_hi:[1,0]
	v_pk_add_f32 v[56:57], v[52:53], 1.0 op_sel_hi:[1,0]
	v_pk_add_f32 v[40:41], v[28:29], v[40:41] neg_lo:[0,1] neg_hi:[0,1]
; __device__ __forceinline__ float log_sigmoid_f(float v) { return fminf(v, 0.f) - log1pf(__expf(-fabsf(v))); }
;     __device__ __forceinline__ void operator()(const f32x4 (&acc)[2][2][4][2], const pg8::Unit& u, int wr, int wc, int fr, int fq) const {
;     ...
;                 for (int nn = 0; nn < 2; ++nn) { const int head = 2 * fq + nn; const f32x4 gb = *(const f32x4*)(gate_b + 4 * head);
; #pragma unroll
;                     for (int ai = 0; ai < 2; ++ai)
; #pragma unroll
;                         for (int m = 0; m < 4; ++m) { const int row = row0 + ai * 128 + m * 16; f32x4 v = acc[ai][0][m][nn] + gb;
;                             v[1] = log_sigmoid_f(v[1]); v[3] = log_sigmoid_f(v[3]);
;                             *(f32x4*)(G + (size_t)row * 16 + 4 * head) = v; } }
	v_pk_add_f32 v[28:29], v[28:29], v[56:57] neg_lo:[0,1] neg_hi:[0,1]
	v_pk_add_f32 v[40:41], v[30:31], v[40:41]
	v_pk_add_f32 v[28:29], v[30:31], v[28:29]
	v_pk_add_f32 v[44:45], v[32:33], v[40:41]
	v_pk_add_f32 v[30:31], v[52:53], v[28:29]
	v_rcp_f32_e32 v48, v44
	v_rcp_f32_e32 v49, v45
	v_pk_add_f32 v[32:33], v[44:45], v[32:33] neg_lo:[0,1] neg_hi:[0,1]
	v_pk_add_f32 v[52:53], v[30:31], v[52:53] neg_lo:[0,1] neg_hi:[0,1]
	v_pk_add_f32 v[32:33], v[40:41], v[32:33] neg_lo:[0,1] neg_hi:[0,1]
	v_pk_mul_f32 v[40:41], v[30:31], v[48:49]
	v_pk_add_f32 v[28:29], v[28:29], v[52:53] neg_lo:[0,1] neg_hi:[0,1]
	v_pk_mul_f32 v[52:53], v[44:45], v[40:41]
	v_cmp_neq_f32_e32 vcc, s17, v0
	v_pk_fma_f32 v[56:57], v[40:41], v[44:45], v[52:53] neg_lo:[0,0,1] neg_hi:[0,0,1]
	s_nop 0
	v_pk_fma_f32 v[56:57], v[40:41], v[32:33], v[56:57]
	s_nop 0
	v_pk_add_f32 v[60:61], v[52:53], v[56:57]
	s_nop 0
	v_pk_add_f32 v[62:63], v[30:31], v[60:61] neg_lo:[0,1] neg_hi:[0,1]
	v_pk_add_f32 v[52:53], v[60:61], v[52:53] neg_lo:[0,1] neg_hi:[0,1]
	v_pk_add_f32 v[30:31], v[30:31], v[62:63] neg_lo:[0,1] neg_hi:[0,1]
	s_nop 0
	v_pk_add_f32 v[30:31], v[30:31], v[60:61] neg_lo:[0,1] neg_hi:[0,1]
	s_nop 0
	v_pk_add_f32 v[28:29], v[28:29], v[30:31]
	v_pk_add_f32 v[30:31], v[52:53], v[56:57] neg_lo:[0,1] neg_hi:[0,1]
	s_nop 0
	v_pk_add_f32 v[28:29], v[30:31], v[28:29]
	s_nop 0
	v_pk_add_f32 v[30:31], v[62:63], v[28:29]
	s_nop 0
	v_pk_mul_f32 v[52:53], v[48:49], v[30:31]
	s_nop 0
	v_pk_mul_f32 v[56:57], v[44:45], v[52:53]
	s_nop 0
	v_pk_fma_f32 v[44:45], v[52:53], v[44:45], v[56:57] neg_lo:[0,0,1] neg_hi:[0,0,1]
	s_nop 0
	v_pk_fma_f32 v[32:33], v[52:53], v[32:33], v[44:45]
	v_pk_add_f32 v[44:45], v[62:63], v[30:31] neg_lo:[0,1] neg_hi:[0,1]
	s_nop 0
	v_pk_add_f32 v[28:29], v[28:29], v[44:45]
	v_pk_add_f32 v[44:45], v[56:57], v[32:33]
	s_nop 0
	v_pk_add_f32 v[60:61], v[30:31], v[44:45] neg_lo:[0,1] neg_hi:[0,1]
	v_pk_add_f32 v[56:57], v[44:45], v[56:57] neg_lo:[0,1] neg_hi:[0,1]
	v_pk_add_f32 v[30:31], v[30:31], v[60:61] neg_lo:[0,1] neg_hi:[0,1]
	s_nop 0
	v_pk_add_f32 v[30:31], v[30:31], v[44:45] neg_lo:[0,1] neg_hi:[0,1]
	s_nop 0
	v_pk_add_f32 v[28:29], v[28:29], v[30:31]
	v_pk_add_f32 v[30:31], v[56:57], v[32:33] neg_lo:[0,1] neg_hi:[0,1]
	s_nop 0
	v_pk_add_f32 v[28:29], v[30:31], v[28:29]
	v_pk_add_f32 v[30:31], v[40:41], v[52:53]
	v_pk_add_f32 v[28:29], v[60:61], v[28:29]
	v_pk_add_f32 v[32:33], v[30:31], v[40:41] neg_lo:[0,1] neg_hi:[0,1]
	v_pk_mul_f32 v[28:29], v[48:49], v[28:29]
	v_pk_add_f32 v[32:33], v[52:53], v[32:33] neg_lo:[0,1] neg_hi:[0,1]
	s_nop 0
	v_pk_add_f32 v[28:29], v[32:33], v[28:29]
	s_nop 0
	v_pk_add_f32 v[32:33], v[30:31], v[28:29]
	s_nop 0
	v_pk_mul_f32 v[40:41], v[32:33], v[32:33]
	v_pk_add_f32 v[30:31], v[32:33], v[30:31] neg_lo:[0,1] neg_hi:[0,1]
	v_pk_fma_f32 v[44:45], v[40:41], s[34:35], v[70:71] op_sel_hi:[1,0,0]
	v_pk_add_f32 v[28:29], v[28:29], v[30:31] neg_lo:[0,1] neg_hi:[0,1]
	v_ldexp_f32 v30, v32, 1
	v_pk_fma_f32 v[44:45], v[40:41], v[44:45], s[36:37] op_sel_hi:[1,1,0]
	v_ldexp_f32 v31, v33, 1
	v_pk_mul_f32 v[32:33], v[32:33], v[40:41]
	v_cvt_f32_i32_e32 v41, v65
	v_cvt_f32_i32_e32 v40, v64
	v_pk_mul_f32 v[32:33], v[32:33], v[44:45]
	v_ldexp_f32 v49, v29, 1
	v_pk_add_f32 v[44:45], v[30:31], v[32:33]
	v_pk_mul_f32 v[52:53], v[40:41], s[38:39] op_sel_hi:[1,0]
	v_pk_add_f32 v[30:31], v[44:45], v[30:31] neg_lo:[0,1] neg_hi:[0,1]
	v_pk_fma_f32 v[56:57], v[40:41], s[38:39], v[52:53] op_sel_hi:[1,0,1] neg_lo:[0,0,1] neg_hi:[0,0,1]
	v_pk_add_f32 v[30:31], v[32:33], v[30:31] neg_lo:[0,1] neg_hi:[0,1]
	v_pk_fma_f32 v[40:41], v[40:41], s[40:41], v[56:57] op_sel_hi:[1,0,1]
	v_ldexp_f32 v28, v28, 1
	v_mov_b32_e32 v32, v52
	v_mov_b32_e32 v33, v31
	v_mov_b32_e32 v48, v40
	v_mov_b32_e32 v29, v49
	v_pk_add_f32 v[32:33], v[32:33], v[48:49]
	v_pk_add_f32 v[48:49], v[28:29], v[30:31]
	v_mov_b32_e32 v31, v45
	v_mov_b32_e32 v29, v49
	v_pk_add_f32 v[56:57], v[52:53], v[40:41]
	v_pk_add_f32 v[28:29], v[28:29], v[30:31]
	v_pk_add_f32 v[30:31], v[44:45], v[48:49]
	v_mov_b32_e32 v68, v44
	v_pk_add_f32 v[60:61], v[56:57], v[30:31]
	v_mov_b32_e32 v66, v30
	v_mov_b32_e32 v67, v61
	v_mov_b32_e32 v69, v57
	v_pk_add_f32 v[66:67], v[66:67], v[68:69] neg_lo:[0,1] neg_hi:[0,1]
	v_mov_b32_e32 v62, v60
	v_mov_b32_e32 v63, v57
	v_mov_b32_e32 v64, v56
	v_mov_b32_e32 v65, v53
	v_mov_b32_e32 v68, v56
	v_mov_b32_e32 v69, v61
	v_mov_b32_e32 v53, v67
	v_pk_add_f32 v[62:63], v[62:63], v[64:65] neg_lo:[0,1] neg_hi:[0,1]
	v_mov_b32_e32 v64, v30
	v_mov_b32_e32 v65, v41
	v_pk_add_f32 v[52:53], v[68:69], v[52:53] neg_lo:[0,1] neg_hi:[0,1]
	v_pk_add_f32 v[64:65], v[64:65], v[62:63] neg_lo:[0,1] neg_hi:[0,1]
	v_mov_b32_e32 v68, v52
	v_mov_b32_e32 v69, v63
	v_mov_b32_e32 v72, v60
	v_mov_b32_e32 v73, v31
	v_mov_b32_e32 v63, v45
	v_pk_add_f32 v[68:69], v[40:41], v[68:69] neg_lo:[0,1] neg_hi:[0,1]
	v_pk_add_f32 v[62:63], v[72:73], v[62:63] neg_lo:[0,1] neg_hi:[0,1]
	v_mov_b32_e32 v41, v57
	v_pk_add_f32 v[32:33], v[32:33], v[62:63] neg_lo:[0,1] neg_hi:[0,1]
	v_pk_add_f32 v[40:41], v[40:41], v[52:53] neg_lo:[0,1] neg_hi:[0,1]
	v_pk_add_f32 v[28:29], v[28:29], v[66:67] neg_lo:[0,1] neg_hi:[0,1]
	v_pk_add_f32 v[30:31], v[30:31], v[44:45] neg_lo:[0,1] neg_hi:[0,1]
	v_pk_add_f32 v[44:45], v[28:29], v[40:41]
	v_mov_b32_e32 v41, v65
	v_mov_b32_e32 v29, v33
	v_pk_add_f32 v[30:31], v[48:49], v[30:31] neg_lo:[0,1] neg_hi:[0,1]
	v_pk_add_f32 v[48:49], v[64:65], v[32:33]
	v_pk_add_f32 v[28:29], v[40:41], v[28:29]
	v_mov_b32_e32 v32, v44
	v_pk_add_f32 v[28:29], v[28:29], v[68:69] neg_lo:[0,1] neg_hi:[0,1]
	v_mov_b32_e32 v33, v49
	v_pk_add_f32 v[32:33], v[32:33], v[28:29] neg_lo:[0,1] neg_hi:[0,1]
; __device__ __forceinline__ float log_sigmoid_f(float v) { return fminf(v, 0.f) - log1pf(__expf(-fabsf(v))); }
;     __device__ __forceinline__ void operator()(const f32x4 (&acc)[2][2][4][2], const pg8::Unit& u, int wr, int wc, int fr, int fq) const {
;     ...
;                 for (int nn = 0; nn < 2; ++nn) { const int head = 2 * fq + nn; const f32x4 gb = *(const f32x4*)(gate_b + 4 * head);
; #pragma unroll
;                     for (int ai = 0; ai < 2; ++ai)
; #pragma unroll
;                         for (int m = 0; m < 4; ++m) { const int row = row0 + ai * 128 + m * 16; f32x4 v = acc[ai][0][m][nn] + gb;
;                             v[1] = log_sigmoid_f(v[1]); v[3] = log_sigmoid_f(v[3]);
;                             *(f32x4*)(G + (size_t)row * 16 + 4 * head) = v; } }
	v_pk_add_f32 v[28:29], v[30:31], v[28:29] neg_lo:[0,1] neg_hi:[0,1]
	v_pk_add_f32 v[32:33], v[40:41], v[32:33] neg_lo:[0,1] neg_hi:[0,1]
	v_pk_add_f32 v[30:31], v[48:49], v[44:45]
	v_pk_add_f32 v[28:29], v[28:29], v[32:33]
	v_pk_add_f32 v[32:33], v[60:61], v[30:31]
	s_nop 0
	v_pk_add_f32 v[40:41], v[32:33], v[60:61] neg_lo:[0,1] neg_hi:[0,1]
	s_nop 0
	v_pk_add_f32 v[30:31], v[30:31], v[40:41] neg_lo:[0,1] neg_hi:[0,1]
	s_nop 0
	v_pk_add_f32 v[28:29], v[28:29], v[30:31]
	s_nop 0
	v_pk_add_f32 v[28:29], v[32:33], v[28:29]
	s_nop 0
	v_cndmask_b32_e32 v25, v199, v28, vcc
	v_cmp_neq_f32_e32 vcc, s17, v23
	s_nop 1
	v_cndmask_b32_e32 v28, v199, v29, vcc
	v_cmp_ngt_f32_e32 vcc, -1.0, v23
	s_nop 1
	v_cndmask_b32_e32 v28, v200, v28, vcc
	v_cmp_ngt_f32_e32 vcc, -1.0, v0
	s_nop 1
	v_cndmask_b32_e32 v25, v200, v25, vcc
	v_cmp_neq_f32_e32 vcc, -1.0, v0
	s_nop 1
	v_cndmask_b32_e32 v25, v201, v25, vcc
	v_cmp_neq_f32_e32 vcc, -1.0, v23
	s_nop 1
	v_cndmask_b32_e32 v28, v201, v28, vcc
	v_cmp_lt_f32_e64 vcc, |v23|, s19
	s_nop 1
	v_cndmask_b32_e32 v29, v28, v23, vcc
	v_cndmask_b32_e64 v28, v25, v0, s[0:1]
	v_mul_f32_e64 v0, |v19|, s8
	v_exp_f32_e32 v0, v0
	v_pk_add_f32 v[26:27], v[26:27], v[28:29] neg_lo:[0,1] neg_hi:[0,1]
	v_cmp_lt_f32_e64 s[0:1], |v0|, s19
	v_mov_b32_e32 v23, v26
	v_mov_b32_e32 v25, v27
	global_store_dwordx4 v[58:59], v[22:25], off offset:16
	s_nop 1
	v_min_f32_e32 v22, 0, v19
	v_add_f32_e32 v19, 1.0, v0
	v_add_f32_e32 v23, -1.0, v19
	v_sub_f32_e32 v24, v23, v19
	v_add_f32_e32 v24, 1.0, v24
	v_sub_f32_e32 v23, v0, v23
	v_add_f32_e32 v23, v23, v24
	v_frexp_mant_f32_e32 v24, v19
	v_cmp_gt_f32_e32 vcc, s9, v24
	v_cvt_f64_f32_e32 v[24:25], v19
	v_frexp_exp_i32_f64_e32 v24, v[24:25]
	v_subbrev_co_u32_e32 v58, vcc, 0, v24, vcc
	v_sub_u32_e32 v25, 0, v58
	v_ldexp_f32 v24, v19, v25
	v_mul_f32_e64 v19, |v21|, s8
	v_exp_f32_e32 v19, v19
	v_ldexp_f32 v26, v23, v25
	v_min_f32_e32 v23, 0, v21
	v_add_f32_e32 v21, 1.0, v19
	v_add_f32_e32 v25, -1.0, v21
	v_sub_f32_e32 v27, v25, v21
	v_add_f32_e32 v27, 1.0, v27
	v_sub_f32_e32 v25, v19, v25
	v_add_f32_e32 v27, v25, v27
	v_frexp_mant_f32_e32 v25, v21
	v_cvt_f64_f32_e32 v[28:29], v21
	v_cmp_gt_f32_e32 vcc, s9, v25
	v_frexp_exp_i32_f64_e32 v25, v[28:29]
	s_nop 0
	v_subbrev_co_u32_e32 v59, vcc, 0, v25, vcc
	v_sub_u32_e32 v28, 0, v59
	v_ldexp_f32 v25, v21, v28
	v_ldexp_f32 v27, v27, v28
	v_pk_add_f32 v[28:29], v[24:25], 1.0 op_sel_hi:[1,0]
	v_pk_add_f32 v[44:45], v[24:25], -1.0 op_sel_hi:[1,0]
	v_pk_add_f32 v[30:31], v[28:29], -1.0 op_sel_hi:[1,0]
	v_pk_add_f32 v[48:49], v[44:45], 1.0 op_sel_hi:[1,0]
	v_pk_add_f32 v[30:31], v[24:25], v[30:31] neg_lo:[0,1] neg_hi:[0,1]
	v_pk_add_f32 v[24:25], v[24:25], v[48:49] neg_lo:[0,1] neg_hi:[0,1]
	v_pk_add_f32 v[30:31], v[26:27], v[30:31]
	v_pk_add_f32 v[24:25], v[26:27], v[24:25]
	v_pk_add_f32 v[32:33], v[28:29], v[30:31]
	v_pk_add_f32 v[26:27], v[44:45], v[24:25]
	v_rcp_f32_e32 v40, v32
	v_rcp_f32_e32 v41, v33
	v_pk_add_f32 v[28:29], v[32:33], v[28:29] neg_lo:[0,1] neg_hi:[0,1]
	v_pk_add_f32 v[44:45], v[26:27], v[44:45] neg_lo:[0,1] neg_hi:[0,1]
	v_pk_add_f32 v[28:29], v[30:31], v[28:29] neg_lo:[0,1] neg_hi:[0,1]
	v_pk_mul_f32 v[30:31], v[26:27], v[40:41]
	v_pk_add_f32 v[24:25], v[24:25], v[44:45] neg_lo:[0,1] neg_hi:[0,1]
	v_pk_mul_f32 v[44:45], v[32:33], v[30:31]
	v_cmp_neq_f32_e32 vcc, s17, v0
	v_pk_fma_f32 v[48:49], v[30:31], v[32:33], v[44:45] neg_lo:[0,0,1] neg_hi:[0,0,1]
	s_nop 0
	v_pk_fma_f32 v[48:49], v[30:31], v[28:29], v[48:49]
	s_nop 0
	v_pk_add_f32 v[52:53], v[44:45], v[48:49]
	s_nop 0
	v_pk_add_f32 v[56:57], v[26:27], v[52:53] neg_lo:[0,1] neg_hi:[0,1]
	v_pk_add_f32 v[44:45], v[52:53], v[44:45] neg_lo:[0,1] neg_hi:[0,1]
	v_pk_add_f32 v[26:27], v[26:27], v[56:57] neg_lo:[0,1] neg_hi:[0,1]
	s_nop 0
	v_pk_add_f32 v[26:27], v[26:27], v[52:53] neg_lo:[0,1] neg_hi:[0,1]
	s_nop 0
	v_pk_add_f32 v[24:25], v[24:25], v[26:27]
	v_pk_add_f32 v[26:27], v[44:45], v[48:49] neg_lo:[0,1] neg_hi:[0,1]
	s_nop 0
	v_pk_add_f32 v[24:25], v[26:27], v[24:25]
	s_nop 0
	v_pk_add_f32 v[26:27], v[56:57], v[24:25]
	s_nop 0
	v_pk_mul_f32 v[44:45], v[40:41], v[26:27]
	s_nop 0
	v_pk_mul_f32 v[48:49], v[32:33], v[44:45]
	s_nop 0
	v_pk_fma_f32 v[32:33], v[44:45], v[32:33], v[48:49] neg_lo:[0,0,1] neg_hi:[0,0,1]
	s_nop 0
	v_pk_fma_f32 v[28:29], v[44:45], v[28:29], v[32:33]
	v_pk_add_f32 v[32:33], v[56:57], v[26:27] neg_lo:[0,1] neg_hi:[0,1]
	s_nop 0
	v_pk_add_f32 v[24:25], v[24:25], v[32:33]
	v_pk_add_f32 v[32:33], v[48:49], v[28:29]
	s_nop 0
	v_pk_add_f32 v[52:53], v[26:27], v[32:33] neg_lo:[0,1] neg_hi:[0,1]
	v_pk_add_f32 v[48:49], v[32:33], v[48:49] neg_lo:[0,1] neg_hi:[0,1]
	v_pk_add_f32 v[26:27], v[26:27], v[52:53] neg_lo:[0,1] neg_hi:[0,1]
	s_nop 0
	v_pk_add_f32 v[26:27], v[26:27], v[32:33] neg_lo:[0,1] neg_hi:[0,1]
	s_nop 0
	v_pk_add_f32 v[24:25], v[24:25], v[26:27]
	v_pk_add_f32 v[26:27], v[48:49], v[28:29] neg_lo:[0,1] neg_hi:[0,1]
	s_nop 0
	v_pk_add_f32 v[24:25], v[26:27], v[24:25]
	v_pk_add_f32 v[26:27], v[30:31], v[44:45]
	v_pk_add_f32 v[24:25], v[52:53], v[24:25]
	v_pk_add_f32 v[28:29], v[26:27], v[30:31] neg_lo:[0,1] neg_hi:[0,1]
	v_pk_mul_f32 v[24:25], v[40:41], v[24:25]
	v_pk_add_f32 v[28:29], v[44:45], v[28:29] neg_lo:[0,1] neg_hi:[0,1]
	s_nop 0
	v_pk_add_f32 v[24:25], v[28:29], v[24:25]
	s_nop 0
	v_pk_add_f32 v[28:29], v[26:27], v[24:25]
	s_nop 0
	v_pk_mul_f32 v[30:31], v[28:29], v[28:29]
	v_pk_add_f32 v[26:27], v[28:29], v[26:27] neg_lo:[0,1] neg_hi:[0,1]
	v_pk_fma_f32 v[32:33], v[30:31], s[34:35], v[70:71] op_sel_hi:[1,0,0]
	v_pk_add_f32 v[24:25], v[24:25], v[26:27] neg_lo:[0,1] neg_hi:[0,1]
	v_ldexp_f32 v26, v28, 1
	v_pk_fma_f32 v[32:33], v[30:31], v[32:33], s[36:37] op_sel_hi:[1,1,0]
; __device__ __forceinline__ float log_sigmoid_f(float v) { return fminf(v, 0.f) - log1pf(__expf(-fabsf(v))); }
;     __device__ __forceinline__ void operator()(const f32x4 (&acc)[2][2][4][2], const pg8::Unit& u, int wr, int wc, int fr, int fq) const {
;     ...
;                 for (int nn = 0; nn < 2; ++nn) { const int head = 2 * fq + nn; const f32x4 gb = *(const f32x4*)(gate_b + 4 * head);
; #pragma unroll
;                     for (int ai = 0; ai < 2; ++ai)
; #pragma unroll
;                         for (int m = 0; m < 4; ++m) { const int row = row0 + ai * 128 + m * 16; f32x4 v = acc[ai][0][m][nn] + gb;
;                             v[1] = log_sigmoid_f(v[1]); v[3] = log_sigmoid_f(v[3]);
;                             *(f32x4*)(G + (size_t)row * 16 + 4 * head) = v; } }
	v_ldexp_f32 v27, v29, 1
	v_pk_mul_f32 v[28:29], v[28:29], v[30:31]
	v_cvt_f32_i32_e32 v31, v59
	v_cvt_f32_i32_e32 v30, v58
	v_pk_mul_f32 v[28:29], v[28:29], v[32:33]
	v_ldexp_f32 v41, v25, 1
	v_pk_add_f32 v[32:33], v[26:27], v[28:29]
	v_pk_mul_f32 v[44:45], v[30:31], s[38:39] op_sel_hi:[1,0]
	v_pk_add_f32 v[26:27], v[32:33], v[26:27] neg_lo:[0,1] neg_hi:[0,1]
	v_pk_fma_f32 v[48:49], v[30:31], s[38:39], v[44:45] op_sel_hi:[1,0,1] neg_lo:[0,0,1] neg_hi:[0,0,1]
	v_pk_add_f32 v[26:27], v[28:29], v[26:27] neg_lo:[0,1] neg_hi:[0,1]
	v_pk_fma_f32 v[30:31], v[30:31], s[40:41], v[48:49] op_sel_hi:[1,0,1]
	v_ldexp_f32 v24, v24, 1
	v_mov_b32_e32 v28, v44
	v_mov_b32_e32 v29, v27
	v_mov_b32_e32 v40, v30
	v_mov_b32_e32 v25, v41
	v_pk_add_f32 v[28:29], v[28:29], v[40:41]
	v_pk_add_f32 v[40:41], v[24:25], v[26:27]
	v_mov_b32_e32 v27, v33
	v_mov_b32_e32 v25, v41
	v_pk_add_f32 v[48:49], v[44:45], v[30:31]
	v_pk_add_f32 v[24:25], v[24:25], v[26:27]
	v_pk_add_f32 v[26:27], v[32:33], v[40:41]
	v_mov_b32_e32 v62, v32
	v_pk_add_f32 v[52:53], v[48:49], v[26:27]
	v_mov_b32_e32 v60, v26
	v_mov_b32_e32 v61, v53
	v_mov_b32_e32 v63, v49
	v_pk_add_f32 v[60:61], v[60:61], v[62:63] neg_lo:[0,1] neg_hi:[0,1]
	v_mov_b32_e32 v56, v52
	v_mov_b32_e32 v57, v49
	v_mov_b32_e32 v58, v48
	v_mov_b32_e32 v59, v45
	v_mov_b32_e32 v62, v48
	v_mov_b32_e32 v63, v53
	v_mov_b32_e32 v45, v61
	v_pk_add_f32 v[56:57], v[56:57], v[58:59] neg_lo:[0,1] neg_hi:[0,1]
	v_mov_b32_e32 v58, v26
	v_mov_b32_e32 v59, v31
	v_pk_add_f32 v[44:45], v[62:63], v[44:45] neg_lo:[0,1] neg_hi:[0,1]
	v_pk_add_f32 v[58:59], v[58:59], v[56:57] neg_lo:[0,1] neg_hi:[0,1]
	v_mov_b32_e32 v62, v44
	v_mov_b32_e32 v63, v57
	v_mov_b32_e32 v64, v52
	v_mov_b32_e32 v65, v27
	v_mov_b32_e32 v57, v33
	v_pk_add_f32 v[62:63], v[30:31], v[62:63] neg_lo:[0,1] neg_hi:[0,1]
	v_pk_add_f32 v[56:57], v[64:65], v[56:57] neg_lo:[0,1] neg_hi:[0,1]
	v_mov_b32_e32 v31, v49
	v_pk_add_f32 v[28:29], v[28:29], v[56:57] neg_lo:[0,1] neg_hi:[0,1]
	v_pk_add_f32 v[30:31], v[30:31], v[44:45] neg_lo:[0,1] neg_hi:[0,1]
	v_pk_add_f32 v[24:25], v[24:25], v[60:61] neg_lo:[0,1] neg_hi:[0,1]
	v_pk_add_f32 v[26:27], v[26:27], v[32:33] neg_lo:[0,1] neg_hi:[0,1]
	v_pk_add_f32 v[32:33], v[24:25], v[30:31]
	v_mov_b32_e32 v31, v59
	v_mov_b32_e32 v25, v29
	v_pk_add_f32 v[26:27], v[40:41], v[26:27] neg_lo:[0,1] neg_hi:[0,1]
	v_pk_add_f32 v[40:41], v[58:59], v[28:29]
	v_pk_add_f32 v[24:25], v[30:31], v[24:25]
	v_mov_b32_e32 v28, v32
	v_pk_add_f32 v[24:25], v[24:25], v[62:63] neg_lo:[0,1] neg_hi:[0,1]
	v_mov_b32_e32 v29, v41
	v_pk_add_f32 v[28:29], v[28:29], v[24:25] neg_lo:[0,1] neg_hi:[0,1]
	v_pk_add_f32 v[24:25], v[26:27], v[24:25] neg_lo:[0,1] neg_hi:[0,1]
	v_pk_add_f32 v[28:29], v[30:31], v[28:29] neg_lo:[0,1] neg_hi:[0,1]
	v_pk_add_f32 v[26:27], v[40:41], v[32:33]
	v_pk_add_f32 v[24:25], v[24:25], v[28:29]
	v_pk_add_f32 v[28:29], v[52:53], v[26:27]
	s_nop 0
	v_pk_add_f32 v[30:31], v[28:29], v[52:53] neg_lo:[0,1] neg_hi:[0,1]
	s_nop 0
	v_pk_add_f32 v[26:27], v[26:27], v[30:31] neg_lo:[0,1] neg_hi:[0,1]
	s_nop 0
	v_pk_add_f32 v[24:25], v[24:25], v[26:27]
	s_nop 0
	v_pk_add_f32 v[24:25], v[28:29], v[24:25]
	s_nop 0
	v_cndmask_b32_e32 v21, v199, v24, vcc
	v_cmp_neq_f32_e32 vcc, s17, v19
	s_nop 1
	v_cndmask_b32_e32 v24, v199, v25, vcc
	v_cmp_ngt_f32_e32 vcc, -1.0, v19
	s_nop 1
	v_cndmask_b32_e32 v24, v200, v24, vcc
	v_cmp_ngt_f32_e32 vcc, -1.0, v0
	s_nop 1
	v_cndmask_b32_e32 v21, v200, v21, vcc
	v_cmp_neq_f32_e32 vcc, -1.0, v0
	s_nop 1
	v_cndmask_b32_e32 v21, v201, v21, vcc
	v_cmp_neq_f32_e32 vcc, -1.0, v19
	s_nop 1
	v_cndmask_b32_e32 v24, v201, v24, vcc
	v_cmp_lt_f32_e64 vcc, |v19|, s19
	s_nop 1
	v_cndmask_b32_e32 v25, v24, v19, vcc
	v_cndmask_b32_e64 v24, v21, v0, s[0:1]
	v_mul_f32_e64 v0, |v15|, s8
	v_exp_f32_e32 v0, v0
	v_pk_add_f32 v[22:23], v[22:23], v[24:25] neg_lo:[0,1] neg_hi:[0,1]
	v_cmp_lt_f32_e64 s[0:1], |v0|, s19
	v_mov_b32_e32 v19, v22
	v_mov_b32_e32 v21, v23
	global_store_dwordx4 v[54:55], v[18:21], off offset:16
	s_nop 1
	v_min_f32_e32 v18, 0, v15
	v_add_f32_e32 v15, 1.0, v0
	v_add_f32_e32 v19, -1.0, v15
	v_sub_f32_e32 v20, v19, v15
	v_add_f32_e32 v20, 1.0, v20
	v_sub_f32_e32 v19, v0, v19
	v_add_f32_e32 v19, v19, v20
	v_frexp_mant_f32_e32 v20, v15
	v_cmp_gt_f32_e32 vcc, s9, v20
	v_cvt_f64_f32_e32 v[20:21], v15
	v_frexp_exp_i32_f64_e32 v20, v[20:21]
	v_subbrev_co_u32_e32 v52, vcc, 0, v20, vcc
	v_sub_u32_e32 v21, 0, v52
	v_ldexp_f32 v20, v15, v21
	v_mul_f32_e64 v15, |v17|, s8
	v_exp_f32_e32 v15, v15
	v_ldexp_f32 v22, v19, v21
	v_min_f32_e32 v19, 0, v17
	v_add_f32_e32 v17, 1.0, v15
	v_add_f32_e32 v21, -1.0, v17
	v_sub_f32_e32 v23, v21, v17
	v_add_f32_e32 v23, 1.0, v23
	v_sub_f32_e32 v21, v15, v21
	v_add_f32_e32 v23, v21, v23
	v_frexp_mant_f32_e32 v21, v17
	v_cvt_f64_f32_e32 v[24:25], v17
	v_cmp_gt_f32_e32 vcc, s9, v21
	v_frexp_exp_i32_f64_e32 v21, v[24:25]
	s_nop 0
	v_subbrev_co_u32_e32 v53, vcc, 0, v21, vcc
	v_sub_u32_e32 v24, 0, v53
	v_ldexp_f32 v21, v17, v24
	v_ldexp_f32 v23, v23, v24
	v_pk_add_f32 v[24:25], v[20:21], 1.0 op_sel_hi:[1,0]
	v_pk_add_f32 v[32:33], v[20:21], -1.0 op_sel_hi:[1,0]
	v_pk_add_f32 v[26:27], v[24:25], -1.0 op_sel_hi:[1,0]
	v_pk_add_f32 v[40:41], v[32:33], 1.0 op_sel_hi:[1,0]
	v_pk_add_f32 v[26:27], v[20:21], v[26:27] neg_lo:[0,1] neg_hi:[0,1]
	v_pk_add_f32 v[20:21], v[20:21], v[40:41] neg_lo:[0,1] neg_hi:[0,1]
	v_pk_add_f32 v[26:27], v[22:23], v[26:27]
	v_pk_add_f32 v[20:21], v[22:23], v[20:21]
	v_pk_add_f32 v[28:29], v[24:25], v[26:27]
	v_pk_add_f32 v[22:23], v[32:33], v[20:21]
	v_rcp_f32_e32 v30, v28
	v_rcp_f32_e32 v31, v29
	v_pk_add_f32 v[24:25], v[28:29], v[24:25] neg_lo:[0,1] neg_hi:[0,1]
; __device__ __forceinline__ float log_sigmoid_f(float v) { return fminf(v, 0.f) - log1pf(__expf(-fabsf(v))); }
;     __device__ __forceinline__ void operator()(const f32x4 (&acc)[2][2][4][2], const pg8::Unit& u, int wr, int wc, int fr, int fq) const {
;     ...
;                 for (int nn = 0; nn < 2; ++nn) { const int head = 2 * fq + nn; const f32x4 gb = *(const f32x4*)(gate_b + 4 * head);
; #pragma unroll
;                     for (int ai = 0; ai < 2; ++ai)
; #pragma unroll
;                         for (int m = 0; m < 4; ++m) { const int row = row0 + ai * 128 + m * 16; f32x4 v = acc[ai][0][m][nn] + gb;
;                             v[1] = log_sigmoid_f(v[1]); v[3] = log_sigmoid_f(v[3]);
;                             *(f32x4*)(G + (size_t)row * 16 + 4 * head) = v; } }
	v_pk_add_f32 v[32:33], v[22:23], v[32:33] neg_lo:[0,1] neg_hi:[0,1]
	v_pk_add_f32 v[24:25], v[26:27], v[24:25] neg_lo:[0,1] neg_hi:[0,1]
	v_pk_mul_f32 v[26:27], v[22:23], v[30:31]
	v_pk_add_f32 v[20:21], v[20:21], v[32:33] neg_lo:[0,1] neg_hi:[0,1]
	v_pk_mul_f32 v[32:33], v[28:29], v[26:27]
	v_cmp_neq_f32_e32 vcc, s17, v0
	v_pk_fma_f32 v[40:41], v[26:27], v[28:29], v[32:33] neg_lo:[0,0,1] neg_hi:[0,0,1]
	s_nop 0
	v_pk_fma_f32 v[40:41], v[26:27], v[24:25], v[40:41]
	s_nop 0
	v_pk_add_f32 v[44:45], v[32:33], v[40:41]
	s_nop 0
	v_pk_add_f32 v[48:49], v[22:23], v[44:45] neg_lo:[0,1] neg_hi:[0,1]
	v_pk_add_f32 v[32:33], v[44:45], v[32:33] neg_lo:[0,1] neg_hi:[0,1]
	v_pk_add_f32 v[22:23], v[22:23], v[48:49] neg_lo:[0,1] neg_hi:[0,1]
	s_nop 0
	v_pk_add_f32 v[22:23], v[22:23], v[44:45] neg_lo:[0,1] neg_hi:[0,1]
	s_nop 0
	v_pk_add_f32 v[20:21], v[20:21], v[22:23]
	v_pk_add_f32 v[22:23], v[32:33], v[40:41] neg_lo:[0,1] neg_hi:[0,1]
	s_nop 0
	v_pk_add_f32 v[20:21], v[22:23], v[20:21]
	s_nop 0
	v_pk_add_f32 v[22:23], v[48:49], v[20:21]
	s_nop 0
	v_pk_mul_f32 v[32:33], v[30:31], v[22:23]
	s_nop 0
	v_pk_mul_f32 v[40:41], v[28:29], v[32:33]
	s_nop 0
	v_pk_fma_f32 v[28:29], v[32:33], v[28:29], v[40:41] neg_lo:[0,0,1] neg_hi:[0,0,1]
	s_nop 0
	v_pk_fma_f32 v[24:25], v[32:33], v[24:25], v[28:29]
	v_pk_add_f32 v[28:29], v[48:49], v[22:23] neg_lo:[0,1] neg_hi:[0,1]
	s_nop 0
	v_pk_add_f32 v[20:21], v[20:21], v[28:29]
	v_pk_add_f32 v[28:29], v[40:41], v[24:25]
	s_nop 0
	v_pk_add_f32 v[44:45], v[22:23], v[28:29] neg_lo:[0,1] neg_hi:[0,1]
	v_pk_add_f32 v[40:41], v[28:29], v[40:41] neg_lo:[0,1] neg_hi:[0,1]
	v_pk_add_f32 v[22:23], v[22:23], v[44:45] neg_lo:[0,1] neg_hi:[0,1]
	s_nop 0
	v_pk_add_f32 v[22:23], v[22:23], v[28:29] neg_lo:[0,1] neg_hi:[0,1]
	s_nop 0
	v_pk_add_f32 v[20:21], v[20:21], v[22:23]
	v_pk_add_f32 v[22:23], v[40:41], v[24:25] neg_lo:[0,1] neg_hi:[0,1]
	s_nop 0
	v_pk_add_f32 v[20:21], v[22:23], v[20:21]
	v_pk_add_f32 v[22:23], v[26:27], v[32:33]
	v_pk_add_f32 v[20:21], v[44:45], v[20:21]
	v_pk_add_f32 v[24:25], v[22:23], v[26:27] neg_lo:[0,1] neg_hi:[0,1]
	v_pk_mul_f32 v[20:21], v[30:31], v[20:21]
	v_pk_add_f32 v[24:25], v[32:33], v[24:25] neg_lo:[0,1] neg_hi:[0,1]
	s_nop 0
	v_pk_add_f32 v[20:21], v[24:25], v[20:21]
	s_nop 0
	v_pk_add_f32 v[24:25], v[22:23], v[20:21]
	s_nop 0
	v_pk_mul_f32 v[26:27], v[24:25], v[24:25]
	v_pk_add_f32 v[22:23], v[24:25], v[22:23] neg_lo:[0,1] neg_hi:[0,1]
	v_pk_fma_f32 v[28:29], v[26:27], s[34:35], v[70:71] op_sel_hi:[1,0,0]
	v_pk_add_f32 v[20:21], v[20:21], v[22:23] neg_lo:[0,1] neg_hi:[0,1]
	v_ldexp_f32 v22, v24, 1
	v_pk_fma_f32 v[28:29], v[26:27], v[28:29], s[36:37] op_sel_hi:[1,1,0]
	v_ldexp_f32 v23, v25, 1
	v_pk_mul_f32 v[24:25], v[24:25], v[26:27]
	v_cvt_f32_i32_e32 v27, v53
	v_cvt_f32_i32_e32 v26, v52
	v_pk_mul_f32 v[24:25], v[24:25], v[28:29]
	v_ldexp_f32 v31, v21, 1
	v_pk_add_f32 v[28:29], v[22:23], v[24:25]
	v_pk_mul_f32 v[32:33], v[26:27], s[38:39] op_sel_hi:[1,0]
	v_pk_add_f32 v[22:23], v[28:29], v[22:23] neg_lo:[0,1] neg_hi:[0,1]
	v_pk_fma_f32 v[40:41], v[26:27], s[38:39], v[32:33] op_sel_hi:[1,0,1] neg_lo:[0,0,1] neg_hi:[0,0,1]
	v_pk_add_f32 v[22:23], v[24:25], v[22:23] neg_lo:[0,1] neg_hi:[0,1]
	v_pk_fma_f32 v[26:27], v[26:27], s[40:41], v[40:41] op_sel_hi:[1,0,1]
	v_ldexp_f32 v20, v20, 1
	v_mov_b32_e32 v24, v32
	v_mov_b32_e32 v25, v23
	v_mov_b32_e32 v30, v26
	v_mov_b32_e32 v21, v31
	v_pk_add_f32 v[24:25], v[24:25], v[30:31]
	v_pk_add_f32 v[30:31], v[20:21], v[22:23]
	v_mov_b32_e32 v23, v29
	v_mov_b32_e32 v21, v31
	v_pk_add_f32 v[40:41], v[32:33], v[26:27]
	v_pk_add_f32 v[20:21], v[20:21], v[22:23]
	v_pk_add_f32 v[22:23], v[28:29], v[30:31]
	v_mov_b32_e32 v56, v28
	v_pk_add_f32 v[44:45], v[40:41], v[22:23]
	v_mov_b32_e32 v54, v22
	v_mov_b32_e32 v55, v45
	v_mov_b32_e32 v57, v41
	v_pk_add_f32 v[54:55], v[54:55], v[56:57] neg_lo:[0,1] neg_hi:[0,1]
	v_mov_b32_e32 v48, v44
	v_mov_b32_e32 v49, v41
	v_mov_b32_e32 v52, v40
	v_mov_b32_e32 v53, v33
	v_mov_b32_e32 v56, v40
	v_mov_b32_e32 v57, v45
	v_mov_b32_e32 v33, v55
	v_pk_add_f32 v[48:49], v[48:49], v[52:53] neg_lo:[0,1] neg_hi:[0,1]
	v_mov_b32_e32 v52, v22
	v_mov_b32_e32 v53, v27
	v_pk_add_f32 v[32:33], v[56:57], v[32:33] neg_lo:[0,1] neg_hi:[0,1]
	v_pk_add_f32 v[52:53], v[52:53], v[48:49] neg_lo:[0,1] neg_hi:[0,1]
	v_mov_b32_e32 v56, v32
	v_mov_b32_e32 v57, v49
	v_mov_b32_e32 v58, v44
	v_mov_b32_e32 v59, v23
	v_mov_b32_e32 v49, v29
	v_pk_add_f32 v[56:57], v[26:27], v[56:57] neg_lo:[0,1] neg_hi:[0,1]
	v_pk_add_f32 v[48:49], v[58:59], v[48:49] neg_lo:[0,1] neg_hi:[0,1]
	v_mov_b32_e32 v27, v41
	v_pk_add_f32 v[24:25], v[24:25], v[48:49] neg_lo:[0,1] neg_hi:[0,1]
	v_pk_add_f32 v[26:27], v[26:27], v[32:33] neg_lo:[0,1] neg_hi:[0,1]
	v_pk_add_f32 v[20:21], v[20:21], v[54:55] neg_lo:[0,1] neg_hi:[0,1]
	v_pk_add_f32 v[22:23], v[22:23], v[28:29] neg_lo:[0,1] neg_hi:[0,1]
	v_pk_add_f32 v[28:29], v[20:21], v[26:27]
	v_mov_b32_e32 v27, v53
	v_mov_b32_e32 v21, v25
	v_pk_add_f32 v[22:23], v[30:31], v[22:23] neg_lo:[0,1] neg_hi:[0,1]
	v_pk_add_f32 v[30:31], v[52:53], v[24:25]
	v_pk_add_f32 v[20:21], v[26:27], v[20:21]
	v_mov_b32_e32 v24, v28
	v_pk_add_f32 v[20:21], v[20:21], v[56:57] neg_lo:[0,1] neg_hi:[0,1]
	v_mov_b32_e32 v25, v31
	v_pk_add_f32 v[24:25], v[24:25], v[20:21] neg_lo:[0,1] neg_hi:[0,1]
	v_pk_add_f32 v[20:21], v[22:23], v[20:21] neg_lo:[0,1] neg_hi:[0,1]
	v_pk_add_f32 v[24:25], v[26:27], v[24:25] neg_lo:[0,1] neg_hi:[0,1]
	v_pk_add_f32 v[22:23], v[30:31], v[28:29]
	v_pk_add_f32 v[20:21], v[20:21], v[24:25]
	v_pk_add_f32 v[24:25], v[44:45], v[22:23]
	s_nop 0
	v_pk_add_f32 v[26:27], v[24:25], v[44:45] neg_lo:[0,1] neg_hi:[0,1]
	s_nop 0
; __device__ __forceinline__ float log_sigmoid_f(float v) { return fminf(v, 0.f) - log1pf(__expf(-fabsf(v))); }
;     __device__ __forceinline__ void operator()(const f32x4 (&acc)[2][2][4][2], const pg8::Unit& u, int wr, int wc, int fr, int fq) const {
;     ...
;                 for (int nn = 0; nn < 2; ++nn) { const int head = 2 * fq + nn; const f32x4 gb = *(const f32x4*)(gate_b + 4 * head);
; #pragma unroll
;                     for (int ai = 0; ai < 2; ++ai)
; #pragma unroll
;                         for (int m = 0; m < 4; ++m) { const int row = row0 + ai * 128 + m * 16; f32x4 v = acc[ai][0][m][nn] + gb;
;                             v[1] = log_sigmoid_f(v[1]); v[3] = log_sigmoid_f(v[3]);
;                             *(f32x4*)(G + (size_t)row * 16 + 4 * head) = v; } }
	v_pk_add_f32 v[22:23], v[22:23], v[26:27] neg_lo:[0,1] neg_hi:[0,1]
	s_nop 0
	v_pk_add_f32 v[20:21], v[20:21], v[22:23]
	s_nop 0
	v_pk_add_f32 v[20:21], v[24:25], v[20:21]
	s_nop 0
	v_cndmask_b32_e32 v17, v199, v20, vcc
	v_cmp_neq_f32_e32 vcc, s17, v15
	s_nop 1
	v_cndmask_b32_e32 v20, v199, v21, vcc
	v_cmp_ngt_f32_e32 vcc, -1.0, v15
	s_nop 1
	v_cndmask_b32_e32 v20, v200, v20, vcc
	v_cmp_ngt_f32_e32 vcc, -1.0, v0
	s_nop 1
	v_cndmask_b32_e32 v17, v200, v17, vcc
	v_cmp_neq_f32_e32 vcc, -1.0, v0
	s_nop 1
	v_cndmask_b32_e32 v17, v201, v17, vcc
	v_cmp_neq_f32_e32 vcc, -1.0, v15
	s_nop 1
	v_cndmask_b32_e32 v20, v201, v20, vcc
	v_cmp_lt_f32_e64 vcc, |v15|, s19
	s_nop 1
	v_cndmask_b32_e32 v21, v20, v15, vcc
	v_cndmask_b32_e64 v20, v17, v0, s[0:1]
	v_mul_f32_e64 v0, |v11|, s8
	v_exp_f32_e32 v0, v0
	v_pk_add_f32 v[18:19], v[18:19], v[20:21] neg_lo:[0,1] neg_hi:[0,1]
	v_cmp_lt_f32_e64 s[0:1], |v0|, s19
	v_mov_b32_e32 v15, v18
	v_mov_b32_e32 v17, v19
	global_store_dwordx4 v[50:51], v[14:17], off offset:16
	s_nop 1
	v_min_f32_e32 v14, 0, v11
	v_add_f32_e32 v11, 1.0, v0
	v_add_f32_e32 v15, -1.0, v11
	v_sub_f32_e32 v16, v15, v11
	v_add_f32_e32 v16, 1.0, v16
	v_sub_f32_e32 v15, v0, v15
	v_add_f32_e32 v15, v15, v16
	v_frexp_mant_f32_e32 v16, v11
	v_cmp_gt_f32_e32 vcc, s9, v16
	v_cvt_f64_f32_e32 v[16:17], v11
	v_frexp_exp_i32_f64_e32 v16, v[16:17]
	v_subbrev_co_u32_e32 v44, vcc, 0, v16, vcc
	v_sub_u32_e32 v17, 0, v44
	v_ldexp_f32 v16, v11, v17
	v_mul_f32_e64 v11, |v13|, s8
	v_exp_f32_e32 v11, v11
	v_ldexp_f32 v18, v15, v17
	v_min_f32_e32 v15, 0, v13
	v_add_f32_e32 v13, 1.0, v11
	v_add_f32_e32 v17, -1.0, v13
	v_sub_f32_e32 v19, v17, v13
	v_add_f32_e32 v19, 1.0, v19
	v_sub_f32_e32 v17, v11, v17
	v_add_f32_e32 v19, v17, v19
	v_frexp_mant_f32_e32 v17, v13
	v_cvt_f64_f32_e32 v[20:21], v13
	v_cmp_gt_f32_e32 vcc, s9, v17
	v_frexp_exp_i32_f64_e32 v17, v[20:21]
	s_nop 0
	v_subbrev_co_u32_e32 v45, vcc, 0, v17, vcc
	v_sub_u32_e32 v20, 0, v45
	v_ldexp_f32 v17, v13, v20
	v_ldexp_f32 v19, v19, v20
	v_pk_add_f32 v[20:21], v[16:17], 1.0 op_sel_hi:[1,0]
	v_pk_add_f32 v[28:29], v[16:17], -1.0 op_sel_hi:[1,0]
	v_pk_add_f32 v[22:23], v[20:21], -1.0 op_sel_hi:[1,0]
	v_pk_add_f32 v[30:31], v[28:29], 1.0 op_sel_hi:[1,0]
	v_pk_add_f32 v[22:23], v[16:17], v[22:23] neg_lo:[0,1] neg_hi:[0,1]
	v_pk_add_f32 v[16:17], v[16:17], v[30:31] neg_lo:[0,1] neg_hi:[0,1]
	v_pk_add_f32 v[22:23], v[18:19], v[22:23]
	v_pk_add_f32 v[16:17], v[18:19], v[16:17]
	v_pk_add_f32 v[24:25], v[20:21], v[22:23]
	v_pk_add_f32 v[18:19], v[28:29], v[16:17]
	v_rcp_f32_e32 v26, v24
	v_rcp_f32_e32 v27, v25
	v_pk_add_f32 v[20:21], v[24:25], v[20:21] neg_lo:[0,1] neg_hi:[0,1]
	v_pk_add_f32 v[28:29], v[18:19], v[28:29] neg_lo:[0,1] neg_hi:[0,1]
	v_pk_add_f32 v[20:21], v[22:23], v[20:21] neg_lo:[0,1] neg_hi:[0,1]
	v_pk_mul_f32 v[22:23], v[18:19], v[26:27]
	v_pk_add_f32 v[16:17], v[16:17], v[28:29] neg_lo:[0,1] neg_hi:[0,1]
	v_pk_mul_f32 v[28:29], v[24:25], v[22:23]
	v_cmp_neq_f32_e32 vcc, s17, v0
	v_pk_fma_f32 v[30:31], v[22:23], v[24:25], v[28:29] neg_lo:[0,0,1] neg_hi:[0,0,1]
	s_nop 0
	v_pk_fma_f32 v[30:31], v[22:23], v[20:21], v[30:31]
	s_nop 0
	v_pk_add_f32 v[32:33], v[28:29], v[30:31]
	s_nop 0
	v_pk_add_f32 v[40:41], v[18:19], v[32:33] neg_lo:[0,1] neg_hi:[0,1]
	v_pk_add_f32 v[28:29], v[32:33], v[28:29] neg_lo:[0,1] neg_hi:[0,1]
	v_pk_add_f32 v[18:19], v[18:19], v[40:41] neg_lo:[0,1] neg_hi:[0,1]
	s_nop 0
	v_pk_add_f32 v[18:19], v[18:19], v[32:33] neg_lo:[0,1] neg_hi:[0,1]
	s_nop 0
	v_pk_add_f32 v[16:17], v[16:17], v[18:19]
	v_pk_add_f32 v[18:19], v[28:29], v[30:31] neg_lo:[0,1] neg_hi:[0,1]
	s_nop 0
	v_pk_add_f32 v[16:17], v[18:19], v[16:17]
	s_nop 0
	v_pk_add_f32 v[18:19], v[40:41], v[16:17]
	s_nop 0
	v_pk_mul_f32 v[28:29], v[26:27], v[18:19]
	s_nop 0
	v_pk_mul_f32 v[30:31], v[24:25], v[28:29]
	s_nop 0
	v_pk_fma_f32 v[24:25], v[28:29], v[24:25], v[30:31] neg_lo:[0,0,1] neg_hi:[0,0,1]
	s_nop 0
	v_pk_fma_f32 v[20:21], v[28:29], v[20:21], v[24:25]
	v_pk_add_f32 v[24:25], v[40:41], v[18:19] neg_lo:[0,1] neg_hi:[0,1]
	s_nop 0
	v_pk_add_f32 v[16:17], v[16:17], v[24:25]
	v_pk_add_f32 v[24:25], v[30:31], v[20:21]
	s_nop 0
	v_pk_add_f32 v[32:33], v[18:19], v[24:25] neg_lo:[0,1] neg_hi:[0,1]
	v_pk_add_f32 v[30:31], v[24:25], v[30:31] neg_lo:[0,1] neg_hi:[0,1]
	v_pk_add_f32 v[18:19], v[18:19], v[32:33] neg_lo:[0,1] neg_hi:[0,1]
	s_nop 0
	v_pk_add_f32 v[18:19], v[18:19], v[24:25] neg_lo:[0,1] neg_hi:[0,1]
	s_nop 0
	v_pk_add_f32 v[16:17], v[16:17], v[18:19]
	v_pk_add_f32 v[18:19], v[30:31], v[20:21] neg_lo:[0,1] neg_hi:[0,1]
	s_nop 0
	v_pk_add_f32 v[16:17], v[18:19], v[16:17]
	v_pk_add_f32 v[18:19], v[22:23], v[28:29]
	v_pk_add_f32 v[16:17], v[32:33], v[16:17]
	v_pk_add_f32 v[20:21], v[18:19], v[22:23] neg_lo:[0,1] neg_hi:[0,1]
	v_pk_mul_f32 v[16:17], v[26:27], v[16:17]
	v_pk_add_f32 v[20:21], v[28:29], v[20:21] neg_lo:[0,1] neg_hi:[0,1]
	s_nop 0
	v_pk_add_f32 v[16:17], v[20:21], v[16:17]
	s_nop 0
	v_pk_add_f32 v[20:21], v[18:19], v[16:17]
	s_nop 0
	v_pk_mul_f32 v[22:23], v[20:21], v[20:21]
	v_pk_add_f32 v[18:19], v[20:21], v[18:19] neg_lo:[0,1] neg_hi:[0,1]
	v_pk_fma_f32 v[24:25], v[22:23], s[34:35], v[70:71] op_sel_hi:[1,0,0]
	v_pk_add_f32 v[16:17], v[16:17], v[18:19] neg_lo:[0,1] neg_hi:[0,1]
	v_ldexp_f32 v18, v20, 1
	v_pk_fma_f32 v[24:25], v[22:23], v[24:25], s[36:37] op_sel_hi:[1,1,0]
	v_ldexp_f32 v19, v21, 1
	v_pk_mul_f32 v[20:21], v[20:21], v[22:23]
	v_cvt_f32_i32_e32 v23, v45
	v_cvt_f32_i32_e32 v22, v44
	v_pk_mul_f32 v[20:21], v[20:21], v[24:25]
	v_ldexp_f32 v27, v17, 1
	v_pk_add_f32 v[24:25], v[18:19], v[20:21]
	v_pk_mul_f32 v[28:29], v[22:23], s[38:39] op_sel_hi:[1,0]
	v_pk_add_f32 v[18:19], v[24:25], v[18:19] neg_lo:[0,1] neg_hi:[0,1]
; __device__ __forceinline__ float log_sigmoid_f(float v) { return fminf(v, 0.f) - log1pf(__expf(-fabsf(v))); }
;     __device__ __forceinline__ void operator()(const f32x4 (&acc)[2][2][4][2], const pg8::Unit& u, int wr, int wc, int fr, int fq) const {
;     ...
;                 for (int nn = 0; nn < 2; ++nn) { const int head = 2 * fq + nn; const f32x4 gb = *(const f32x4*)(gate_b + 4 * head);
; #pragma unroll
;                     for (int ai = 0; ai < 2; ++ai)
; #pragma unroll
;                         for (int m = 0; m < 4; ++m) { const int row = row0 + ai * 128 + m * 16; f32x4 v = acc[ai][0][m][nn] + gb;
;                             v[1] = log_sigmoid_f(v[1]); v[3] = log_sigmoid_f(v[3]);
;                             *(f32x4*)(G + (size_t)row * 16 + 4 * head) = v; } }
	v_pk_fma_f32 v[30:31], v[22:23], s[38:39], v[28:29] op_sel_hi:[1,0,1] neg_lo:[0,0,1] neg_hi:[0,0,1]
	v_pk_add_f32 v[18:19], v[20:21], v[18:19] neg_lo:[0,1] neg_hi:[0,1]
	v_pk_fma_f32 v[22:23], v[22:23], s[40:41], v[30:31] op_sel_hi:[1,0,1]
	v_ldexp_f32 v16, v16, 1
	v_mov_b32_e32 v20, v28
	v_mov_b32_e32 v21, v19
	v_mov_b32_e32 v26, v22
	v_mov_b32_e32 v17, v27
	v_pk_add_f32 v[20:21], v[20:21], v[26:27]
	v_pk_add_f32 v[26:27], v[16:17], v[18:19]
	v_mov_b32_e32 v19, v25
	v_mov_b32_e32 v17, v27
	v_pk_add_f32 v[30:31], v[28:29], v[22:23]
	v_pk_add_f32 v[16:17], v[16:17], v[18:19]
	v_pk_add_f32 v[18:19], v[24:25], v[26:27]
	v_mov_b32_e32 v50, v24
	v_pk_add_f32 v[32:33], v[30:31], v[18:19]
	v_mov_b32_e32 v48, v18
	v_mov_b32_e32 v49, v33
	v_mov_b32_e32 v51, v31
	v_pk_add_f32 v[48:49], v[48:49], v[50:51] neg_lo:[0,1] neg_hi:[0,1]
	v_mov_b32_e32 v40, v32
	v_mov_b32_e32 v41, v31
	v_mov_b32_e32 v44, v30
	v_mov_b32_e32 v45, v29
	v_mov_b32_e32 v50, v30
	v_mov_b32_e32 v51, v33
	v_mov_b32_e32 v29, v49
	v_pk_add_f32 v[40:41], v[40:41], v[44:45] neg_lo:[0,1] neg_hi:[0,1]
	v_mov_b32_e32 v44, v18
	v_mov_b32_e32 v45, v23
	v_pk_add_f32 v[28:29], v[50:51], v[28:29] neg_lo:[0,1] neg_hi:[0,1]
	v_pk_add_f32 v[44:45], v[44:45], v[40:41] neg_lo:[0,1] neg_hi:[0,1]
	v_mov_b32_e32 v50, v28
	v_mov_b32_e32 v51, v41
	v_mov_b32_e32 v52, v32
	v_mov_b32_e32 v53, v19
	v_mov_b32_e32 v41, v25
	v_pk_add_f32 v[50:51], v[22:23], v[50:51] neg_lo:[0,1] neg_hi:[0,1]
	v_pk_add_f32 v[40:41], v[52:53], v[40:41] neg_lo:[0,1] neg_hi:[0,1]
	v_mov_b32_e32 v23, v31
	v_pk_add_f32 v[20:21], v[20:21], v[40:41] neg_lo:[0,1] neg_hi:[0,1]
	v_pk_add_f32 v[22:23], v[22:23], v[28:29] neg_lo:[0,1] neg_hi:[0,1]
	v_pk_add_f32 v[16:17], v[16:17], v[48:49] neg_lo:[0,1] neg_hi:[0,1]
	v_pk_add_f32 v[18:19], v[18:19], v[24:25] neg_lo:[0,1] neg_hi:[0,1]
	v_pk_add_f32 v[24:25], v[16:17], v[22:23]
	v_mov_b32_e32 v23, v45
	v_mov_b32_e32 v17, v21
	v_pk_add_f32 v[18:19], v[26:27], v[18:19] neg_lo:[0,1] neg_hi:[0,1]
	v_pk_add_f32 v[26:27], v[44:45], v[20:21]
	v_pk_add_f32 v[16:17], v[22:23], v[16:17]
	v_mov_b32_e32 v20, v24
	v_pk_add_f32 v[16:17], v[16:17], v[50:51] neg_lo:[0,1] neg_hi:[0,1]
	v_mov_b32_e32 v21, v27
	v_pk_add_f32 v[20:21], v[20:21], v[16:17] neg_lo:[0,1] neg_hi:[0,1]
	v_pk_add_f32 v[16:17], v[18:19], v[16:17] neg_lo:[0,1] neg_hi:[0,1]
	v_pk_add_f32 v[20:21], v[22:23], v[20:21] neg_lo:[0,1] neg_hi:[0,1]
	v_pk_add_f32 v[18:19], v[26:27], v[24:25]
	v_pk_add_f32 v[16:17], v[16:17], v[20:21]
	v_pk_add_f32 v[20:21], v[32:33], v[18:19]
	s_nop 0
	v_pk_add_f32 v[22:23], v[20:21], v[32:33] neg_lo:[0,1] neg_hi:[0,1]
	s_nop 0
	v_pk_add_f32 v[18:19], v[18:19], v[22:23] neg_lo:[0,1] neg_hi:[0,1]
	s_nop 0
	v_pk_add_f32 v[16:17], v[16:17], v[18:19]
	s_nop 0
	v_pk_add_f32 v[16:17], v[20:21], v[16:17]
	s_nop 0
	v_cndmask_b32_e32 v13, v199, v16, vcc
	v_cmp_neq_f32_e32 vcc, s17, v11
	s_nop 1
	v_cndmask_b32_e32 v16, v199, v17, vcc
	v_cmp_ngt_f32_e32 vcc, -1.0, v11
	s_nop 1
	v_cndmask_b32_e32 v16, v200, v16, vcc
	v_cmp_ngt_f32_e32 vcc, -1.0, v0
	s_nop 1
	v_cndmask_b32_e32 v13, v200, v13, vcc
	v_cmp_neq_f32_e32 vcc, -1.0, v0
	s_nop 1
	v_cndmask_b32_e32 v13, v201, v13, vcc
	v_cmp_neq_f32_e32 vcc, -1.0, v11
	s_nop 1
	v_cndmask_b32_e32 v16, v201, v16, vcc
	v_cmp_lt_f32_e64 vcc, |v11|, s19
	s_nop 1
	v_cndmask_b32_e32 v17, v16, v11, vcc
	v_cndmask_b32_e64 v16, v13, v0, s[0:1]
	v_mul_f32_e64 v0, |v7|, s8
	v_exp_f32_e32 v0, v0
	v_pk_add_f32 v[14:15], v[14:15], v[16:17] neg_lo:[0,1] neg_hi:[0,1]
	v_cmp_lt_f32_e64 s[0:1], |v0|, s19
	v_mov_b32_e32 v11, v14
	v_mov_b32_e32 v13, v15
	global_store_dwordx4 v[46:47], v[10:13], off offset:16
	s_nop 1
	v_min_f32_e32 v10, 0, v7
	v_add_f32_e32 v7, 1.0, v0
	v_add_f32_e32 v11, -1.0, v7
	v_sub_f32_e32 v12, v11, v7
	v_add_f32_e32 v12, 1.0, v12
	v_sub_f32_e32 v11, v0, v11
	v_add_f32_e32 v11, v11, v12
	v_frexp_mant_f32_e32 v12, v7
	v_cmp_gt_f32_e32 vcc, s9, v12
	v_cvt_f64_f32_e32 v[12:13], v7
	v_frexp_exp_i32_f64_e32 v12, v[12:13]
	v_subbrev_co_u32_e32 v32, vcc, 0, v12, vcc
	v_sub_u32_e32 v13, 0, v32
	v_ldexp_f32 v12, v7, v13
	v_mul_f32_e64 v7, |v9|, s8
	v_exp_f32_e32 v7, v7
	v_ldexp_f32 v14, v11, v13
	v_min_f32_e32 v11, 0, v9
	v_add_f32_e32 v9, 1.0, v7
	v_add_f32_e32 v13, -1.0, v9
	v_sub_f32_e32 v15, v13, v9
	v_add_f32_e32 v15, 1.0, v15
	v_sub_f32_e32 v13, v7, v13
	v_add_f32_e32 v15, v13, v15
	v_frexp_mant_f32_e32 v13, v9
	v_cvt_f64_f32_e32 v[16:17], v9
	v_cmp_gt_f32_e32 vcc, s9, v13
	v_frexp_exp_i32_f64_e32 v13, v[16:17]
	s_nop 0
	v_subbrev_co_u32_e32 v33, vcc, 0, v13, vcc
	v_sub_u32_e32 v16, 0, v33
	v_ldexp_f32 v13, v9, v16
	v_ldexp_f32 v15, v15, v16
	v_pk_add_f32 v[16:17], v[12:13], 1.0 op_sel_hi:[1,0]
	v_pk_add_f32 v[24:25], v[12:13], -1.0 op_sel_hi:[1,0]
	v_pk_add_f32 v[18:19], v[16:17], -1.0 op_sel_hi:[1,0]
	v_pk_add_f32 v[26:27], v[24:25], 1.0 op_sel_hi:[1,0]
	v_pk_add_f32 v[18:19], v[12:13], v[18:19] neg_lo:[0,1] neg_hi:[0,1]
	v_pk_add_f32 v[12:13], v[12:13], v[26:27] neg_lo:[0,1] neg_hi:[0,1]
	v_pk_add_f32 v[18:19], v[14:15], v[18:19]
	v_pk_add_f32 v[12:13], v[14:15], v[12:13]
	v_pk_add_f32 v[20:21], v[16:17], v[18:19]
	v_pk_add_f32 v[14:15], v[24:25], v[12:13]
	v_rcp_f32_e32 v22, v20
	v_rcp_f32_e32 v23, v21
	v_pk_add_f32 v[16:17], v[20:21], v[16:17] neg_lo:[0,1] neg_hi:[0,1]
	v_pk_add_f32 v[24:25], v[14:15], v[24:25] neg_lo:[0,1] neg_hi:[0,1]
	v_pk_add_f32 v[16:17], v[18:19], v[16:17] neg_lo:[0,1] neg_hi:[0,1]
	v_pk_mul_f32 v[18:19], v[14:15], v[22:23]
	v_pk_add_f32 v[12:13], v[12:13], v[24:25] neg_lo:[0,1] neg_hi:[0,1]
	v_pk_mul_f32 v[24:25], v[20:21], v[18:19]
	v_cmp_neq_f32_e32 vcc, s17, v0
	v_pk_fma_f32 v[26:27], v[18:19], v[20:21], v[24:25] neg_lo:[0,0,1] neg_hi:[0,0,1]
	s_nop 0
; __device__ __forceinline__ float log_sigmoid_f(float v) { return fminf(v, 0.f) - log1pf(__expf(-fabsf(v))); }
;     __device__ __forceinline__ void operator()(const f32x4 (&acc)[2][2][4][2], const pg8::Unit& u, int wr, int wc, int fr, int fq) const {
;     ...
;                 for (int nn = 0; nn < 2; ++nn) { const int head = 2 * fq + nn; const f32x4 gb = *(const f32x4*)(gate_b + 4 * head);
; #pragma unroll
;                     for (int ai = 0; ai < 2; ++ai)
; #pragma unroll
;                         for (int m = 0; m < 4; ++m) { const int row = row0 + ai * 128 + m * 16; f32x4 v = acc[ai][0][m][nn] + gb;
;                             v[1] = log_sigmoid_f(v[1]); v[3] = log_sigmoid_f(v[3]);
;                             *(f32x4*)(G + (size_t)row * 16 + 4 * head) = v; } }
	v_pk_fma_f32 v[26:27], v[18:19], v[16:17], v[26:27]
	s_nop 0
	v_pk_add_f32 v[28:29], v[24:25], v[26:27]
	s_nop 0
	v_pk_add_f32 v[30:31], v[14:15], v[28:29] neg_lo:[0,1] neg_hi:[0,1]
	v_pk_add_f32 v[24:25], v[28:29], v[24:25] neg_lo:[0,1] neg_hi:[0,1]
	v_pk_add_f32 v[14:15], v[14:15], v[30:31] neg_lo:[0,1] neg_hi:[0,1]
	s_nop 0
	v_pk_add_f32 v[14:15], v[14:15], v[28:29] neg_lo:[0,1] neg_hi:[0,1]
	s_nop 0
	v_pk_add_f32 v[12:13], v[12:13], v[14:15]
	v_pk_add_f32 v[14:15], v[24:25], v[26:27] neg_lo:[0,1] neg_hi:[0,1]
	s_nop 0
	v_pk_add_f32 v[12:13], v[14:15], v[12:13]
	s_nop 0
	v_pk_add_f32 v[14:15], v[30:31], v[12:13]
	s_nop 0
	v_pk_mul_f32 v[24:25], v[22:23], v[14:15]
	s_nop 0
	v_pk_mul_f32 v[26:27], v[20:21], v[24:25]
	s_nop 0
	v_pk_fma_f32 v[20:21], v[24:25], v[20:21], v[26:27] neg_lo:[0,0,1] neg_hi:[0,0,1]
	s_nop 0
	v_pk_fma_f32 v[16:17], v[24:25], v[16:17], v[20:21]
	v_pk_add_f32 v[20:21], v[30:31], v[14:15] neg_lo:[0,1] neg_hi:[0,1]
	s_nop 0
	v_pk_add_f32 v[12:13], v[12:13], v[20:21]
	v_pk_add_f32 v[20:21], v[26:27], v[16:17]
	s_nop 0
	v_pk_add_f32 v[28:29], v[14:15], v[20:21] neg_lo:[0,1] neg_hi:[0,1]
	v_pk_add_f32 v[26:27], v[20:21], v[26:27] neg_lo:[0,1] neg_hi:[0,1]
	v_pk_add_f32 v[14:15], v[14:15], v[28:29] neg_lo:[0,1] neg_hi:[0,1]
	s_nop 0
	v_pk_add_f32 v[14:15], v[14:15], v[20:21] neg_lo:[0,1] neg_hi:[0,1]
	s_nop 0
	v_pk_add_f32 v[12:13], v[12:13], v[14:15]
	v_pk_add_f32 v[14:15], v[26:27], v[16:17] neg_lo:[0,1] neg_hi:[0,1]
	s_nop 0
	v_pk_add_f32 v[12:13], v[14:15], v[12:13]
	v_pk_add_f32 v[14:15], v[18:19], v[24:25]
	v_pk_add_f32 v[12:13], v[28:29], v[12:13]
	v_pk_add_f32 v[16:17], v[14:15], v[18:19] neg_lo:[0,1] neg_hi:[0,1]
	v_pk_mul_f32 v[12:13], v[22:23], v[12:13]
	v_pk_add_f32 v[16:17], v[24:25], v[16:17] neg_lo:[0,1] neg_hi:[0,1]
	s_nop 0
	v_pk_add_f32 v[12:13], v[16:17], v[12:13]
	s_nop 0
	v_pk_add_f32 v[16:17], v[14:15], v[12:13]
	s_nop 0
	v_pk_mul_f32 v[18:19], v[16:17], v[16:17]
	v_pk_add_f32 v[14:15], v[16:17], v[14:15] neg_lo:[0,1] neg_hi:[0,1]
	v_pk_fma_f32 v[20:21], v[18:19], s[34:35], v[70:71] op_sel_hi:[1,0,0]
	v_pk_add_f32 v[12:13], v[12:13], v[14:15] neg_lo:[0,1] neg_hi:[0,1]
	v_ldexp_f32 v14, v16, 1
	v_pk_fma_f32 v[20:21], v[18:19], v[20:21], s[36:37] op_sel_hi:[1,1,0]
	v_ldexp_f32 v15, v17, 1
	v_pk_mul_f32 v[16:17], v[16:17], v[18:19]
	v_cvt_f32_i32_e32 v19, v33
	v_cvt_f32_i32_e32 v18, v32
	v_pk_mul_f32 v[16:17], v[16:17], v[20:21]
	v_ldexp_f32 v23, v13, 1
	v_pk_add_f32 v[20:21], v[14:15], v[16:17]
	v_pk_mul_f32 v[24:25], v[18:19], s[38:39] op_sel_hi:[1,0]
	v_pk_add_f32 v[14:15], v[20:21], v[14:15] neg_lo:[0,1] neg_hi:[0,1]
	v_pk_fma_f32 v[26:27], v[18:19], s[38:39], v[24:25] op_sel_hi:[1,0,1] neg_lo:[0,0,1] neg_hi:[0,0,1]
	v_pk_add_f32 v[14:15], v[16:17], v[14:15] neg_lo:[0,1] neg_hi:[0,1]
	v_pk_fma_f32 v[18:19], v[18:19], s[40:41], v[26:27] op_sel_hi:[1,0,1]
	v_ldexp_f32 v12, v12, 1
	v_mov_b32_e32 v16, v24
	v_mov_b32_e32 v17, v15
	v_mov_b32_e32 v22, v18
	v_mov_b32_e32 v13, v23
	v_pk_add_f32 v[16:17], v[16:17], v[22:23]
	v_pk_add_f32 v[22:23], v[12:13], v[14:15]
	v_mov_b32_e32 v15, v21
	v_mov_b32_e32 v13, v23
	v_pk_add_f32 v[26:27], v[24:25], v[18:19]
	v_pk_add_f32 v[12:13], v[12:13], v[14:15]
	v_pk_add_f32 v[14:15], v[20:21], v[22:23]
	v_mov_b32_e32 v44, v20
	v_pk_add_f32 v[28:29], v[26:27], v[14:15]
	v_mov_b32_e32 v40, v14
	v_mov_b32_e32 v41, v29
	v_mov_b32_e32 v45, v27
	v_pk_add_f32 v[40:41], v[40:41], v[44:45] neg_lo:[0,1] neg_hi:[0,1]
	v_mov_b32_e32 v30, v28
	v_mov_b32_e32 v31, v27
	v_mov_b32_e32 v32, v26
	v_mov_b32_e32 v33, v25
	v_mov_b32_e32 v44, v26
	v_mov_b32_e32 v45, v29
	v_mov_b32_e32 v25, v41
	v_pk_add_f32 v[30:31], v[30:31], v[32:33] neg_lo:[0,1] neg_hi:[0,1]
	v_mov_b32_e32 v32, v14
	v_mov_b32_e32 v33, v19
	v_pk_add_f32 v[24:25], v[44:45], v[24:25] neg_lo:[0,1] neg_hi:[0,1]
	v_pk_add_f32 v[32:33], v[32:33], v[30:31] neg_lo:[0,1] neg_hi:[0,1]
	v_mov_b32_e32 v44, v24
	v_mov_b32_e32 v45, v31
	v_mov_b32_e32 v46, v28
	v_mov_b32_e32 v47, v15
	v_mov_b32_e32 v31, v21
	v_pk_add_f32 v[44:45], v[18:19], v[44:45] neg_lo:[0,1] neg_hi:[0,1]
	v_pk_add_f32 v[30:31], v[46:47], v[30:31] neg_lo:[0,1] neg_hi:[0,1]
	v_mov_b32_e32 v19, v27
	v_pk_add_f32 v[16:17], v[16:17], v[30:31] neg_lo:[0,1] neg_hi:[0,1]
	v_pk_add_f32 v[18:19], v[18:19], v[24:25] neg_lo:[0,1] neg_hi:[0,1]
	v_pk_add_f32 v[12:13], v[12:13], v[40:41] neg_lo:[0,1] neg_hi:[0,1]
	v_pk_add_f32 v[14:15], v[14:15], v[20:21] neg_lo:[0,1] neg_hi:[0,1]
	v_pk_add_f32 v[20:21], v[12:13], v[18:19]
	v_mov_b32_e32 v19, v33
	v_mov_b32_e32 v13, v17
	v_pk_add_f32 v[14:15], v[22:23], v[14:15] neg_lo:[0,1] neg_hi:[0,1]
	v_pk_add_f32 v[22:23], v[32:33], v[16:17]
	v_pk_add_f32 v[12:13], v[18:19], v[12:13]
	v_mov_b32_e32 v16, v20
	v_pk_add_f32 v[12:13], v[12:13], v[44:45] neg_lo:[0,1] neg_hi:[0,1]
	v_mov_b32_e32 v17, v23
	v_pk_add_f32 v[16:17], v[16:17], v[12:13] neg_lo:[0,1] neg_hi:[0,1]
	v_pk_add_f32 v[12:13], v[14:15], v[12:13] neg_lo:[0,1] neg_hi:[0,1]
	v_pk_add_f32 v[16:17], v[18:19], v[16:17] neg_lo:[0,1] neg_hi:[0,1]
	v_pk_add_f32 v[14:15], v[22:23], v[20:21]
	v_pk_add_f32 v[12:13], v[12:13], v[16:17]
	v_pk_add_f32 v[16:17], v[28:29], v[14:15]
	s_nop 0
	v_pk_add_f32 v[18:19], v[16:17], v[28:29] neg_lo:[0,1] neg_hi:[0,1]
	s_nop 0
	v_pk_add_f32 v[14:15], v[14:15], v[18:19] neg_lo:[0,1] neg_hi:[0,1]
	s_nop 0
	v_pk_add_f32 v[12:13], v[12:13], v[14:15]
	s_nop 0
	v_pk_add_f32 v[12:13], v[16:17], v[12:13]
	s_nop 0
	v_cndmask_b32_e32 v9, v199, v12, vcc
	v_cmp_neq_f32_e32 vcc, s17, v7
	s_nop 1
	v_cndmask_b32_e32 v12, v199, v13, vcc
	v_cmp_ngt_f32_e32 vcc, -1.0, v7
	s_nop 1
	v_cndmask_b32_e32 v12, v200, v12, vcc
	v_cmp_ngt_f32_e32 vcc, -1.0, v0
	s_nop 1
; __device__ __forceinline__ float log_sigmoid_f(float v) { return fminf(v, 0.f) - log1pf(__expf(-fabsf(v))); }
;     __device__ __forceinline__ void operator()(const f32x4 (&acc)[2][2][4][2], const pg8::Unit& u, int wr, int wc, int fr, int fq) const {
;     ...
;                 for (int nn = 0; nn < 2; ++nn) { const int head = 2 * fq + nn; const f32x4 gb = *(const f32x4*)(gate_b + 4 * head);
; #pragma unroll
;                     for (int ai = 0; ai < 2; ++ai)
; #pragma unroll
;                         for (int m = 0; m < 4; ++m) { const int row = row0 + ai * 128 + m * 16; f32x4 v = acc[ai][0][m][nn] + gb;
;                             v[1] = log_sigmoid_f(v[1]); v[3] = log_sigmoid_f(v[3]);
;                             *(f32x4*)(G + (size_t)row * 16 + 4 * head) = v; } }
	v_cndmask_b32_e32 v9, v200, v9, vcc
	v_cmp_neq_f32_e32 vcc, -1.0, v0
	s_nop 1
	v_cndmask_b32_e32 v9, v201, v9, vcc
	v_cmp_neq_f32_e32 vcc, -1.0, v7
	s_nop 1
	v_cndmask_b32_e32 v12, v201, v12, vcc
	v_cmp_lt_f32_e64 vcc, |v7|, s19
	s_nop 1
	v_cndmask_b32_e32 v13, v12, v7, vcc
	v_cndmask_b32_e64 v12, v9, v0, s[0:1]
	v_mul_f32_e64 v0, |v3|, s8
	v_exp_f32_e32 v0, v0
	v_pk_add_f32 v[10:11], v[10:11], v[12:13] neg_lo:[0,1] neg_hi:[0,1]
	v_cmp_lt_f32_e64 s[0:1], |v0|, s19
	v_mov_b32_e32 v7, v10
	v_mov_b32_e32 v9, v11
	global_store_dwordx4 v[42:43], v[6:9], off offset:16
	s_nop 1
	v_min_f32_e32 v6, 0, v3
	v_add_f32_e32 v3, 1.0, v0
	v_add_f32_e32 v7, -1.0, v3
	v_sub_f32_e32 v8, v7, v3
	v_add_f32_e32 v8, 1.0, v8
	v_sub_f32_e32 v7, v0, v7
	v_add_f32_e32 v7, v7, v8
	v_frexp_mant_f32_e32 v8, v3
	v_cmp_gt_f32_e32 vcc, s9, v8
	v_cvt_f64_f32_e32 v[8:9], v3
	v_frexp_exp_i32_f64_e32 v8, v[8:9]
	v_subbrev_co_u32_e32 v28, vcc, 0, v8, vcc
	v_sub_u32_e32 v9, 0, v28
	v_ldexp_f32 v8, v3, v9
	v_mul_f32_e64 v3, |v5|, s8
	v_exp_f32_e32 v3, v3
	v_ldexp_f32 v10, v7, v9
	v_min_f32_e32 v7, 0, v5
	v_add_f32_e32 v5, 1.0, v3
	v_add_f32_e32 v9, -1.0, v5
	v_sub_f32_e32 v11, v9, v5
	v_add_f32_e32 v11, 1.0, v11
	v_sub_f32_e32 v9, v3, v9
	v_add_f32_e32 v11, v9, v11
	v_frexp_mant_f32_e32 v9, v5
	v_cvt_f64_f32_e32 v[12:13], v5
	v_cmp_gt_f32_e32 vcc, s9, v9
	v_frexp_exp_i32_f64_e32 v9, v[12:13]
	s_nop 0
	v_subbrev_co_u32_e32 v29, vcc, 0, v9, vcc
	v_sub_u32_e32 v12, 0, v29
	v_ldexp_f32 v9, v5, v12
	v_ldexp_f32 v11, v11, v12
	v_pk_add_f32 v[12:13], v[8:9], 1.0 op_sel_hi:[1,0]
	v_pk_add_f32 v[20:21], v[8:9], -1.0 op_sel_hi:[1,0]
	v_pk_add_f32 v[14:15], v[12:13], -1.0 op_sel_hi:[1,0]
	v_pk_add_f32 v[22:23], v[20:21], 1.0 op_sel_hi:[1,0]
	v_pk_add_f32 v[14:15], v[8:9], v[14:15] neg_lo:[0,1] neg_hi:[0,1]
	v_pk_add_f32 v[8:9], v[8:9], v[22:23] neg_lo:[0,1] neg_hi:[0,1]
	v_pk_add_f32 v[14:15], v[10:11], v[14:15]
	v_pk_add_f32 v[8:9], v[10:11], v[8:9]
	v_pk_add_f32 v[16:17], v[12:13], v[14:15]
	v_pk_add_f32 v[10:11], v[20:21], v[8:9]
	v_rcp_f32_e32 v18, v16
	v_rcp_f32_e32 v19, v17
	v_pk_add_f32 v[12:13], v[16:17], v[12:13] neg_lo:[0,1] neg_hi:[0,1]
	v_pk_add_f32 v[20:21], v[10:11], v[20:21] neg_lo:[0,1] neg_hi:[0,1]
	v_pk_add_f32 v[12:13], v[14:15], v[12:13] neg_lo:[0,1] neg_hi:[0,1]
	v_pk_mul_f32 v[14:15], v[10:11], v[18:19]
	v_pk_add_f32 v[8:9], v[8:9], v[20:21] neg_lo:[0,1] neg_hi:[0,1]
	v_pk_mul_f32 v[20:21], v[16:17], v[14:15]
	v_cmp_neq_f32_e32 vcc, s17, v0
	v_pk_fma_f32 v[22:23], v[14:15], v[16:17], v[20:21] neg_lo:[0,0,1] neg_hi:[0,0,1]
	s_nop 0
	v_pk_fma_f32 v[22:23], v[14:15], v[12:13], v[22:23]
	s_nop 0
	v_pk_add_f32 v[24:25], v[20:21], v[22:23]
	s_nop 0
	v_pk_add_f32 v[26:27], v[10:11], v[24:25] neg_lo:[0,1] neg_hi:[0,1]
	v_pk_add_f32 v[20:21], v[24:25], v[20:21] neg_lo:[0,1] neg_hi:[0,1]
	v_pk_add_f32 v[10:11], v[10:11], v[26:27] neg_lo:[0,1] neg_hi:[0,1]
	s_nop 0
	v_pk_add_f32 v[10:11], v[10:11], v[24:25] neg_lo:[0,1] neg_hi:[0,1]
	s_nop 0
	v_pk_add_f32 v[8:9], v[8:9], v[10:11]
	v_pk_add_f32 v[10:11], v[20:21], v[22:23] neg_lo:[0,1] neg_hi:[0,1]
	s_nop 0
	v_pk_add_f32 v[8:9], v[10:11], v[8:9]
	s_nop 0
	v_pk_add_f32 v[10:11], v[26:27], v[8:9]
	s_nop 0
	v_pk_mul_f32 v[20:21], v[18:19], v[10:11]
	s_nop 0
	v_pk_mul_f32 v[22:23], v[16:17], v[20:21]
	s_nop 0
	v_pk_fma_f32 v[16:17], v[20:21], v[16:17], v[22:23] neg_lo:[0,0,1] neg_hi:[0,0,1]
	s_nop 0
	v_pk_fma_f32 v[12:13], v[20:21], v[12:13], v[16:17]
	v_pk_add_f32 v[16:17], v[26:27], v[10:11] neg_lo:[0,1] neg_hi:[0,1]
	s_nop 0
	v_pk_add_f32 v[8:9], v[8:9], v[16:17]
	v_pk_add_f32 v[16:17], v[22:23], v[12:13]
	s_nop 0
	v_pk_add_f32 v[24:25], v[10:11], v[16:17] neg_lo:[0,1] neg_hi:[0,1]
	v_pk_add_f32 v[22:23], v[16:17], v[22:23] neg_lo:[0,1] neg_hi:[0,1]
	v_pk_add_f32 v[10:11], v[10:11], v[24:25] neg_lo:[0,1] neg_hi:[0,1]
	s_nop 0
	v_pk_add_f32 v[10:11], v[10:11], v[16:17] neg_lo:[0,1] neg_hi:[0,1]
	s_nop 0
	v_pk_add_f32 v[8:9], v[8:9], v[10:11]
	v_pk_add_f32 v[10:11], v[22:23], v[12:13] neg_lo:[0,1] neg_hi:[0,1]
	s_nop 0
	v_pk_add_f32 v[8:9], v[10:11], v[8:9]
	v_pk_add_f32 v[10:11], v[14:15], v[20:21]
	v_pk_add_f32 v[8:9], v[24:25], v[8:9]
	v_pk_add_f32 v[12:13], v[10:11], v[14:15] neg_lo:[0,1] neg_hi:[0,1]
	v_pk_mul_f32 v[8:9], v[18:19], v[8:9]
	v_pk_add_f32 v[12:13], v[20:21], v[12:13] neg_lo:[0,1] neg_hi:[0,1]
; __device__ __forceinline__ float log_sigmoid_f(float v) { return fminf(v, 0.f) - log1pf(__expf(-fabsf(v))); }
;     __device__ __forceinline__ void operator()(const f32x4 (&acc)[2][2][4][2], const pg8::Unit& u, int wr, int wc, int fr, int fq) const {
;     ...
;                 for (int nn = 0; nn < 2; ++nn) { const int head = 2 * fq + nn; const f32x4 gb = *(const f32x4*)(gate_b + 4 * head);
; #pragma unroll
;                     for (int ai = 0; ai < 2; ++ai)
; #pragma unroll
;                         for (int m = 0; m < 4; ++m) { const int row = row0 + ai * 128 + m * 16; f32x4 v = acc[ai][0][m][nn] + gb;
;                             v[1] = log_sigmoid_f(v[1]); v[3] = log_sigmoid_f(v[3]);
;                             *(f32x4*)(G + (size_t)row * 16 + 4 * head) = v; } }
	s_nop 0
	v_pk_add_f32 v[8:9], v[12:13], v[8:9]
	s_nop 0
	v_pk_add_f32 v[12:13], v[10:11], v[8:9]
	s_nop 0
	v_pk_mul_f32 v[14:15], v[12:13], v[12:13]
	v_pk_add_f32 v[10:11], v[12:13], v[10:11] neg_lo:[0,1] neg_hi:[0,1]
	v_pk_fma_f32 v[16:17], v[14:15], s[34:35], v[70:71] op_sel_hi:[1,0,0]
	v_pk_add_f32 v[8:9], v[8:9], v[10:11] neg_lo:[0,1] neg_hi:[0,1]
	v_ldexp_f32 v10, v12, 1
	v_pk_fma_f32 v[16:17], v[14:15], v[16:17], s[36:37] op_sel_hi:[1,1,0]
	v_ldexp_f32 v11, v13, 1
	v_pk_mul_f32 v[12:13], v[12:13], v[14:15]
	v_cvt_f32_i32_e32 v15, v29
	v_cvt_f32_i32_e32 v14, v28
	v_pk_mul_f32 v[12:13], v[12:13], v[16:17]
	v_ldexp_f32 v19, v9, 1
	v_pk_add_f32 v[16:17], v[10:11], v[12:13]
	v_pk_mul_f32 v[20:21], v[14:15], s[38:39] op_sel_hi:[1,0]
	v_pk_add_f32 v[10:11], v[16:17], v[10:11] neg_lo:[0,1] neg_hi:[0,1]
	v_pk_fma_f32 v[22:23], v[14:15], s[38:39], v[20:21] op_sel_hi:[1,0,1] neg_lo:[0,0,1] neg_hi:[0,0,1]
	v_pk_add_f32 v[10:11], v[12:13], v[10:11] neg_lo:[0,1] neg_hi:[0,1]
	v_pk_fma_f32 v[14:15], v[14:15], s[40:41], v[22:23] op_sel_hi:[1,0,1]
	v_ldexp_f32 v8, v8, 1
	v_mov_b32_e32 v12, v20
	v_mov_b32_e32 v13, v11
	v_mov_b32_e32 v18, v14
	v_mov_b32_e32 v9, v19
	v_pk_add_f32 v[12:13], v[12:13], v[18:19]
	v_pk_add_f32 v[18:19], v[8:9], v[10:11]
	v_mov_b32_e32 v11, v17
	v_mov_b32_e32 v9, v19
	v_pk_add_f32 v[22:23], v[20:21], v[14:15]
	v_pk_add_f32 v[8:9], v[8:9], v[10:11]
	v_pk_add_f32 v[10:11], v[16:17], v[18:19]
	v_mov_b32_e32 v32, v16
	v_pk_add_f32 v[24:25], v[22:23], v[10:11]
	v_mov_b32_e32 v30, v10
	v_mov_b32_e32 v31, v25
	v_mov_b32_e32 v33, v23
	v_pk_add_f32 v[30:31], v[30:31], v[32:33] neg_lo:[0,1] neg_hi:[0,1]
	v_mov_b32_e32 v26, v24
	v_mov_b32_e32 v27, v23
	v_mov_b32_e32 v28, v22
	v_mov_b32_e32 v29, v21
	v_mov_b32_e32 v32, v22
	v_mov_b32_e32 v33, v25
	v_mov_b32_e32 v21, v31
	v_pk_add_f32 v[26:27], v[26:27], v[28:29] neg_lo:[0,1] neg_hi:[0,1]
	v_mov_b32_e32 v28, v10
	v_mov_b32_e32 v29, v15
	v_pk_add_f32 v[20:21], v[32:33], v[20:21] neg_lo:[0,1] neg_hi:[0,1]
	v_pk_add_f32 v[28:29], v[28:29], v[26:27] neg_lo:[0,1] neg_hi:[0,1]
	v_mov_b32_e32 v32, v20
	v_mov_b32_e32 v33, v27
	v_mov_b32_e32 v34, v24
	v_mov_b32_e32 v35, v11
	v_mov_b32_e32 v27, v17
	v_pk_add_f32 v[32:33], v[14:15], v[32:33] neg_lo:[0,1] neg_hi:[0,1]
	v_pk_add_f32 v[26:27], v[34:35], v[26:27] neg_lo:[0,1] neg_hi:[0,1]
	v_mov_b32_e32 v15, v23
	v_pk_add_f32 v[12:13], v[12:13], v[26:27] neg_lo:[0,1] neg_hi:[0,1]
	v_pk_add_f32 v[14:15], v[14:15], v[20:21] neg_lo:[0,1] neg_hi:[0,1]
	v_pk_add_f32 v[8:9], v[8:9], v[30:31] neg_lo:[0,1] neg_hi:[0,1]
	v_pk_add_f32 v[10:11], v[10:11], v[16:17] neg_lo:[0,1] neg_hi:[0,1]
	v_pk_add_f32 v[16:17], v[8:9], v[14:15]
	v_mov_b32_e32 v15, v29
	v_mov_b32_e32 v9, v13
	v_pk_add_f32 v[10:11], v[18:19], v[10:11] neg_lo:[0,1] neg_hi:[0,1]
	v_pk_add_f32 v[18:19], v[28:29], v[12:13]
	v_pk_add_f32 v[8:9], v[14:15], v[8:9]
	v_mov_b32_e32 v12, v16
	v_pk_add_f32 v[8:9], v[8:9], v[32:33] neg_lo:[0,1] neg_hi:[0,1]
	v_mov_b32_e32 v13, v19
	v_pk_add_f32 v[12:13], v[12:13], v[8:9] neg_lo:[0,1] neg_hi:[0,1]
	v_pk_add_f32 v[8:9], v[10:11], v[8:9] neg_lo:[0,1] neg_hi:[0,1]
	v_pk_add_f32 v[12:13], v[14:15], v[12:13] neg_lo:[0,1] neg_hi:[0,1]
	v_pk_add_f32 v[10:11], v[18:19], v[16:17]
	v_pk_add_f32 v[8:9], v[8:9], v[12:13]
	v_pk_add_f32 v[12:13], v[24:25], v[10:11]
	s_nop 0
	v_pk_add_f32 v[14:15], v[12:13], v[24:25] neg_lo:[0,1] neg_hi:[0,1]
	s_nop 0
	v_pk_add_f32 v[10:11], v[10:11], v[14:15] neg_lo:[0,1] neg_hi:[0,1]
	s_nop 0
	v_pk_add_f32 v[8:9], v[8:9], v[10:11]
	s_nop 0
	v_pk_add_f32 v[8:9], v[12:13], v[8:9]
	s_nop 0
	v_cndmask_b32_e32 v5, v199, v8, vcc
	v_cmp_neq_f32_e32 vcc, s17, v3
	s_nop 1
	v_cndmask_b32_e32 v8, v199, v9, vcc
	v_cmp_ngt_f32_e32 vcc, -1.0, v3
	s_nop 1
	v_cndmask_b32_e32 v8, v200, v8, vcc
	v_cmp_ngt_f32_e32 vcc, -1.0, v0
	s_nop 1
	v_cndmask_b32_e32 v5, v200, v5, vcc
	v_cmp_neq_f32_e32 vcc, -1.0, v0
	s_nop 1
	v_cndmask_b32_e32 v5, v201, v5, vcc
	v_cmp_neq_f32_e32 vcc, -1.0, v3
	s_nop 1
	v_cndmask_b32_e32 v8, v201, v8, vcc
	v_cmp_lt_f32_e64 vcc, |v3|, s19
	s_nop 1
	v_cndmask_b32_e32 v9, v8, v3, vcc
	v_cndmask_b32_e64 v8, v5, v0, s[0:1]
	v_pk_add_f32 v[6:7], v[6:7], v[8:9] neg_lo:[0,1] neg_hi:[0,1]
	s_nop 0
	v_mov_b32_e32 v3, v6
	v_mov_b32_e32 v5, v7
	global_store_dwordx4 v[38:39], v[2:5], off offset:16

; #define PG8_STAGE(bufoff, gbase, voff) do { _Pragma("unroll") for (int _i = 0; _i < 2; ++_i) \
;         __builtin_amdgcn_global_load_lds((const unsigned*)((const char*)(gbase) + (voff)[_i]), (LAS unsigned*)(lds + (bufoff) + ldsw + _i * 8192), 16, 0, 0); } while (0)
; #define PG8_LDA(dst, b, h) do { _Pragma("unroll") for (int m = 0; m < 4; ++m) _Pragma("unroll") for (int k = 0; k < 2; ++k) dst[m][k] = *(const LAS bf16x8*)(lds + PG8_SA(b, h) + aoff + m * 2048 + k * 1024); } while (0)
; #define PG8_LDB(dst, b, h) do { _Pragma("unroll") for (int n = 0; n < 2; ++n) _Pragma("unroll") for (int k = 0; k < 2; ++k) dst[n][k] = *(const LAS bf16x8*)(lds + PG8_SB(b, h) + boff + n * 2048 + k * 1024); } while (0)
; #define PG8_MMA(ai, bj, At, Bt) do { __builtin_amdgcn_s_setprio(1); _Pragma("unroll") for (int m = 0; m < 4; ++m) _Pragma("unroll") for (int n = 0; n < 2; ++n) _Pragma("unroll") for (int k = 0; k < 2; ++k) \
;         acc[ai][bj][m][n] = __builtin_amdgcn_mfma_f32_16x16x32_bf16(Bt[n][k], At[m][k], acc[ai][bj][m][n], 0, 0, 0); __builtin_amdgcn_s_setprio(0); } while (0)
; #define PG8_WAIT_V(n) asm volatile("s_waitcnt vmcnt(" #n ")" ::: "memory")
; #define PG8_WAIT_L(n) asm volatile("s_waitcnt lgkmcnt(" #n ")" ::: "memory")
; #define PG8_BAR __builtin_amdgcn_s_barrier()
; template <class Epi, bool ALIGN_EPI = PG8_ALIGN, bool SP2 = PG8_SP2>
; __device__ __forceinline__ void gemm_phase(LAS unsigned char* lds, const Gemm g, const StaticOrder& S, const Epi& E) {
;     ...
;         for (int t = 0; t < nt; t += 2) {
;             const bool last = (t == nt - 2);
;             const char* a1 = cA + (size_t)(t + 1) * kstepA;
;             const char* a2 = last ? nA : cA + (size_t)(t + 2) * kstepA; const char* b2 = last ? nB : cB + (size_t)(t + 2) * kstepB;
;             const char* a3 = a2 + kstepA; const char* b3 = b2 + kstepB;
;             if constexpr (SP2) {
;             PG8_LDB(B0, 0, 0); PG8_LDB(B1, 0, 1); PG8_SCHED; PG8_LDA(At, 0, 0); PG8_STAGE(PG8_SA(1, 1), a1 + hstepA, voffA);
;             PG8_WAIT_V(8); PG8_WAIT_L(0); PG8_BAR; PG8_MMA(0, 0, At, B0); PG8_MMA(0, 1, At, B1); PG8_BAR; PG8_SCHED;
;             PG8_LDA(At, 0, 1); PG8_STAGE(PG8_SB(0, 0), b2, voffB); PG8_STAGE(PG8_SB(0, 1), b2 + hstepB, voffB); PG8_STAGE(PG8_SA(0, 0), a2, voffA);
;             PG8_WAIT_V(8); PG8_WAIT_L(0); PG8_BAR; PG8_MMA(1, 0, At, B0); PG8_MMA(1, 1, At, B1); PG8_BAR; PG8_SCHED;
.LBB0_582:
	s_add_u32 s71, s26, s38
	s_addc_u32 s72, s27, s33
	s_mov_b64 s[28:29], 0
.LBB0_583:
	s_cmp_eq_u32 s28, 0
	s_cbranch_scc1 .Lfirst_iter_u583
	s_add_u32 s74, s28, 1
	s_addc_u32 s75, s29, 0
	s_add_u32 s30, s28, 2
	s_addc_u32 s31, s29, 0
	s_lshl_b64 s[34:35], s[30:31], s56
	s_add_u32 s29, s26, s34
	s_addc_u32 s36, s27, s35
	s_add_u32 s34, s24, s34
	s_addc_u32 s35, s25, s35
	s_cmp_eq_u32 s66, s28
	s_cselect_b32 s37, s21, s36
	s_cselect_b32 s36, s20, s29
	s_cselect_b32 s34, s22, s34
	s_cselect_b32 s35, s23, s35
	s_add_u32 s28, s36, s52
	s_addc_u32 s29, s37, 0
	s_add_i32 s73, 0, 0x10000
	s_add_i32 s76, 0, 0x14000
	v_add_u32_e32 v144, s73, v155
	v_add_u32_e32 v152, s76, v155
	ds_read_b128 v[132:135], v144
	ds_read_b128 v[136:139], v144 offset:1024
	ds_read_b128 v[140:143], v144 offset:2048
	ds_read_b128 v[144:147], v144 offset:3072
	ds_read_b128 v[148:151], v152
	ds_read_b128 v[158:161], v152 offset:1024
	ds_read_b128 v[170:173], v152 offset:2048
	ds_read_b128 v[174:177], v152 offset:3072
	s_lshl_b64 s[74:75], s[74:75], s56
	s_add_u32 s74, s71, s74
	s_addc_u32 s75, s72, s75
	v_lshl_add_u64 v[152:153], s[74:75], 0, v[0:1]
	s_add_i32 m0, s41, 0xc000
	ds_read_b128 v[178:181], v157
	ds_read_b128 v[182:185], v157 offset:1024
	ds_read_b128 v[186:189], v157 offset:2048
	ds_read_b128 v[206:209], v157 offset:3072
	ds_read_b128 v[210:213], v157 offset:4096
	ds_read_b128 v[214:217], v157 offset:5120
	ds_read_b128 v[218:221], v157 offset:6144
	ds_read_b128 v[222:225], v157 offset:7168
	global_load_lds_dwordx4 v[152:153], off
	v_lshl_add_u64 v[152:153], s[74:75], 0, v[130:131]
	s_add_i32 m0, s41, 0xe000
	s_nop 0
	global_load_lds_dwordx4 v[152:153], off
	s_waitcnt vmcnt(8)
	s_waitcnt lgkmcnt(0)
	s_barrier
	s_setprio 1
	s_waitcnt lgkmcnt(0)
	v_mfma_f32_16x16x32_bf16 v[126:129], v[132:135], v[178:181], v[126:129]
	v_mfma_f32_16x16x32_bf16 v[122:125], v[140:143], v[178:181], v[122:125]
	v_mfma_f32_16x16x32_bf16 v[118:121], v[132:135], v[186:189], v[118:121]
	v_mfma_f32_16x16x32_bf16 v[114:117], v[140:143], v[186:189], v[114:117]
	v_mfma_f32_16x16x32_bf16 v[110:113], v[132:135], v[210:213], v[110:113]
	v_mfma_f32_16x16x32_bf16 v[90:93], v[140:143], v[210:213], v[90:93]
	v_mfma_f32_16x16x32_bf16 v[86:89], v[132:135], v[218:221], v[86:89]
	v_mfma_f32_16x16x32_bf16 v[78:81], v[140:143], v[218:221], v[78:81]
	v_mfma_f32_16x16x32_bf16 v[126:129], v[136:139], v[182:185], v[126:129]
	v_mfma_f32_16x16x32_bf16 v[122:125], v[144:147], v[182:185], v[122:125]
	v_mfma_f32_16x16x32_bf16 v[118:121], v[136:139], v[206:209], v[118:121]
	v_mfma_f32_16x16x32_bf16 v[114:117], v[144:147], v[206:209], v[114:117]
	v_mfma_f32_16x16x32_bf16 v[110:113], v[136:139], v[214:217], v[110:113]
	v_mfma_f32_16x16x32_bf16 v[90:93], v[144:147], v[214:217], v[90:93]
	v_mfma_f32_16x16x32_bf16 v[86:89], v[136:139], v[222:225], v[86:89]
	v_mfma_f32_16x16x32_bf16 v[78:81], v[144:147], v[222:225], v[78:81]
	s_setprio 0
	s_setprio 1
	v_mfma_f32_16x16x32_bf16 v[106:109], v[148:151], v[178:181], v[106:109]
	v_mfma_f32_16x16x32_bf16 v[102:105], v[170:173], v[178:181], v[102:105]
	v_mfma_f32_16x16x32_bf16 v[98:101], v[148:151], v[186:189], v[98:101]
	v_mfma_f32_16x16x32_bf16 v[94:97], v[170:173], v[186:189], v[94:97]
	v_mfma_f32_16x16x32_bf16 v[82:85], v[148:151], v[210:213], v[82:85]
	v_mfma_f32_16x16x32_bf16 v[74:77], v[170:173], v[210:213], v[74:77]
	v_mfma_f32_16x16x32_bf16 v[70:73], v[148:151], v[218:221], v[70:73]
	v_mfma_f32_16x16x32_bf16 v[66:69], v[170:173], v[218:221], v[66:69]
	v_mfma_f32_16x16x32_bf16 v[106:109], v[158:161], v[182:185], v[106:109]
	v_mfma_f32_16x16x32_bf16 v[102:105], v[174:177], v[182:185], v[102:105]
	v_mfma_f32_16x16x32_bf16 v[98:101], v[158:161], v[206:209], v[98:101]
	v_mfma_f32_16x16x32_bf16 v[94:97], v[174:177], v[206:209], v[94:97]
	v_mfma_f32_16x16x32_bf16 v[82:85], v[158:161], v[214:217], v[82:85]
	v_mfma_f32_16x16x32_bf16 v[74:77], v[174:177], v[214:217], v[74:77]
	v_mfma_f32_16x16x32_bf16 v[70:73], v[158:161], v[222:225], v[70:73]
	v_mfma_f32_16x16x32_bf16 v[66:69], v[174:177], v[222:225], v[66:69]
	s_setprio 0
	s_barrier
	s_add_i32 s73, s73, s40
	v_lshl_add_u64 v[152:153], s[34:35], 0, v[0:1]
	s_mov_b32 m0, s73
	ds_read_b128 v[178:181], v157 offset:16384
	ds_read_b128 v[182:185], v157 offset:17408
	ds_read_b128 v[186:189], v157 offset:18432
	ds_read_b128 v[206:209], v157 offset:19456
	ds_read_b128 v[210:213], v157 offset:20480
	ds_read_b128 v[214:217], v157 offset:21504
	ds_read_b128 v[218:221], v157 offset:22528
	ds_read_b128 v[222:225], v157 offset:23552
	global_load_lds_dwordx4 v[152:153], off
	s_add_i32 m0, s73, 0x2000
	s_add_u32 s74, s34, s38
	v_lshl_add_u64 v[152:153], s[34:35], 0, v[130:131]
	s_addc_u32 s75, s35, s33
	s_add_i32 s73, s76, s40
	global_load_lds_dwordx4 v[152:153], off
	v_lshl_add_u64 v[152:153], s[74:75], 0, v[0:1]
	s_mov_b32 m0, s73
	s_nop 0
	global_load_lds_dwordx4 v[152:153], off
	v_lshl_add_u64 v[152:153], s[74:75], 0, v[130:131]
	s_add_i32 m0, s73, 0x2000
	s_nop 0
	global_load_lds_dwordx4 v[152:153], off
	v_lshl_add_u64 v[152:153], s[36:37], 0, v[0:1]
	s_mov_b32 m0, s41
	s_nop 0
	global_load_lds_dwordx4 v[152:153], off
	v_lshl_add_u64 v[152:153], s[36:37], 0, v[130:131]
	s_mov_b32 m0, s42
	s_nop 0
	global_load_lds_dwordx4 v[152:153], off
	s_waitcnt vmcnt(8)
	s_waitcnt lgkmcnt(0)
	s_barrier
; #define PG8_STAGE(bufoff, gbase, voff) do { _Pragma("unroll") for (int _i = 0; _i < 2; ++_i) \
;         __builtin_amdgcn_global_load_lds((const unsigned*)((const char*)(gbase) + (voff)[_i]), (LAS unsigned*)(lds + (bufoff) + ldsw + _i * 8192), 16, 0, 0); } while (0)
; #define PG8_LDA(dst, b, h) do { _Pragma("unroll") for (int m = 0; m < 4; ++m) _Pragma("unroll") for (int k = 0; k < 2; ++k) dst[m][k] = *(const LAS bf16x8*)(lds + PG8_SA(b, h) + aoff + m * 2048 + k * 1024); } while (0)
; #define PG8_LDB(dst, b, h) do { _Pragma("unroll") for (int n = 0; n < 2; ++n) _Pragma("unroll") for (int k = 0; k < 2; ++k) dst[n][k] = *(const LAS bf16x8*)(lds + PG8_SB(b, h) + boff + n * 2048 + k * 1024); } while (0)
; #define PG8_MMA(ai, bj, At, Bt) do { __builtin_amdgcn_s_setprio(1); _Pragma("unroll") for (int m = 0; m < 4; ++m) _Pragma("unroll") for (int n = 0; n < 2; ++n) _Pragma("unroll") for (int k = 0; k < 2; ++k) \
;         acc[ai][bj][m][n] = __builtin_amdgcn_mfma_f32_16x16x32_bf16(Bt[n][k], At[m][k], acc[ai][bj][m][n], 0, 0, 0); __builtin_amdgcn_s_setprio(0); } while (0)
; #define PG8_WAIT_V(n) asm volatile("s_waitcnt vmcnt(" #n ")" ::: "memory")
; #define PG8_WAIT_L(n) asm volatile("s_waitcnt lgkmcnt(" #n ")" ::: "memory")
; #define PG8_BAR __builtin_amdgcn_s_barrier()
; #define PG8_SCHED __builtin_amdgcn_sched_barrier(0)
; template <class Epi, bool ALIGN_EPI = PG8_ALIGN, bool SP2 = PG8_SP2>
; __device__ __forceinline__ void gemm_phase(LAS unsigned char* lds, const Gemm g, const StaticOrder& S, const Epi& E) {
;     ...
;             PG8_WAIT_V(8); PG8_WAIT_L(0); PG8_BAR; PG8_MMA(1, 0, At, B0); PG8_MMA(1, 1, At, B1); PG8_BAR; PG8_SCHED;
;             PG8_LDB(B0, 1, 0); PG8_LDB(B1, 1, 1); PG8_SCHED; PG8_LDA(At, 1, 0); PG8_STAGE(PG8_SA(0, 1), a2 + hstepA, voffA);
;             PG8_WAIT_V(8); PG8_WAIT_L(0); PG8_BAR; PG8_MMA(0, 0, At, B0); PG8_MMA(0, 1, At, B1); PG8_BAR; PG8_SCHED;
;             PG8_LDA(At, 1, 1); PG8_STAGE(PG8_SB(1, 0), b3, voffB); PG8_STAGE(PG8_SB(1, 1), b3 + hstepB, voffB); PG8_STAGE(PG8_SA(1, 0), a3, voffA);
;             PG8_WAIT_V(8); PG8_WAIT_L(0); PG8_BAR; PG8_MMA(1, 0, At, B0); PG8_MMA(1, 1, At, B1); PG8_BAR; PG8_SCHED;
	s_setprio 1
	s_waitcnt lgkmcnt(0)
	v_mfma_f32_16x16x32_bf16 v[62:65], v[132:135], v[178:181], v[62:65]
	v_mfma_f32_16x16x32_bf16 v[58:61], v[140:143], v[178:181], v[58:61]
	v_mfma_f32_16x16x32_bf16 v[54:57], v[132:135], v[186:189], v[54:57]
	v_mfma_f32_16x16x32_bf16 v[50:53], v[140:143], v[186:189], v[50:53]
	v_mfma_f32_16x16x32_bf16 v[46:49], v[132:135], v[210:213], v[46:49]
	v_mfma_f32_16x16x32_bf16 v[34:37], v[140:143], v[210:213], v[34:37]
	v_mfma_f32_16x16x32_bf16 v[18:21], v[132:135], v[218:221], v[18:21]
	v_mfma_f32_16x16x32_bf16 v[14:17], v[140:143], v[218:221], v[14:17]
	v_mfma_f32_16x16x32_bf16 v[62:65], v[136:139], v[182:185], v[62:65]
	v_mfma_f32_16x16x32_bf16 v[58:61], v[144:147], v[182:185], v[58:61]
	v_mfma_f32_16x16x32_bf16 v[54:57], v[136:139], v[206:209], v[54:57]
	v_mfma_f32_16x16x32_bf16 v[50:53], v[144:147], v[206:209], v[50:53]
	v_mfma_f32_16x16x32_bf16 v[46:49], v[136:139], v[214:217], v[46:49]
	v_mfma_f32_16x16x32_bf16 v[34:37], v[144:147], v[214:217], v[34:37]
	v_mfma_f32_16x16x32_bf16 v[18:21], v[136:139], v[222:225], v[18:21]
	v_mfma_f32_16x16x32_bf16 v[14:17], v[144:147], v[222:225], v[14:17]
	s_setprio 0
	s_setprio 1
	v_mfma_f32_16x16x32_bf16 v[42:45], v[148:151], v[178:181], v[42:45]
	v_mfma_f32_16x16x32_bf16 v[38:41], v[170:173], v[178:181], v[38:41]
	v_mfma_f32_16x16x32_bf16 v[30:33], v[148:151], v[186:189], v[30:33]
	v_mfma_f32_16x16x32_bf16 v[26:29], v[170:173], v[186:189], v[26:29]
	v_mfma_f32_16x16x32_bf16 v[22:25], v[148:151], v[210:213], v[22:25]
	v_mfma_f32_16x16x32_bf16 v[10:13], v[170:173], v[210:213], v[10:13]
	v_mfma_f32_16x16x32_bf16 v[6:9], v[148:151], v[218:221], v[6:9]
	v_mfma_f32_16x16x32_bf16 v[2:5], v[170:173], v[218:221], v[2:5]
	v_mfma_f32_16x16x32_bf16 v[42:45], v[158:161], v[182:185], v[42:45]
	v_mfma_f32_16x16x32_bf16 v[38:41], v[174:177], v[182:185], v[38:41]
	v_mfma_f32_16x16x32_bf16 v[30:33], v[158:161], v[206:209], v[30:33]
	v_mfma_f32_16x16x32_bf16 v[26:29], v[174:177], v[206:209], v[26:29]
	v_mfma_f32_16x16x32_bf16 v[22:25], v[158:161], v[214:217], v[22:25]
	v_mfma_f32_16x16x32_bf16 v[10:13], v[174:177], v[214:217], v[10:13]
	v_mfma_f32_16x16x32_bf16 v[6:9], v[158:161], v[222:225], v[6:9]
	v_mfma_f32_16x16x32_bf16 v[2:5], v[174:177], v[222:225], v[2:5]
	s_setprio 0
	s_barrier
	s_add_i32 s73, 0, 0x18000
	s_add_i32 s74, 0, 0x1c000
	v_add_u32_e32 v144, s73, v155
	v_add_u32_e32 v152, s74, v155
	ds_read_b128 v[132:135], v144
	ds_read_b128 v[136:139], v144 offset:1024
	ds_read_b128 v[140:143], v144 offset:2048
	ds_read_b128 v[144:147], v144 offset:3072
	ds_read_b128 v[148:151], v152
	ds_read_b128 v[158:161], v152 offset:1024
	ds_read_b128 v[170:173], v152 offset:2048
	ds_read_b128 v[174:177], v152 offset:3072
	s_add_u32 s36, s36, s38
	s_addc_u32 s37, s37, s33
	s_mov_b32 m0, s43
	v_lshl_add_u64 v[152:153], s[36:37], 0, v[0:1]
	ds_read_b128 v[178:181], v157 offset:32768
	ds_read_b128 v[182:185], v157 offset:33792
	ds_read_b128 v[186:189], v157 offset:34816
	ds_read_b128 v[206:209], v157 offset:35840
	ds_read_b128 v[210:213], v157 offset:36864
	ds_read_b128 v[214:217], v157 offset:37888
	ds_read_b128 v[218:221], v157 offset:38912
	ds_read_b128 v[222:225], v157 offset:39936
	global_load_lds_dwordx4 v[152:153], off
	v_lshl_add_u64 v[152:153], s[36:37], 0, v[130:131]
	s_mov_b32 m0, s44
	s_nop 0
	global_load_lds_dwordx4 v[152:153], off
	s_waitcnt vmcnt(8)
	s_waitcnt lgkmcnt(0)
	s_barrier
	s_setprio 1
	s_waitcnt lgkmcnt(0)
	v_mfma_f32_16x16x32_bf16 v[126:129], v[132:135], v[178:181], v[126:129]
	v_mfma_f32_16x16x32_bf16 v[122:125], v[140:143], v[178:181], v[122:125]
	v_mfma_f32_16x16x32_bf16 v[118:121], v[132:135], v[186:189], v[118:121]
	v_mfma_f32_16x16x32_bf16 v[114:117], v[140:143], v[186:189], v[114:117]
	v_mfma_f32_16x16x32_bf16 v[110:113], v[132:135], v[210:213], v[110:113]
	v_mfma_f32_16x16x32_bf16 v[90:93], v[140:143], v[210:213], v[90:93]
	v_mfma_f32_16x16x32_bf16 v[86:89], v[132:135], v[218:221], v[86:89]
	v_mfma_f32_16x16x32_bf16 v[78:81], v[140:143], v[218:221], v[78:81]
	v_mfma_f32_16x16x32_bf16 v[126:129], v[136:139], v[182:185], v[126:129]
	v_mfma_f32_16x16x32_bf16 v[122:125], v[144:147], v[182:185], v[122:125]
	v_mfma_f32_16x16x32_bf16 v[118:121], v[136:139], v[206:209], v[118:121]
	v_mfma_f32_16x16x32_bf16 v[114:117], v[144:147], v[206:209], v[114:117]
	v_mfma_f32_16x16x32_bf16 v[110:113], v[136:139], v[214:217], v[110:113]
	v_mfma_f32_16x16x32_bf16 v[90:93], v[144:147], v[214:217], v[90:93]
	v_mfma_f32_16x16x32_bf16 v[86:89], v[136:139], v[222:225], v[86:89]
	v_mfma_f32_16x16x32_bf16 v[78:81], v[144:147], v[222:225], v[78:81]
	s_setprio 0
	s_setprio 1
	v_mfma_f32_16x16x32_bf16 v[106:109], v[148:151], v[178:181], v[106:109]
	v_mfma_f32_16x16x32_bf16 v[102:105], v[170:173], v[178:181], v[102:105]
	v_mfma_f32_16x16x32_bf16 v[98:101], v[148:151], v[186:189], v[98:101]
	v_mfma_f32_16x16x32_bf16 v[94:97], v[170:173], v[186:189], v[94:97]
	v_mfma_f32_16x16x32_bf16 v[82:85], v[148:151], v[210:213], v[82:85]
	v_mfma_f32_16x16x32_bf16 v[74:77], v[170:173], v[210:213], v[74:77]
	v_mfma_f32_16x16x32_bf16 v[70:73], v[148:151], v[218:221], v[70:73]
	v_mfma_f32_16x16x32_bf16 v[66:69], v[170:173], v[218:221], v[66:69]
	v_mfma_f32_16x16x32_bf16 v[106:109], v[158:161], v[182:185], v[106:109]
	v_mfma_f32_16x16x32_bf16 v[102:105], v[174:177], v[182:185], v[102:105]
	v_mfma_f32_16x16x32_bf16 v[98:101], v[158:161], v[206:209], v[98:101]
	v_mfma_f32_16x16x32_bf16 v[94:97], v[174:177], v[206:209], v[94:97]
	v_mfma_f32_16x16x32_bf16 v[82:85], v[158:161], v[214:217], v[82:85]
	v_mfma_f32_16x16x32_bf16 v[74:77], v[174:177], v[214:217], v[74:77]
	v_mfma_f32_16x16x32_bf16 v[70:73], v[158:161], v[222:225], v[70:73]
	v_mfma_f32_16x16x32_bf16 v[66:69], v[174:177], v[222:225], v[66:69]
	s_setprio 0
	s_barrier
; #define PG8_STAGE(bufoff, gbase, voff) do { _Pragma("unroll") for (int _i = 0; _i < 2; ++_i) \
;         __builtin_amdgcn_global_load_lds((const unsigned*)((const char*)(gbase) + (voff)[_i]), (LAS unsigned*)(lds + (bufoff) + ldsw + _i * 8192), 16, 0, 0); } while (0)
; #define PG8_LDA(dst, b, h) do { _Pragma("unroll") for (int m = 0; m < 4; ++m) _Pragma("unroll") for (int k = 0; k < 2; ++k) dst[m][k] = *(const LAS bf16x8*)(lds + PG8_SA(b, h) + aoff + m * 2048 + k * 1024); } while (0)
; #define PG8_MMA(ai, bj, At, Bt) do { __builtin_amdgcn_s_setprio(1); _Pragma("unroll") for (int m = 0; m < 4; ++m) _Pragma("unroll") for (int n = 0; n < 2; ++n) _Pragma("unroll") for (int k = 0; k < 2; ++k) \
;         acc[ai][bj][m][n] = __builtin_amdgcn_mfma_f32_16x16x32_bf16(Bt[n][k], At[m][k], acc[ai][bj][m][n], 0, 0, 0); __builtin_amdgcn_s_setprio(0); } while (0)
; #define PG8_WAIT_V(n) asm volatile("s_waitcnt vmcnt(" #n ")" ::: "memory")
; #define PG8_WAIT_L(n) asm volatile("s_waitcnt lgkmcnt(" #n ")" ::: "memory")
; #define PG8_BAR __builtin_amdgcn_s_barrier()
; #define PG8_SCHED __builtin_amdgcn_sched_barrier(0)
; template <class Epi, bool ALIGN_EPI = PG8_ALIGN, bool SP2 = PG8_SP2>
; __device__ __forceinline__ void gemm_phase(LAS unsigned char* lds, const Gemm g, const StaticOrder& S, const Epi& E) {
;     ...
;             PG8_LDA(At, 1, 1); PG8_STAGE(PG8_SB(1, 0), b3, voffB); PG8_STAGE(PG8_SB(1, 1), b3 + hstepB, voffB); PG8_STAGE(PG8_SA(1, 0), a3, voffA);
;             PG8_WAIT_V(8); PG8_WAIT_L(0); PG8_BAR; PG8_MMA(1, 0, At, B0); PG8_MMA(1, 1, At, B1); PG8_BAR; PG8_SCHED;
;     ...
;         }
;         if constexpr (ALIGN_EPI) { if (wr == 0) PG8_BAR; }
	s_add_u32 s34, s34, s52
	s_addc_u32 s35, s35, 0
	s_add_i32 s36, s73, s40
	v_lshl_add_u64 v[152:153], s[34:35], 0, v[0:1]
	s_mov_b32 m0, s36
	ds_read_b128 v[178:181], v157 offset:49152
	ds_read_b128 v[182:185], v157 offset:50176
	ds_read_b128 v[186:189], v157 offset:51200
	ds_read_b128 v[206:209], v157 offset:52224
	ds_read_b128 v[210:213], v157 offset:53248
	ds_read_b128 v[214:217], v157 offset:54272
	ds_read_b128 v[218:221], v157 offset:55296
	ds_read_b128 v[222:225], v157 offset:56320
	global_load_lds_dwordx4 v[152:153], off
	s_add_i32 m0, s36, 0x2000
	v_lshl_add_u64 v[152:153], s[34:35], 0, v[130:131]
	s_add_u32 s34, s34, s38
	s_addc_u32 s35, s35, s33
	s_add_i32 s36, s74, s40
	global_load_lds_dwordx4 v[152:153], off
	v_lshl_add_u64 v[152:153], s[34:35], 0, v[0:1]
	s_mov_b32 m0, s36
	s_nop 0
	global_load_lds_dwordx4 v[152:153], off
	v_lshl_add_u64 v[152:153], s[34:35], 0, v[130:131]
	s_add_i32 m0, s36, 0x2000
	s_nop 0
	global_load_lds_dwordx4 v[152:153], off
	v_lshl_add_u64 v[152:153], s[28:29], 0, v[0:1]
	s_mov_b32 m0, s53
	s_nop 0
	global_load_lds_dwordx4 v[152:153], off
	v_lshl_add_u64 v[152:153], s[28:29], 0, v[130:131]
	s_mov_b32 m0, s54
	s_nop 0
	global_load_lds_dwordx4 v[152:153], off
	s_waitcnt vmcnt(8)
	s_waitcnt lgkmcnt(0)
	s_barrier
	s_setprio 1
	s_waitcnt lgkmcnt(0)
	v_mfma_f32_16x16x32_bf16 v[62:65], v[132:135], v[178:181], v[62:65]
	v_mfma_f32_16x16x32_bf16 v[58:61], v[140:143], v[178:181], v[58:61]
	v_mfma_f32_16x16x32_bf16 v[54:57], v[132:135], v[186:189], v[54:57]
	v_mfma_f32_16x16x32_bf16 v[50:53], v[140:143], v[186:189], v[50:53]
	v_mfma_f32_16x16x32_bf16 v[46:49], v[132:135], v[210:213], v[46:49]
	v_mfma_f32_16x16x32_bf16 v[34:37], v[140:143], v[210:213], v[34:37]
	v_mfma_f32_16x16x32_bf16 v[18:21], v[132:135], v[218:221], v[18:21]
	v_mfma_f32_16x16x32_bf16 v[14:17], v[140:143], v[218:221], v[14:17]
	v_mfma_f32_16x16x32_bf16 v[62:65], v[136:139], v[182:185], v[62:65]
	v_mfma_f32_16x16x32_bf16 v[58:61], v[144:147], v[182:185], v[58:61]
	v_mfma_f32_16x16x32_bf16 v[54:57], v[136:139], v[206:209], v[54:57]
	v_mfma_f32_16x16x32_bf16 v[50:53], v[144:147], v[206:209], v[50:53]
	v_mfma_f32_16x16x32_bf16 v[46:49], v[136:139], v[214:217], v[46:49]
	v_mfma_f32_16x16x32_bf16 v[34:37], v[144:147], v[214:217], v[34:37]
	v_mfma_f32_16x16x32_bf16 v[18:21], v[136:139], v[222:225], v[18:21]
	v_mfma_f32_16x16x32_bf16 v[14:17], v[144:147], v[222:225], v[14:17]
	s_setprio 0
	s_setprio 1
	v_mfma_f32_16x16x32_bf16 v[42:45], v[148:151], v[178:181], v[42:45]
	v_mfma_f32_16x16x32_bf16 v[38:41], v[170:173], v[178:181], v[38:41]
	v_mfma_f32_16x16x32_bf16 v[30:33], v[148:151], v[186:189], v[30:33]
	v_mfma_f32_16x16x32_bf16 v[26:29], v[170:173], v[186:189], v[26:29]
	v_mfma_f32_16x16x32_bf16 v[22:25], v[148:151], v[210:213], v[22:25]
	v_mfma_f32_16x16x32_bf16 v[10:13], v[170:173], v[210:213], v[10:13]
	v_mfma_f32_16x16x32_bf16 v[6:9], v[148:151], v[218:221], v[6:9]
	v_mfma_f32_16x16x32_bf16 v[2:5], v[170:173], v[218:221], v[2:5]
	v_mfma_f32_16x16x32_bf16 v[42:45], v[158:161], v[182:185], v[42:45]
	v_mfma_f32_16x16x32_bf16 v[38:41], v[174:177], v[182:185], v[38:41]
	v_mfma_f32_16x16x32_bf16 v[30:33], v[158:161], v[206:209], v[30:33]
	v_mfma_f32_16x16x32_bf16 v[26:29], v[174:177], v[206:209], v[26:29]
	v_mfma_f32_16x16x32_bf16 v[22:25], v[158:161], v[214:217], v[22:25]
	v_mfma_f32_16x16x32_bf16 v[10:13], v[174:177], v[214:217], v[10:13]
	v_mfma_f32_16x16x32_bf16 v[6:9], v[158:161], v[222:225], v[6:9]
	v_mfma_f32_16x16x32_bf16 v[2:5], v[174:177], v[222:225], v[2:5]
	s_setprio 0
	s_barrier
	s_cmp_ge_u32 s30, s49
	s_mov_b64 s[28:29], s[30:31]
	s_cbranch_scc0 .LBB0_583
	s_and_b64 vcc, exec, s[18:19]
	s_cbranch_vccz .LBB0_586
	s_barrier

; #define PG8_STAGE(bufoff, gbase, voff) do { _Pragma("unroll") for (int _i = 0; _i < 2; ++_i) \
;         __builtin_amdgcn_global_load_lds((const unsigned*)((const char*)(gbase) + (voff)[_i]), (LAS unsigned*)(lds + (bufoff) + ldsw + _i * 8192), 16, 0, 0); } while (0)
; #define PG8_LDA(dst, b, h) do { _Pragma("unroll") for (int m = 0; m < 4; ++m) _Pragma("unroll") for (int k = 0; k < 2; ++k) dst[m][k] = *(const LAS bf16x8*)(lds + PG8_SA(b, h) + aoff + m * 2048 + k * 1024); } while (0)
; #define PG8_LDB(dst, b, h) do { _Pragma("unroll") for (int n = 0; n < 2; ++n) _Pragma("unroll") for (int k = 0; k < 2; ++k) dst[n][k] = *(const LAS bf16x8*)(lds + PG8_SB(b, h) + boff + n * 2048 + k * 1024); } while (0)
; #define PG8_MMA(ai, bj, At, Bt) do { __builtin_amdgcn_s_setprio(1); _Pragma("unroll") for (int m = 0; m < 4; ++m) _Pragma("unroll") for (int n = 0; n < 2; ++n) _Pragma("unroll") for (int k = 0; k < 2; ++k) \
;         acc[ai][bj][m][n] = __builtin_amdgcn_mfma_f32_16x16x32_bf16(Bt[n][k], At[m][k], acc[ai][bj][m][n], 0, 0, 0); __builtin_amdgcn_s_setprio(0); } while (0)
; #define PG8_WAIT_V(n) asm volatile("s_waitcnt vmcnt(" #n ")" ::: "memory")
; template <class Epi, bool ALIGN_EPI = PG8_ALIGN, bool SP2 = PG8_SP2>
; __device__ __forceinline__ void gemm_phase(LAS unsigned char* lds, const Gemm g, const StaticOrder& S, const Epi& E) {
;     ...
;                 for (int n = 0; n < 2; ++n) acc[a][b][m][n] = (f32x4){0.f, 0.f, 0.f, 0.f};
;     ...
;         for (int t = 0; t < nt; t += 2) {
;             const bool last = (t == nt - 2);
;             const char* a1 = cA + (size_t)(t + 1) * kstepA;
;             const char* a2 = last ? nA : cA + (size_t)(t + 2) * kstepA; const char* b2 = last ? nB : cB + (size_t)(t + 2) * kstepB;
;             const char* a3 = a2 + kstepA; const char* b3 = b2 + kstepB;
;             if constexpr (SP2) {
;             PG8_LDB(B0, 0, 0); PG8_LDB(B1, 0, 1); PG8_SCHED; PG8_LDA(At, 0, 0); PG8_STAGE(PG8_SA(1, 1), a1 + hstepA, voffA);
;             PG8_WAIT_V(8); PG8_WAIT_L(0); PG8_BAR; PG8_MMA(0, 0, At, B0); PG8_MMA(0, 1, At, B1); PG8_BAR; PG8_SCHED;
;             PG8_LDA(At, 0, 1); PG8_STAGE(PG8_SB(0, 0), b2, voffB); PG8_STAGE(PG8_SB(0, 1), b2 + hstepB, voffB); PG8_STAGE(PG8_SA(0, 0), a2, voffA);
;             PG8_WAIT_V(8); PG8_WAIT_L(0); PG8_BAR; PG8_MMA(1, 0, At, B0); PG8_MMA(1, 1, At, B1); PG8_BAR; PG8_SCHED;
.Lfirst_iter_u583:
	s_add_u32 s74, s28, 1
	s_addc_u32 s75, s29, 0
	s_add_u32 s30, s28, 2
	s_addc_u32 s31, s29, 0
	s_lshl_b64 s[34:35], s[30:31], s56
	s_add_u32 s29, s26, s34
	s_addc_u32 s36, s27, s35
	s_add_u32 s34, s24, s34
	s_addc_u32 s35, s25, s35
	s_cmp_eq_u32 s66, s28
	s_cselect_b32 s37, s21, s36
	s_cselect_b32 s36, s20, s29
	s_cselect_b32 s34, s22, s34
	s_cselect_b32 s35, s23, s35
	s_add_u32 s28, s36, s52
	s_addc_u32 s29, s37, 0
	s_add_i32 s73, 0, 0x10000
	s_add_i32 s76, 0, 0x14000
	v_add_u32_e32 v144, s73, v155
	v_add_u32_e32 v152, s76, v155
	ds_read_b128 v[132:135], v144
	ds_read_b128 v[136:139], v144 offset:1024
	ds_read_b128 v[140:143], v144 offset:2048
	ds_read_b128 v[144:147], v144 offset:3072
	ds_read_b128 v[148:151], v152
	ds_read_b128 v[158:161], v152 offset:1024
	ds_read_b128 v[170:173], v152 offset:2048
	ds_read_b128 v[174:177], v152 offset:3072
	s_lshl_b64 s[74:75], s[74:75], s56
	s_add_u32 s74, s71, s74
	s_addc_u32 s75, s72, s75
	v_lshl_add_u64 v[152:153], s[74:75], 0, v[0:1]
	s_add_i32 m0, s41, 0xc000
	ds_read_b128 v[178:181], v157
	ds_read_b128 v[182:185], v157 offset:1024
	ds_read_b128 v[186:189], v157 offset:2048
	ds_read_b128 v[206:209], v157 offset:3072
	ds_read_b128 v[210:213], v157 offset:4096
	ds_read_b128 v[214:217], v157 offset:5120
	ds_read_b128 v[218:221], v157 offset:6144
	ds_read_b128 v[222:225], v157 offset:7168
	global_load_lds_dwordx4 v[152:153], off
	v_lshl_add_u64 v[152:153], s[74:75], 0, v[130:131]
	s_add_i32 m0, s41, 0xe000
	s_nop 0
	global_load_lds_dwordx4 v[152:153], off
	s_waitcnt vmcnt(8)
	s_waitcnt lgkmcnt(0)
	s_barrier
	s_setprio 1
	s_waitcnt lgkmcnt(0)
	v_mfma_f32_16x16x32_bf16 v[126:129], v[132:135], v[178:181], 0
	v_mfma_f32_16x16x32_bf16 v[122:125], v[140:143], v[178:181], 0
	v_mfma_f32_16x16x32_bf16 v[118:121], v[132:135], v[186:189], 0
	v_mfma_f32_16x16x32_bf16 v[114:117], v[140:143], v[186:189], 0
	v_mfma_f32_16x16x32_bf16 v[110:113], v[132:135], v[210:213], 0
	v_mfma_f32_16x16x32_bf16 v[90:93], v[140:143], v[210:213], 0
	v_mfma_f32_16x16x32_bf16 v[86:89], v[132:135], v[218:221], 0
	v_mfma_f32_16x16x32_bf16 v[78:81], v[140:143], v[218:221], 0
	v_mfma_f32_16x16x32_bf16 v[126:129], v[136:139], v[182:185], v[126:129]
	v_mfma_f32_16x16x32_bf16 v[122:125], v[144:147], v[182:185], v[122:125]
	v_mfma_f32_16x16x32_bf16 v[118:121], v[136:139], v[206:209], v[118:121]
	v_mfma_f32_16x16x32_bf16 v[114:117], v[144:147], v[206:209], v[114:117]
	v_mfma_f32_16x16x32_bf16 v[110:113], v[136:139], v[214:217], v[110:113]
	v_mfma_f32_16x16x32_bf16 v[90:93], v[144:147], v[214:217], v[90:93]
	v_mfma_f32_16x16x32_bf16 v[86:89], v[136:139], v[222:225], v[86:89]
	v_mfma_f32_16x16x32_bf16 v[78:81], v[144:147], v[222:225], v[78:81]
	s_setprio 0
	s_setprio 1
	v_mfma_f32_16x16x32_bf16 v[106:109], v[148:151], v[178:181], 0
	v_mfma_f32_16x16x32_bf16 v[102:105], v[170:173], v[178:181], 0
	v_mfma_f32_16x16x32_bf16 v[98:101], v[148:151], v[186:189], 0
	v_mfma_f32_16x16x32_bf16 v[94:97], v[170:173], v[186:189], 0
	v_mfma_f32_16x16x32_bf16 v[82:85], v[148:151], v[210:213], 0
	v_mfma_f32_16x16x32_bf16 v[74:77], v[170:173], v[210:213], 0
	v_mfma_f32_16x16x32_bf16 v[70:73], v[148:151], v[218:221], 0
	v_mfma_f32_16x16x32_bf16 v[66:69], v[170:173], v[218:221], 0
	v_mfma_f32_16x16x32_bf16 v[106:109], v[158:161], v[182:185], v[106:109]
	v_mfma_f32_16x16x32_bf16 v[102:105], v[174:177], v[182:185], v[102:105]
	v_mfma_f32_16x16x32_bf16 v[98:101], v[158:161], v[206:209], v[98:101]
	v_mfma_f32_16x16x32_bf16 v[94:97], v[174:177], v[206:209], v[94:97]
	v_mfma_f32_16x16x32_bf16 v[82:85], v[158:161], v[214:217], v[82:85]
	v_mfma_f32_16x16x32_bf16 v[74:77], v[174:177], v[214:217], v[74:77]
	v_mfma_f32_16x16x32_bf16 v[70:73], v[158:161], v[222:225], v[70:73]
	v_mfma_f32_16x16x32_bf16 v[66:69], v[174:177], v[222:225], v[66:69]
	s_setprio 0
	s_barrier
	s_add_i32 s73, s73, s40
	v_lshl_add_u64 v[152:153], s[34:35], 0, v[0:1]
	s_mov_b32 m0, s73
	ds_read_b128 v[178:181], v157 offset:16384
	ds_read_b128 v[182:185], v157 offset:17408
	ds_read_b128 v[186:189], v157 offset:18432
	ds_read_b128 v[206:209], v157 offset:19456
	ds_read_b128 v[210:213], v157 offset:20480
	ds_read_b128 v[214:217], v157 offset:21504
	ds_read_b128 v[218:221], v157 offset:22528
	ds_read_b128 v[222:225], v157 offset:23552
	global_load_lds_dwordx4 v[152:153], off
	s_add_i32 m0, s73, 0x2000
	s_add_u32 s74, s34, s38
	v_lshl_add_u64 v[152:153], s[34:35], 0, v[130:131]
	s_addc_u32 s75, s35, s33
	s_add_i32 s73, s76, s40
	global_load_lds_dwordx4 v[152:153], off
	v_lshl_add_u64 v[152:153], s[74:75], 0, v[0:1]
	s_mov_b32 m0, s73
	s_nop 0
	global_load_lds_dwordx4 v[152:153], off
	v_lshl_add_u64 v[152:153], s[74:75], 0, v[130:131]
	s_add_i32 m0, s73, 0x2000
	s_nop 0
	global_load_lds_dwordx4 v[152:153], off
	v_lshl_add_u64 v[152:153], s[36:37], 0, v[0:1]
	s_mov_b32 m0, s41
	s_nop 0
	global_load_lds_dwordx4 v[152:153], off
	v_lshl_add_u64 v[152:153], s[36:37], 0, v[130:131]
	s_mov_b32 m0, s42
	s_nop 0
	global_load_lds_dwordx4 v[152:153], off
	s_waitcnt vmcnt(8)
	s_waitcnt lgkmcnt(0)
	s_barrier
; #define PG8_STAGE(bufoff, gbase, voff) do { _Pragma("unroll") for (int _i = 0; _i < 2; ++_i) \
;         __builtin_amdgcn_global_load_lds((const unsigned*)((const char*)(gbase) + (voff)[_i]), (LAS unsigned*)(lds + (bufoff) + ldsw + _i * 8192), 16, 0, 0); } while (0)
; #define PG8_LDA(dst, b, h) do { _Pragma("unroll") for (int m = 0; m < 4; ++m) _Pragma("unroll") for (int k = 0; k < 2; ++k) dst[m][k] = *(const LAS bf16x8*)(lds + PG8_SA(b, h) + aoff + m * 2048 + k * 1024); } while (0)
; #define PG8_LDB(dst, b, h) do { _Pragma("unroll") for (int n = 0; n < 2; ++n) _Pragma("unroll") for (int k = 0; k < 2; ++k) dst[n][k] = *(const LAS bf16x8*)(lds + PG8_SB(b, h) + boff + n * 2048 + k * 1024); } while (0)
; #define PG8_MMA(ai, bj, At, Bt) do { __builtin_amdgcn_s_setprio(1); _Pragma("unroll") for (int m = 0; m < 4; ++m) _Pragma("unroll") for (int n = 0; n < 2; ++n) _Pragma("unroll") for (int k = 0; k < 2; ++k) \
;         acc[ai][bj][m][n] = __builtin_amdgcn_mfma_f32_16x16x32_bf16(Bt[n][k], At[m][k], acc[ai][bj][m][n], 0, 0, 0); __builtin_amdgcn_s_setprio(0); } while (0)
; #define PG8_WAIT_V(n) asm volatile("s_waitcnt vmcnt(" #n ")" ::: "memory")
; #define PG8_WAIT_L(n) asm volatile("s_waitcnt lgkmcnt(" #n ")" ::: "memory")
; #define PG8_BAR __builtin_amdgcn_s_barrier()
; #define PG8_SCHED __builtin_amdgcn_sched_barrier(0)
; template <class Epi, bool ALIGN_EPI = PG8_ALIGN, bool SP2 = PG8_SP2>
; __device__ __forceinline__ void gemm_phase(LAS unsigned char* lds, const Gemm g, const StaticOrder& S, const Epi& E) {
;     ...
;             PG8_WAIT_V(8); PG8_WAIT_L(0); PG8_BAR; PG8_MMA(1, 0, At, B0); PG8_MMA(1, 1, At, B1); PG8_BAR; PG8_SCHED;
;             PG8_LDB(B0, 1, 0); PG8_LDB(B1, 1, 1); PG8_SCHED; PG8_LDA(At, 1, 0); PG8_STAGE(PG8_SA(0, 1), a2 + hstepA, voffA);
;             PG8_WAIT_V(8); PG8_WAIT_L(0); PG8_BAR; PG8_MMA(0, 0, At, B0); PG8_MMA(0, 1, At, B1); PG8_BAR; PG8_SCHED;
	s_setprio 1
	s_waitcnt lgkmcnt(0)
	v_mfma_f32_16x16x32_bf16 v[62:65], v[132:135], v[178:181], 0
	v_mfma_f32_16x16x32_bf16 v[58:61], v[140:143], v[178:181], 0
	v_mfma_f32_16x16x32_bf16 v[54:57], v[132:135], v[186:189], 0
	v_mfma_f32_16x16x32_bf16 v[50:53], v[140:143], v[186:189], 0
	v_mfma_f32_16x16x32_bf16 v[46:49], v[132:135], v[210:213], 0
	v_mfma_f32_16x16x32_bf16 v[34:37], v[140:143], v[210:213], 0
	v_mfma_f32_16x16x32_bf16 v[18:21], v[132:135], v[218:221], 0
	v_mfma_f32_16x16x32_bf16 v[14:17], v[140:143], v[218:221], 0
	v_mfma_f32_16x16x32_bf16 v[62:65], v[136:139], v[182:185], v[62:65]
	v_mfma_f32_16x16x32_bf16 v[58:61], v[144:147], v[182:185], v[58:61]
	v_mfma_f32_16x16x32_bf16 v[54:57], v[136:139], v[206:209], v[54:57]
	v_mfma_f32_16x16x32_bf16 v[50:53], v[144:147], v[206:209], v[50:53]
	v_mfma_f32_16x16x32_bf16 v[46:49], v[136:139], v[214:217], v[46:49]
	v_mfma_f32_16x16x32_bf16 v[34:37], v[144:147], v[214:217], v[34:37]
	v_mfma_f32_16x16x32_bf16 v[18:21], v[136:139], v[222:225], v[18:21]
	v_mfma_f32_16x16x32_bf16 v[14:17], v[144:147], v[222:225], v[14:17]
	s_setprio 0
	s_setprio 1
	v_mfma_f32_16x16x32_bf16 v[42:45], v[148:151], v[178:181], 0
	v_mfma_f32_16x16x32_bf16 v[38:41], v[170:173], v[178:181], 0
	v_mfma_f32_16x16x32_bf16 v[30:33], v[148:151], v[186:189], 0
	v_mfma_f32_16x16x32_bf16 v[26:29], v[170:173], v[186:189], 0
	v_mfma_f32_16x16x32_bf16 v[22:25], v[148:151], v[210:213], 0
	v_mfma_f32_16x16x32_bf16 v[10:13], v[170:173], v[210:213], 0
	v_mfma_f32_16x16x32_bf16 v[6:9], v[148:151], v[218:221], 0
	v_mfma_f32_16x16x32_bf16 v[2:5], v[170:173], v[218:221], 0
	v_mfma_f32_16x16x32_bf16 v[42:45], v[158:161], v[182:185], v[42:45]
	v_mfma_f32_16x16x32_bf16 v[38:41], v[174:177], v[182:185], v[38:41]
	v_mfma_f32_16x16x32_bf16 v[30:33], v[158:161], v[206:209], v[30:33]
	v_mfma_f32_16x16x32_bf16 v[26:29], v[174:177], v[206:209], v[26:29]
	v_mfma_f32_16x16x32_bf16 v[22:25], v[158:161], v[214:217], v[22:25]
	v_mfma_f32_16x16x32_bf16 v[10:13], v[174:177], v[214:217], v[10:13]
	v_mfma_f32_16x16x32_bf16 v[6:9], v[158:161], v[222:225], v[6:9]
	v_mfma_f32_16x16x32_bf16 v[2:5], v[174:177], v[222:225], v[2:5]
	s_setprio 0
	s_barrier
	s_add_i32 s73, 0, 0x18000
	s_add_i32 s74, 0, 0x1c000
	v_add_u32_e32 v144, s73, v155
	v_add_u32_e32 v152, s74, v155
	ds_read_b128 v[132:135], v144
	ds_read_b128 v[136:139], v144 offset:1024
	ds_read_b128 v[140:143], v144 offset:2048
	ds_read_b128 v[144:147], v144 offset:3072
	ds_read_b128 v[148:151], v152
	ds_read_b128 v[158:161], v152 offset:1024
	ds_read_b128 v[170:173], v152 offset:2048
	ds_read_b128 v[174:177], v152 offset:3072
	s_add_u32 s36, s36, s38
	s_addc_u32 s37, s37, s33
	s_mov_b32 m0, s43
	v_lshl_add_u64 v[152:153], s[36:37], 0, v[0:1]
	ds_read_b128 v[178:181], v157 offset:32768
	ds_read_b128 v[182:185], v157 offset:33792
	ds_read_b128 v[186:189], v157 offset:34816
	ds_read_b128 v[206:209], v157 offset:35840
	ds_read_b128 v[210:213], v157 offset:36864
	ds_read_b128 v[214:217], v157 offset:37888
	ds_read_b128 v[218:221], v157 offset:38912
	ds_read_b128 v[222:225], v157 offset:39936
	global_load_lds_dwordx4 v[152:153], off
	v_lshl_add_u64 v[152:153], s[36:37], 0, v[130:131]
	s_mov_b32 m0, s44
	s_nop 0
	global_load_lds_dwordx4 v[152:153], off
	s_waitcnt vmcnt(8)
	s_waitcnt lgkmcnt(0)
	s_barrier
	s_setprio 1
	s_waitcnt lgkmcnt(0)
	v_mfma_f32_16x16x32_bf16 v[126:129], v[132:135], v[178:181], v[126:129]
	v_mfma_f32_16x16x32_bf16 v[122:125], v[140:143], v[178:181], v[122:125]
	v_mfma_f32_16x16x32_bf16 v[118:121], v[132:135], v[186:189], v[118:121]
	v_mfma_f32_16x16x32_bf16 v[114:117], v[140:143], v[186:189], v[114:117]
	v_mfma_f32_16x16x32_bf16 v[110:113], v[132:135], v[210:213], v[110:113]
	v_mfma_f32_16x16x32_bf16 v[90:93], v[140:143], v[210:213], v[90:93]
	v_mfma_f32_16x16x32_bf16 v[86:89], v[132:135], v[218:221], v[86:89]
	v_mfma_f32_16x16x32_bf16 v[78:81], v[140:143], v[218:221], v[78:81]
	v_mfma_f32_16x16x32_bf16 v[126:129], v[136:139], v[182:185], v[126:129]
	v_mfma_f32_16x16x32_bf16 v[122:125], v[144:147], v[182:185], v[122:125]
	v_mfma_f32_16x16x32_bf16 v[118:121], v[136:139], v[206:209], v[118:121]
	v_mfma_f32_16x16x32_bf16 v[114:117], v[144:147], v[206:209], v[114:117]
	v_mfma_f32_16x16x32_bf16 v[110:113], v[136:139], v[214:217], v[110:113]
	v_mfma_f32_16x16x32_bf16 v[90:93], v[144:147], v[214:217], v[90:93]
	v_mfma_f32_16x16x32_bf16 v[86:89], v[136:139], v[222:225], v[86:89]
	v_mfma_f32_16x16x32_bf16 v[78:81], v[144:147], v[222:225], v[78:81]
	s_setprio 0
	s_setprio 1
	v_mfma_f32_16x16x32_bf16 v[106:109], v[148:151], v[178:181], v[106:109]
	v_mfma_f32_16x16x32_bf16 v[102:105], v[170:173], v[178:181], v[102:105]
	v_mfma_f32_16x16x32_bf16 v[98:101], v[148:151], v[186:189], v[98:101]
	v_mfma_f32_16x16x32_bf16 v[94:97], v[170:173], v[186:189], v[94:97]
	v_mfma_f32_16x16x32_bf16 v[82:85], v[148:151], v[210:213], v[82:85]
	v_mfma_f32_16x16x32_bf16 v[74:77], v[170:173], v[210:213], v[74:77]
	v_mfma_f32_16x16x32_bf16 v[70:73], v[148:151], v[218:221], v[70:73]
	v_mfma_f32_16x16x32_bf16 v[66:69], v[170:173], v[218:221], v[66:69]
	v_mfma_f32_16x16x32_bf16 v[106:109], v[158:161], v[182:185], v[106:109]
	v_mfma_f32_16x16x32_bf16 v[102:105], v[174:177], v[182:185], v[102:105]
	v_mfma_f32_16x16x32_bf16 v[98:101], v[158:161], v[206:209], v[98:101]
	v_mfma_f32_16x16x32_bf16 v[94:97], v[174:177], v[206:209], v[94:97]
	v_mfma_f32_16x16x32_bf16 v[82:85], v[158:161], v[214:217], v[82:85]
	v_mfma_f32_16x16x32_bf16 v[74:77], v[174:177], v[214:217], v[74:77]
	v_mfma_f32_16x16x32_bf16 v[70:73], v[158:161], v[222:225], v[70:73]
	v_mfma_f32_16x16x32_bf16 v[66:69], v[174:177], v[222:225], v[66:69]
	s_setprio 0
	s_barrier
; #define PG8_STAGE(bufoff, gbase, voff) do { _Pragma("unroll") for (int _i = 0; _i < 2; ++_i) \
;         __builtin_amdgcn_global_load_lds((const unsigned*)((const char*)(gbase) + (voff)[_i]), (LAS unsigned*)(lds + (bufoff) + ldsw + _i * 8192), 16, 0, 0); } while (0)
; #define PG8_LDA(dst, b, h) do { _Pragma("unroll") for (int m = 0; m < 4; ++m) _Pragma("unroll") for (int k = 0; k < 2; ++k) dst[m][k] = *(const LAS bf16x8*)(lds + PG8_SA(b, h) + aoff + m * 2048 + k * 1024); } while (0)
; #define PG8_MMA(ai, bj, At, Bt) do { __builtin_amdgcn_s_setprio(1); _Pragma("unroll") for (int m = 0; m < 4; ++m) _Pragma("unroll") for (int n = 0; n < 2; ++n) _Pragma("unroll") for (int k = 0; k < 2; ++k) \
;         acc[ai][bj][m][n] = __builtin_amdgcn_mfma_f32_16x16x32_bf16(Bt[n][k], At[m][k], acc[ai][bj][m][n], 0, 0, 0); __builtin_amdgcn_s_setprio(0); } while (0)
; #define PG8_WAIT_V(n) asm volatile("s_waitcnt vmcnt(" #n ")" ::: "memory")
; #define PG8_WAIT_L(n) asm volatile("s_waitcnt lgkmcnt(" #n ")" ::: "memory")
; #define PG8_BAR __builtin_amdgcn_s_barrier()
; #define PG8_SCHED __builtin_amdgcn_sched_barrier(0)
; template <class Epi, bool ALIGN_EPI = PG8_ALIGN, bool SP2 = PG8_SP2>
; __device__ __forceinline__ void gemm_phase(LAS unsigned char* lds, const Gemm g, const StaticOrder& S, const Epi& E) {
;     ...
;             PG8_LDA(At, 1, 1); PG8_STAGE(PG8_SB(1, 0), b3, voffB); PG8_STAGE(PG8_SB(1, 1), b3 + hstepB, voffB); PG8_STAGE(PG8_SA(1, 0), a3, voffA);
;             PG8_WAIT_V(8); PG8_WAIT_L(0); PG8_BAR; PG8_MMA(1, 0, At, B0); PG8_MMA(1, 1, At, B1); PG8_BAR; PG8_SCHED;
	s_add_u32 s34, s34, s52
	s_addc_u32 s35, s35, 0
	s_add_i32 s36, s73, s40
	v_lshl_add_u64 v[152:153], s[34:35], 0, v[0:1]
	s_mov_b32 m0, s36
	ds_read_b128 v[178:181], v157 offset:49152
	ds_read_b128 v[182:185], v157 offset:50176
	ds_read_b128 v[186:189], v157 offset:51200
	ds_read_b128 v[206:209], v157 offset:52224
	ds_read_b128 v[210:213], v157 offset:53248
	ds_read_b128 v[214:217], v157 offset:54272
	ds_read_b128 v[218:221], v157 offset:55296
	ds_read_b128 v[222:225], v157 offset:56320
	global_load_lds_dwordx4 v[152:153], off
	s_add_i32 m0, s36, 0x2000
	v_lshl_add_u64 v[152:153], s[34:35], 0, v[130:131]
	s_add_u32 s34, s34, s38
	s_addc_u32 s35, s35, s33
	s_add_i32 s36, s74, s40
	global_load_lds_dwordx4 v[152:153], off
	v_lshl_add_u64 v[152:153], s[34:35], 0, v[0:1]
	s_mov_b32 m0, s36
	s_nop 0
	global_load_lds_dwordx4 v[152:153], off
	v_lshl_add_u64 v[152:153], s[34:35], 0, v[130:131]
	s_add_i32 m0, s36, 0x2000
	s_nop 0
	global_load_lds_dwordx4 v[152:153], off
	v_lshl_add_u64 v[152:153], s[28:29], 0, v[0:1]
	s_mov_b32 m0, s53
	s_nop 0
	global_load_lds_dwordx4 v[152:153], off
	v_lshl_add_u64 v[152:153], s[28:29], 0, v[130:131]
	s_mov_b32 m0, s54
	s_nop 0
	global_load_lds_dwordx4 v[152:153], off
	s_waitcnt vmcnt(8)
	s_waitcnt lgkmcnt(0)
	s_barrier
	s_setprio 1
	s_waitcnt lgkmcnt(0)
	v_mfma_f32_16x16x32_bf16 v[62:65], v[132:135], v[178:181], v[62:65]
	v_mfma_f32_16x16x32_bf16 v[58:61], v[140:143], v[178:181], v[58:61]
	v_mfma_f32_16x16x32_bf16 v[54:57], v[132:135], v[186:189], v[54:57]
	v_mfma_f32_16x16x32_bf16 v[50:53], v[140:143], v[186:189], v[50:53]
	v_mfma_f32_16x16x32_bf16 v[46:49], v[132:135], v[210:213], v[46:49]
	v_mfma_f32_16x16x32_bf16 v[34:37], v[140:143], v[210:213], v[34:37]
	v_mfma_f32_16x16x32_bf16 v[18:21], v[132:135], v[218:221], v[18:21]
	v_mfma_f32_16x16x32_bf16 v[14:17], v[140:143], v[218:221], v[14:17]
	v_mfma_f32_16x16x32_bf16 v[62:65], v[136:139], v[182:185], v[62:65]
	v_mfma_f32_16x16x32_bf16 v[58:61], v[144:147], v[182:185], v[58:61]
	v_mfma_f32_16x16x32_bf16 v[54:57], v[136:139], v[206:209], v[54:57]
	v_mfma_f32_16x16x32_bf16 v[50:53], v[144:147], v[206:209], v[50:53]
	v_mfma_f32_16x16x32_bf16 v[46:49], v[136:139], v[214:217], v[46:49]
	v_mfma_f32_16x16x32_bf16 v[34:37], v[144:147], v[214:217], v[34:37]
	v_mfma_f32_16x16x32_bf16 v[18:21], v[136:139], v[222:225], v[18:21]
	v_mfma_f32_16x16x32_bf16 v[14:17], v[144:147], v[222:225], v[14:17]
	s_setprio 0
	s_setprio 1
	v_mfma_f32_16x16x32_bf16 v[42:45], v[148:151], v[178:181], v[42:45]
	v_mfma_f32_16x16x32_bf16 v[38:41], v[170:173], v[178:181], v[38:41]
	v_mfma_f32_16x16x32_bf16 v[30:33], v[148:151], v[186:189], v[30:33]
	v_mfma_f32_16x16x32_bf16 v[26:29], v[170:173], v[186:189], v[26:29]
	v_mfma_f32_16x16x32_bf16 v[22:25], v[148:151], v[210:213], v[22:25]
	v_mfma_f32_16x16x32_bf16 v[10:13], v[170:173], v[210:213], v[10:13]
	v_mfma_f32_16x16x32_bf16 v[6:9], v[148:151], v[218:221], v[6:9]
	v_mfma_f32_16x16x32_bf16 v[2:5], v[170:173], v[218:221], v[2:5]
	v_mfma_f32_16x16x32_bf16 v[42:45], v[158:161], v[182:185], v[42:45]
	v_mfma_f32_16x16x32_bf16 v[38:41], v[174:177], v[182:185], v[38:41]
	v_mfma_f32_16x16x32_bf16 v[30:33], v[158:161], v[206:209], v[30:33]
	v_mfma_f32_16x16x32_bf16 v[26:29], v[174:177], v[206:209], v[26:29]
	v_mfma_f32_16x16x32_bf16 v[22:25], v[158:161], v[214:217], v[22:25]
	v_mfma_f32_16x16x32_bf16 v[10:13], v[174:177], v[214:217], v[10:13]
	v_mfma_f32_16x16x32_bf16 v[6:9], v[158:161], v[222:225], v[6:9]
	v_mfma_f32_16x16x32_bf16 v[2:5], v[174:177], v[222:225], v[2:5]
	s_setprio 0
	s_barrier
	s_cmp_ge_u32 s30, s49
	s_mov_b64 s[28:29], s[30:31]
	s_branch .LBB0_583
